# EpiRes ssq 32-lane reduction via DPP instead of ds_bpermute butterfly; attention QK fragment ring prefetch
# speedup vs baseline: 1.0693x; 1.0071x over previous
.LBB0_145:
	s_or_b64 exec, exec, s[8:9]
	s_movk_i32 s9, 0x410
	v_lshrrev_b32_e32 v130, 2, v140
	v_lshlrev_b32_e32 v131, 1, v140
	v_and_b32_e32 v0, 15, v140
	v_and_b32_e32 v130, 0xfffffcc, v130
	v_and_b32_e32 v131, 0x180, v131
	v_add_u32_e32 v131, 0, v131
	v_lshlrev_b32_e32 v0, 2, v0
	v_mul_lo_u32 v130, v130, s9
	v_add3_u32 v130, v131, v0, v130
	s_waitcnt vmcnt(0)
	s_barrier
	ds_write2_b32 v130, v114, v126 offset1:16
	v_add_u32_e32 v114, 0x400, v130
	ds_write2_b32 v114, v115, v127 offset0:4 offset1:20
	v_add_u32_e32 v115, 0x800, v130
	ds_write2_b32 v115, v116, v128 offset0:8 offset1:24
	v_add_u32_e32 v116, 0xc00, v130
	ds_write2_b32 v116, v117, v129 offset0:12 offset1:28
	v_add_u32_e32 v117, 0x4000, v130
	ds_write2_b32 v117, v82, v94 offset0:64 offset1:80
	v_add_u32_e32 v82, 0x4400, v130
	ds_write2_b32 v82, v83, v95 offset0:68 offset1:84
	v_add_u32_e32 v83, 0x4800, v130
	ds_write2_b32 v83, v84, v96 offset0:72 offset1:88
	v_add_u32_e32 v84, 0x4c00, v130
	ds_write2_b32 v84, v85, v97 offset0:76 offset1:92
	v_add_u32_e32 v85, 0x8000, v130
	ds_write2_b32 v85, v74, v78 offset0:128 offset1:144
	v_add_u32_e32 v74, 0x8400, v130
	ds_write2_b32 v74, v75, v79 offset0:132 offset1:148
	v_add_u32_e32 v75, 0x8800, v130
	ds_write2_b32 v75, v76, v80 offset0:136 offset1:152
	v_add_u32_e32 v76, 0x8c00, v130
	v_add_u32_e32 v80, 0xc000, v130
	ds_write2_b32 v76, v77, v81 offset0:140 offset1:156
	ds_write2_b32 v80, v66, v70 offset0:192 offset1:208
	v_add_u32_e32 v77, 0xc400, v130
	v_add_u32_e32 v78, 0xc800, v130
	v_add_u32_e32 v79, 0xcc00, v130
	v_add_u32_e32 v81, 0x9000, v130
	v_lshlrev_b32_e32 v66, 2, v140
	ds_write2_b32 v77, v67, v71 offset0:196 offset1:212
	ds_write2_b32 v78, v68, v72 offset0:200 offset1:216
	ds_write2_b32 v79, v69, v73 offset0:204 offset1:220
	ds_write2_b32 v130, v98, v118 offset0:128 offset1:144
	ds_write2_b32 v114, v99, v119 offset0:132 offset1:148
	ds_write2_b32 v115, v100, v120 offset0:136 offset1:152
	ds_write2_b32 v116, v101, v121 offset0:140 offset1:156
	ds_write2_b32 v117, v102, v122 offset0:192 offset1:208
	ds_write2_b32 v82, v103, v123 offset0:196 offset1:212
	ds_write2_b32 v83, v104, v124 offset0:200 offset1:216
	ds_write2_b32 v84, v105, v125 offset0:204 offset1:220
	ds_write2_b32 v74, v90, v110 offset1:16
	ds_write2_b32 v75, v91, v111 offset0:4 offset1:20
	ds_write2_b32 v76, v92, v112 offset0:8 offset1:24
	ds_write2_b32 v81, v93, v113 offset0:12 offset1:28
	ds_write2_b32 v77, v86, v106 offset0:64 offset1:80
	ds_write2_b32 v78, v87, v107 offset0:68 offset1:84
	ds_write2_b32 v79, v88, v108 offset0:72 offset1:88
	v_lshlrev_b32_e32 v0, 3, v140
	v_and_b32_e32 v66, 12, v66
	s_movk_i32 s8, 0xe0
	v_ashrrev_i32_e32 v87, 5, v140
	v_and_or_b32 v0, v0, s8, v66
	v_add_u32_e32 v68, s39, v87
	v_or_b32_e32 v66, s36, v0
	v_ashrrev_i32_e32 v69, 31, v68
	v_ashrrev_i32_e32 v67, 31, v66
	v_lshlrev_b64 v[70:71], 10, v[68:69]
	v_lshl_add_u64 v[98:99], v[70:71], 0, v[66:67]
	v_add_u32_e32 v86, 0xd000, v130
	v_lshl_add_u64 v[110:111], v[98:99], 2, s[26:27]
	ds_write2_b32 v86, v89, v109 offset0:76 offset1:92
	s_waitcnt lgkmcnt(0)
	s_barrier
	v_lshlrev_b32_e32 v141, 2, v98
	global_load_dwordx4 v[132:135], v141, s[26:27]
	global_load_dwordx4 v[136:139], v141, s[26:27] offset:64
	v_add_u32_e32 v141, 0x10000, v141
	global_load_dwordx4 v[142:145], v141, s[26:27]
	global_load_dwordx4 v[146:149], v141, s[26:27] offset:64
	v_add_u32_e32 v141, 0x10000, v141
	global_load_dwordx4 v[150:153], v141, s[26:27]
	global_load_dwordx4 v[154:157], v141, s[26:27] offset:64
	v_add_u32_e32 v141, 0x10000, v141
	global_load_dwordx4 v[158:161], v141, s[26:27]
	global_load_dwordx4 v[162:165], v141, s[26:27] offset:64
	v_add_u32_e32 v141, 0x10000, v141
	global_load_dwordx4 v[166:169], v141, s[26:27]
	global_load_dwordx4 v[170:173], v141, s[26:27] offset:64
	v_add_u32_e32 v141, 0x10000, v141
	global_load_dwordx4 v[174:177], v141, s[26:27]
	global_load_dwordx4 v[178:181], v141, s[26:27] offset:64
	v_add_u32_e32 v141, 0x10000, v141
	global_load_dwordx4 v[182:185], v141, s[26:27]
	global_load_dwordx4 v[186:189], v141, s[26:27] offset:64
	v_add_u32_e32 v141, 0x10000, v141
	global_load_dwordx4 v[190:193], v141, s[26:27]
	global_load_dwordx4 v[194:197], v141, s[26:27] offset:64
	v_lshl_add_u32 v101, v0, 2, 0
	v_mul_lo_u32 v72, v87, s9
	v_add_u32_e32 v88, v101, v72
	ds_read_b128 v[102:105], v88
	ds_read_b128 v[106:109], v88 offset:64
	v_and_b32_e32 v70, 64, v218
	v_xor_b32_e32 v0, 1, v218
	v_add_u32_e32 v100, 64, v70
	v_cmp_lt_i32_e32 vcc, v0, v100
	v_xor_b32_e32 v70, 2, v218
	v_xor_b32_e32 v71, 4, v218
	v_cndmask_b32_e32 v0, v218, v0, vcc
	v_lshlrev_b32_e32 v0, 2, v0
	v_cmp_lt_i32_e32 vcc, v70, v100
	v_xor_b32_e32 v112, 8, v218
	v_and_b32_e32 v89, 31, v140
	v_cndmask_b32_e32 v70, v218, v70, vcc
	v_lshlrev_b32_e32 v70, 2, v70
	v_cmp_lt_i32_e32 vcc, v71, v100
	s_ashr_i32 s57, s56, 31
	s_lshl_b64 s[8:9], s[56:57], 2
	v_cndmask_b32_e32 v71, v218, v71, vcc
	v_cmp_lt_i32_e32 vcc, v112, v100
	v_lshlrev_b32_e32 v71, 2, v71
	s_add_u32 s8, s46, s8
	s_movk_i32 s14, 0x410
	s_addc_u32 s9, s47, s9
	s_waitcnt lgkmcnt(1)
	s_waitcnt vmcnt(15)
	v_pk_fma_f32 v[90:91], v[102:103], 0.5, v[132:133] op_sel_hi:[1,0,1]
	s_waitcnt vmcnt(15)
	v_pk_fma_f32 v[92:93], v[104:105], 0.5, v[134:135] op_sel_hi:[1,0,1]
	v_pk_mul_f32 v[72:73], v[90:91], v[90:91]
	v_pk_mul_f32 v[102:103], v[92:93], v[92:93]
	v_add_f32_e32 v72, v72, v73
	s_waitcnt lgkmcnt(0)
	s_waitcnt vmcnt(14)
	v_pk_fma_f32 v[94:95], v[106:107], 0.5, v[136:137] op_sel_hi:[1,0,1]
	v_add_f32_e32 v72, v102, v72
	v_pk_mul_f32 v[104:105], v[94:95], v[94:95]
	v_add_f32_e32 v72, v103, v72
	s_waitcnt vmcnt(14)
	v_pk_fma_f32 v[96:97], v[108:109], 0.5, v[138:139] op_sel_hi:[1,0,1]
	v_add_f32_e32 v72, v104, v72
	v_pk_mul_f32 v[106:107], v[96:97], v[96:97]
	v_add_f32_e32 v72, v105, v72
	v_add_f32_e32 v72, v106, v72
	v_add_f32_e32 v72, v107, v72
	ds_bpermute_b32 v102, v0, v72
	v_xor_b32_e32 v103, 16, v218
	v_cndmask_b32_e32 v73, v218, v112, vcc
	v_cmp_lt_i32_e32 vcc, v103, v100
	v_lshlrev_b32_e32 v73, 2, v73
	s_waitcnt lgkmcnt(0)
	v_add_f32_e32 v102, v72, v102
	ds_bpermute_b32 v104, v70, v102
	v_cndmask_b32_e32 v72, v218, v103, vcc
	v_cmp_eq_u32_e32 vcc, 31, v89
	v_lshlrev_b32_e32 v72, 2, v72
	global_store_dwordx4 v[110:111], v[90:93], off
	s_waitcnt lgkmcnt(0)
	v_add_f32_e32 v89, v102, v104
	ds_bpermute_b32 v100, v71, v89
	v_cvt_pk_bf16_f32 v102, v90, v91
	global_store_dwordx4 v[110:111], v[94:97], off offset:64
	v_cvt_pk_bf16_f32 v103, v92, v93
	v_lshl_add_u64 v[92:93], v[98:99], 1, s[44:45]
	s_waitcnt lgkmcnt(0)
	v_add_f32_e32 v89, v89, v100
	ds_bpermute_b32 v100, v73, v89
	v_cvt_pk_bf16_f32 v94, v94, v95
	v_cvt_pk_bf16_f32 v95, v96, v97
	global_store_dwordx2 v[92:93], v[102:103], off
	global_store_dwordx2 v[92:93], v[94:95], off offset:32
	s_waitcnt lgkmcnt(0)
	v_add_f32_e32 v89, v89, v100
	ds_bpermute_b32 v90, v72, v89
	s_and_saveexec_b64 s[10:11], vcc
	v_readlane_b32 s62, v253, 50
	s_cbranch_execz .LBB0_147
	s_waitcnt lgkmcnt(0)
	v_add_f32_e32 v89, v89, v90
	v_lshl_add_u64 v[68:69], v[68:69], 4, s[8:9]
	global_store_dword v[68:69], v89, off
.LBB0_147:
	s_or_b64 exec, exec, s[10:11]
	v_add_u32_e32 v68, 0x200, v140
	s_waitcnt lgkmcnt(0)
	v_ashrrev_i32_e32 v90, 5, v68
	v_mul_lo_u32 v68, v90, s14
	v_add_u32_e32 v89, v101, v68
	v_add_u32_e32 v68, s39, v90
	v_ashrrev_i32_e32 v69, 31, v68
	v_lshlrev_b64 v[92:93], 10, v[68:69]
	v_lshl_add_u64 v[106:107], v[92:93], 0, v[66:67]
	v_lshl_add_u64 v[108:109], v[106:107], 2, s[26:27]
	ds_read_b128 v[92:95], v89
	s_waitcnt lgkmcnt(0)
	s_waitcnt vmcnt(18)
	v_pk_fma_f32 v[92:93], v[92:93], 0.5, v[142:143] op_sel_hi:[1,0,1]
	s_waitcnt vmcnt(18)
	v_pk_fma_f32 v[94:95], v[94:95], 0.5, v[144:145] op_sel_hi:[1,0,1]
	ds_read_b128 v[96:99], v89 offset:64
	global_store_dwordx4 v[108:109], v[92:95], off
	s_waitcnt lgkmcnt(0)
	s_waitcnt vmcnt(18)
	v_pk_fma_f32 v[96:97], v[96:97], 0.5, v[146:147] op_sel_hi:[1,0,1]
	v_cvt_pk_bf16_f32 v102, v92, v93
	v_pk_mul_f32 v[92:93], v[92:93], v[92:93]
	v_cvt_pk_bf16_f32 v103, v94, v95
	v_pk_mul_f32 v[94:95], v[94:95], v[94:95]
	v_add_f32_e32 v91, v92, v93
	s_waitcnt vmcnt(18)
	v_pk_fma_f32 v[98:99], v[98:99], 0.5, v[148:149] op_sel_hi:[1,0,1]
	v_lshl_add_u64 v[104:105], v[106:107], 1, s[44:45]
	v_add_f32_e32 v91, v94, v91
	global_store_dwordx4 v[108:109], v[96:99], off offset:64
	global_store_dwordx2 v[104:105], v[102:103], off
	v_cvt_pk_bf16_f32 v102, v96, v97
	v_pk_mul_f32 v[96:97], v[96:97], v[96:97]
	v_add_f32_e32 v91, v95, v91
	v_add_f32_e32 v91, v96, v91
	v_cvt_pk_bf16_f32 v103, v98, v99
	v_pk_mul_f32 v[98:99], v[98:99], v[98:99]
	v_add_f32_e32 v91, v97, v91
	v_add_f32_e32 v91, v98, v91
	v_add_f32_e32 v91, v99, v91
	s_nop 1
	v_add_f32_dpp v91, v91, v91 quad_perm:[1,0,3,2] row_mask:0xf bank_mask:0xf
	s_nop 1
	v_add_f32_dpp v91, v91, v91 quad_perm:[2,3,0,1] row_mask:0xf bank_mask:0xf
	s_nop 1
	v_add_f32_dpp v91, v91, v91 row_half_mirror row_mask:0xf bank_mask:0xf
	s_nop 1
	v_add_f32_dpp v91, v91, v91 row_mirror row_mask:0xf bank_mask:0xf
	s_nop 1
	v_add_f32_dpp v91, v91, v91 row_bcast:15 row_mask:0xa bank_mask:0xf
	global_store_dwordx2 v[104:105], v[102:103], off offset:32
	s_and_saveexec_b64 s[10:11], vcc
	s_cbranch_execz .LBB0_149
	v_lshl_add_u64 v[68:69], v[68:69], 4, s[8:9]
	global_store_dword v[68:69], v91, off
.LBB0_149:
	s_or_b64 exec, exec, s[10:11]
	v_add_u32_e32 v68, 0x400, v140
	s_waitcnt lgkmcnt(0)
	v_ashrrev_i32_e32 v92, 5, v68
	v_mul_lo_u32 v68, v92, s14
	v_add_u32_e32 v91, v101, v68
	v_add_u32_e32 v68, s39, v92
	v_ashrrev_i32_e32 v69, 31, v68
	v_lshlrev_b64 v[94:95], 10, v[68:69]
	v_lshl_add_u64 v[98:99], v[94:95], 0, v[66:67]
	v_lshl_add_u64 v[110:111], v[98:99], 2, s[26:27]
	ds_read_b128 v[94:97], v91
	v_lshl_add_u64 v[98:99], v[98:99], 1, s[44:45]
	s_waitcnt lgkmcnt(0)
	s_waitcnt vmcnt(21)
	v_pk_fma_f32 v[94:95], v[94:95], 0.5, v[150:151] op_sel_hi:[1,0,1]
	s_waitcnt vmcnt(21)
	v_pk_fma_f32 v[96:97], v[96:97], 0.5, v[152:153] op_sel_hi:[1,0,1]
	ds_read_b128 v[102:105], v91 offset:64
	global_store_dwordx4 v[110:111], v[94:97], off
	s_waitcnt lgkmcnt(0)
	s_waitcnt vmcnt(21)
	v_pk_fma_f32 v[102:103], v[102:103], 0.5, v[154:155] op_sel_hi:[1,0,1]
	v_cvt_pk_bf16_f32 v106, v94, v95
	v_pk_mul_f32 v[94:95], v[94:95], v[94:95]
	s_waitcnt vmcnt(21)
	v_pk_fma_f32 v[104:105], v[104:105], 0.5, v[156:157] op_sel_hi:[1,0,1]
	v_cvt_pk_bf16_f32 v107, v96, v97
	v_pk_mul_f32 v[96:97], v[96:97], v[96:97]
	v_add_f32_e32 v93, v94, v95
	global_store_dwordx4 v[110:111], v[102:105], off offset:64
	global_store_dwordx2 v[98:99], v[106:107], off
	v_cvt_pk_bf16_f32 v106, v102, v103
	v_cvt_pk_bf16_f32 v107, v104, v105
	v_add_f32_e32 v93, v96, v93
	global_store_dwordx2 v[98:99], v[106:107], off offset:32
	v_pk_mul_f32 v[98:99], v[102:103], v[102:103]
	v_add_f32_e32 v93, v97, v93
	v_add_f32_e32 v93, v98, v93
	v_pk_mul_f32 v[102:103], v[104:105], v[104:105]
	v_add_f32_e32 v93, v99, v93
	v_add_f32_e32 v93, v102, v93
	v_add_f32_e32 v93, v103, v93
	s_nop 1
	v_add_f32_dpp v93, v93, v93 quad_perm:[1,0,3,2] row_mask:0xf bank_mask:0xf
	s_nop 1
	v_add_f32_dpp v93, v93, v93 quad_perm:[2,3,0,1] row_mask:0xf bank_mask:0xf
	s_nop 1
	v_add_f32_dpp v93, v93, v93 row_half_mirror row_mask:0xf bank_mask:0xf
	s_nop 1
	v_add_f32_dpp v93, v93, v93 row_mirror row_mask:0xf bank_mask:0xf
	s_nop 1
	v_add_f32_dpp v93, v93, v93 row_bcast:15 row_mask:0xa bank_mask:0xf
	s_and_saveexec_b64 s[10:11], vcc
	s_cbranch_execz .LBB0_151
	v_lshl_add_u64 v[68:69], v[68:69], 4, s[8:9]
	global_store_dword v[68:69], v93, off
.LBB0_151:
	s_or_b64 exec, exec, s[10:11]
	v_add_u32_e32 v68, 0x600, v140
	s_waitcnt lgkmcnt(0)
	v_ashrrev_i32_e32 v94, 5, v68
	v_mul_lo_u32 v68, v94, s14
	v_add_u32_e32 v93, v101, v68
	v_add_u32_e32 v68, s39, v94
	v_ashrrev_i32_e32 v69, 31, v68
	v_lshlrev_b64 v[96:97], 10, v[68:69]
	v_lshl_add_u64 v[110:111], v[96:97], 0, v[66:67]
	v_lshl_add_u64 v[112:113], v[110:111], 2, s[26:27]
	ds_read_b128 v[96:99], v93
	s_waitcnt lgkmcnt(0)
	s_waitcnt vmcnt(24)
	v_pk_fma_f32 v[96:97], v[96:97], 0.5, v[158:159] op_sel_hi:[1,0,1]
	s_waitcnt vmcnt(24)
	v_pk_fma_f32 v[98:99], v[98:99], 0.5, v[160:161] op_sel_hi:[1,0,1]
	ds_read_b128 v[102:105], v93 offset:64
	global_store_dwordx4 v[112:113], v[96:99], off
	s_waitcnt lgkmcnt(0)
	s_waitcnt vmcnt(24)
	v_pk_fma_f32 v[102:103], v[102:103], 0.5, v[162:163] op_sel_hi:[1,0,1]
	v_cvt_pk_bf16_f32 v106, v96, v97
	v_pk_mul_f32 v[96:97], v[96:97], v[96:97]
	v_cvt_pk_bf16_f32 v107, v98, v99
	v_pk_mul_f32 v[98:99], v[98:99], v[98:99]
	v_add_f32_e32 v95, v96, v97
	s_waitcnt vmcnt(24)
	v_pk_fma_f32 v[104:105], v[104:105], 0.5, v[164:165] op_sel_hi:[1,0,1]
	v_lshl_add_u64 v[108:109], v[110:111], 1, s[44:45]
	v_add_f32_e32 v95, v98, v95
	global_store_dwordx4 v[112:113], v[102:105], off offset:64
	global_store_dwordx2 v[108:109], v[106:107], off
	v_cvt_pk_bf16_f32 v106, v102, v103
	v_pk_mul_f32 v[102:103], v[102:103], v[102:103]
	v_add_f32_e32 v95, v99, v95
	v_add_f32_e32 v95, v102, v95
	v_cvt_pk_bf16_f32 v107, v104, v105
	v_pk_mul_f32 v[104:105], v[104:105], v[104:105]
	v_add_f32_e32 v95, v103, v95
	v_add_f32_e32 v95, v104, v95
	v_add_f32_e32 v95, v105, v95
	s_nop 1
	v_add_f32_dpp v95, v95, v95 quad_perm:[1,0,3,2] row_mask:0xf bank_mask:0xf
	s_nop 1
	v_add_f32_dpp v95, v95, v95 quad_perm:[2,3,0,1] row_mask:0xf bank_mask:0xf
	s_nop 1
	v_add_f32_dpp v95, v95, v95 row_half_mirror row_mask:0xf bank_mask:0xf
	s_nop 1
	v_add_f32_dpp v95, v95, v95 row_mirror row_mask:0xf bank_mask:0xf
	s_nop 1
	v_add_f32_dpp v95, v95, v95 row_bcast:15 row_mask:0xa bank_mask:0xf
	global_store_dwordx2 v[108:109], v[106:107], off offset:32
	s_and_saveexec_b64 s[10:11], vcc
	s_cbranch_execz .LBB0_153
	v_lshl_add_u64 v[68:69], v[68:69], 4, s[8:9]
	global_store_dword v[68:69], v95, off
.LBB0_153:
	s_or_b64 exec, exec, s[10:11]
	v_add_u32_e32 v68, 0x800, v140
	s_waitcnt lgkmcnt(0)
	v_ashrrev_i32_e32 v96, 5, v68
	v_mul_lo_u32 v68, v96, s14
	v_add_u32_e32 v95, v101, v68
	v_add_u32_e32 v68, s39, v96
	v_ashrrev_i32_e32 v69, 31, v68
	v_lshlrev_b64 v[98:99], 10, v[68:69]
	v_lshl_add_u64 v[98:99], v[98:99], 0, v[66:67]
	v_lshl_add_u64 v[118:119], v[98:99], 2, s[26:27]
	ds_read_b128 v[102:105], v95
	v_lshl_add_u64 v[98:99], v[98:99], 1, s[44:45]
	s_waitcnt lgkmcnt(0)
	s_waitcnt vmcnt(27)
	v_pk_fma_f32 v[102:103], v[102:103], 0.5, v[166:167] op_sel_hi:[1,0,1]
	s_waitcnt vmcnt(27)
	v_pk_fma_f32 v[104:105], v[104:105], 0.5, v[168:169] op_sel_hi:[1,0,1]
	ds_read_b128 v[106:109], v95 offset:64
	global_store_dwordx4 v[118:119], v[102:105], off
	s_waitcnt lgkmcnt(0)
	s_waitcnt vmcnt(27)
	v_pk_fma_f32 v[106:107], v[106:107], 0.5, v[170:171] op_sel_hi:[1,0,1]
	s_waitcnt vmcnt(27)
	v_pk_fma_f32 v[108:109], v[108:109], 0.5, v[172:173] op_sel_hi:[1,0,1]
	v_cvt_pk_bf16_f32 v110, v102, v103
	v_cvt_pk_bf16_f32 v111, v104, v105
	global_store_dwordx4 v[118:119], v[106:109], off offset:64
	global_store_dwordx2 v[98:99], v[110:111], off
	v_cvt_pk_bf16_f32 v110, v106, v107
	v_cvt_pk_bf16_f32 v111, v108, v109
	global_store_dwordx2 v[98:99], v[110:111], off offset:32
	v_pk_mul_f32 v[98:99], v[102:103], v[102:103]
	v_pk_mul_f32 v[102:103], v[104:105], v[104:105]
	v_add_f32_e32 v97, v98, v99
	v_add_f32_e32 v97, v102, v97
	v_pk_mul_f32 v[104:105], v[106:107], v[106:107]
	v_add_f32_e32 v97, v103, v97
	v_add_f32_e32 v97, v104, v97
	v_pk_mul_f32 v[106:107], v[108:109], v[108:109]
	v_add_f32_e32 v97, v105, v97
	v_add_f32_e32 v97, v106, v97
	v_add_f32_e32 v97, v107, v97
	s_nop 1
	v_add_f32_dpp v97, v97, v97 quad_perm:[1,0,3,2] row_mask:0xf bank_mask:0xf
	s_nop 1
	v_add_f32_dpp v97, v97, v97 quad_perm:[2,3,0,1] row_mask:0xf bank_mask:0xf
	s_nop 1
	v_add_f32_dpp v97, v97, v97 row_half_mirror row_mask:0xf bank_mask:0xf
	s_nop 1
	v_add_f32_dpp v97, v97, v97 row_mirror row_mask:0xf bank_mask:0xf
	s_nop 1
	v_add_f32_dpp v97, v97, v97 row_bcast:15 row_mask:0xa bank_mask:0xf
	s_and_saveexec_b64 s[10:11], vcc
	s_cbranch_execz .LBB0_155
	v_lshl_add_u64 v[68:69], v[68:69], 4, s[8:9]
	global_store_dword v[68:69], v97, off
.LBB0_155:
	s_or_b64 exec, exec, s[10:11]
	v_add_u32_e32 v68, 0xa00, v140
	s_waitcnt lgkmcnt(0)
	v_ashrrev_i32_e32 v98, 5, v68
	v_mul_lo_u32 v68, v98, s14
	v_add_u32_e32 v97, v101, v68
	v_add_u32_e32 v68, s39, v98
	v_ashrrev_i32_e32 v69, 31, v68
	v_lshlrev_b64 v[102:103], 10, v[68:69]
	v_lshl_add_u64 v[118:119], v[102:103], 0, v[66:67]
	v_lshl_add_u64 v[120:121], v[118:119], 2, s[26:27]
	ds_read_b128 v[102:105], v97
	s_waitcnt lgkmcnt(0)
	s_waitcnt vmcnt(30)
	v_pk_fma_f32 v[102:103], v[102:103], 0.5, v[174:175] op_sel_hi:[1,0,1]
	s_waitcnt vmcnt(30)
	v_pk_fma_f32 v[104:105], v[104:105], 0.5, v[176:177] op_sel_hi:[1,0,1]
	ds_read_b128 v[106:109], v97 offset:64
	global_store_dwordx4 v[120:121], v[102:105], off
	s_waitcnt lgkmcnt(0)
	s_waitcnt vmcnt(30)
	v_pk_fma_f32 v[106:107], v[106:107], 0.5, v[178:179] op_sel_hi:[1,0,1]
	v_cvt_pk_bf16_f32 v110, v102, v103
	v_pk_mul_f32 v[102:103], v[102:103], v[102:103]
	v_cvt_pk_bf16_f32 v111, v104, v105
	v_pk_mul_f32 v[104:105], v[104:105], v[104:105]
	v_add_f32_e32 v99, v102, v103
	s_waitcnt vmcnt(30)
	v_pk_fma_f32 v[108:109], v[108:109], 0.5, v[180:181] op_sel_hi:[1,0,1]
	v_lshl_add_u64 v[112:113], v[118:119], 1, s[44:45]
	v_add_f32_e32 v99, v104, v99
	global_store_dwordx4 v[120:121], v[106:109], off offset:64
	global_store_dwordx2 v[112:113], v[110:111], off
	v_cvt_pk_bf16_f32 v110, v106, v107
	v_pk_mul_f32 v[106:107], v[106:107], v[106:107]
	v_add_f32_e32 v99, v105, v99
	v_add_f32_e32 v99, v106, v99
	v_cvt_pk_bf16_f32 v111, v108, v109
	v_pk_mul_f32 v[108:109], v[108:109], v[108:109]
	v_add_f32_e32 v99, v107, v99
	v_add_f32_e32 v99, v108, v99
	v_add_f32_e32 v99, v109, v99
	s_nop 1
	v_add_f32_dpp v99, v99, v99 quad_perm:[1,0,3,2] row_mask:0xf bank_mask:0xf
	s_nop 1
	v_add_f32_dpp v99, v99, v99 quad_perm:[2,3,0,1] row_mask:0xf bank_mask:0xf
	s_nop 1
	v_add_f32_dpp v99, v99, v99 row_half_mirror row_mask:0xf bank_mask:0xf
	s_nop 1
	v_add_f32_dpp v99, v99, v99 row_mirror row_mask:0xf bank_mask:0xf
	s_nop 1
	v_add_f32_dpp v99, v99, v99 row_bcast:15 row_mask:0xa bank_mask:0xf
	global_store_dwordx2 v[112:113], v[110:111], off offset:32
	s_and_saveexec_b64 s[10:11], vcc
	s_cbranch_execz .LBB0_157
	v_lshl_add_u64 v[68:69], v[68:69], 4, s[8:9]
	global_store_dword v[68:69], v99, off
.LBB0_157:
	s_or_b64 exec, exec, s[10:11]
	v_add_u32_e32 v68, 0xc00, v140
	s_waitcnt lgkmcnt(0)
	v_ashrrev_i32_e32 v100, 5, v68
	v_mul_lo_u32 v68, v100, s14
	v_add_u32_e32 v99, v101, v68
	v_add_u32_e32 v68, s39, v100
	v_ashrrev_i32_e32 v69, 31, v68
	v_lshlrev_b64 v[102:103], 10, v[68:69]
	v_lshl_add_u64 v[118:119], v[102:103], 0, v[66:67]
	v_lshl_add_u64 v[120:121], v[118:119], 2, s[26:27]
	ds_read_b128 v[102:105], v99
	s_waitcnt lgkmcnt(0)
	s_waitcnt vmcnt(33)
	v_pk_fma_f32 v[102:103], v[102:103], 0.5, v[182:183] op_sel_hi:[1,0,1]
	s_waitcnt vmcnt(33)
	v_pk_fma_f32 v[104:105], v[104:105], 0.5, v[184:185] op_sel_hi:[1,0,1]
	ds_read_b128 v[106:109], v99 offset:64
	global_store_dwordx4 v[120:121], v[102:105], off
	s_waitcnt lgkmcnt(0)
	s_waitcnt vmcnt(33)
	v_pk_fma_f32 v[106:107], v[106:107], 0.5, v[186:187] op_sel_hi:[1,0,1]
	v_cvt_pk_bf16_f32 v110, v102, v103
	v_pk_mul_f32 v[102:103], v[102:103], v[102:103]
	v_cvt_pk_bf16_f32 v111, v104, v105
	v_pk_mul_f32 v[104:105], v[104:105], v[104:105]
	v_add_f32_e32 v102, v102, v103
	s_waitcnt vmcnt(33)
	v_pk_fma_f32 v[108:109], v[108:109], 0.5, v[188:189] op_sel_hi:[1,0,1]
	v_lshl_add_u64 v[112:113], v[118:119], 1, s[44:45]
	v_add_f32_e32 v102, v104, v102
	global_store_dwordx4 v[120:121], v[106:109], off offset:64
	global_store_dwordx2 v[112:113], v[110:111], off
	v_cvt_pk_bf16_f32 v110, v106, v107
	v_pk_mul_f32 v[106:107], v[106:107], v[106:107]
	v_add_f32_e32 v102, v105, v102
	v_add_f32_e32 v102, v106, v102
	v_cvt_pk_bf16_f32 v111, v108, v109
	v_pk_mul_f32 v[108:109], v[108:109], v[108:109]
	v_add_f32_e32 v102, v107, v102
	v_add_f32_e32 v102, v108, v102
	v_add_f32_e32 v102, v109, v102
	s_nop 1
	v_add_f32_dpp v102, v102, v102 quad_perm:[1,0,3,2] row_mask:0xf bank_mask:0xf
	s_nop 1
	v_add_f32_dpp v102, v102, v102 quad_perm:[2,3,0,1] row_mask:0xf bank_mask:0xf
	s_nop 1
	v_add_f32_dpp v102, v102, v102 row_half_mirror row_mask:0xf bank_mask:0xf
	s_nop 1
	v_add_f32_dpp v102, v102, v102 row_mirror row_mask:0xf bank_mask:0xf
	s_nop 1
	v_add_f32_dpp v102, v102, v102 row_bcast:15 row_mask:0xa bank_mask:0xf
	global_store_dwordx2 v[112:113], v[110:111], off offset:32
	s_and_saveexec_b64 s[10:11], vcc
	s_cbranch_execz .LBB0_159
	v_lshl_add_u64 v[68:69], v[68:69], 4, s[8:9]
	global_store_dword v[68:69], v102, off
.LBB0_159:
	s_or_b64 exec, exec, s[10:11]
	v_add_u32_e32 v68, 0xe00, v140
	v_ashrrev_i32_e32 v102, 5, v68
	v_mul_lo_u32 v68, v102, s14
	v_add_u32_e32 v101, v101, v68
	v_add_u32_e32 v68, s39, v102
	v_ashrrev_i32_e32 v69, 31, v68
	v_lshlrev_b64 v[104:105], 10, v[68:69]
	v_lshl_add_u64 v[112:113], v[104:105], 0, v[66:67]
	v_lshl_add_u64 v[122:123], v[112:113], 2, s[26:27]
	ds_read_b128 v[104:107], v101
	v_lshl_add_u64 v[112:113], v[112:113], 1, s[44:45]
	s_waitcnt lgkmcnt(0)
	s_waitcnt vmcnt(36)
	v_pk_fma_f32 v[104:105], v[104:105], 0.5, v[190:191] op_sel_hi:[1,0,1]
	s_waitcnt vmcnt(36)
	v_pk_fma_f32 v[106:107], v[106:107], 0.5, v[192:193] op_sel_hi:[1,0,1]
	ds_read_b128 v[108:111], v101 offset:64
	global_store_dwordx4 v[122:123], v[104:107], off
	s_waitcnt lgkmcnt(0)
	s_waitcnt vmcnt(36)
	v_pk_fma_f32 v[108:109], v[108:109], 0.5, v[194:195] op_sel_hi:[1,0,1]
	v_cvt_pk_bf16_f32 v118, v104, v105
	v_pk_mul_f32 v[104:105], v[104:105], v[104:105]
	v_cvt_pk_bf16_f32 v119, v106, v107
	v_pk_mul_f32 v[106:107], v[106:107], v[106:107]
	v_add_f32_e32 v103, v104, v105
	s_waitcnt vmcnt(36)
	v_pk_fma_f32 v[110:111], v[110:111], 0.5, v[196:197] op_sel_hi:[1,0,1]
	v_add_f32_e32 v103, v106, v103
	global_store_dwordx4 v[122:123], v[108:111], off offset:64
	global_store_dwordx2 v[112:113], v[118:119], off
	v_cvt_pk_bf16_f32 v118, v108, v109
	v_pk_mul_f32 v[108:109], v[108:109], v[108:109]
	v_add_f32_e32 v103, v107, v103
	v_add_f32_e32 v103, v108, v103
	v_cvt_pk_bf16_f32 v119, v110, v111
	v_pk_mul_f32 v[110:111], v[110:111], v[110:111]
	v_add_f32_e32 v103, v109, v103
	v_add_f32_e32 v103, v110, v103
	v_add_f32_e32 v103, v111, v103
	s_nop 1
	v_add_f32_dpp v103, v103, v103 quad_perm:[1,0,3,2] row_mask:0xf bank_mask:0xf
	s_nop 1
	v_add_f32_dpp v103, v103, v103 quad_perm:[2,3,0,1] row_mask:0xf bank_mask:0xf
	s_nop 1
	v_add_f32_dpp v103, v103, v103 row_half_mirror row_mask:0xf bank_mask:0xf
	s_nop 1
	v_add_f32_dpp v103, v103, v103 row_mirror row_mask:0xf bank_mask:0xf
	s_nop 1
	v_add_f32_dpp v103, v103, v103 row_bcast:15 row_mask:0xa bank_mask:0xf
	global_store_dwordx2 v[112:113], v[118:119], off offset:32
	s_and_saveexec_b64 s[10:11], vcc
	s_cbranch_execz .LBB0_161
	v_lshl_add_u64 v[68:69], v[68:69], 4, s[8:9]
	global_store_dword v[68:69], v103, off

.LBB0_163:
	s_or_b64 exec, exec, s[10:11]
	v_add_u32_e32 v2, s38, v90
	v_ashrrev_i32_e32 v3, 31, v2
	s_waitcnt lgkmcnt(0)
	v_lshlrev_b64 v[4:5], 10, v[2:3]
	v_lshl_add_u64 v[16:17], v[4:5], 0, v[66:67]
	v_lshl_add_u64 v[18:19], v[16:17], 2, s[26:27]
	ds_read_b128 v[4:7], v89
	s_waitcnt lgkmcnt(0)
	s_waitcnt vmcnt(18)
	v_pk_fma_f32 v[4:5], v[4:5], 0.5, v[142:143] op_sel_hi:[1,0,1]
	s_waitcnt vmcnt(18)
	v_pk_fma_f32 v[6:7], v[6:7], 0.5, v[144:145] op_sel_hi:[1,0,1]
	ds_read_b128 v[8:11], v89 offset:64
	global_store_dwordx4 v[18:19], v[4:7], off
	s_waitcnt lgkmcnt(0)
	s_waitcnt vmcnt(18)
	v_pk_fma_f32 v[8:9], v[8:9], 0.5, v[146:147] op_sel_hi:[1,0,1]
	v_cvt_pk_bf16_f32 v12, v4, v5
	v_pk_mul_f32 v[4:5], v[4:5], v[4:5]
	v_cvt_pk_bf16_f32 v13, v6, v7
	v_pk_mul_f32 v[6:7], v[6:7], v[6:7]
	v_add_f32_e32 v4, v4, v5
	s_waitcnt vmcnt(18)
	v_pk_fma_f32 v[10:11], v[10:11], 0.5, v[148:149] op_sel_hi:[1,0,1]
	v_lshl_add_u64 v[14:15], v[16:17], 1, s[44:45]
	v_add_f32_e32 v4, v6, v4
	global_store_dwordx4 v[18:19], v[8:11], off offset:64
	global_store_dwordx2 v[14:15], v[12:13], off
	v_cvt_pk_bf16_f32 v12, v8, v9
	v_pk_mul_f32 v[8:9], v[8:9], v[8:9]
	v_add_f32_e32 v4, v7, v4
	v_add_f32_e32 v4, v8, v4
	v_cvt_pk_bf16_f32 v13, v10, v11
	v_pk_mul_f32 v[10:11], v[10:11], v[10:11]
	v_add_f32_e32 v4, v9, v4
	v_add_f32_e32 v4, v10, v4
	v_add_f32_e32 v4, v11, v4
	s_nop 1
	v_add_f32_dpp v4, v4, v4 quad_perm:[1,0,3,2] row_mask:0xf bank_mask:0xf
	s_nop 1
	v_add_f32_dpp v4, v4, v4 quad_perm:[2,3,0,1] row_mask:0xf bank_mask:0xf
	s_nop 1
	v_add_f32_dpp v4, v4, v4 row_half_mirror row_mask:0xf bank_mask:0xf
	s_nop 1
	v_add_f32_dpp v4, v4, v4 row_mirror row_mask:0xf bank_mask:0xf
	s_nop 1
	v_add_f32_dpp v4, v4, v4 row_bcast:15 row_mask:0xa bank_mask:0xf
	global_store_dwordx2 v[14:15], v[12:13], off offset:32
	s_and_saveexec_b64 s[10:11], vcc
	s_cbranch_execz .LBB0_165
	v_lshl_add_u64 v[2:3], v[2:3], 4, s[8:9]
	global_store_dword v[2:3], v4, off
.LBB0_165:
	s_or_b64 exec, exec, s[10:11]
	v_add_u32_e32 v2, s38, v92
	v_ashrrev_i32_e32 v3, 31, v2
	s_waitcnt lgkmcnt(0)
	v_lshlrev_b64 v[4:5], 10, v[2:3]
	v_lshl_add_u64 v[16:17], v[4:5], 0, v[66:67]
	v_lshl_add_u64 v[18:19], v[16:17], 2, s[26:27]
	ds_read_b128 v[4:7], v91
	s_waitcnt lgkmcnt(0)
	s_waitcnt vmcnt(21)
	v_pk_fma_f32 v[4:5], v[4:5], 0.5, v[150:151] op_sel_hi:[1,0,1]
	s_waitcnt vmcnt(21)
	v_pk_fma_f32 v[6:7], v[6:7], 0.5, v[152:153] op_sel_hi:[1,0,1]
	ds_read_b128 v[8:11], v91 offset:64
	global_store_dwordx4 v[18:19], v[4:7], off
	s_waitcnt lgkmcnt(0)
	s_waitcnt vmcnt(21)
	v_pk_fma_f32 v[8:9], v[8:9], 0.5, v[154:155] op_sel_hi:[1,0,1]
	v_cvt_pk_bf16_f32 v12, v4, v5
	v_pk_mul_f32 v[4:5], v[4:5], v[4:5]
	v_cvt_pk_bf16_f32 v13, v6, v7
	v_pk_mul_f32 v[6:7], v[6:7], v[6:7]
	v_add_f32_e32 v4, v4, v5
	s_waitcnt vmcnt(21)
	v_pk_fma_f32 v[10:11], v[10:11], 0.5, v[156:157] op_sel_hi:[1,0,1]
	v_lshl_add_u64 v[14:15], v[16:17], 1, s[44:45]
	v_add_f32_e32 v4, v6, v4
	global_store_dwordx4 v[18:19], v[8:11], off offset:64
	global_store_dwordx2 v[14:15], v[12:13], off
	v_cvt_pk_bf16_f32 v12, v8, v9
	v_pk_mul_f32 v[8:9], v[8:9], v[8:9]
	v_add_f32_e32 v4, v7, v4
	v_add_f32_e32 v4, v8, v4
	v_cvt_pk_bf16_f32 v13, v10, v11
	v_pk_mul_f32 v[10:11], v[10:11], v[10:11]
	v_add_f32_e32 v4, v9, v4
	v_add_f32_e32 v4, v10, v4
	v_add_f32_e32 v4, v11, v4
	s_nop 1
	v_add_f32_dpp v4, v4, v4 quad_perm:[1,0,3,2] row_mask:0xf bank_mask:0xf
	s_nop 1
	v_add_f32_dpp v4, v4, v4 quad_perm:[2,3,0,1] row_mask:0xf bank_mask:0xf
	s_nop 1
	v_add_f32_dpp v4, v4, v4 row_half_mirror row_mask:0xf bank_mask:0xf
	s_nop 1
	v_add_f32_dpp v4, v4, v4 row_mirror row_mask:0xf bank_mask:0xf
	s_nop 1
	v_add_f32_dpp v4, v4, v4 row_bcast:15 row_mask:0xa bank_mask:0xf
	global_store_dwordx2 v[14:15], v[12:13], off offset:32
	s_and_saveexec_b64 s[10:11], vcc
	s_cbranch_execz .LBB0_167
	v_lshl_add_u64 v[2:3], v[2:3], 4, s[8:9]
	global_store_dword v[2:3], v4, off
.LBB0_167:
	s_or_b64 exec, exec, s[10:11]
	v_add_u32_e32 v2, s38, v94
	v_ashrrev_i32_e32 v3, 31, v2
	s_waitcnt lgkmcnt(0)
	v_lshlrev_b64 v[4:5], 10, v[2:3]
	v_lshl_add_u64 v[16:17], v[4:5], 0, v[66:67]
	v_lshl_add_u64 v[18:19], v[16:17], 2, s[26:27]
	ds_read_b128 v[4:7], v93
	s_waitcnt lgkmcnt(0)
	s_waitcnt vmcnt(24)
	v_pk_fma_f32 v[4:5], v[4:5], 0.5, v[158:159] op_sel_hi:[1,0,1]
	s_waitcnt vmcnt(24)
	v_pk_fma_f32 v[6:7], v[6:7], 0.5, v[160:161] op_sel_hi:[1,0,1]
	ds_read_b128 v[8:11], v93 offset:64
	global_store_dwordx4 v[18:19], v[4:7], off
	s_waitcnt lgkmcnt(0)
	s_waitcnt vmcnt(24)
	v_pk_fma_f32 v[8:9], v[8:9], 0.5, v[162:163] op_sel_hi:[1,0,1]
	v_cvt_pk_bf16_f32 v12, v4, v5
	v_pk_mul_f32 v[4:5], v[4:5], v[4:5]
	v_cvt_pk_bf16_f32 v13, v6, v7
	v_pk_mul_f32 v[6:7], v[6:7], v[6:7]
	v_add_f32_e32 v4, v4, v5
	s_waitcnt vmcnt(24)
	v_pk_fma_f32 v[10:11], v[10:11], 0.5, v[164:165] op_sel_hi:[1,0,1]
	v_lshl_add_u64 v[14:15], v[16:17], 1, s[44:45]
	v_add_f32_e32 v4, v6, v4
	global_store_dwordx4 v[18:19], v[8:11], off offset:64
	global_store_dwordx2 v[14:15], v[12:13], off
	v_cvt_pk_bf16_f32 v12, v8, v9
	v_pk_mul_f32 v[8:9], v[8:9], v[8:9]
	v_add_f32_e32 v4, v7, v4
	v_add_f32_e32 v4, v8, v4
	v_cvt_pk_bf16_f32 v13, v10, v11
	v_pk_mul_f32 v[10:11], v[10:11], v[10:11]
	v_add_f32_e32 v4, v9, v4
	v_add_f32_e32 v4, v10, v4
	v_add_f32_e32 v4, v11, v4
	s_nop 1
	v_add_f32_dpp v4, v4, v4 quad_perm:[1,0,3,2] row_mask:0xf bank_mask:0xf
	s_nop 1
	v_add_f32_dpp v4, v4, v4 quad_perm:[2,3,0,1] row_mask:0xf bank_mask:0xf
	s_nop 1
	v_add_f32_dpp v4, v4, v4 row_half_mirror row_mask:0xf bank_mask:0xf
	s_nop 1
	v_add_f32_dpp v4, v4, v4 row_mirror row_mask:0xf bank_mask:0xf
	s_nop 1
	v_add_f32_dpp v4, v4, v4 row_bcast:15 row_mask:0xa bank_mask:0xf
	global_store_dwordx2 v[14:15], v[12:13], off offset:32
	s_and_saveexec_b64 s[10:11], vcc
	s_cbranch_execz .LBB0_169
	v_lshl_add_u64 v[2:3], v[2:3], 4, s[8:9]
	global_store_dword v[2:3], v4, off
.LBB0_169:
	s_or_b64 exec, exec, s[10:11]
	v_add_u32_e32 v2, s38, v96
	v_ashrrev_i32_e32 v3, 31, v2
	s_waitcnt lgkmcnt(0)
	v_lshlrev_b64 v[4:5], 10, v[2:3]
	v_lshl_add_u64 v[16:17], v[4:5], 0, v[66:67]
	v_lshl_add_u64 v[18:19], v[16:17], 2, s[26:27]
	ds_read_b128 v[4:7], v95
	s_waitcnt lgkmcnt(0)
	s_waitcnt vmcnt(27)
	v_pk_fma_f32 v[4:5], v[4:5], 0.5, v[166:167] op_sel_hi:[1,0,1]
	s_waitcnt vmcnt(27)
	v_pk_fma_f32 v[6:7], v[6:7], 0.5, v[168:169] op_sel_hi:[1,0,1]
	ds_read_b128 v[8:11], v95 offset:64
	global_store_dwordx4 v[18:19], v[4:7], off
	s_waitcnt lgkmcnt(0)
	s_waitcnt vmcnt(27)
	v_pk_fma_f32 v[8:9], v[8:9], 0.5, v[170:171] op_sel_hi:[1,0,1]
	v_cvt_pk_bf16_f32 v12, v4, v5
	v_pk_mul_f32 v[4:5], v[4:5], v[4:5]
	v_cvt_pk_bf16_f32 v13, v6, v7
	v_pk_mul_f32 v[6:7], v[6:7], v[6:7]
	v_add_f32_e32 v4, v4, v5
	s_waitcnt vmcnt(27)
	v_pk_fma_f32 v[10:11], v[10:11], 0.5, v[172:173] op_sel_hi:[1,0,1]
	v_lshl_add_u64 v[14:15], v[16:17], 1, s[44:45]
	v_add_f32_e32 v4, v6, v4
	global_store_dwordx4 v[18:19], v[8:11], off offset:64
	global_store_dwordx2 v[14:15], v[12:13], off
	v_cvt_pk_bf16_f32 v12, v8, v9
	v_pk_mul_f32 v[8:9], v[8:9], v[8:9]
	v_add_f32_e32 v4, v7, v4
	v_add_f32_e32 v4, v8, v4
	v_cvt_pk_bf16_f32 v13, v10, v11
	v_pk_mul_f32 v[10:11], v[10:11], v[10:11]
	v_add_f32_e32 v4, v9, v4
	v_add_f32_e32 v4, v10, v4
	v_add_f32_e32 v4, v11, v4
	s_nop 1
	v_add_f32_dpp v4, v4, v4 quad_perm:[1,0,3,2] row_mask:0xf bank_mask:0xf
	s_nop 1
	v_add_f32_dpp v4, v4, v4 quad_perm:[2,3,0,1] row_mask:0xf bank_mask:0xf
	s_nop 1
	v_add_f32_dpp v4, v4, v4 row_half_mirror row_mask:0xf bank_mask:0xf
	s_nop 1
	v_add_f32_dpp v4, v4, v4 row_mirror row_mask:0xf bank_mask:0xf
	s_nop 1
	v_add_f32_dpp v4, v4, v4 row_bcast:15 row_mask:0xa bank_mask:0xf
	global_store_dwordx2 v[14:15], v[12:13], off offset:32
	s_and_saveexec_b64 s[10:11], vcc
	s_cbranch_execz .LBB0_171
	v_lshl_add_u64 v[2:3], v[2:3], 4, s[8:9]
	global_store_dword v[2:3], v4, off
.LBB0_171:
	s_or_b64 exec, exec, s[10:11]
	v_add_u32_e32 v2, s38, v98
	v_ashrrev_i32_e32 v3, 31, v2
	s_waitcnt lgkmcnt(0)
	v_lshlrev_b64 v[4:5], 10, v[2:3]
	v_lshl_add_u64 v[16:17], v[4:5], 0, v[66:67]
	v_lshl_add_u64 v[18:19], v[16:17], 2, s[26:27]
	ds_read_b128 v[4:7], v97
	s_waitcnt lgkmcnt(0)
	s_waitcnt vmcnt(30)
	v_pk_fma_f32 v[4:5], v[4:5], 0.5, v[174:175] op_sel_hi:[1,0,1]
	s_waitcnt vmcnt(30)
	v_pk_fma_f32 v[6:7], v[6:7], 0.5, v[176:177] op_sel_hi:[1,0,1]
	ds_read_b128 v[8:11], v97 offset:64
	global_store_dwordx4 v[18:19], v[4:7], off
	s_waitcnt lgkmcnt(0)
	s_waitcnt vmcnt(30)
	v_pk_fma_f32 v[8:9], v[8:9], 0.5, v[178:179] op_sel_hi:[1,0,1]
	v_cvt_pk_bf16_f32 v12, v4, v5
	v_pk_mul_f32 v[4:5], v[4:5], v[4:5]
	v_cvt_pk_bf16_f32 v13, v6, v7
	v_pk_mul_f32 v[6:7], v[6:7], v[6:7]
	v_add_f32_e32 v4, v4, v5
	s_waitcnt vmcnt(30)
	v_pk_fma_f32 v[10:11], v[10:11], 0.5, v[180:181] op_sel_hi:[1,0,1]
	v_lshl_add_u64 v[14:15], v[16:17], 1, s[44:45]
	v_add_f32_e32 v4, v6, v4
	global_store_dwordx4 v[18:19], v[8:11], off offset:64
	global_store_dwordx2 v[14:15], v[12:13], off
	v_cvt_pk_bf16_f32 v12, v8, v9
	v_pk_mul_f32 v[8:9], v[8:9], v[8:9]
	v_add_f32_e32 v4, v7, v4
	v_add_f32_e32 v4, v8, v4
	v_cvt_pk_bf16_f32 v13, v10, v11
	v_pk_mul_f32 v[10:11], v[10:11], v[10:11]
	v_add_f32_e32 v4, v9, v4
	v_add_f32_e32 v4, v10, v4
	v_add_f32_e32 v4, v11, v4
	s_nop 1
	v_add_f32_dpp v4, v4, v4 quad_perm:[1,0,3,2] row_mask:0xf bank_mask:0xf
	s_nop 1
	v_add_f32_dpp v4, v4, v4 quad_perm:[2,3,0,1] row_mask:0xf bank_mask:0xf
	s_nop 1
	v_add_f32_dpp v4, v4, v4 row_half_mirror row_mask:0xf bank_mask:0xf
	s_nop 1
	v_add_f32_dpp v4, v4, v4 row_mirror row_mask:0xf bank_mask:0xf
	s_nop 1
	v_add_f32_dpp v4, v4, v4 row_bcast:15 row_mask:0xa bank_mask:0xf
	global_store_dwordx2 v[14:15], v[12:13], off offset:32
	s_and_saveexec_b64 s[10:11], vcc
	s_cbranch_execz .LBB0_173
	v_lshl_add_u64 v[2:3], v[2:3], 4, s[8:9]
	global_store_dword v[2:3], v4, off
.LBB0_173:
	s_or_b64 exec, exec, s[10:11]
	v_add_u32_e32 v2, s38, v100
	v_ashrrev_i32_e32 v3, 31, v2
	s_waitcnt lgkmcnt(0)
	v_lshlrev_b64 v[4:5], 10, v[2:3]
	v_lshl_add_u64 v[16:17], v[4:5], 0, v[66:67]
	v_lshl_add_u64 v[18:19], v[16:17], 2, s[26:27]
	ds_read_b128 v[4:7], v99
	s_waitcnt lgkmcnt(0)
	s_waitcnt vmcnt(33)
	v_pk_fma_f32 v[4:5], v[4:5], 0.5, v[182:183] op_sel_hi:[1,0,1]
	s_waitcnt vmcnt(33)
	v_pk_fma_f32 v[6:7], v[6:7], 0.5, v[184:185] op_sel_hi:[1,0,1]
	ds_read_b128 v[8:11], v99 offset:64
	global_store_dwordx4 v[18:19], v[4:7], off
	s_waitcnt lgkmcnt(0)
	s_waitcnt vmcnt(33)
	v_pk_fma_f32 v[8:9], v[8:9], 0.5, v[186:187] op_sel_hi:[1,0,1]
	v_cvt_pk_bf16_f32 v12, v4, v5
	v_pk_mul_f32 v[4:5], v[4:5], v[4:5]
	v_cvt_pk_bf16_f32 v13, v6, v7
	v_pk_mul_f32 v[6:7], v[6:7], v[6:7]
	v_add_f32_e32 v4, v4, v5
	s_waitcnt vmcnt(33)
	v_pk_fma_f32 v[10:11], v[10:11], 0.5, v[188:189] op_sel_hi:[1,0,1]
	v_lshl_add_u64 v[14:15], v[16:17], 1, s[44:45]
	v_add_f32_e32 v4, v6, v4
	global_store_dwordx4 v[18:19], v[8:11], off offset:64
	global_store_dwordx2 v[14:15], v[12:13], off
	v_cvt_pk_bf16_f32 v12, v8, v9
	v_pk_mul_f32 v[8:9], v[8:9], v[8:9]
	v_add_f32_e32 v4, v7, v4
	v_add_f32_e32 v4, v8, v4
	v_cvt_pk_bf16_f32 v13, v10, v11
	v_pk_mul_f32 v[10:11], v[10:11], v[10:11]
	v_add_f32_e32 v4, v9, v4
	v_add_f32_e32 v4, v10, v4
	v_add_f32_e32 v4, v11, v4
	s_nop 1
	v_add_f32_dpp v4, v4, v4 quad_perm:[1,0,3,2] row_mask:0xf bank_mask:0xf
	s_nop 1
	v_add_f32_dpp v4, v4, v4 quad_perm:[2,3,0,1] row_mask:0xf bank_mask:0xf
	s_nop 1
	v_add_f32_dpp v4, v4, v4 row_half_mirror row_mask:0xf bank_mask:0xf
	s_nop 1
	v_add_f32_dpp v4, v4, v4 row_mirror row_mask:0xf bank_mask:0xf
	s_nop 1
	v_add_f32_dpp v4, v4, v4 row_bcast:15 row_mask:0xa bank_mask:0xf
	global_store_dwordx2 v[14:15], v[12:13], off offset:32
	s_and_saveexec_b64 s[10:11], vcc
	s_cbranch_execz .LBB0_175
	v_lshl_add_u64 v[2:3], v[2:3], 4, s[8:9]
	global_store_dword v[2:3], v4, off

.LBB0_260:
	s_or_b64 exec, exec, s[12:13]
	s_movk_i32 s9, 0x410
	v_lshrrev_b32_e32 v130, 2, v142
	v_lshlrev_b32_e32 v131, 1, v142
	v_and_b32_e32 v0, 15, v142
	v_and_b32_e32 v130, 0xfffffcc, v130
	v_and_b32_e32 v131, 0x180, v131
	v_add_u32_e32 v131, 0, v131
	v_lshlrev_b32_e32 v0, 2, v0
	v_mul_lo_u32 v130, v130, s9
	v_add3_u32 v130, v131, v0, v130
	s_waitcnt vmcnt(0)
	s_barrier
	ds_write2_b32 v130, v114, v126 offset1:16
	v_add_u32_e32 v114, 0x400, v130
	ds_write2_b32 v114, v115, v127 offset0:4 offset1:20
	v_add_u32_e32 v115, 0x800, v130
	ds_write2_b32 v115, v116, v128 offset0:8 offset1:24
	v_add_u32_e32 v116, 0xc00, v130
	ds_write2_b32 v116, v117, v129 offset0:12 offset1:28
	v_add_u32_e32 v117, 0x4000, v130
	ds_write2_b32 v117, v82, v94 offset0:64 offset1:80
	v_add_u32_e32 v82, 0x4400, v130
	ds_write2_b32 v82, v83, v95 offset0:68 offset1:84
	v_add_u32_e32 v83, 0x4800, v130
	ds_write2_b32 v83, v84, v96 offset0:72 offset1:88
	v_add_u32_e32 v84, 0x4c00, v130
	ds_write2_b32 v84, v85, v97 offset0:76 offset1:92
	v_add_u32_e32 v85, 0x8000, v130
	ds_write2_b32 v85, v74, v78 offset0:128 offset1:144
	v_add_u32_e32 v74, 0x8400, v130
	ds_write2_b32 v74, v75, v79 offset0:132 offset1:148
	v_add_u32_e32 v75, 0x8800, v130
	ds_write2_b32 v75, v76, v80 offset0:136 offset1:152
	v_add_u32_e32 v76, 0x8c00, v130
	v_add_u32_e32 v80, 0xc000, v130
	ds_write2_b32 v76, v77, v81 offset0:140 offset1:156
	ds_write2_b32 v80, v66, v70 offset0:192 offset1:208
	v_add_u32_e32 v77, 0xc400, v130
	v_add_u32_e32 v78, 0xc800, v130
	v_add_u32_e32 v79, 0xcc00, v130
	v_add_u32_e32 v81, 0x9000, v130
	v_lshlrev_b32_e32 v66, 2, v142
	ds_write2_b32 v77, v67, v71 offset0:196 offset1:212
	ds_write2_b32 v78, v68, v72 offset0:200 offset1:216
	ds_write2_b32 v79, v69, v73 offset0:204 offset1:220
	ds_write2_b32 v130, v98, v118 offset0:128 offset1:144
	ds_write2_b32 v114, v99, v119 offset0:132 offset1:148
	ds_write2_b32 v115, v100, v120 offset0:136 offset1:152
	ds_write2_b32 v116, v101, v121 offset0:140 offset1:156
	ds_write2_b32 v117, v102, v122 offset0:192 offset1:208
	ds_write2_b32 v82, v103, v123 offset0:196 offset1:212
	ds_write2_b32 v83, v104, v124 offset0:200 offset1:216
	ds_write2_b32 v84, v105, v125 offset0:204 offset1:220
	ds_write2_b32 v74, v90, v110 offset1:16
	ds_write2_b32 v75, v91, v111 offset0:4 offset1:20
	ds_write2_b32 v76, v92, v112 offset0:8 offset1:24
	ds_write2_b32 v81, v93, v113 offset0:12 offset1:28
	ds_write2_b32 v77, v86, v106 offset0:64 offset1:80
	ds_write2_b32 v78, v87, v107 offset0:68 offset1:84
	ds_write2_b32 v79, v88, v108 offset0:72 offset1:88
	v_lshlrev_b32_e32 v0, 3, v142
	v_and_b32_e32 v66, 12, v66
	s_movk_i32 s7, 0xe0
	v_ashrrev_i32_e32 v87, 5, v142
	v_and_or_b32 v0, v0, s7, v66
	v_add_u32_e32 v68, s8, v87
	v_or_b32_e32 v66, s10, v0
	v_ashrrev_i32_e32 v69, 31, v68
	v_ashrrev_i32_e32 v67, 31, v66
	v_lshlrev_b64 v[70:71], 10, v[68:69]
	v_lshl_add_u64 v[98:99], v[70:71], 0, v[66:67]
	v_add_u32_e32 v86, 0xd000, v130
	v_lshl_add_u64 v[110:111], v[98:99], 2, s[26:27]
	ds_write2_b32 v86, v89, v109 offset0:76 offset1:92
	s_waitcnt lgkmcnt(0)
	s_barrier
	v_lshlrev_b32_e32 v140, 2, v98
	global_load_dwordx4 v[132:135], v140, s[26:27]
	global_load_dwordx4 v[136:139], v140, s[26:27] offset:64
	v_add_u32_e32 v140, 0x10000, v140
	global_load_dwordx4 v[144:147], v140, s[26:27]
	global_load_dwordx4 v[148:151], v140, s[26:27] offset:64
	v_add_u32_e32 v140, 0x10000, v140
	global_load_dwordx4 v[152:155], v140, s[26:27]
	global_load_dwordx4 v[156:159], v140, s[26:27] offset:64
	v_add_u32_e32 v140, 0x10000, v140
	global_load_dwordx4 v[160:163], v140, s[26:27]
	global_load_dwordx4 v[164:167], v140, s[26:27] offset:64
	v_add_u32_e32 v140, 0x10000, v140
	global_load_dwordx4 v[168:171], v140, s[26:27]
	global_load_dwordx4 v[172:175], v140, s[26:27] offset:64
	v_add_u32_e32 v140, 0x10000, v140
	global_load_dwordx4 v[176:179], v140, s[26:27]
	global_load_dwordx4 v[180:183], v140, s[26:27] offset:64
	v_add_u32_e32 v140, 0x10000, v140
	global_load_dwordx4 v[184:187], v140, s[26:27]
	global_load_dwordx4 v[188:191], v140, s[26:27] offset:64
	v_add_u32_e32 v140, 0x10000, v140
	global_load_dwordx4 v[192:195], v140, s[26:27]
	global_load_dwordx4 v[196:199], v140, s[26:27] offset:64
	v_lshl_add_u32 v101, v0, 2, 0
	v_mul_lo_u32 v72, v87, s9
	v_add_u32_e32 v88, v101, v72
	ds_read_b128 v[102:105], v88
	ds_read_b128 v[106:109], v88 offset:64
	v_and_b32_e32 v70, 64, v218
	v_xor_b32_e32 v0, 1, v218
	v_add_u32_e32 v100, 64, v70
	v_cmp_lt_i32_e32 vcc, v0, v100
	v_xor_b32_e32 v70, 2, v218
	v_xor_b32_e32 v71, 4, v218
	v_cndmask_b32_e32 v0, v218, v0, vcc
	v_lshlrev_b32_e32 v0, 2, v0
	v_cmp_lt_i32_e32 vcc, v70, v100
	v_xor_b32_e32 v112, 8, v218
	v_and_b32_e32 v89, 31, v142
	v_cndmask_b32_e32 v70, v218, v70, vcc
	v_lshlrev_b32_e32 v70, 2, v70
	v_cmp_lt_i32_e32 vcc, v71, v100
	s_ashr_i32 s57, s56, 31
	s_lshl_b64 s[10:11], s[56:57], 2
	v_cndmask_b32_e32 v71, v218, v71, vcc
	v_cmp_lt_i32_e32 vcc, v112, v100
	v_lshlrev_b32_e32 v71, 2, v71
	s_add_u32 s10, s46, s10
	s_movk_i32 s7, 0x410
	s_addc_u32 s11, s47, s11
	s_waitcnt lgkmcnt(1)
	s_waitcnt vmcnt(15)
	v_pk_add_f32 v[90:91], v[102:103], v[132:133]
	s_waitcnt vmcnt(15)
	v_pk_add_f32 v[92:93], v[104:105], v[134:135]
	v_pk_mul_f32 v[72:73], v[90:91], v[90:91]
	v_pk_mul_f32 v[102:103], v[92:93], v[92:93]
	v_add_f32_e32 v72, v72, v73
	s_waitcnt lgkmcnt(0)
	s_waitcnt vmcnt(14)
	v_pk_add_f32 v[94:95], v[106:107], v[136:137]
	v_add_f32_e32 v72, v102, v72
	v_pk_mul_f32 v[104:105], v[94:95], v[94:95]
	v_add_f32_e32 v72, v103, v72
	s_waitcnt vmcnt(14)
	v_pk_add_f32 v[96:97], v[108:109], v[138:139]
	v_add_f32_e32 v72, v104, v72
	v_pk_mul_f32 v[106:107], v[96:97], v[96:97]
	v_add_f32_e32 v72, v105, v72
	v_add_f32_e32 v72, v106, v72
	v_add_f32_e32 v72, v107, v72
	ds_bpermute_b32 v102, v0, v72
	v_xor_b32_e32 v103, 16, v218
	v_cndmask_b32_e32 v73, v218, v112, vcc
	v_cmp_lt_i32_e32 vcc, v103, v100
	v_lshlrev_b32_e32 v73, 2, v73
	s_waitcnt lgkmcnt(0)
	v_add_f32_e32 v102, v72, v102
	ds_bpermute_b32 v104, v70, v102
	v_cndmask_b32_e32 v72, v218, v103, vcc
	v_cmp_eq_u32_e32 vcc, 31, v89
	v_lshlrev_b32_e32 v72, 2, v72
	global_store_dwordx4 v[110:111], v[90:93], off
	s_waitcnt lgkmcnt(0)
	v_add_f32_e32 v89, v102, v104
	ds_bpermute_b32 v100, v71, v89
	v_cvt_pk_bf16_f32 v102, v90, v91
	global_store_dwordx4 v[110:111], v[94:97], off offset:64
	v_cvt_pk_bf16_f32 v103, v92, v93
	v_lshl_add_u64 v[92:93], v[98:99], 1, s[44:45]
	s_waitcnt lgkmcnt(0)
	v_add_f32_e32 v89, v89, v100
	ds_bpermute_b32 v100, v73, v89
	v_cvt_pk_bf16_f32 v94, v94, v95
	v_cvt_pk_bf16_f32 v95, v96, v97
	global_store_dwordx2 v[92:93], v[102:103], off
	global_store_dwordx2 v[92:93], v[94:95], off offset:32
	s_waitcnt lgkmcnt(0)
	v_add_f32_e32 v89, v89, v100
	ds_bpermute_b32 v90, v72, v89
	s_and_saveexec_b64 s[12:13], vcc
	s_cbranch_execz .LBB0_262
	s_waitcnt lgkmcnt(0)
	v_add_f32_e32 v89, v89, v90
	v_lshl_add_u64 v[68:69], v[68:69], 4, s[10:11]
	global_store_dword v[68:69], v89, off
.LBB0_262:
	s_or_b64 exec, exec, s[12:13]
	v_add_u32_e32 v68, 0x200, v142
	s_waitcnt lgkmcnt(0)
	v_ashrrev_i32_e32 v90, 5, v68
	v_mul_lo_u32 v68, v90, s7
	v_add_u32_e32 v89, v101, v68
	v_add_u32_e32 v68, s8, v90
	v_ashrrev_i32_e32 v69, 31, v68
	v_lshlrev_b64 v[92:93], 10, v[68:69]
	v_lshl_add_u64 v[106:107], v[92:93], 0, v[66:67]
	v_lshl_add_u64 v[108:109], v[106:107], 2, s[26:27]
	ds_read_b128 v[92:95], v89
	s_waitcnt lgkmcnt(0)
	s_waitcnt vmcnt(18)
	v_pk_add_f32 v[92:93], v[92:93], v[144:145]
	s_waitcnt vmcnt(18)
	v_pk_add_f32 v[94:95], v[94:95], v[146:147]
	ds_read_b128 v[96:99], v89 offset:64
	global_store_dwordx4 v[108:109], v[92:95], off
	s_waitcnt lgkmcnt(0)
	s_waitcnt vmcnt(18)
	v_pk_add_f32 v[96:97], v[96:97], v[148:149]
	v_cvt_pk_bf16_f32 v102, v92, v93
	v_pk_mul_f32 v[92:93], v[92:93], v[92:93]
	v_cvt_pk_bf16_f32 v103, v94, v95
	v_pk_mul_f32 v[94:95], v[94:95], v[94:95]
	v_add_f32_e32 v91, v92, v93
	s_waitcnt vmcnt(18)
	v_pk_add_f32 v[98:99], v[98:99], v[150:151]
	v_lshl_add_u64 v[104:105], v[106:107], 1, s[44:45]
	v_add_f32_e32 v91, v94, v91
	global_store_dwordx4 v[108:109], v[96:99], off offset:64
	global_store_dwordx2 v[104:105], v[102:103], off
	v_cvt_pk_bf16_f32 v102, v96, v97
	v_pk_mul_f32 v[96:97], v[96:97], v[96:97]
	v_add_f32_e32 v91, v95, v91
	v_add_f32_e32 v91, v96, v91
	v_cvt_pk_bf16_f32 v103, v98, v99
	v_pk_mul_f32 v[98:99], v[98:99], v[98:99]
	v_add_f32_e32 v91, v97, v91
	v_add_f32_e32 v91, v98, v91
	v_add_f32_e32 v91, v99, v91
	s_nop 1
	v_add_f32_dpp v91, v91, v91 quad_perm:[1,0,3,2] row_mask:0xf bank_mask:0xf
	s_nop 1
	v_add_f32_dpp v91, v91, v91 quad_perm:[2,3,0,1] row_mask:0xf bank_mask:0xf
	s_nop 1
	v_add_f32_dpp v91, v91, v91 row_half_mirror row_mask:0xf bank_mask:0xf
	s_nop 1
	v_add_f32_dpp v91, v91, v91 row_mirror row_mask:0xf bank_mask:0xf
	s_nop 1
	v_add_f32_dpp v91, v91, v91 row_bcast:15 row_mask:0xa bank_mask:0xf
	global_store_dwordx2 v[104:105], v[102:103], off offset:32
	s_and_saveexec_b64 s[12:13], vcc
	s_cbranch_execz .LBB0_264
	v_lshl_add_u64 v[68:69], v[68:69], 4, s[10:11]
	global_store_dword v[68:69], v91, off
.LBB0_264:
	s_or_b64 exec, exec, s[12:13]
	v_add_u32_e32 v68, 0x400, v142
	s_waitcnt lgkmcnt(0)
	v_ashrrev_i32_e32 v92, 5, v68
	v_mul_lo_u32 v68, v92, s7
	v_add_u32_e32 v91, v101, v68
	v_add_u32_e32 v68, s8, v92
	v_ashrrev_i32_e32 v69, 31, v68
	v_lshlrev_b64 v[94:95], 10, v[68:69]
	v_lshl_add_u64 v[98:99], v[94:95], 0, v[66:67]
	v_lshl_add_u64 v[110:111], v[98:99], 2, s[26:27]
	ds_read_b128 v[94:97], v91
	v_lshl_add_u64 v[98:99], v[98:99], 1, s[44:45]
	s_waitcnt lgkmcnt(0)
	s_waitcnt vmcnt(21)
	v_pk_add_f32 v[94:95], v[94:95], v[152:153]
	s_waitcnt vmcnt(21)
	v_pk_add_f32 v[96:97], v[96:97], v[154:155]
	ds_read_b128 v[102:105], v91 offset:64
	global_store_dwordx4 v[110:111], v[94:97], off
	s_waitcnt lgkmcnt(0)
	s_waitcnt vmcnt(21)
	v_pk_add_f32 v[102:103], v[102:103], v[156:157]
	v_cvt_pk_bf16_f32 v106, v94, v95
	v_pk_mul_f32 v[94:95], v[94:95], v[94:95]
	s_waitcnt vmcnt(21)
	v_pk_add_f32 v[104:105], v[104:105], v[158:159]
	v_cvt_pk_bf16_f32 v107, v96, v97
	v_pk_mul_f32 v[96:97], v[96:97], v[96:97]
	v_add_f32_e32 v93, v94, v95
	global_store_dwordx4 v[110:111], v[102:105], off offset:64
	global_store_dwordx2 v[98:99], v[106:107], off
	v_cvt_pk_bf16_f32 v106, v102, v103
	v_cvt_pk_bf16_f32 v107, v104, v105
	v_add_f32_e32 v93, v96, v93
	global_store_dwordx2 v[98:99], v[106:107], off offset:32
	v_pk_mul_f32 v[98:99], v[102:103], v[102:103]
	v_add_f32_e32 v93, v97, v93
	v_add_f32_e32 v93, v98, v93
	v_pk_mul_f32 v[102:103], v[104:105], v[104:105]
	v_add_f32_e32 v93, v99, v93
	v_add_f32_e32 v93, v102, v93
	v_add_f32_e32 v93, v103, v93
	s_nop 1
	v_add_f32_dpp v93, v93, v93 quad_perm:[1,0,3,2] row_mask:0xf bank_mask:0xf
	s_nop 1
	v_add_f32_dpp v93, v93, v93 quad_perm:[2,3,0,1] row_mask:0xf bank_mask:0xf
	s_nop 1
	v_add_f32_dpp v93, v93, v93 row_half_mirror row_mask:0xf bank_mask:0xf
	s_nop 1
	v_add_f32_dpp v93, v93, v93 row_mirror row_mask:0xf bank_mask:0xf
	s_nop 1
	v_add_f32_dpp v93, v93, v93 row_bcast:15 row_mask:0xa bank_mask:0xf
	s_and_saveexec_b64 s[12:13], vcc
	s_cbranch_execz .LBB0_266
	v_lshl_add_u64 v[68:69], v[68:69], 4, s[10:11]
	global_store_dword v[68:69], v93, off
.LBB0_266:
	s_or_b64 exec, exec, s[12:13]
	v_add_u32_e32 v68, 0x600, v142
	s_waitcnt lgkmcnt(0)
	v_ashrrev_i32_e32 v94, 5, v68
	v_mul_lo_u32 v68, v94, s7
	v_add_u32_e32 v93, v101, v68
	v_add_u32_e32 v68, s8, v94
	v_ashrrev_i32_e32 v69, 31, v68
	v_lshlrev_b64 v[96:97], 10, v[68:69]
	v_lshl_add_u64 v[110:111], v[96:97], 0, v[66:67]
	v_lshl_add_u64 v[112:113], v[110:111], 2, s[26:27]
	ds_read_b128 v[96:99], v93
	s_waitcnt lgkmcnt(0)
	s_waitcnt vmcnt(24)
	v_pk_add_f32 v[96:97], v[96:97], v[160:161]
	s_waitcnt vmcnt(24)
	v_pk_add_f32 v[98:99], v[98:99], v[162:163]
	ds_read_b128 v[102:105], v93 offset:64
	global_store_dwordx4 v[112:113], v[96:99], off
	s_waitcnt lgkmcnt(0)
	s_waitcnt vmcnt(24)
	v_pk_add_f32 v[102:103], v[102:103], v[164:165]
	v_cvt_pk_bf16_f32 v106, v96, v97
	v_pk_mul_f32 v[96:97], v[96:97], v[96:97]
	v_cvt_pk_bf16_f32 v107, v98, v99
	v_pk_mul_f32 v[98:99], v[98:99], v[98:99]
	v_add_f32_e32 v95, v96, v97
	s_waitcnt vmcnt(24)
	v_pk_add_f32 v[104:105], v[104:105], v[166:167]
	v_lshl_add_u64 v[108:109], v[110:111], 1, s[44:45]
	v_add_f32_e32 v95, v98, v95
	global_store_dwordx4 v[112:113], v[102:105], off offset:64
	global_store_dwordx2 v[108:109], v[106:107], off
	v_cvt_pk_bf16_f32 v106, v102, v103
	v_pk_mul_f32 v[102:103], v[102:103], v[102:103]
	v_add_f32_e32 v95, v99, v95
	v_add_f32_e32 v95, v102, v95
	v_cvt_pk_bf16_f32 v107, v104, v105
	v_pk_mul_f32 v[104:105], v[104:105], v[104:105]
	v_add_f32_e32 v95, v103, v95
	v_add_f32_e32 v95, v104, v95
	v_add_f32_e32 v95, v105, v95
	s_nop 1
	v_add_f32_dpp v95, v95, v95 quad_perm:[1,0,3,2] row_mask:0xf bank_mask:0xf
	s_nop 1
	v_add_f32_dpp v95, v95, v95 quad_perm:[2,3,0,1] row_mask:0xf bank_mask:0xf
	s_nop 1
	v_add_f32_dpp v95, v95, v95 row_half_mirror row_mask:0xf bank_mask:0xf
	s_nop 1
	v_add_f32_dpp v95, v95, v95 row_mirror row_mask:0xf bank_mask:0xf
	s_nop 1
	v_add_f32_dpp v95, v95, v95 row_bcast:15 row_mask:0xa bank_mask:0xf
	global_store_dwordx2 v[108:109], v[106:107], off offset:32
	s_and_saveexec_b64 s[12:13], vcc
	s_cbranch_execz .LBB0_268
	v_lshl_add_u64 v[68:69], v[68:69], 4, s[10:11]
	global_store_dword v[68:69], v95, off
.LBB0_268:
	s_or_b64 exec, exec, s[12:13]
	v_add_u32_e32 v68, 0x800, v142
	s_waitcnt lgkmcnt(0)
	v_ashrrev_i32_e32 v96, 5, v68
	v_mul_lo_u32 v68, v96, s7
	v_add_u32_e32 v95, v101, v68
	v_add_u32_e32 v68, s8, v96
	v_ashrrev_i32_e32 v69, 31, v68
	v_lshlrev_b64 v[98:99], 10, v[68:69]
	v_lshl_add_u64 v[98:99], v[98:99], 0, v[66:67]
	v_lshl_add_u64 v[118:119], v[98:99], 2, s[26:27]
	ds_read_b128 v[102:105], v95
	v_lshl_add_u64 v[98:99], v[98:99], 1, s[44:45]
	s_waitcnt lgkmcnt(0)
	s_waitcnt vmcnt(27)
	v_pk_add_f32 v[102:103], v[102:103], v[168:169]
	s_waitcnt vmcnt(27)
	v_pk_add_f32 v[104:105], v[104:105], v[170:171]
	ds_read_b128 v[106:109], v95 offset:64
	global_store_dwordx4 v[118:119], v[102:105], off
	s_waitcnt lgkmcnt(0)
	s_waitcnt vmcnt(27)
	v_pk_add_f32 v[106:107], v[106:107], v[172:173]
	s_waitcnt vmcnt(27)
	v_pk_add_f32 v[108:109], v[108:109], v[174:175]
	v_cvt_pk_bf16_f32 v110, v102, v103
	v_cvt_pk_bf16_f32 v111, v104, v105
	global_store_dwordx4 v[118:119], v[106:109], off offset:64
	global_store_dwordx2 v[98:99], v[110:111], off
	v_cvt_pk_bf16_f32 v110, v106, v107
	v_cvt_pk_bf16_f32 v111, v108, v109
	global_store_dwordx2 v[98:99], v[110:111], off offset:32
	v_pk_mul_f32 v[98:99], v[102:103], v[102:103]
	v_pk_mul_f32 v[102:103], v[104:105], v[104:105]
	v_add_f32_e32 v97, v98, v99
	v_add_f32_e32 v97, v102, v97
	v_pk_mul_f32 v[104:105], v[106:107], v[106:107]
	v_add_f32_e32 v97, v103, v97
	v_add_f32_e32 v97, v104, v97
	v_pk_mul_f32 v[106:107], v[108:109], v[108:109]
	v_add_f32_e32 v97, v105, v97
	v_add_f32_e32 v97, v106, v97
	v_add_f32_e32 v97, v107, v97
	s_nop 1
	v_add_f32_dpp v97, v97, v97 quad_perm:[1,0,3,2] row_mask:0xf bank_mask:0xf
	s_nop 1
	v_add_f32_dpp v97, v97, v97 quad_perm:[2,3,0,1] row_mask:0xf bank_mask:0xf
	s_nop 1
	v_add_f32_dpp v97, v97, v97 row_half_mirror row_mask:0xf bank_mask:0xf
	s_nop 1
	v_add_f32_dpp v97, v97, v97 row_mirror row_mask:0xf bank_mask:0xf
	s_nop 1
	v_add_f32_dpp v97, v97, v97 row_bcast:15 row_mask:0xa bank_mask:0xf
	s_and_saveexec_b64 s[12:13], vcc
	s_cbranch_execz .LBB0_270
	v_lshl_add_u64 v[68:69], v[68:69], 4, s[10:11]
	global_store_dword v[68:69], v97, off
.LBB0_270:
	s_or_b64 exec, exec, s[12:13]
	v_add_u32_e32 v68, 0xa00, v142
	s_waitcnt lgkmcnt(0)
	v_ashrrev_i32_e32 v98, 5, v68
	v_mul_lo_u32 v68, v98, s7
	v_add_u32_e32 v97, v101, v68
	v_add_u32_e32 v68, s8, v98
	v_ashrrev_i32_e32 v69, 31, v68
	v_lshlrev_b64 v[102:103], 10, v[68:69]
	v_lshl_add_u64 v[118:119], v[102:103], 0, v[66:67]
	v_lshl_add_u64 v[120:121], v[118:119], 2, s[26:27]
	ds_read_b128 v[102:105], v97
	s_waitcnt lgkmcnt(0)
	s_waitcnt vmcnt(30)
	v_pk_add_f32 v[102:103], v[102:103], v[176:177]
	s_waitcnt vmcnt(30)
	v_pk_add_f32 v[104:105], v[104:105], v[178:179]
	ds_read_b128 v[106:109], v97 offset:64
	global_store_dwordx4 v[120:121], v[102:105], off
	s_waitcnt lgkmcnt(0)
	s_waitcnt vmcnt(30)
	v_pk_add_f32 v[106:107], v[106:107], v[180:181]
	v_cvt_pk_bf16_f32 v110, v102, v103
	v_pk_mul_f32 v[102:103], v[102:103], v[102:103]
	v_cvt_pk_bf16_f32 v111, v104, v105
	v_pk_mul_f32 v[104:105], v[104:105], v[104:105]
	v_add_f32_e32 v99, v102, v103
	s_waitcnt vmcnt(30)
	v_pk_add_f32 v[108:109], v[108:109], v[182:183]
	v_lshl_add_u64 v[112:113], v[118:119], 1, s[44:45]
	v_add_f32_e32 v99, v104, v99
	global_store_dwordx4 v[120:121], v[106:109], off offset:64
	global_store_dwordx2 v[112:113], v[110:111], off
	v_cvt_pk_bf16_f32 v110, v106, v107
	v_pk_mul_f32 v[106:107], v[106:107], v[106:107]
	v_add_f32_e32 v99, v105, v99
	v_add_f32_e32 v99, v106, v99
	v_cvt_pk_bf16_f32 v111, v108, v109
	v_pk_mul_f32 v[108:109], v[108:109], v[108:109]
	v_add_f32_e32 v99, v107, v99
	v_add_f32_e32 v99, v108, v99
	v_add_f32_e32 v99, v109, v99
	s_nop 1
	v_add_f32_dpp v99, v99, v99 quad_perm:[1,0,3,2] row_mask:0xf bank_mask:0xf
	s_nop 1
	v_add_f32_dpp v99, v99, v99 quad_perm:[2,3,0,1] row_mask:0xf bank_mask:0xf
	s_nop 1
	v_add_f32_dpp v99, v99, v99 row_half_mirror row_mask:0xf bank_mask:0xf
	s_nop 1
	v_add_f32_dpp v99, v99, v99 row_mirror row_mask:0xf bank_mask:0xf
	s_nop 1
	v_add_f32_dpp v99, v99, v99 row_bcast:15 row_mask:0xa bank_mask:0xf
	global_store_dwordx2 v[112:113], v[110:111], off offset:32
	s_and_saveexec_b64 s[12:13], vcc
	s_cbranch_execz .LBB0_272
	v_lshl_add_u64 v[68:69], v[68:69], 4, s[10:11]
	global_store_dword v[68:69], v99, off
.LBB0_272:
	s_or_b64 exec, exec, s[12:13]
	v_add_u32_e32 v68, 0xc00, v142
	s_waitcnt lgkmcnt(0)
	v_ashrrev_i32_e32 v100, 5, v68
	v_mul_lo_u32 v68, v100, s7
	v_add_u32_e32 v99, v101, v68
	v_add_u32_e32 v68, s8, v100
	v_ashrrev_i32_e32 v69, 31, v68
	v_lshlrev_b64 v[102:103], 10, v[68:69]
	v_lshl_add_u64 v[118:119], v[102:103], 0, v[66:67]
	v_lshl_add_u64 v[120:121], v[118:119], 2, s[26:27]
	ds_read_b128 v[102:105], v99
	s_waitcnt lgkmcnt(0)
	s_waitcnt vmcnt(33)
	v_pk_add_f32 v[102:103], v[102:103], v[184:185]
	s_waitcnt vmcnt(33)
	v_pk_add_f32 v[104:105], v[104:105], v[186:187]
	ds_read_b128 v[106:109], v99 offset:64
	global_store_dwordx4 v[120:121], v[102:105], off
	s_waitcnt lgkmcnt(0)
	s_waitcnt vmcnt(33)
	v_pk_add_f32 v[106:107], v[106:107], v[188:189]
	v_cvt_pk_bf16_f32 v110, v102, v103
	v_pk_mul_f32 v[102:103], v[102:103], v[102:103]
	v_cvt_pk_bf16_f32 v111, v104, v105
	v_pk_mul_f32 v[104:105], v[104:105], v[104:105]
	v_add_f32_e32 v102, v102, v103
	s_waitcnt vmcnt(33)
	v_pk_add_f32 v[108:109], v[108:109], v[190:191]
	v_lshl_add_u64 v[112:113], v[118:119], 1, s[44:45]
	v_add_f32_e32 v102, v104, v102
	global_store_dwordx4 v[120:121], v[106:109], off offset:64
	global_store_dwordx2 v[112:113], v[110:111], off
	v_cvt_pk_bf16_f32 v110, v106, v107
	v_pk_mul_f32 v[106:107], v[106:107], v[106:107]
	v_add_f32_e32 v102, v105, v102
	v_add_f32_e32 v102, v106, v102
	v_cvt_pk_bf16_f32 v111, v108, v109
	v_pk_mul_f32 v[108:109], v[108:109], v[108:109]
	v_add_f32_e32 v102, v107, v102
	v_add_f32_e32 v102, v108, v102
	v_add_f32_e32 v102, v109, v102
	s_nop 1
	v_add_f32_dpp v102, v102, v102 quad_perm:[1,0,3,2] row_mask:0xf bank_mask:0xf
	s_nop 1
	v_add_f32_dpp v102, v102, v102 quad_perm:[2,3,0,1] row_mask:0xf bank_mask:0xf
	s_nop 1
	v_add_f32_dpp v102, v102, v102 row_half_mirror row_mask:0xf bank_mask:0xf
	s_nop 1
	v_add_f32_dpp v102, v102, v102 row_mirror row_mask:0xf bank_mask:0xf
	s_nop 1
	v_add_f32_dpp v102, v102, v102 row_bcast:15 row_mask:0xa bank_mask:0xf
	global_store_dwordx2 v[112:113], v[110:111], off offset:32
	s_and_saveexec_b64 s[12:13], vcc
	s_cbranch_execz .LBB0_274
	v_lshl_add_u64 v[68:69], v[68:69], 4, s[10:11]
	global_store_dword v[68:69], v102, off
.LBB0_274:
	s_or_b64 exec, exec, s[12:13]
	v_add_u32_e32 v68, 0xe00, v142
	v_ashrrev_i32_e32 v102, 5, v68
	v_mul_lo_u32 v68, v102, s7
	v_add_u32_e32 v101, v101, v68
	v_add_u32_e32 v68, s8, v102
	v_ashrrev_i32_e32 v69, 31, v68
	v_lshlrev_b64 v[104:105], 10, v[68:69]
	v_lshl_add_u64 v[112:113], v[104:105], 0, v[66:67]
	v_lshl_add_u64 v[122:123], v[112:113], 2, s[26:27]
	ds_read_b128 v[104:107], v101
	v_lshl_add_u64 v[112:113], v[112:113], 1, s[44:45]
	s_waitcnt lgkmcnt(0)
	s_waitcnt vmcnt(36)
	v_pk_add_f32 v[104:105], v[104:105], v[192:193]
	s_waitcnt vmcnt(36)
	v_pk_add_f32 v[106:107], v[106:107], v[194:195]
	ds_read_b128 v[108:111], v101 offset:64
	global_store_dwordx4 v[122:123], v[104:107], off
	s_waitcnt lgkmcnt(0)
	s_waitcnt vmcnt(36)
	v_pk_add_f32 v[108:109], v[108:109], v[196:197]
	v_cvt_pk_bf16_f32 v118, v104, v105
	v_pk_mul_f32 v[104:105], v[104:105], v[104:105]
	v_cvt_pk_bf16_f32 v119, v106, v107
	v_pk_mul_f32 v[106:107], v[106:107], v[106:107]
	v_add_f32_e32 v103, v104, v105
	s_waitcnt vmcnt(36)
	v_pk_add_f32 v[110:111], v[110:111], v[198:199]
	v_add_f32_e32 v103, v106, v103
	global_store_dwordx4 v[122:123], v[108:111], off offset:64
	global_store_dwordx2 v[112:113], v[118:119], off
	v_cvt_pk_bf16_f32 v118, v108, v109
	v_pk_mul_f32 v[108:109], v[108:109], v[108:109]
	v_add_f32_e32 v103, v107, v103
	v_add_f32_e32 v103, v108, v103
	v_cvt_pk_bf16_f32 v119, v110, v111
	v_pk_mul_f32 v[110:111], v[110:111], v[110:111]
	v_add_f32_e32 v103, v109, v103
	v_add_f32_e32 v103, v110, v103
	v_add_f32_e32 v103, v111, v103
	s_nop 1
	v_add_f32_dpp v103, v103, v103 quad_perm:[1,0,3,2] row_mask:0xf bank_mask:0xf
	s_nop 1
	v_add_f32_dpp v103, v103, v103 quad_perm:[2,3,0,1] row_mask:0xf bank_mask:0xf
	s_nop 1
	v_add_f32_dpp v103, v103, v103 row_half_mirror row_mask:0xf bank_mask:0xf
	s_nop 1
	v_add_f32_dpp v103, v103, v103 row_mirror row_mask:0xf bank_mask:0xf
	s_nop 1
	v_add_f32_dpp v103, v103, v103 row_bcast:15 row_mask:0xa bank_mask:0xf
	global_store_dwordx2 v[112:113], v[118:119], off offset:32
	s_and_saveexec_b64 s[8:9], vcc
	s_cbranch_execz .LBB0_276
	v_lshl_add_u64 v[68:69], v[68:69], 4, s[10:11]
	global_store_dword v[68:69], v103, off

.LBB0_278:
	s_or_b64 exec, exec, s[8:9]
	v_add_u32_e32 v2, s6, v90
	v_ashrrev_i32_e32 v3, 31, v2
	s_waitcnt lgkmcnt(0)
	v_lshlrev_b64 v[4:5], 10, v[2:3]
	v_lshl_add_u64 v[16:17], v[4:5], 0, v[66:67]
	v_lshl_add_u64 v[18:19], v[16:17], 2, s[26:27]
	ds_read_b128 v[4:7], v89
	s_waitcnt lgkmcnt(0)
	s_waitcnt vmcnt(18)
	v_pk_add_f32 v[4:5], v[4:5], v[144:145]
	s_waitcnt vmcnt(18)
	v_pk_add_f32 v[6:7], v[6:7], v[146:147]
	ds_read_b128 v[8:11], v89 offset:64
	global_store_dwordx4 v[18:19], v[4:7], off
	s_waitcnt lgkmcnt(0)
	s_waitcnt vmcnt(18)
	v_pk_add_f32 v[8:9], v[8:9], v[148:149]
	v_cvt_pk_bf16_f32 v12, v4, v5
	v_pk_mul_f32 v[4:5], v[4:5], v[4:5]
	v_cvt_pk_bf16_f32 v13, v6, v7
	v_pk_mul_f32 v[6:7], v[6:7], v[6:7]
	v_add_f32_e32 v4, v4, v5
	s_waitcnt vmcnt(18)
	v_pk_add_f32 v[10:11], v[10:11], v[150:151]
	v_lshl_add_u64 v[14:15], v[16:17], 1, s[44:45]
	v_add_f32_e32 v4, v6, v4
	global_store_dwordx4 v[18:19], v[8:11], off offset:64
	global_store_dwordx2 v[14:15], v[12:13], off
	v_cvt_pk_bf16_f32 v12, v8, v9
	v_pk_mul_f32 v[8:9], v[8:9], v[8:9]
	v_add_f32_e32 v4, v7, v4
	v_add_f32_e32 v4, v8, v4
	v_cvt_pk_bf16_f32 v13, v10, v11
	v_pk_mul_f32 v[10:11], v[10:11], v[10:11]
	v_add_f32_e32 v4, v9, v4
	v_add_f32_e32 v4, v10, v4
	v_add_f32_e32 v4, v11, v4
	s_nop 1
	v_add_f32_dpp v4, v4, v4 quad_perm:[1,0,3,2] row_mask:0xf bank_mask:0xf
	s_nop 1
	v_add_f32_dpp v4, v4, v4 quad_perm:[2,3,0,1] row_mask:0xf bank_mask:0xf
	s_nop 1
	v_add_f32_dpp v4, v4, v4 row_half_mirror row_mask:0xf bank_mask:0xf
	s_nop 1
	v_add_f32_dpp v4, v4, v4 row_mirror row_mask:0xf bank_mask:0xf
	s_nop 1
	v_add_f32_dpp v4, v4, v4 row_bcast:15 row_mask:0xa bank_mask:0xf
	global_store_dwordx2 v[14:15], v[12:13], off offset:32
	s_and_saveexec_b64 s[8:9], vcc
	s_cbranch_execz .LBB0_280
	v_lshl_add_u64 v[2:3], v[2:3], 4, s[10:11]
	global_store_dword v[2:3], v4, off
.LBB0_280:
	s_or_b64 exec, exec, s[8:9]
	v_add_u32_e32 v2, s6, v92
	v_ashrrev_i32_e32 v3, 31, v2
	s_waitcnt lgkmcnt(0)
	v_lshlrev_b64 v[4:5], 10, v[2:3]
	v_lshl_add_u64 v[16:17], v[4:5], 0, v[66:67]
	v_lshl_add_u64 v[18:19], v[16:17], 2, s[26:27]
	ds_read_b128 v[4:7], v91
	s_waitcnt lgkmcnt(0)
	s_waitcnt vmcnt(21)
	v_pk_add_f32 v[4:5], v[4:5], v[152:153]
	s_waitcnt vmcnt(21)
	v_pk_add_f32 v[6:7], v[6:7], v[154:155]
	ds_read_b128 v[8:11], v91 offset:64
	global_store_dwordx4 v[18:19], v[4:7], off
	s_waitcnt lgkmcnt(0)
	s_waitcnt vmcnt(21)
	v_pk_add_f32 v[8:9], v[8:9], v[156:157]
	v_cvt_pk_bf16_f32 v12, v4, v5
	v_pk_mul_f32 v[4:5], v[4:5], v[4:5]
	v_cvt_pk_bf16_f32 v13, v6, v7
	v_pk_mul_f32 v[6:7], v[6:7], v[6:7]
	v_add_f32_e32 v4, v4, v5
	s_waitcnt vmcnt(21)
	v_pk_add_f32 v[10:11], v[10:11], v[158:159]
	v_lshl_add_u64 v[14:15], v[16:17], 1, s[44:45]
	v_add_f32_e32 v4, v6, v4
	global_store_dwordx4 v[18:19], v[8:11], off offset:64
	global_store_dwordx2 v[14:15], v[12:13], off
	v_cvt_pk_bf16_f32 v12, v8, v9
	v_pk_mul_f32 v[8:9], v[8:9], v[8:9]
	v_add_f32_e32 v4, v7, v4
	v_add_f32_e32 v4, v8, v4
	v_cvt_pk_bf16_f32 v13, v10, v11
	v_pk_mul_f32 v[10:11], v[10:11], v[10:11]
	v_add_f32_e32 v4, v9, v4
	v_add_f32_e32 v4, v10, v4
	v_add_f32_e32 v4, v11, v4
	s_nop 1
	v_add_f32_dpp v4, v4, v4 quad_perm:[1,0,3,2] row_mask:0xf bank_mask:0xf
	s_nop 1
	v_add_f32_dpp v4, v4, v4 quad_perm:[2,3,0,1] row_mask:0xf bank_mask:0xf
	s_nop 1
	v_add_f32_dpp v4, v4, v4 row_half_mirror row_mask:0xf bank_mask:0xf
	s_nop 1
	v_add_f32_dpp v4, v4, v4 row_mirror row_mask:0xf bank_mask:0xf
	s_nop 1
	v_add_f32_dpp v4, v4, v4 row_bcast:15 row_mask:0xa bank_mask:0xf
	global_store_dwordx2 v[14:15], v[12:13], off offset:32
	s_and_saveexec_b64 s[8:9], vcc
	s_cbranch_execz .LBB0_282
	v_lshl_add_u64 v[2:3], v[2:3], 4, s[10:11]
	global_store_dword v[2:3], v4, off
.LBB0_282:
	s_or_b64 exec, exec, s[8:9]
	v_add_u32_e32 v2, s6, v94
	v_ashrrev_i32_e32 v3, 31, v2
	s_waitcnt lgkmcnt(0)
	v_lshlrev_b64 v[4:5], 10, v[2:3]
	v_lshl_add_u64 v[16:17], v[4:5], 0, v[66:67]
	v_lshl_add_u64 v[18:19], v[16:17], 2, s[26:27]
	ds_read_b128 v[4:7], v93
	s_waitcnt lgkmcnt(0)
	s_waitcnt vmcnt(24)
	v_pk_add_f32 v[4:5], v[4:5], v[160:161]
	s_waitcnt vmcnt(24)
	v_pk_add_f32 v[6:7], v[6:7], v[162:163]
	ds_read_b128 v[8:11], v93 offset:64
	global_store_dwordx4 v[18:19], v[4:7], off
	s_waitcnt lgkmcnt(0)
	s_waitcnt vmcnt(24)
	v_pk_add_f32 v[8:9], v[8:9], v[164:165]
	v_cvt_pk_bf16_f32 v12, v4, v5
	v_pk_mul_f32 v[4:5], v[4:5], v[4:5]
	v_cvt_pk_bf16_f32 v13, v6, v7
	v_pk_mul_f32 v[6:7], v[6:7], v[6:7]
	v_add_f32_e32 v4, v4, v5
	s_waitcnt vmcnt(24)
	v_pk_add_f32 v[10:11], v[10:11], v[166:167]
	v_lshl_add_u64 v[14:15], v[16:17], 1, s[44:45]
	v_add_f32_e32 v4, v6, v4
	global_store_dwordx4 v[18:19], v[8:11], off offset:64
	global_store_dwordx2 v[14:15], v[12:13], off
	v_cvt_pk_bf16_f32 v12, v8, v9
	v_pk_mul_f32 v[8:9], v[8:9], v[8:9]
	v_add_f32_e32 v4, v7, v4
	v_add_f32_e32 v4, v8, v4
	v_cvt_pk_bf16_f32 v13, v10, v11
	v_pk_mul_f32 v[10:11], v[10:11], v[10:11]
	v_add_f32_e32 v4, v9, v4
	v_add_f32_e32 v4, v10, v4
	v_add_f32_e32 v4, v11, v4
	s_nop 1
	v_add_f32_dpp v4, v4, v4 quad_perm:[1,0,3,2] row_mask:0xf bank_mask:0xf
	s_nop 1
	v_add_f32_dpp v4, v4, v4 quad_perm:[2,3,0,1] row_mask:0xf bank_mask:0xf
	s_nop 1
	v_add_f32_dpp v4, v4, v4 row_half_mirror row_mask:0xf bank_mask:0xf
	s_nop 1
	v_add_f32_dpp v4, v4, v4 row_mirror row_mask:0xf bank_mask:0xf
	s_nop 1
	v_add_f32_dpp v4, v4, v4 row_bcast:15 row_mask:0xa bank_mask:0xf
	global_store_dwordx2 v[14:15], v[12:13], off offset:32
	s_and_saveexec_b64 s[8:9], vcc
	s_cbranch_execz .LBB0_284
	v_lshl_add_u64 v[2:3], v[2:3], 4, s[10:11]
	global_store_dword v[2:3], v4, off
.LBB0_284:
	s_or_b64 exec, exec, s[8:9]
	v_add_u32_e32 v2, s6, v96
	v_ashrrev_i32_e32 v3, 31, v2
	s_waitcnt lgkmcnt(0)
	v_lshlrev_b64 v[4:5], 10, v[2:3]
	v_lshl_add_u64 v[16:17], v[4:5], 0, v[66:67]
	v_lshl_add_u64 v[18:19], v[16:17], 2, s[26:27]
	ds_read_b128 v[4:7], v95
	s_waitcnt lgkmcnt(0)
	s_waitcnt vmcnt(27)
	v_pk_add_f32 v[4:5], v[4:5], v[168:169]
	s_waitcnt vmcnt(27)
	v_pk_add_f32 v[6:7], v[6:7], v[170:171]
	ds_read_b128 v[8:11], v95 offset:64
	global_store_dwordx4 v[18:19], v[4:7], off
	s_waitcnt lgkmcnt(0)
	s_waitcnt vmcnt(27)
	v_pk_add_f32 v[8:9], v[8:9], v[172:173]
	v_cvt_pk_bf16_f32 v12, v4, v5
	v_pk_mul_f32 v[4:5], v[4:5], v[4:5]
	v_cvt_pk_bf16_f32 v13, v6, v7
	v_pk_mul_f32 v[6:7], v[6:7], v[6:7]
	v_add_f32_e32 v4, v4, v5
	s_waitcnt vmcnt(27)
	v_pk_add_f32 v[10:11], v[10:11], v[174:175]
	v_lshl_add_u64 v[14:15], v[16:17], 1, s[44:45]
	v_add_f32_e32 v4, v6, v4
	global_store_dwordx4 v[18:19], v[8:11], off offset:64
	global_store_dwordx2 v[14:15], v[12:13], off
	v_cvt_pk_bf16_f32 v12, v8, v9
	v_pk_mul_f32 v[8:9], v[8:9], v[8:9]
	v_add_f32_e32 v4, v7, v4
	v_add_f32_e32 v4, v8, v4
	v_cvt_pk_bf16_f32 v13, v10, v11
	v_pk_mul_f32 v[10:11], v[10:11], v[10:11]
	v_add_f32_e32 v4, v9, v4
	v_add_f32_e32 v4, v10, v4
	v_add_f32_e32 v4, v11, v4
	s_nop 1
	v_add_f32_dpp v4, v4, v4 quad_perm:[1,0,3,2] row_mask:0xf bank_mask:0xf
	s_nop 1
	v_add_f32_dpp v4, v4, v4 quad_perm:[2,3,0,1] row_mask:0xf bank_mask:0xf
	s_nop 1
	v_add_f32_dpp v4, v4, v4 row_half_mirror row_mask:0xf bank_mask:0xf
	s_nop 1
	v_add_f32_dpp v4, v4, v4 row_mirror row_mask:0xf bank_mask:0xf
	s_nop 1
	v_add_f32_dpp v4, v4, v4 row_bcast:15 row_mask:0xa bank_mask:0xf
	global_store_dwordx2 v[14:15], v[12:13], off offset:32
	s_and_saveexec_b64 s[8:9], vcc
	s_cbranch_execz .LBB0_286
	v_lshl_add_u64 v[2:3], v[2:3], 4, s[10:11]
	global_store_dword v[2:3], v4, off
.LBB0_286:
	s_or_b64 exec, exec, s[8:9]
	v_add_u32_e32 v2, s6, v98
	v_ashrrev_i32_e32 v3, 31, v2
	s_waitcnt lgkmcnt(0)
	v_lshlrev_b64 v[4:5], 10, v[2:3]
	v_lshl_add_u64 v[16:17], v[4:5], 0, v[66:67]
	v_lshl_add_u64 v[18:19], v[16:17], 2, s[26:27]
	ds_read_b128 v[4:7], v97
	s_waitcnt lgkmcnt(0)
	s_waitcnt vmcnt(30)
	v_pk_add_f32 v[4:5], v[4:5], v[176:177]
	s_waitcnt vmcnt(30)
	v_pk_add_f32 v[6:7], v[6:7], v[178:179]
	ds_read_b128 v[8:11], v97 offset:64
	global_store_dwordx4 v[18:19], v[4:7], off
	s_waitcnt lgkmcnt(0)
	s_waitcnt vmcnt(30)
	v_pk_add_f32 v[8:9], v[8:9], v[180:181]
	v_cvt_pk_bf16_f32 v12, v4, v5
	v_pk_mul_f32 v[4:5], v[4:5], v[4:5]
	v_cvt_pk_bf16_f32 v13, v6, v7
	v_pk_mul_f32 v[6:7], v[6:7], v[6:7]
	v_add_f32_e32 v4, v4, v5
	s_waitcnt vmcnt(30)
	v_pk_add_f32 v[10:11], v[10:11], v[182:183]
	v_lshl_add_u64 v[14:15], v[16:17], 1, s[44:45]
	v_add_f32_e32 v4, v6, v4
	global_store_dwordx4 v[18:19], v[8:11], off offset:64
	global_store_dwordx2 v[14:15], v[12:13], off
	v_cvt_pk_bf16_f32 v12, v8, v9
	v_pk_mul_f32 v[8:9], v[8:9], v[8:9]
	v_add_f32_e32 v4, v7, v4
	v_add_f32_e32 v4, v8, v4
	v_cvt_pk_bf16_f32 v13, v10, v11
	v_pk_mul_f32 v[10:11], v[10:11], v[10:11]
	v_add_f32_e32 v4, v9, v4
	v_add_f32_e32 v4, v10, v4
	v_add_f32_e32 v4, v11, v4
	s_nop 1
	v_add_f32_dpp v4, v4, v4 quad_perm:[1,0,3,2] row_mask:0xf bank_mask:0xf
	s_nop 1
	v_add_f32_dpp v4, v4, v4 quad_perm:[2,3,0,1] row_mask:0xf bank_mask:0xf
	s_nop 1
	v_add_f32_dpp v4, v4, v4 row_half_mirror row_mask:0xf bank_mask:0xf
	s_nop 1
	v_add_f32_dpp v4, v4, v4 row_mirror row_mask:0xf bank_mask:0xf
	s_nop 1
	v_add_f32_dpp v4, v4, v4 row_bcast:15 row_mask:0xa bank_mask:0xf
	global_store_dwordx2 v[14:15], v[12:13], off offset:32
	s_and_saveexec_b64 s[8:9], vcc
	s_cbranch_execz .LBB0_288
	v_lshl_add_u64 v[2:3], v[2:3], 4, s[10:11]
	global_store_dword v[2:3], v4, off
.LBB0_288:
	s_or_b64 exec, exec, s[8:9]
	v_add_u32_e32 v2, s6, v100
	v_ashrrev_i32_e32 v3, 31, v2
	s_waitcnt lgkmcnt(0)
	v_lshlrev_b64 v[4:5], 10, v[2:3]
	v_lshl_add_u64 v[16:17], v[4:5], 0, v[66:67]
	v_lshl_add_u64 v[18:19], v[16:17], 2, s[26:27]
	ds_read_b128 v[4:7], v99
	s_waitcnt lgkmcnt(0)
	s_waitcnt vmcnt(33)
	v_pk_add_f32 v[4:5], v[4:5], v[184:185]
	s_waitcnt vmcnt(33)
	v_pk_add_f32 v[6:7], v[6:7], v[186:187]
	ds_read_b128 v[8:11], v99 offset:64
	global_store_dwordx4 v[18:19], v[4:7], off
	s_waitcnt lgkmcnt(0)
	s_waitcnt vmcnt(33)
	v_pk_add_f32 v[8:9], v[8:9], v[188:189]
	v_cvt_pk_bf16_f32 v12, v4, v5
	v_pk_mul_f32 v[4:5], v[4:5], v[4:5]
	v_cvt_pk_bf16_f32 v13, v6, v7
	v_pk_mul_f32 v[6:7], v[6:7], v[6:7]
	v_add_f32_e32 v4, v4, v5
	s_waitcnt vmcnt(33)
	v_pk_add_f32 v[10:11], v[10:11], v[190:191]
	v_lshl_add_u64 v[14:15], v[16:17], 1, s[44:45]
	v_add_f32_e32 v4, v6, v4
	global_store_dwordx4 v[18:19], v[8:11], off offset:64
	global_store_dwordx2 v[14:15], v[12:13], off
	v_cvt_pk_bf16_f32 v12, v8, v9
	v_pk_mul_f32 v[8:9], v[8:9], v[8:9]
	v_add_f32_e32 v4, v7, v4
	v_add_f32_e32 v4, v8, v4
	v_cvt_pk_bf16_f32 v13, v10, v11
	v_pk_mul_f32 v[10:11], v[10:11], v[10:11]
	v_add_f32_e32 v4, v9, v4
	v_add_f32_e32 v4, v10, v4
	v_add_f32_e32 v4, v11, v4
	s_nop 1
	v_add_f32_dpp v4, v4, v4 quad_perm:[1,0,3,2] row_mask:0xf bank_mask:0xf
	s_nop 1
	v_add_f32_dpp v4, v4, v4 quad_perm:[2,3,0,1] row_mask:0xf bank_mask:0xf
	s_nop 1
	v_add_f32_dpp v4, v4, v4 row_half_mirror row_mask:0xf bank_mask:0xf
	s_nop 1
	v_add_f32_dpp v4, v4, v4 row_mirror row_mask:0xf bank_mask:0xf
	s_nop 1
	v_add_f32_dpp v4, v4, v4 row_bcast:15 row_mask:0xa bank_mask:0xf
	global_store_dwordx2 v[14:15], v[12:13], off offset:32
	s_and_saveexec_b64 s[8:9], vcc
	s_cbranch_execz .LBB0_290
	v_lshl_add_u64 v[2:3], v[2:3], 4, s[10:11]
	global_store_dword v[2:3], v4, off

.LBB0_323:
	s_and_saveexec_b64 s[72:73], s[6:7]
	s_cbranch_execz .LBB0_310
	ds_read_b128 v[220:223], v245
	ds_read_b128 v[224:227], v245 offset:32
	ds_read_b128 v[2:5], v245 offset:64
	ds_read_b128 v[6:9], v245 offset:96
	s_waitcnt lgkmcnt(3)
	v_mfma_f32_32x32x16_bf16 v[96:111], v[220:223], v[172:175], 0
	ds_read_b128 v[220:223], v245 offset:128
	s_waitcnt lgkmcnt(3)
	v_mfma_f32_32x32x16_bf16 v[96:111], v[224:227], v[168:171], v[96:111]
	ds_read_b128 v[224:227], v245 offset:160
	s_waitcnt lgkmcnt(3)
	v_mfma_f32_32x32x16_bf16 v[96:111], v[2:5], v[164:167], v[96:111]
	ds_read_b128 v[2:5], v245 offset:192
	s_waitcnt lgkmcnt(3)
	v_mfma_f32_32x32x16_bf16 v[96:111], v[6:9], v[160:163], v[96:111]
	ds_read_b128 v[6:9], v245 offset:224
	s_waitcnt lgkmcnt(3)
	v_mfma_f32_32x32x16_bf16 v[96:111], v[220:223], v[156:159], v[96:111]
	ds_read_b128 v[220:223], v245 offset:256
	s_waitcnt lgkmcnt(3)
	v_mfma_f32_32x32x16_bf16 v[96:111], v[224:227], v[152:155], v[96:111]
	ds_read_b128 v[224:227], v245 offset:288
	s_waitcnt lgkmcnt(3)
	v_mfma_f32_32x32x16_bf16 v[96:111], v[2:5], v[148:151], v[96:111]
	ds_read_b128 v[2:5], v245 offset:320
	s_waitcnt lgkmcnt(3)
	v_mfma_f32_32x32x16_bf16 v[96:111], v[6:9], v[144:147], v[96:111]
	ds_read_b128 v[6:9], v245 offset:352
	s_waitcnt lgkmcnt(3)
	v_mfma_f32_32x32x16_bf16 v[96:111], v[220:223], v[140:143], v[96:111]
	ds_read_b128 v[220:223], v245 offset:384
	s_waitcnt lgkmcnt(3)
	v_mfma_f32_32x32x16_bf16 v[96:111], v[224:227], v[136:139], v[96:111]
	ds_read_b128 v[224:227], v245 offset:416
	s_waitcnt lgkmcnt(3)
	v_mfma_f32_32x32x16_bf16 v[96:111], v[2:5], v[132:135], v[96:111]
	ds_read_b128 v[2:5], v245 offset:448
	s_waitcnt lgkmcnt(3)
	v_mfma_f32_32x32x16_bf16 v[96:111], v[6:9], v[128:131], v[96:111]
	ds_read_b128 v[6:9], v245 offset:480
	s_waitcnt lgkmcnt(3)
	v_mfma_f32_32x32x16_bf16 v[96:111], v[220:223], v[124:127], v[96:111]
	ds_read_b128 v[220:223], v245 offset:16896
	s_waitcnt lgkmcnt(3)
	v_mfma_f32_32x32x16_bf16 v[96:111], v[224:227], v[120:123], v[96:111]
	ds_read_b128 v[224:227], v245 offset:16928
	s_waitcnt lgkmcnt(3)
	v_mfma_f32_32x32x16_bf16 v[96:111], v[2:5], v[116:119], v[96:111]
	ds_read_b128 v[2:5], v245 offset:16960
	s_waitcnt lgkmcnt(3)
	v_mfma_f32_32x32x16_bf16 v[96:111], v[6:9], v[112:115], v[96:111]
	ds_read_b128 v[6:9], v245 offset:16992
	s_waitcnt lgkmcnt(3)
	v_mfma_f32_32x32x16_bf16 v[80:95], v[220:223], v[172:175], 0
	ds_read_b128 v[220:223], v245 offset:17024
	s_waitcnt lgkmcnt(3)
	v_mfma_f32_32x32x16_bf16 v[80:95], v[224:227], v[168:171], v[80:95]
	ds_read_b128 v[224:227], v245 offset:17056
	s_waitcnt lgkmcnt(3)
	v_mfma_f32_32x32x16_bf16 v[80:95], v[2:5], v[164:167], v[80:95]
	ds_read_b128 v[2:5], v245 offset:17088
	s_waitcnt lgkmcnt(3)
	v_mfma_f32_32x32x16_bf16 v[80:95], v[6:9], v[160:163], v[80:95]
	ds_read_b128 v[6:9], v245 offset:17120
	s_waitcnt lgkmcnt(3)
	v_mfma_f32_32x32x16_bf16 v[80:95], v[220:223], v[156:159], v[80:95]
	ds_read_b128 v[220:223], v245 offset:17152
	s_waitcnt lgkmcnt(3)
	v_mfma_f32_32x32x16_bf16 v[80:95], v[224:227], v[152:155], v[80:95]
	ds_read_b128 v[224:227], v245 offset:17184
	s_waitcnt lgkmcnt(3)
	v_mfma_f32_32x32x16_bf16 v[80:95], v[2:5], v[148:151], v[80:95]
	ds_read_b128 v[2:5], v245 offset:17216
	s_waitcnt lgkmcnt(3)
	v_mfma_f32_32x32x16_bf16 v[80:95], v[6:9], v[144:147], v[80:95]
	ds_read_b128 v[6:9], v245 offset:17248
	s_waitcnt lgkmcnt(3)
	v_mfma_f32_32x32x16_bf16 v[80:95], v[220:223], v[140:143], v[80:95]
	ds_read_b128 v[220:223], v245 offset:17280
	s_waitcnt lgkmcnt(3)
	v_mfma_f32_32x32x16_bf16 v[80:95], v[224:227], v[136:139], v[80:95]
	ds_read_b128 v[224:227], v245 offset:17312
	s_waitcnt lgkmcnt(3)
	v_mfma_f32_32x32x16_bf16 v[80:95], v[2:5], v[132:135], v[80:95]
	ds_read_b128 v[2:5], v245 offset:17344
	s_waitcnt lgkmcnt(3)
	v_mfma_f32_32x32x16_bf16 v[80:95], v[6:9], v[128:131], v[80:95]
	ds_read_b128 v[6:9], v245 offset:17376
	s_waitcnt lgkmcnt(3)
	v_mfma_f32_32x32x16_bf16 v[80:95], v[220:223], v[124:127], v[80:95]
	s_waitcnt lgkmcnt(2)
	v_mfma_f32_32x32x16_bf16 v[80:95], v[224:227], v[120:123], v[80:95]
	s_waitcnt lgkmcnt(1)
	v_mfma_f32_32x32x16_bf16 v[80:95], v[2:5], v[116:119], v[80:95]
	s_waitcnt lgkmcnt(0)
	v_mfma_f32_32x32x16_bf16 v[80:95], v[6:9], v[112:115], v[80:95]
	v_max_f32_e32 v0, v97, v97
	v_max_f32_e32 v10, v96, v96
	v_max_f32_e32 v0, v10, v0
	v_max3_f32 v0, v0, v98, v99
	v_max3_f32 v0, v0, v100, v101
	v_max3_f32 v0, v0, v102, v103
	v_max3_f32 v0, v0, v104, v105
	v_max3_f32 v0, v0, v106, v107
	v_max3_f32 v0, v0, v108, v109
	v_max3_f32 v0, v0, v110, v111
	v_and_b32_e32 v3, 64, v218
	v_xor_b32_e32 v2, 32, v218
	v_add_u32_e32 v3, 64, v3
	v_cmp_lt_i32_e32 vcc, v2, v3
	s_nop 1
	v_cndmask_b32_e32 v2, v218, v2, vcc
	v_lshlrev_b32_e32 v2, 2, v2
	s_nop 10
	v_max3_f32 v0, v0, v80, v81
	v_max3_f32 v0, v0, v82, v83
	v_max3_f32 v0, v0, v84, v85
	v_max3_f32 v0, v0, v86, v87
	v_max3_f32 v0, v0, v88, v89
	v_max3_f32 v0, v0, v90, v91
	v_max3_f32 v0, v0, v92, v93
	v_max3_f32 v0, v0, v94, v95
	ds_bpermute_b32 v2, v2, v0
	s_waitcnt lgkmcnt(0)
	v_max3_f32 v0, v236, v0, v2
	v_sub_f32 v4, v97, v0
	v_sub_f32 v3, v96, v0
	v_sub_f32 v5, v100, v0
	v_sub_f32_e32 v2, v236, v0
	v_exp_f32_e32 v8, v4
	v_sub_f32 v4, v98, v0
	v_exp_f32_e32 v3, v3
	v_exp_f32_e32 v9, v4
	v_sub_f32 v4, v99, v0
	v_exp_f32_e32 v11, v5
	v_exp_f32_e32 v10, v4
	v_add_f32 v4, v1, v3
	v_sub_f32 v5, v101, v0
	v_exp_f32_e32 v2, v2
	v_add_f32 v4, v4, v8
	v_exp_f32_e32 v12, v5
	v_add_f32 v4, v4, v9
	v_sub_f32 v5, v102, v0
	v_cvt_pk_bf16_f32 v8, v3, v8
	v_add_f32 v4, v4, v10
	v_exp_f32_e32 v13, v5
	v_add_f32 v4, v4, v11
	v_sub_f32 v5, v103, v0
	v_add_u32_e32 v3, 0x9000, v219
	v_add_f32 v4, v4, v12
	v_exp_f32_e32 v14, v5
	v_add_f32 v4, v4, v13
	v_cvt_pk_bf16_f32 v9, v9, v10
	v_add_f32 v96, v4, v14
	v_sub_f32 v4, v104, v0
	v_add_u32_e32 v104, 0x8000, v219
	v_exp_f32_e32 v97, v4
	v_sub_f32 v4, v105, v0
	v_cvt_pk_bf16_f32 v10, v11, v12
	v_exp_f32_e32 v98, v4
	v_sub_f32 v4, v106, v0
	v_cvt_pk_bf16_f32 v11, v13, v14
	v_exp_f32_e32 v99, v4
	v_sub_f32 v4, v107, v0
	ds_read2_b64 v[12:15], v3 offset0:160 offset1:162
	v_exp_f32_e32 v100, v4
	v_sub_f32 v4, v108, v0
	v_mul_f32 v64, v64, v2
	v_mul_f32 v65, v65, v2
	v_mul_f32 v66, v66, v2
	v_mul_f32 v67, v67, v2
	v_mul_f32 v68, v68, v2
	s_nop 0
	v_exp_f32_e32 v101, v4
	v_sub_f32 v4, v109, v0
	v_mul_f32 v69, v69, v2
	v_mul_f32 v70, v70, v2
	v_mul_f32 v71, v71, v2
	v_mul_f32 v72, v72, v2
	v_mul_f32 v73, v73, v2
	s_nop 0
	v_exp_f32_e32 v102, v4
	v_sub_f32 v4, v110, v0
	v_mul_f32 v74, v74, v2
	v_mul_f32 v75, v75, v2
	v_mul_f32 v76, v76, v2
	v_mul_f32 v77, v77, v2
	v_mul_f32 v78, v78, v2
	s_nop 0
	v_exp_f32_e32 v103, v4
	ds_read2_b64 v[4:7], v104 offset0:128 offset1:130
	v_mul_f32 v79, v79, v2
	v_add_u32_e32 v105, 0xa000, v219
	s_waitcnt lgkmcnt(0)
	v_mfma_f32_32x32x16_bf16 v[64:79], v[4:7], v[8:11], v[64:79]
	ds_read2_b64 v[4:7], v105 offset0:192 offset1:194
	v_mul_f32 v48, v48, v2
	v_mul_f32 v49, v49, v2
	v_mul_f32 v50, v50, v2
	v_mul_f32 v51, v51, v2
	v_mul_f32 v52, v52, v2
	v_mul_f32 v53, v53, v2
	v_mul_f32 v54, v54, v2
	v_mul_f32 v55, v55, v2
	v_mul_f32 v56, v56, v2
	v_mul_f32 v57, v57, v2
	v_mul_f32 v58, v58, v2
	v_mul_f32 v59, v59, v2
	v_mul_f32 v60, v60, v2
	v_mul_f32 v61, v61, v2
	v_mul_f32 v62, v62, v2
	v_mul_f32 v63, v63, v2
	v_add_u32_e32 v106, 0xb000, v219
	v_mfma_f32_32x32x16_bf16 v[48:63], v[12:15], v[8:11], v[48:63]
	ds_read2_b64 v[12:15], v106 offset0:224 offset1:226
	v_mul_f32 v32, v32, v2
	v_mul_f32 v33, v33, v2
	v_mul_f32 v34, v34, v2
	v_mul_f32 v35, v35, v2
	v_mul_f32 v36, v36, v2
	v_mul_f32 v37, v37, v2
	v_mul_f32 v38, v38, v2
	v_mul_f32 v39, v39, v2
	v_mul_f32 v40, v40, v2
	v_mul_f32 v41, v41, v2
	v_mul_f32 v42, v42, v2
	v_mul_f32 v43, v43, v2
	v_mul_f32 v44, v44, v2
	v_mul_f32 v45, v45, v2
	v_mul_f32 v46, v46, v2
	v_mul_f32 v47, v47, v2
	v_mul_f32 v16, v16, v2
	v_mul_f32 v17, v17, v2
	v_mul_f32 v18, v18, v2
	v_mul_f32 v19, v19, v2
	v_mul_f32 v20, v20, v2
	s_waitcnt lgkmcnt(1)
	v_mfma_f32_32x32x16_bf16 v[32:47], v[4:7], v[8:11], v[32:47]
	ds_read2_b64 v[4:7], v104 offset0:132 offset1:134
	v_mul_f32 v21, v21, v2
	v_mul_f32 v22, v22, v2
	v_mul_f32 v23, v23, v2
	v_mul_f32 v24, v24, v2
	v_mul_f32 v25, v25, v2
	v_mul_f32 v26, v26, v2
	v_mul_f32 v27, v27, v2
	v_mul_f32 v28, v28, v2
	v_mul_f32 v29, v29, v2
	v_mul_f32 v30, v30, v2
	v_mul_f32 v31, v31, v2
	v_mov_b32_e32 v236, v0
	s_waitcnt lgkmcnt(1)
	v_mfma_f32_32x32x16_bf16 v[16:31], v[12:15], v[8:11], v[16:31]
	v_sub_f32 v8, v111, v0
	v_cvt_pk_bf16_f32 v9, v99, v100
	v_exp_f32_e32 v107, v8
	v_cvt_pk_bf16_f32 v8, v97, v98
	v_cvt_pk_bf16_f32 v10, v101, v102
	ds_read2_b64 v[12:15], v3 offset0:164 offset1:166
	v_cvt_pk_bf16_f32 v11, v103, v107
	s_waitcnt lgkmcnt(1)
	s_nop 0
	v_mfma_f32_32x32x16_bf16 v[64:79], v[4:7], v[8:11], v[64:79]
	v_add_f32 v4, v96, v97
	s_nop 0
	v_add_f32 v4, v4, v98
	s_nop 0
	v_add_f32 v4, v4, v99
	s_nop 0
	v_add_f32 v96, v4, v100
	v_sub_f32 v4, v80, v0
	s_waitcnt lgkmcnt(0)
	v_mfma_f32_32x32x16_bf16 v[48:63], v[12:15], v[8:11], v[48:63]
	v_exp_f32_e32 v80, v4
	ds_read2_b64 v[4:7], v105 offset0:196 offset1:198
	v_sub_f32 v12, v81, v0
	s_nop 0
	v_exp_f32_e32 v81, v12
	v_sub_f32 v12, v82, v0
	s_nop 0
	v_exp_f32_e32 v82, v12
	v_sub_f32 v12, v83, v0
	s_waitcnt lgkmcnt(0)
	v_mfma_f32_32x32x16_bf16 v[32:47], v[4:7], v[8:11], v[32:47]
	v_exp_f32_e32 v83, v12
	ds_read2_b64 v[12:15], v106 offset0:228 offset1:230
	v_sub_f32 v4, v84, v0
	s_nop 0
	v_exp_f32_e32 v84, v4
	v_sub_f32 v4, v85, v0
	s_nop 0
	v_exp_f32_e32 v85, v4
	v_sub_f32 v4, v86, v0
	s_waitcnt lgkmcnt(0)
	v_mfma_f32_32x32x16_bf16 v[16:31], v[12:15], v[8:11], v[16:31]
	v_exp_f32_e32 v86, v4
	ds_read2_b64 v[4:7], v104 offset0:136 offset1:138
	v_sub_f32 v8, v87, v0
	ds_read2_b64 v[12:15], v3 offset0:168 offset1:170
	v_exp_f32_e32 v87, v8
	v_cvt_pk_bf16_f32 v8, v80, v81
	v_cvt_pk_bf16_f32 v9, v82, v83
	v_cvt_pk_bf16_f32 v10, v84, v85
	v_cvt_pk_bf16_f32 v11, v86, v87
	s_waitcnt lgkmcnt(1)
	s_nop 0
	v_mfma_f32_32x32x16_bf16 v[64:79], v[4:7], v[8:11], v[64:79]
	v_add_f32 v4, v96, v101
	s_nop 0
	v_add_f32 v4, v4, v102
	s_nop 0
	v_add_f32 v4, v4, v103
	s_nop 0
	v_add_f32 v96, v4, v107
	v_sub_f32 v4, v88, v0
	s_waitcnt lgkmcnt(0)
	v_mfma_f32_32x32x16_bf16 v[48:63], v[12:15], v[8:11], v[48:63]
	v_exp_f32_e32 v88, v4
	ds_read2_b64 v[4:7], v105 offset0:200 offset1:202
	v_sub_f32 v12, v89, v0
	s_nop 0
	v_exp_f32_e32 v89, v12
	v_sub_f32 v12, v90, v0
	s_nop 0
	v_exp_f32_e32 v90, v12
	v_sub_f32 v12, v91, v0
	s_waitcnt lgkmcnt(0)
	v_mfma_f32_32x32x16_bf16 v[32:47], v[4:7], v[8:11], v[32:47]
	v_exp_f32_e32 v91, v12
	ds_read2_b64 v[12:15], v106 offset0:232 offset1:234
	v_sub_f32 v4, v92, v0
	s_nop 0
	v_exp_f32_e32 v92, v4
	v_sub_f32 v4, v93, v0
	s_nop 0
	v_exp_f32_e32 v93, v4
	v_sub_f32 v4, v94, v0
	s_waitcnt lgkmcnt(0)
	v_mfma_f32_32x32x16_bf16 v[16:31], v[12:15], v[8:11], v[16:31]
	v_exp_f32_e32 v94, v4
	ds_read2_b64 v[4:7], v104 offset0:140 offset1:142
	ds_read2_b64 v[12:15], v3 offset0:172 offset1:174
	v_sub_f32 v8, v95, v0
	v_cvt_pk_bf16_f32 v9, v90, v91
	v_exp_f32_e32 v95, v8
	v_cvt_pk_bf16_f32 v8, v88, v89
	v_cvt_pk_bf16_f32 v10, v92, v93
	v_add_f32 v3, v96, v80
	v_cvt_pk_bf16_f32 v11, v94, v95
	v_add_f32 v3, v3, v81
	s_nop 0
	v_add_f32 v3, v3, v82
	s_waitcnt lgkmcnt(1)
	v_mfma_f32_32x32x16_bf16 v[64:79], v[4:7], v[8:11], v[64:79]
	ds_read2_b64 v[4:7], v105 offset0:204 offset1:206
	v_add_f32 v3, v3, v83
	s_nop 0
	v_add_f32 v3, v3, v84
	s_nop 0
	v_add_f32 v3, v3, v85
	s_waitcnt lgkmcnt(1)
	v_mfma_f32_32x32x16_bf16 v[48:63], v[12:15], v[8:11], v[48:63]
	ds_read2_b64 v[12:15], v106 offset0:236 offset1:238
	v_add_f32 v3, v3, v86
	s_nop 0
	v_add_f32 v3, v3, v87
	s_nop 0
	v_add_f32 v3, v3, v88
	s_nop 0
	v_add_f32 v3, v3, v89
	s_waitcnt lgkmcnt(1)
	v_mfma_f32_32x32x16_bf16 v[32:47], v[4:7], v[8:11], v[32:47]
	v_add_f32 v3, v3, v90
	s_nop 0
	v_add_f32 v3, v3, v91
	s_nop 0
	v_add_f32 v3, v3, v92
	s_nop 0
	v_add_f32 v3, v3, v93
	s_waitcnt lgkmcnt(0)
	v_mfma_f32_32x32x16_bf16 v[16:31], v[12:15], v[8:11], v[16:31]
	v_add_f32 v3, v3, v94
	s_nop 0
	v_add_f32 v3, v3, v95
	s_nop 0
	v_fmac_f32_e32 v3, v246, v2
	v_mov_b32_e32 v246, v3
	s_branch .LBB0_310

.LBB0_417:
	s_or_b64 exec, exec, s[6:7]
	s_movk_i32 s7, 0x410
	v_lshrrev_b32_e32 v130, 2, v142
	v_lshlrev_b32_e32 v131, 1, v142
	v_and_b32_e32 v0, 15, v142
	v_and_b32_e32 v130, 0xfffffcc, v130
	v_and_b32_e32 v131, 0x180, v131
	v_add_u32_e32 v131, 0, v131
	v_lshlrev_b32_e32 v0, 2, v0
	v_mul_lo_u32 v130, v130, s7
	v_add3_u32 v130, v131, v0, v130
	s_waitcnt vmcnt(0)
	s_barrier
	ds_write2_b32 v130, v114, v126 offset1:16
	v_add_u32_e32 v114, 0x400, v130
	ds_write2_b32 v114, v115, v127 offset0:4 offset1:20
	v_add_u32_e32 v115, 0x800, v130
	ds_write2_b32 v115, v116, v128 offset0:8 offset1:24
	v_add_u32_e32 v116, 0xc00, v130
	ds_write2_b32 v116, v117, v129 offset0:12 offset1:28
	v_add_u32_e32 v117, 0x4000, v130
	ds_write2_b32 v117, v82, v94 offset0:64 offset1:80
	v_add_u32_e32 v82, 0x4400, v130
	ds_write2_b32 v82, v83, v95 offset0:68 offset1:84
	v_add_u32_e32 v83, 0x4800, v130
	ds_write2_b32 v83, v84, v96 offset0:72 offset1:88
	v_add_u32_e32 v84, 0x4c00, v130
	ds_write2_b32 v84, v85, v97 offset0:76 offset1:92
	v_add_u32_e32 v85, 0x8000, v130
	ds_write2_b32 v85, v74, v78 offset0:128 offset1:144
	v_add_u32_e32 v74, 0x8400, v130
	ds_write2_b32 v74, v75, v79 offset0:132 offset1:148
	v_add_u32_e32 v75, 0x8800, v130
	ds_write2_b32 v75, v76, v80 offset0:136 offset1:152
	v_add_u32_e32 v76, 0x8c00, v130
	v_add_u32_e32 v80, 0xc000, v130
	ds_write2_b32 v76, v77, v81 offset0:140 offset1:156
	ds_write2_b32 v80, v66, v70 offset0:192 offset1:208
	v_add_u32_e32 v77, 0xc400, v130
	v_add_u32_e32 v78, 0xc800, v130
	v_add_u32_e32 v79, 0xcc00, v130
	v_add_u32_e32 v81, 0x9000, v130
	v_lshlrev_b32_e32 v66, 2, v142
	ds_write2_b32 v77, v67, v71 offset0:196 offset1:212
	ds_write2_b32 v78, v68, v72 offset0:200 offset1:216
	ds_write2_b32 v79, v69, v73 offset0:204 offset1:220
	ds_write2_b32 v130, v98, v118 offset0:128 offset1:144
	ds_write2_b32 v114, v99, v119 offset0:132 offset1:148
	ds_write2_b32 v115, v100, v120 offset0:136 offset1:152
	ds_write2_b32 v116, v101, v121 offset0:140 offset1:156
	ds_write2_b32 v117, v102, v122 offset0:192 offset1:208
	ds_write2_b32 v82, v103, v123 offset0:196 offset1:212
	ds_write2_b32 v83, v104, v124 offset0:200 offset1:216
	ds_write2_b32 v84, v105, v125 offset0:204 offset1:220
	ds_write2_b32 v74, v90, v110 offset1:16
	ds_write2_b32 v75, v91, v111 offset0:4 offset1:20
	ds_write2_b32 v76, v92, v112 offset0:8 offset1:24
	ds_write2_b32 v81, v93, v113 offset0:12 offset1:28
	ds_write2_b32 v77, v86, v106 offset0:64 offset1:80
	ds_write2_b32 v78, v87, v107 offset0:68 offset1:84
	ds_write2_b32 v79, v88, v108 offset0:72 offset1:88
	v_lshlrev_b32_e32 v0, 3, v142
	v_and_b32_e32 v66, 12, v66
	s_movk_i32 s6, 0xe0
	v_ashrrev_i32_e32 v87, 5, v142
	v_and_or_b32 v0, v0, s6, v66
	v_add_u32_e32 v68, s15, v87
	v_or_b32_e32 v66, s36, v0
	v_ashrrev_i32_e32 v69, 31, v68
	v_ashrrev_i32_e32 v67, 31, v66
	v_lshlrev_b64 v[70:71], 10, v[68:69]
	v_lshl_add_u64 v[98:99], v[70:71], 0, v[66:67]
	v_add_u32_e32 v86, 0xd000, v130
	v_lshl_add_u64 v[110:111], v[98:99], 2, s[26:27]
	ds_write2_b32 v86, v89, v109 offset0:76 offset1:92
	s_waitcnt lgkmcnt(0)
	s_barrier
	v_lshlrev_b32_e32 v140, 2, v98
	global_load_dwordx4 v[132:135], v140, s[26:27]
	global_load_dwordx4 v[136:139], v140, s[26:27] offset:64
	v_add_u32_e32 v140, 0x10000, v140
	global_load_dwordx4 v[144:147], v140, s[26:27]
	global_load_dwordx4 v[148:151], v140, s[26:27] offset:64
	v_add_u32_e32 v140, 0x10000, v140
	global_load_dwordx4 v[152:155], v140, s[26:27]
	global_load_dwordx4 v[156:159], v140, s[26:27] offset:64
	v_add_u32_e32 v140, 0x10000, v140
	global_load_dwordx4 v[160:163], v140, s[26:27]
	global_load_dwordx4 v[164:167], v140, s[26:27] offset:64
	v_add_u32_e32 v140, 0x10000, v140
	global_load_dwordx4 v[168:171], v140, s[26:27]
	global_load_dwordx4 v[172:175], v140, s[26:27] offset:64
	v_add_u32_e32 v140, 0x10000, v140
	global_load_dwordx4 v[176:179], v140, s[26:27]
	global_load_dwordx4 v[180:183], v140, s[26:27] offset:64
	v_add_u32_e32 v140, 0x10000, v140
	global_load_dwordx4 v[184:187], v140, s[26:27]
	global_load_dwordx4 v[188:191], v140, s[26:27] offset:64
	v_add_u32_e32 v140, 0x10000, v140
	global_load_dwordx4 v[192:195], v140, s[26:27]
	global_load_dwordx4 v[196:199], v140, s[26:27] offset:64
	v_lshl_add_u32 v101, v0, 2, 0
	v_mul_lo_u32 v72, v87, s7
	v_add_u32_e32 v88, v101, v72
	ds_read_b128 v[102:105], v88
	ds_read_b128 v[106:109], v88 offset:64
	v_and_b32_e32 v70, 64, v218
	v_xor_b32_e32 v0, 1, v218
	v_add_u32_e32 v100, 64, v70
	v_cmp_lt_i32_e32 vcc, v0, v100
	v_xor_b32_e32 v70, 2, v218
	v_xor_b32_e32 v71, 4, v218
	v_cndmask_b32_e32 v0, v218, v0, vcc
	v_lshlrev_b32_e32 v0, 2, v0
	v_cmp_lt_i32_e32 vcc, v70, v100
	v_xor_b32_e32 v112, 8, v218
	v_and_b32_e32 v89, 31, v142
	v_cndmask_b32_e32 v70, v218, v70, vcc
	v_lshlrev_b32_e32 v70, 2, v70
	v_cmp_lt_i32_e32 vcc, v71, v100
	s_ashr_i32 s57, s56, 31
	s_lshl_b64 s[6:7], s[56:57], 2
	v_cndmask_b32_e32 v71, v218, v71, vcc
	v_cmp_lt_i32_e32 vcc, v112, v100
	v_lshlrev_b32_e32 v71, 2, v71
	s_add_u32 s6, s46, s6
	s_movk_i32 s12, 0x410
	s_addc_u32 s7, s47, s7
	s_waitcnt lgkmcnt(1)
	s_waitcnt vmcnt(15)
	v_pk_add_f32 v[90:91], v[102:103], v[132:133]
	s_waitcnt vmcnt(15)
	v_pk_add_f32 v[92:93], v[104:105], v[134:135]
	v_pk_mul_f32 v[72:73], v[90:91], v[90:91]
	v_pk_mul_f32 v[102:103], v[92:93], v[92:93]
	v_add_f32_e32 v72, v72, v73
	s_waitcnt lgkmcnt(0)
	s_waitcnt vmcnt(14)
	v_pk_add_f32 v[94:95], v[106:107], v[136:137]
	v_add_f32_e32 v72, v102, v72
	v_pk_mul_f32 v[104:105], v[94:95], v[94:95]
	v_add_f32_e32 v72, v103, v72
	s_waitcnt vmcnt(14)
	v_pk_add_f32 v[96:97], v[108:109], v[138:139]
	v_add_f32_e32 v72, v104, v72
	v_pk_mul_f32 v[106:107], v[96:97], v[96:97]
	v_add_f32_e32 v72, v105, v72
	v_add_f32_e32 v72, v106, v72
	v_add_f32_e32 v72, v107, v72
	ds_bpermute_b32 v102, v0, v72
	v_xor_b32_e32 v103, 16, v218
	v_cndmask_b32_e32 v73, v218, v112, vcc
	v_cmp_lt_i32_e32 vcc, v103, v100
	v_lshlrev_b32_e32 v73, 2, v73
	s_waitcnt lgkmcnt(0)
	v_add_f32_e32 v102, v72, v102
	ds_bpermute_b32 v104, v70, v102
	v_cndmask_b32_e32 v72, v218, v103, vcc
	v_cmp_eq_u32_e32 vcc, 31, v89
	v_lshlrev_b32_e32 v72, 2, v72
	global_store_dwordx4 v[110:111], v[90:93], off
	s_waitcnt lgkmcnt(0)
	v_add_f32_e32 v89, v102, v104
	ds_bpermute_b32 v100, v71, v89
	v_cvt_pk_bf16_f32 v102, v90, v91
	global_store_dwordx4 v[110:111], v[94:97], off offset:64
	v_cvt_pk_bf16_f32 v103, v92, v93
	v_lshl_add_u64 v[92:93], v[98:99], 1, s[44:45]
	s_waitcnt lgkmcnt(0)
	v_add_f32_e32 v89, v89, v100
	ds_bpermute_b32 v100, v73, v89
	v_cvt_pk_bf16_f32 v94, v94, v95
	v_cvt_pk_bf16_f32 v95, v96, v97
	global_store_dwordx2 v[92:93], v[102:103], off
	global_store_dwordx2 v[92:93], v[94:95], off offset:32
	s_waitcnt lgkmcnt(0)
	v_add_f32_e32 v89, v89, v100
	ds_bpermute_b32 v90, v72, v89
	s_and_saveexec_b64 s[8:9], vcc
	s_cbranch_execz .LBB0_419
	s_waitcnt lgkmcnt(0)
	v_add_f32_e32 v89, v89, v90
	v_lshl_add_u64 v[68:69], v[68:69], 4, s[6:7]
	global_store_dword v[68:69], v89, off
.LBB0_419:
	s_or_b64 exec, exec, s[8:9]
	v_add_u32_e32 v68, 0x200, v142
	s_waitcnt lgkmcnt(0)
	v_ashrrev_i32_e32 v90, 5, v68
	v_mul_lo_u32 v68, v90, s12
	v_add_u32_e32 v89, v101, v68
	v_add_u32_e32 v68, s15, v90
	v_ashrrev_i32_e32 v69, 31, v68
	v_lshlrev_b64 v[92:93], 10, v[68:69]
	v_lshl_add_u64 v[106:107], v[92:93], 0, v[66:67]
	v_lshl_add_u64 v[108:109], v[106:107], 2, s[26:27]
	ds_read_b128 v[92:95], v89
	s_waitcnt lgkmcnt(0)
	s_waitcnt vmcnt(18)
	v_pk_add_f32 v[92:93], v[92:93], v[144:145]
	s_waitcnt vmcnt(18)
	v_pk_add_f32 v[94:95], v[94:95], v[146:147]
	ds_read_b128 v[96:99], v89 offset:64
	global_store_dwordx4 v[108:109], v[92:95], off
	s_waitcnt lgkmcnt(0)
	s_waitcnt vmcnt(18)
	v_pk_add_f32 v[96:97], v[96:97], v[148:149]
	v_cvt_pk_bf16_f32 v102, v92, v93
	v_pk_mul_f32 v[92:93], v[92:93], v[92:93]
	v_cvt_pk_bf16_f32 v103, v94, v95
	v_pk_mul_f32 v[94:95], v[94:95], v[94:95]
	v_add_f32_e32 v91, v92, v93
	s_waitcnt vmcnt(18)
	v_pk_add_f32 v[98:99], v[98:99], v[150:151]
	v_lshl_add_u64 v[104:105], v[106:107], 1, s[44:45]
	v_add_f32_e32 v91, v94, v91
	global_store_dwordx4 v[108:109], v[96:99], off offset:64
	global_store_dwordx2 v[104:105], v[102:103], off
	v_cvt_pk_bf16_f32 v102, v96, v97
	v_pk_mul_f32 v[96:97], v[96:97], v[96:97]
	v_add_f32_e32 v91, v95, v91
	v_add_f32_e32 v91, v96, v91
	v_cvt_pk_bf16_f32 v103, v98, v99
	v_pk_mul_f32 v[98:99], v[98:99], v[98:99]
	v_add_f32_e32 v91, v97, v91
	v_add_f32_e32 v91, v98, v91
	v_add_f32_e32 v91, v99, v91
	s_nop 1
	v_add_f32_dpp v91, v91, v91 quad_perm:[1,0,3,2] row_mask:0xf bank_mask:0xf
	s_nop 1
	v_add_f32_dpp v91, v91, v91 quad_perm:[2,3,0,1] row_mask:0xf bank_mask:0xf
	s_nop 1
	v_add_f32_dpp v91, v91, v91 row_half_mirror row_mask:0xf bank_mask:0xf
	s_nop 1
	v_add_f32_dpp v91, v91, v91 row_mirror row_mask:0xf bank_mask:0xf
	s_nop 1
	v_add_f32_dpp v91, v91, v91 row_bcast:15 row_mask:0xa bank_mask:0xf
	global_store_dwordx2 v[104:105], v[102:103], off offset:32
	s_and_saveexec_b64 s[8:9], vcc
	s_cbranch_execz .LBB0_421
	v_lshl_add_u64 v[68:69], v[68:69], 4, s[6:7]
	global_store_dword v[68:69], v91, off
.LBB0_421:
	s_or_b64 exec, exec, s[8:9]
	v_add_u32_e32 v68, 0x400, v142
	s_waitcnt lgkmcnt(0)
	v_ashrrev_i32_e32 v92, 5, v68
	v_mul_lo_u32 v68, v92, s12
	v_add_u32_e32 v91, v101, v68
	v_add_u32_e32 v68, s15, v92
	v_ashrrev_i32_e32 v69, 31, v68
	v_lshlrev_b64 v[94:95], 10, v[68:69]
	v_lshl_add_u64 v[98:99], v[94:95], 0, v[66:67]
	v_lshl_add_u64 v[110:111], v[98:99], 2, s[26:27]
	ds_read_b128 v[94:97], v91
	v_lshl_add_u64 v[98:99], v[98:99], 1, s[44:45]
	s_waitcnt lgkmcnt(0)
	s_waitcnt vmcnt(21)
	v_pk_add_f32 v[94:95], v[94:95], v[152:153]
	s_waitcnt vmcnt(21)
	v_pk_add_f32 v[96:97], v[96:97], v[154:155]
	ds_read_b128 v[102:105], v91 offset:64
	global_store_dwordx4 v[110:111], v[94:97], off
	s_waitcnt lgkmcnt(0)
	s_waitcnt vmcnt(21)
	v_pk_add_f32 v[102:103], v[102:103], v[156:157]
	v_cvt_pk_bf16_f32 v106, v94, v95
	v_pk_mul_f32 v[94:95], v[94:95], v[94:95]
	s_waitcnt vmcnt(21)
	v_pk_add_f32 v[104:105], v[104:105], v[158:159]
	v_cvt_pk_bf16_f32 v107, v96, v97
	v_pk_mul_f32 v[96:97], v[96:97], v[96:97]
	v_add_f32_e32 v93, v94, v95
	global_store_dwordx4 v[110:111], v[102:105], off offset:64
	global_store_dwordx2 v[98:99], v[106:107], off
	v_cvt_pk_bf16_f32 v106, v102, v103
	v_cvt_pk_bf16_f32 v107, v104, v105
	v_add_f32_e32 v93, v96, v93
	global_store_dwordx2 v[98:99], v[106:107], off offset:32
	v_pk_mul_f32 v[98:99], v[102:103], v[102:103]
	v_add_f32_e32 v93, v97, v93
	v_add_f32_e32 v93, v98, v93
	v_pk_mul_f32 v[102:103], v[104:105], v[104:105]
	v_add_f32_e32 v93, v99, v93
	v_add_f32_e32 v93, v102, v93
	v_add_f32_e32 v93, v103, v93
	s_nop 1
	v_add_f32_dpp v93, v93, v93 quad_perm:[1,0,3,2] row_mask:0xf bank_mask:0xf
	s_nop 1
	v_add_f32_dpp v93, v93, v93 quad_perm:[2,3,0,1] row_mask:0xf bank_mask:0xf
	s_nop 1
	v_add_f32_dpp v93, v93, v93 row_half_mirror row_mask:0xf bank_mask:0xf
	s_nop 1
	v_add_f32_dpp v93, v93, v93 row_mirror row_mask:0xf bank_mask:0xf
	s_nop 1
	v_add_f32_dpp v93, v93, v93 row_bcast:15 row_mask:0xa bank_mask:0xf
	s_and_saveexec_b64 s[8:9], vcc
	s_cbranch_execz .LBB0_423
	v_lshl_add_u64 v[68:69], v[68:69], 4, s[6:7]
	global_store_dword v[68:69], v93, off
.LBB0_423:
	s_or_b64 exec, exec, s[8:9]
	v_add_u32_e32 v68, 0x600, v142
	s_waitcnt lgkmcnt(0)
	v_ashrrev_i32_e32 v94, 5, v68
	v_mul_lo_u32 v68, v94, s12
	v_add_u32_e32 v93, v101, v68
	v_add_u32_e32 v68, s15, v94
	v_ashrrev_i32_e32 v69, 31, v68
	v_lshlrev_b64 v[96:97], 10, v[68:69]
	v_lshl_add_u64 v[110:111], v[96:97], 0, v[66:67]
	v_lshl_add_u64 v[112:113], v[110:111], 2, s[26:27]
	ds_read_b128 v[96:99], v93
	s_waitcnt lgkmcnt(0)
	s_waitcnt vmcnt(24)
	v_pk_add_f32 v[96:97], v[96:97], v[160:161]
	s_waitcnt vmcnt(24)
	v_pk_add_f32 v[98:99], v[98:99], v[162:163]
	ds_read_b128 v[102:105], v93 offset:64
	global_store_dwordx4 v[112:113], v[96:99], off
	s_waitcnt lgkmcnt(0)
	s_waitcnt vmcnt(24)
	v_pk_add_f32 v[102:103], v[102:103], v[164:165]
	v_cvt_pk_bf16_f32 v106, v96, v97
	v_pk_mul_f32 v[96:97], v[96:97], v[96:97]
	v_cvt_pk_bf16_f32 v107, v98, v99
	v_pk_mul_f32 v[98:99], v[98:99], v[98:99]
	v_add_f32_e32 v95, v96, v97
	s_waitcnt vmcnt(24)
	v_pk_add_f32 v[104:105], v[104:105], v[166:167]
	v_lshl_add_u64 v[108:109], v[110:111], 1, s[44:45]
	v_add_f32_e32 v95, v98, v95
	global_store_dwordx4 v[112:113], v[102:105], off offset:64
	global_store_dwordx2 v[108:109], v[106:107], off
	v_cvt_pk_bf16_f32 v106, v102, v103
	v_pk_mul_f32 v[102:103], v[102:103], v[102:103]
	v_add_f32_e32 v95, v99, v95
	v_add_f32_e32 v95, v102, v95
	v_cvt_pk_bf16_f32 v107, v104, v105
	v_pk_mul_f32 v[104:105], v[104:105], v[104:105]
	v_add_f32_e32 v95, v103, v95
	v_add_f32_e32 v95, v104, v95
	v_add_f32_e32 v95, v105, v95
	s_nop 1
	v_add_f32_dpp v95, v95, v95 quad_perm:[1,0,3,2] row_mask:0xf bank_mask:0xf
	s_nop 1
	v_add_f32_dpp v95, v95, v95 quad_perm:[2,3,0,1] row_mask:0xf bank_mask:0xf
	s_nop 1
	v_add_f32_dpp v95, v95, v95 row_half_mirror row_mask:0xf bank_mask:0xf
	s_nop 1
	v_add_f32_dpp v95, v95, v95 row_mirror row_mask:0xf bank_mask:0xf
	s_nop 1
	v_add_f32_dpp v95, v95, v95 row_bcast:15 row_mask:0xa bank_mask:0xf
	global_store_dwordx2 v[108:109], v[106:107], off offset:32
	s_and_saveexec_b64 s[8:9], vcc
	s_cbranch_execz .LBB0_425
	v_lshl_add_u64 v[68:69], v[68:69], 4, s[6:7]
	global_store_dword v[68:69], v95, off
.LBB0_425:
	s_or_b64 exec, exec, s[8:9]
	v_add_u32_e32 v68, 0x800, v142
	s_waitcnt lgkmcnt(0)
	v_ashrrev_i32_e32 v96, 5, v68
	v_mul_lo_u32 v68, v96, s12
	v_add_u32_e32 v95, v101, v68
	v_add_u32_e32 v68, s15, v96
	v_ashrrev_i32_e32 v69, 31, v68
	v_lshlrev_b64 v[98:99], 10, v[68:69]
	v_lshl_add_u64 v[98:99], v[98:99], 0, v[66:67]
	v_lshl_add_u64 v[118:119], v[98:99], 2, s[26:27]
	ds_read_b128 v[102:105], v95
	v_lshl_add_u64 v[98:99], v[98:99], 1, s[44:45]
	s_waitcnt lgkmcnt(0)
	s_waitcnt vmcnt(27)
	v_pk_add_f32 v[102:103], v[102:103], v[168:169]
	s_waitcnt vmcnt(27)
	v_pk_add_f32 v[104:105], v[104:105], v[170:171]
	ds_read_b128 v[106:109], v95 offset:64
	global_store_dwordx4 v[118:119], v[102:105], off
	s_waitcnt lgkmcnt(0)
	s_waitcnt vmcnt(27)
	v_pk_add_f32 v[106:107], v[106:107], v[172:173]
	s_waitcnt vmcnt(27)
	v_pk_add_f32 v[108:109], v[108:109], v[174:175]
	v_cvt_pk_bf16_f32 v110, v102, v103
	v_cvt_pk_bf16_f32 v111, v104, v105
	global_store_dwordx4 v[118:119], v[106:109], off offset:64
	global_store_dwordx2 v[98:99], v[110:111], off
	v_cvt_pk_bf16_f32 v110, v106, v107
	v_cvt_pk_bf16_f32 v111, v108, v109
	global_store_dwordx2 v[98:99], v[110:111], off offset:32
	v_pk_mul_f32 v[98:99], v[102:103], v[102:103]
	v_pk_mul_f32 v[102:103], v[104:105], v[104:105]
	v_add_f32_e32 v97, v98, v99
	v_add_f32_e32 v97, v102, v97
	v_pk_mul_f32 v[104:105], v[106:107], v[106:107]
	v_add_f32_e32 v97, v103, v97
	v_add_f32_e32 v97, v104, v97
	v_pk_mul_f32 v[106:107], v[108:109], v[108:109]
	v_add_f32_e32 v97, v105, v97
	v_add_f32_e32 v97, v106, v97
	v_add_f32_e32 v97, v107, v97
	s_nop 1
	v_add_f32_dpp v97, v97, v97 quad_perm:[1,0,3,2] row_mask:0xf bank_mask:0xf
	s_nop 1
	v_add_f32_dpp v97, v97, v97 quad_perm:[2,3,0,1] row_mask:0xf bank_mask:0xf
	s_nop 1
	v_add_f32_dpp v97, v97, v97 row_half_mirror row_mask:0xf bank_mask:0xf
	s_nop 1
	v_add_f32_dpp v97, v97, v97 row_mirror row_mask:0xf bank_mask:0xf
	s_nop 1
	v_add_f32_dpp v97, v97, v97 row_bcast:15 row_mask:0xa bank_mask:0xf
	s_and_saveexec_b64 s[8:9], vcc
	s_cbranch_execz .LBB0_427
	v_lshl_add_u64 v[68:69], v[68:69], 4, s[6:7]
	global_store_dword v[68:69], v97, off
.LBB0_427:
	s_or_b64 exec, exec, s[8:9]
	v_add_u32_e32 v68, 0xa00, v142
	s_waitcnt lgkmcnt(0)
	v_ashrrev_i32_e32 v98, 5, v68
	v_mul_lo_u32 v68, v98, s12
	v_add_u32_e32 v97, v101, v68
	v_add_u32_e32 v68, s15, v98
	v_ashrrev_i32_e32 v69, 31, v68
	v_lshlrev_b64 v[102:103], 10, v[68:69]
	v_lshl_add_u64 v[118:119], v[102:103], 0, v[66:67]
	v_lshl_add_u64 v[120:121], v[118:119], 2, s[26:27]
	ds_read_b128 v[102:105], v97
	s_waitcnt lgkmcnt(0)
	s_waitcnt vmcnt(30)
	v_pk_add_f32 v[102:103], v[102:103], v[176:177]
	s_waitcnt vmcnt(30)
	v_pk_add_f32 v[104:105], v[104:105], v[178:179]
	ds_read_b128 v[106:109], v97 offset:64
	global_store_dwordx4 v[120:121], v[102:105], off
	s_waitcnt lgkmcnt(0)
	s_waitcnt vmcnt(30)
	v_pk_add_f32 v[106:107], v[106:107], v[180:181]
	v_cvt_pk_bf16_f32 v110, v102, v103
	v_pk_mul_f32 v[102:103], v[102:103], v[102:103]
	v_cvt_pk_bf16_f32 v111, v104, v105
	v_pk_mul_f32 v[104:105], v[104:105], v[104:105]
	v_add_f32_e32 v99, v102, v103
	s_waitcnt vmcnt(30)
	v_pk_add_f32 v[108:109], v[108:109], v[182:183]
	v_lshl_add_u64 v[112:113], v[118:119], 1, s[44:45]
	v_add_f32_e32 v99, v104, v99
	global_store_dwordx4 v[120:121], v[106:109], off offset:64
	global_store_dwordx2 v[112:113], v[110:111], off
	v_cvt_pk_bf16_f32 v110, v106, v107
	v_pk_mul_f32 v[106:107], v[106:107], v[106:107]
	v_add_f32_e32 v99, v105, v99
	v_add_f32_e32 v99, v106, v99
	v_cvt_pk_bf16_f32 v111, v108, v109
	v_pk_mul_f32 v[108:109], v[108:109], v[108:109]
	v_add_f32_e32 v99, v107, v99
	v_add_f32_e32 v99, v108, v99
	v_add_f32_e32 v99, v109, v99
	s_nop 1
	v_add_f32_dpp v99, v99, v99 quad_perm:[1,0,3,2] row_mask:0xf bank_mask:0xf
	s_nop 1
	v_add_f32_dpp v99, v99, v99 quad_perm:[2,3,0,1] row_mask:0xf bank_mask:0xf
	s_nop 1
	v_add_f32_dpp v99, v99, v99 row_half_mirror row_mask:0xf bank_mask:0xf
	s_nop 1
	v_add_f32_dpp v99, v99, v99 row_mirror row_mask:0xf bank_mask:0xf
	s_nop 1
	v_add_f32_dpp v99, v99, v99 row_bcast:15 row_mask:0xa bank_mask:0xf
	global_store_dwordx2 v[112:113], v[110:111], off offset:32
	s_and_saveexec_b64 s[8:9], vcc
	s_cbranch_execz .LBB0_429
	v_lshl_add_u64 v[68:69], v[68:69], 4, s[6:7]
	global_store_dword v[68:69], v99, off
.LBB0_429:
	s_or_b64 exec, exec, s[8:9]
	v_add_u32_e32 v68, 0xc00, v142
	s_waitcnt lgkmcnt(0)
	v_ashrrev_i32_e32 v100, 5, v68
	v_mul_lo_u32 v68, v100, s12
	v_add_u32_e32 v99, v101, v68
	v_add_u32_e32 v68, s15, v100
	v_ashrrev_i32_e32 v69, 31, v68
	v_lshlrev_b64 v[102:103], 10, v[68:69]
	v_lshl_add_u64 v[118:119], v[102:103], 0, v[66:67]
	v_lshl_add_u64 v[120:121], v[118:119], 2, s[26:27]
	ds_read_b128 v[102:105], v99
	s_waitcnt lgkmcnt(0)
	s_waitcnt vmcnt(33)
	v_pk_add_f32 v[102:103], v[102:103], v[184:185]
	s_waitcnt vmcnt(33)
	v_pk_add_f32 v[104:105], v[104:105], v[186:187]
	ds_read_b128 v[106:109], v99 offset:64
	global_store_dwordx4 v[120:121], v[102:105], off
	s_waitcnt lgkmcnt(0)
	s_waitcnt vmcnt(33)
	v_pk_add_f32 v[106:107], v[106:107], v[188:189]
	v_cvt_pk_bf16_f32 v110, v102, v103
	v_pk_mul_f32 v[102:103], v[102:103], v[102:103]
	v_cvt_pk_bf16_f32 v111, v104, v105
	v_pk_mul_f32 v[104:105], v[104:105], v[104:105]
	v_add_f32_e32 v102, v102, v103
	s_waitcnt vmcnt(33)
	v_pk_add_f32 v[108:109], v[108:109], v[190:191]
	v_lshl_add_u64 v[112:113], v[118:119], 1, s[44:45]
	v_add_f32_e32 v102, v104, v102
	global_store_dwordx4 v[120:121], v[106:109], off offset:64
	global_store_dwordx2 v[112:113], v[110:111], off
	v_cvt_pk_bf16_f32 v110, v106, v107
	v_pk_mul_f32 v[106:107], v[106:107], v[106:107]
	v_add_f32_e32 v102, v105, v102
	v_add_f32_e32 v102, v106, v102
	v_cvt_pk_bf16_f32 v111, v108, v109
	v_pk_mul_f32 v[108:109], v[108:109], v[108:109]
	v_add_f32_e32 v102, v107, v102
	v_add_f32_e32 v102, v108, v102
	v_add_f32_e32 v102, v109, v102
	s_nop 1
	v_add_f32_dpp v102, v102, v102 quad_perm:[1,0,3,2] row_mask:0xf bank_mask:0xf
	s_nop 1
	v_add_f32_dpp v102, v102, v102 quad_perm:[2,3,0,1] row_mask:0xf bank_mask:0xf
	s_nop 1
	v_add_f32_dpp v102, v102, v102 row_half_mirror row_mask:0xf bank_mask:0xf
	s_nop 1
	v_add_f32_dpp v102, v102, v102 row_mirror row_mask:0xf bank_mask:0xf
	s_nop 1
	v_add_f32_dpp v102, v102, v102 row_bcast:15 row_mask:0xa bank_mask:0xf
	global_store_dwordx2 v[112:113], v[110:111], off offset:32
	s_and_saveexec_b64 s[8:9], vcc
	s_cbranch_execz .LBB0_431
	v_lshl_add_u64 v[68:69], v[68:69], 4, s[6:7]
	global_store_dword v[68:69], v102, off
.LBB0_431:
	s_or_b64 exec, exec, s[8:9]
	v_add_u32_e32 v68, 0xe00, v142
	v_ashrrev_i32_e32 v102, 5, v68
	v_mul_lo_u32 v68, v102, s12
	v_add_u32_e32 v101, v101, v68
	v_add_u32_e32 v68, s15, v102
	v_ashrrev_i32_e32 v69, 31, v68
	v_lshlrev_b64 v[104:105], 10, v[68:69]
	v_lshl_add_u64 v[112:113], v[104:105], 0, v[66:67]
	v_lshl_add_u64 v[122:123], v[112:113], 2, s[26:27]
	ds_read_b128 v[104:107], v101
	v_lshl_add_u64 v[112:113], v[112:113], 1, s[44:45]
	s_waitcnt lgkmcnt(0)
	s_waitcnt vmcnt(36)
	v_pk_add_f32 v[104:105], v[104:105], v[192:193]
	s_waitcnt vmcnt(36)
	v_pk_add_f32 v[106:107], v[106:107], v[194:195]
	ds_read_b128 v[108:111], v101 offset:64
	global_store_dwordx4 v[122:123], v[104:107], off
	s_waitcnt lgkmcnt(0)
	s_waitcnt vmcnt(36)
	v_pk_add_f32 v[108:109], v[108:109], v[196:197]
	v_cvt_pk_bf16_f32 v118, v104, v105
	v_pk_mul_f32 v[104:105], v[104:105], v[104:105]
	v_cvt_pk_bf16_f32 v119, v106, v107
	v_pk_mul_f32 v[106:107], v[106:107], v[106:107]
	v_add_f32_e32 v103, v104, v105
	s_waitcnt vmcnt(36)
	v_pk_add_f32 v[110:111], v[110:111], v[198:199]
	v_add_f32_e32 v103, v106, v103
	global_store_dwordx4 v[122:123], v[108:111], off offset:64
	global_store_dwordx2 v[112:113], v[118:119], off
	v_cvt_pk_bf16_f32 v118, v108, v109
	v_pk_mul_f32 v[108:109], v[108:109], v[108:109]
	v_add_f32_e32 v103, v107, v103
	v_add_f32_e32 v103, v108, v103
	v_cvt_pk_bf16_f32 v119, v110, v111
	v_pk_mul_f32 v[110:111], v[110:111], v[110:111]
	v_add_f32_e32 v103, v109, v103
	v_add_f32_e32 v103, v110, v103
	v_add_f32_e32 v103, v111, v103
	s_nop 1
	v_add_f32_dpp v103, v103, v103 quad_perm:[1,0,3,2] row_mask:0xf bank_mask:0xf
	s_nop 1
	v_add_f32_dpp v103, v103, v103 quad_perm:[2,3,0,1] row_mask:0xf bank_mask:0xf
	s_nop 1
	v_add_f32_dpp v103, v103, v103 row_half_mirror row_mask:0xf bank_mask:0xf
	s_nop 1
	v_add_f32_dpp v103, v103, v103 row_mirror row_mask:0xf bank_mask:0xf
	s_nop 1
	v_add_f32_dpp v103, v103, v103 row_bcast:15 row_mask:0xa bank_mask:0xf
	global_store_dwordx2 v[112:113], v[118:119], off offset:32
	s_and_saveexec_b64 s[8:9], vcc
	s_cbranch_execz .LBB0_433
	v_lshl_add_u64 v[68:69], v[68:69], 4, s[6:7]
	global_store_dword v[68:69], v103, off

.LBB0_435:
	s_or_b64 exec, exec, s[8:9]
	v_add_u32_e32 v2, s14, v90
	v_ashrrev_i32_e32 v3, 31, v2
	s_waitcnt lgkmcnt(0)
	v_lshlrev_b64 v[4:5], 10, v[2:3]
	v_lshl_add_u64 v[16:17], v[4:5], 0, v[66:67]
	v_lshl_add_u64 v[18:19], v[16:17], 2, s[26:27]
	ds_read_b128 v[4:7], v89
	s_waitcnt lgkmcnt(0)
	s_waitcnt vmcnt(18)
	v_pk_add_f32 v[4:5], v[4:5], v[144:145]
	s_waitcnt vmcnt(18)
	v_pk_add_f32 v[6:7], v[6:7], v[146:147]
	ds_read_b128 v[8:11], v89 offset:64
	global_store_dwordx4 v[18:19], v[4:7], off
	s_waitcnt lgkmcnt(0)
	s_waitcnt vmcnt(18)
	v_pk_add_f32 v[8:9], v[8:9], v[148:149]
	v_cvt_pk_bf16_f32 v12, v4, v5
	v_pk_mul_f32 v[4:5], v[4:5], v[4:5]
	v_cvt_pk_bf16_f32 v13, v6, v7
	v_pk_mul_f32 v[6:7], v[6:7], v[6:7]
	v_add_f32_e32 v4, v4, v5
	s_waitcnt vmcnt(18)
	v_pk_add_f32 v[10:11], v[10:11], v[150:151]
	v_lshl_add_u64 v[14:15], v[16:17], 1, s[44:45]
	v_add_f32_e32 v4, v6, v4
	global_store_dwordx4 v[18:19], v[8:11], off offset:64
	global_store_dwordx2 v[14:15], v[12:13], off
	v_cvt_pk_bf16_f32 v12, v8, v9
	v_pk_mul_f32 v[8:9], v[8:9], v[8:9]
	v_add_f32_e32 v4, v7, v4
	v_add_f32_e32 v4, v8, v4
	v_cvt_pk_bf16_f32 v13, v10, v11
	v_pk_mul_f32 v[10:11], v[10:11], v[10:11]
	v_add_f32_e32 v4, v9, v4
	v_add_f32_e32 v4, v10, v4
	v_add_f32_e32 v4, v11, v4
	s_nop 1
	v_add_f32_dpp v4, v4, v4 quad_perm:[1,0,3,2] row_mask:0xf bank_mask:0xf
	s_nop 1
	v_add_f32_dpp v4, v4, v4 quad_perm:[2,3,0,1] row_mask:0xf bank_mask:0xf
	s_nop 1
	v_add_f32_dpp v4, v4, v4 row_half_mirror row_mask:0xf bank_mask:0xf
	s_nop 1
	v_add_f32_dpp v4, v4, v4 row_mirror row_mask:0xf bank_mask:0xf
	s_nop 1
	v_add_f32_dpp v4, v4, v4 row_bcast:15 row_mask:0xa bank_mask:0xf
	global_store_dwordx2 v[14:15], v[12:13], off offset:32
	s_and_saveexec_b64 s[8:9], vcc
	s_cbranch_execz .LBB0_437
	v_lshl_add_u64 v[2:3], v[2:3], 4, s[6:7]
	global_store_dword v[2:3], v4, off
.LBB0_437:
	s_or_b64 exec, exec, s[8:9]
	v_add_u32_e32 v2, s14, v92
	v_ashrrev_i32_e32 v3, 31, v2
	s_waitcnt lgkmcnt(0)
	v_lshlrev_b64 v[4:5], 10, v[2:3]
	v_lshl_add_u64 v[16:17], v[4:5], 0, v[66:67]
	v_lshl_add_u64 v[18:19], v[16:17], 2, s[26:27]
	ds_read_b128 v[4:7], v91
	s_waitcnt lgkmcnt(0)
	s_waitcnt vmcnt(21)
	v_pk_add_f32 v[4:5], v[4:5], v[152:153]
	s_waitcnt vmcnt(21)
	v_pk_add_f32 v[6:7], v[6:7], v[154:155]
	ds_read_b128 v[8:11], v91 offset:64
	global_store_dwordx4 v[18:19], v[4:7], off
	s_waitcnt lgkmcnt(0)
	s_waitcnt vmcnt(21)
	v_pk_add_f32 v[8:9], v[8:9], v[156:157]
	v_cvt_pk_bf16_f32 v12, v4, v5
	v_pk_mul_f32 v[4:5], v[4:5], v[4:5]
	v_cvt_pk_bf16_f32 v13, v6, v7
	v_pk_mul_f32 v[6:7], v[6:7], v[6:7]
	v_add_f32_e32 v4, v4, v5
	s_waitcnt vmcnt(21)
	v_pk_add_f32 v[10:11], v[10:11], v[158:159]
	v_lshl_add_u64 v[14:15], v[16:17], 1, s[44:45]
	v_add_f32_e32 v4, v6, v4
	global_store_dwordx4 v[18:19], v[8:11], off offset:64
	global_store_dwordx2 v[14:15], v[12:13], off
	v_cvt_pk_bf16_f32 v12, v8, v9
	v_pk_mul_f32 v[8:9], v[8:9], v[8:9]
	v_add_f32_e32 v4, v7, v4
	v_add_f32_e32 v4, v8, v4
	v_cvt_pk_bf16_f32 v13, v10, v11
	v_pk_mul_f32 v[10:11], v[10:11], v[10:11]
	v_add_f32_e32 v4, v9, v4
	v_add_f32_e32 v4, v10, v4
	v_add_f32_e32 v4, v11, v4
	s_nop 1
	v_add_f32_dpp v4, v4, v4 quad_perm:[1,0,3,2] row_mask:0xf bank_mask:0xf
	s_nop 1
	v_add_f32_dpp v4, v4, v4 quad_perm:[2,3,0,1] row_mask:0xf bank_mask:0xf
	s_nop 1
	v_add_f32_dpp v4, v4, v4 row_half_mirror row_mask:0xf bank_mask:0xf
	s_nop 1
	v_add_f32_dpp v4, v4, v4 row_mirror row_mask:0xf bank_mask:0xf
	s_nop 1
	v_add_f32_dpp v4, v4, v4 row_bcast:15 row_mask:0xa bank_mask:0xf
	global_store_dwordx2 v[14:15], v[12:13], off offset:32
	s_and_saveexec_b64 s[8:9], vcc
	s_cbranch_execz .LBB0_439
	v_lshl_add_u64 v[2:3], v[2:3], 4, s[6:7]
	global_store_dword v[2:3], v4, off
.LBB0_439:
	s_or_b64 exec, exec, s[8:9]
	v_add_u32_e32 v2, s14, v94
	v_ashrrev_i32_e32 v3, 31, v2
	s_waitcnt lgkmcnt(0)
	v_lshlrev_b64 v[4:5], 10, v[2:3]
	v_lshl_add_u64 v[16:17], v[4:5], 0, v[66:67]
	v_lshl_add_u64 v[18:19], v[16:17], 2, s[26:27]
	ds_read_b128 v[4:7], v93
	s_waitcnt lgkmcnt(0)
	s_waitcnt vmcnt(24)
	v_pk_add_f32 v[4:5], v[4:5], v[160:161]
	s_waitcnt vmcnt(24)
	v_pk_add_f32 v[6:7], v[6:7], v[162:163]
	ds_read_b128 v[8:11], v93 offset:64
	global_store_dwordx4 v[18:19], v[4:7], off
	s_waitcnt lgkmcnt(0)
	s_waitcnt vmcnt(24)
	v_pk_add_f32 v[8:9], v[8:9], v[164:165]
	v_cvt_pk_bf16_f32 v12, v4, v5
	v_pk_mul_f32 v[4:5], v[4:5], v[4:5]
	v_cvt_pk_bf16_f32 v13, v6, v7
	v_pk_mul_f32 v[6:7], v[6:7], v[6:7]
	v_add_f32_e32 v4, v4, v5
	s_waitcnt vmcnt(24)
	v_pk_add_f32 v[10:11], v[10:11], v[166:167]
	v_lshl_add_u64 v[14:15], v[16:17], 1, s[44:45]
	v_add_f32_e32 v4, v6, v4
	global_store_dwordx4 v[18:19], v[8:11], off offset:64
	global_store_dwordx2 v[14:15], v[12:13], off
	v_cvt_pk_bf16_f32 v12, v8, v9
	v_pk_mul_f32 v[8:9], v[8:9], v[8:9]
	v_add_f32_e32 v4, v7, v4
	v_add_f32_e32 v4, v8, v4
	v_cvt_pk_bf16_f32 v13, v10, v11
	v_pk_mul_f32 v[10:11], v[10:11], v[10:11]
	v_add_f32_e32 v4, v9, v4
	v_add_f32_e32 v4, v10, v4
	v_add_f32_e32 v4, v11, v4
	s_nop 1
	v_add_f32_dpp v4, v4, v4 quad_perm:[1,0,3,2] row_mask:0xf bank_mask:0xf
	s_nop 1
	v_add_f32_dpp v4, v4, v4 quad_perm:[2,3,0,1] row_mask:0xf bank_mask:0xf
	s_nop 1
	v_add_f32_dpp v4, v4, v4 row_half_mirror row_mask:0xf bank_mask:0xf
	s_nop 1
	v_add_f32_dpp v4, v4, v4 row_mirror row_mask:0xf bank_mask:0xf
	s_nop 1
	v_add_f32_dpp v4, v4, v4 row_bcast:15 row_mask:0xa bank_mask:0xf
	global_store_dwordx2 v[14:15], v[12:13], off offset:32
	s_and_saveexec_b64 s[8:9], vcc
	s_cbranch_execz .LBB0_441
	v_lshl_add_u64 v[2:3], v[2:3], 4, s[6:7]
	global_store_dword v[2:3], v4, off
.LBB0_441:
	s_or_b64 exec, exec, s[8:9]
	v_add_u32_e32 v2, s14, v96
	v_ashrrev_i32_e32 v3, 31, v2
	s_waitcnt lgkmcnt(0)
	v_lshlrev_b64 v[4:5], 10, v[2:3]
	v_lshl_add_u64 v[16:17], v[4:5], 0, v[66:67]
	v_lshl_add_u64 v[18:19], v[16:17], 2, s[26:27]
	ds_read_b128 v[4:7], v95
	s_waitcnt lgkmcnt(0)
	s_waitcnt vmcnt(27)
	v_pk_add_f32 v[4:5], v[4:5], v[168:169]
	s_waitcnt vmcnt(27)
	v_pk_add_f32 v[6:7], v[6:7], v[170:171]
	ds_read_b128 v[8:11], v95 offset:64
	global_store_dwordx4 v[18:19], v[4:7], off
	s_waitcnt lgkmcnt(0)
	s_waitcnt vmcnt(27)
	v_pk_add_f32 v[8:9], v[8:9], v[172:173]
	v_cvt_pk_bf16_f32 v12, v4, v5
	v_pk_mul_f32 v[4:5], v[4:5], v[4:5]
	v_cvt_pk_bf16_f32 v13, v6, v7
	v_pk_mul_f32 v[6:7], v[6:7], v[6:7]
	v_add_f32_e32 v4, v4, v5
	s_waitcnt vmcnt(27)
	v_pk_add_f32 v[10:11], v[10:11], v[174:175]
	v_lshl_add_u64 v[14:15], v[16:17], 1, s[44:45]
	v_add_f32_e32 v4, v6, v4
	global_store_dwordx4 v[18:19], v[8:11], off offset:64
	global_store_dwordx2 v[14:15], v[12:13], off
	v_cvt_pk_bf16_f32 v12, v8, v9
	v_pk_mul_f32 v[8:9], v[8:9], v[8:9]
	v_add_f32_e32 v4, v7, v4
	v_add_f32_e32 v4, v8, v4
	v_cvt_pk_bf16_f32 v13, v10, v11
	v_pk_mul_f32 v[10:11], v[10:11], v[10:11]
	v_add_f32_e32 v4, v9, v4
	v_add_f32_e32 v4, v10, v4
	v_add_f32_e32 v4, v11, v4
	s_nop 1
	v_add_f32_dpp v4, v4, v4 quad_perm:[1,0,3,2] row_mask:0xf bank_mask:0xf
	s_nop 1
	v_add_f32_dpp v4, v4, v4 quad_perm:[2,3,0,1] row_mask:0xf bank_mask:0xf
	s_nop 1
	v_add_f32_dpp v4, v4, v4 row_half_mirror row_mask:0xf bank_mask:0xf
	s_nop 1
	v_add_f32_dpp v4, v4, v4 row_mirror row_mask:0xf bank_mask:0xf
	s_nop 1
	v_add_f32_dpp v4, v4, v4 row_bcast:15 row_mask:0xa bank_mask:0xf
	global_store_dwordx2 v[14:15], v[12:13], off offset:32
	s_and_saveexec_b64 s[8:9], vcc
	s_cbranch_execz .LBB0_443
	v_lshl_add_u64 v[2:3], v[2:3], 4, s[6:7]
	global_store_dword v[2:3], v4, off
.LBB0_443:
	s_or_b64 exec, exec, s[8:9]
	v_add_u32_e32 v2, s14, v98
	v_ashrrev_i32_e32 v3, 31, v2
	s_waitcnt lgkmcnt(0)
	v_lshlrev_b64 v[4:5], 10, v[2:3]
	v_lshl_add_u64 v[16:17], v[4:5], 0, v[66:67]
	v_lshl_add_u64 v[18:19], v[16:17], 2, s[26:27]
	ds_read_b128 v[4:7], v97
	s_waitcnt lgkmcnt(0)
	s_waitcnt vmcnt(30)
	v_pk_add_f32 v[4:5], v[4:5], v[176:177]
	s_waitcnt vmcnt(30)
	v_pk_add_f32 v[6:7], v[6:7], v[178:179]
	ds_read_b128 v[8:11], v97 offset:64
	global_store_dwordx4 v[18:19], v[4:7], off
	s_waitcnt lgkmcnt(0)
	s_waitcnt vmcnt(30)
	v_pk_add_f32 v[8:9], v[8:9], v[180:181]
	v_cvt_pk_bf16_f32 v12, v4, v5
	v_pk_mul_f32 v[4:5], v[4:5], v[4:5]
	v_cvt_pk_bf16_f32 v13, v6, v7
	v_pk_mul_f32 v[6:7], v[6:7], v[6:7]
	v_add_f32_e32 v4, v4, v5
	s_waitcnt vmcnt(30)
	v_pk_add_f32 v[10:11], v[10:11], v[182:183]
	v_lshl_add_u64 v[14:15], v[16:17], 1, s[44:45]
	v_add_f32_e32 v4, v6, v4
	global_store_dwordx4 v[18:19], v[8:11], off offset:64
	global_store_dwordx2 v[14:15], v[12:13], off
	v_cvt_pk_bf16_f32 v12, v8, v9
	v_pk_mul_f32 v[8:9], v[8:9], v[8:9]
	v_add_f32_e32 v4, v7, v4
	v_add_f32_e32 v4, v8, v4
	v_cvt_pk_bf16_f32 v13, v10, v11
	v_pk_mul_f32 v[10:11], v[10:11], v[10:11]
	v_add_f32_e32 v4, v9, v4
	v_add_f32_e32 v4, v10, v4
	v_add_f32_e32 v4, v11, v4
	s_nop 1
	v_add_f32_dpp v4, v4, v4 quad_perm:[1,0,3,2] row_mask:0xf bank_mask:0xf
	s_nop 1
	v_add_f32_dpp v4, v4, v4 quad_perm:[2,3,0,1] row_mask:0xf bank_mask:0xf
	s_nop 1
	v_add_f32_dpp v4, v4, v4 row_half_mirror row_mask:0xf bank_mask:0xf
	s_nop 1
	v_add_f32_dpp v4, v4, v4 row_mirror row_mask:0xf bank_mask:0xf
	s_nop 1
	v_add_f32_dpp v4, v4, v4 row_bcast:15 row_mask:0xa bank_mask:0xf
	global_store_dwordx2 v[14:15], v[12:13], off offset:32
	s_and_saveexec_b64 s[8:9], vcc
	s_cbranch_execz .LBB0_445
	v_lshl_add_u64 v[2:3], v[2:3], 4, s[6:7]
	global_store_dword v[2:3], v4, off
.LBB0_445:
	s_or_b64 exec, exec, s[8:9]
	v_add_u32_e32 v2, s14, v100
	v_ashrrev_i32_e32 v3, 31, v2
	s_waitcnt lgkmcnt(0)
	v_lshlrev_b64 v[4:5], 10, v[2:3]
	v_lshl_add_u64 v[16:17], v[4:5], 0, v[66:67]
	v_lshl_add_u64 v[18:19], v[16:17], 2, s[26:27]
	ds_read_b128 v[4:7], v99
	s_waitcnt lgkmcnt(0)
	s_waitcnt vmcnt(33)
	v_pk_add_f32 v[4:5], v[4:5], v[184:185]
	s_waitcnt vmcnt(33)
	v_pk_add_f32 v[6:7], v[6:7], v[186:187]
	ds_read_b128 v[8:11], v99 offset:64
	global_store_dwordx4 v[18:19], v[4:7], off
	s_waitcnt lgkmcnt(0)
	s_waitcnt vmcnt(33)
	v_pk_add_f32 v[8:9], v[8:9], v[188:189]
	v_cvt_pk_bf16_f32 v12, v4, v5
	v_pk_mul_f32 v[4:5], v[4:5], v[4:5]
	v_cvt_pk_bf16_f32 v13, v6, v7
	v_pk_mul_f32 v[6:7], v[6:7], v[6:7]
	v_add_f32_e32 v4, v4, v5
	s_waitcnt vmcnt(33)
	v_pk_add_f32 v[10:11], v[10:11], v[190:191]
	v_lshl_add_u64 v[14:15], v[16:17], 1, s[44:45]
	v_add_f32_e32 v4, v6, v4
	global_store_dwordx4 v[18:19], v[8:11], off offset:64
	global_store_dwordx2 v[14:15], v[12:13], off
	v_cvt_pk_bf16_f32 v12, v8, v9
	v_pk_mul_f32 v[8:9], v[8:9], v[8:9]
	v_add_f32_e32 v4, v7, v4
	v_add_f32_e32 v4, v8, v4
	v_cvt_pk_bf16_f32 v13, v10, v11
	v_pk_mul_f32 v[10:11], v[10:11], v[10:11]
	v_add_f32_e32 v4, v9, v4
	v_add_f32_e32 v4, v10, v4
	v_add_f32_e32 v4, v11, v4
	s_nop 1
	v_add_f32_dpp v4, v4, v4 quad_perm:[1,0,3,2] row_mask:0xf bank_mask:0xf
	s_nop 1
	v_add_f32_dpp v4, v4, v4 quad_perm:[2,3,0,1] row_mask:0xf bank_mask:0xf
	s_nop 1
	v_add_f32_dpp v4, v4, v4 row_half_mirror row_mask:0xf bank_mask:0xf
	s_nop 1
	v_add_f32_dpp v4, v4, v4 row_mirror row_mask:0xf bank_mask:0xf
	s_nop 1
	v_add_f32_dpp v4, v4, v4 row_bcast:15 row_mask:0xa bank_mask:0xf
	global_store_dwordx2 v[14:15], v[12:13], off offset:32
	s_and_saveexec_b64 s[8:9], vcc
	s_cbranch_execz .LBB0_447
	v_lshl_add_u64 v[2:3], v[2:3], 4, s[6:7]
	global_store_dword v[2:3], v4, off

.LBB0_566:
	s_and_saveexec_b64 s[22:23], vcc
	s_cbranch_execz .LBB0_555
	ds_read_b128 v[196:199], v188
	ds_read_b128 v[202:205], v188 offset:32
	ds_read_b128 v[206:209], v188 offset:64
	ds_read_b128 v[210:213], v188 offset:96
	ds_read_b128 v[220:223], v188 offset:128
	ds_read_b128 v[224:227], v188 offset:160
	ds_read_b128 v[2:5], v188 offset:192
	ds_read_b128 v[6:9], v188 offset:224
	s_waitcnt lgkmcnt(7)
	v_mfma_f32_32x32x16_bf16 v[96:111], v[196:199], v[148:151], 0
	ds_read_b128 v[196:199], v188 offset:256
	s_waitcnt lgkmcnt(7)
	v_mfma_f32_32x32x16_bf16 v[96:111], v[202:205], v[144:147], v[96:111]
	ds_read_b128 v[202:205], v188 offset:288
	s_waitcnt lgkmcnt(7)
	v_mfma_f32_32x32x16_bf16 v[96:111], v[206:209], v[140:143], v[96:111]
	ds_read_b128 v[206:209], v188 offset:10752
	s_waitcnt lgkmcnt(7)
	v_mfma_f32_32x32x16_bf16 v[96:111], v[210:213], v[136:139], v[96:111]
	ds_read_b128 v[210:213], v188 offset:10784
	s_waitcnt lgkmcnt(7)
	v_mfma_f32_32x32x16_bf16 v[96:111], v[220:223], v[132:135], v[96:111]
	ds_read_b128 v[220:223], v188 offset:10816
	s_waitcnt lgkmcnt(7)
	v_mfma_f32_32x32x16_bf16 v[96:111], v[224:227], v[128:131], v[96:111]
	ds_read_b128 v[224:227], v188 offset:10848
	s_waitcnt lgkmcnt(7)
	v_mfma_f32_32x32x16_bf16 v[96:111], v[2:5], v[124:127], v[96:111]
	ds_read_b128 v[2:5], v188 offset:10880
	s_waitcnt lgkmcnt(7)
	v_mfma_f32_32x32x16_bf16 v[96:111], v[6:9], v[120:123], v[96:111]
	ds_read_b128 v[6:9], v188 offset:10912
	s_waitcnt lgkmcnt(7)
	v_mfma_f32_32x32x16_bf16 v[96:111], v[196:199], v[116:119], v[96:111]
	ds_read_b128 v[196:199], v188 offset:10944
	s_waitcnt lgkmcnt(7)
	v_mfma_f32_32x32x16_bf16 v[96:111], v[202:205], v[112:115], v[96:111]
	ds_read_b128 v[202:205], v188 offset:10976
	s_waitcnt lgkmcnt(7)
	v_mfma_f32_32x32x16_bf16 v[80:95], v[206:209], v[148:151], 0
	ds_read_b128 v[206:209], v188 offset:11008
	s_waitcnt lgkmcnt(7)
	v_mfma_f32_32x32x16_bf16 v[80:95], v[210:213], v[144:147], v[80:95]
	ds_read_b128 v[210:213], v188 offset:11040
	s_waitcnt lgkmcnt(7)
	v_mfma_f32_32x32x16_bf16 v[80:95], v[220:223], v[140:143], v[80:95]
	s_waitcnt lgkmcnt(6)
	v_mfma_f32_32x32x16_bf16 v[80:95], v[224:227], v[136:139], v[80:95]
	s_waitcnt lgkmcnt(5)
	v_mfma_f32_32x32x16_bf16 v[80:95], v[2:5], v[132:135], v[80:95]
	s_waitcnt lgkmcnt(4)
	v_mfma_f32_32x32x16_bf16 v[80:95], v[6:9], v[128:131], v[80:95]
	s_waitcnt lgkmcnt(3)
	v_mfma_f32_32x32x16_bf16 v[80:95], v[196:199], v[124:127], v[80:95]
	v_max_f32_e32 v0, v97, v97
	v_max_f32_e32 v10, v96, v96
	v_max_f32_e32 v0, v10, v0
	v_max3_f32 v0, v0, v98, v99
	v_max3_f32 v0, v0, v100, v101
	v_max3_f32 v0, v0, v102, v103
	v_max3_f32 v0, v0, v104, v105
	v_max3_f32 v0, v0, v106, v107
	v_max3_f32 v0, v0, v108, v109
	v_max3_f32 v0, v0, v110, v111
	v_and_b32_e32 v3, 64, v218
	v_xor_b32_e32 v2, 32, v218
	v_add_u32_e32 v3, 64, v3
	v_cmp_lt_i32_e64 s[12:13], v2, v3
	s_nop 1
	v_cndmask_b32_e64 v2, v218, v2, s[12:13]
	s_waitcnt lgkmcnt(2)
	v_mfma_f32_32x32x16_bf16 v[80:95], v[202:205], v[120:123], v[80:95]
	s_waitcnt lgkmcnt(1)
	v_mfma_f32_32x32x16_bf16 v[80:95], v[206:209], v[116:119], v[80:95]
	s_waitcnt lgkmcnt(0)
	v_mfma_f32_32x32x16_bf16 v[80:95], v[210:213], v[112:115], v[80:95]
	v_lshlrev_b32_e32 v2, 2, v2
	s_nop 10
	v_max3_f32 v0, v0, v80, v81
	v_max3_f32 v0, v0, v82, v83
	v_max3_f32 v0, v0, v84, v85
	v_max3_f32 v0, v0, v86, v87
	v_max3_f32 v0, v0, v88, v89
	v_max3_f32 v0, v0, v90, v91
	v_max3_f32 v0, v0, v92, v93
	v_max3_f32 v0, v0, v94, v95
	ds_bpermute_b32 v2, v2, v0
	s_waitcnt lgkmcnt(0)
	v_max3_f32 v0, v195, v0, v2
	v_sub_f32 v4, v97, v0
	v_sub_f32 v3, v96, v0
	v_sub_f32 v5, v100, v0
	v_sub_f32_e32 v2, v195, v0
	v_exp_f32_e32 v8, v4
	v_sub_f32 v4, v98, v0
	v_exp_f32_e32 v3, v3
	v_exp_f32_e32 v9, v4
	v_sub_f32 v4, v99, v0
	v_exp_f32_e32 v11, v5
	v_exp_f32_e32 v10, v4
	v_add_f32 v4, v1, v3
	v_sub_f32 v5, v101, v0
	v_exp_f32_e32 v2, v2
	v_add_f32 v4, v4, v8
	v_exp_f32_e32 v12, v5
	v_add_f32 v4, v4, v9
	v_sub_f32 v5, v102, v0
	v_cvt_pk_bf16_f32 v8, v3, v8
	v_add_f32 v4, v4, v10
	v_exp_f32_e32 v13, v5
	v_add_f32 v4, v4, v11
	v_sub_f32 v5, v103, v0
	v_add_u32_e32 v3, 0x6000, v194
	v_add_f32 v4, v4, v12
	v_exp_f32_e32 v14, v5
	v_add_f32 v4, v4, v13
	v_cvt_pk_bf16_f32 v9, v9, v10
	v_add_f32 v96, v4, v14
	v_sub_f32 v4, v104, v0
	v_add_u32_e32 v104, 0x5000, v194
	v_exp_f32_e32 v97, v4
	v_sub_f32 v4, v105, v0
	v_cvt_pk_bf16_f32 v10, v11, v12
	v_exp_f32_e32 v98, v4
	v_sub_f32 v4, v106, v0
	v_cvt_pk_bf16_f32 v11, v13, v14
	v_exp_f32_e32 v99, v4
	v_sub_f32 v4, v107, v0
	ds_read2_b64 v[12:15], v3 offset0:160 offset1:162
	v_exp_f32_e32 v100, v4
	v_sub_f32 v4, v108, v0
	v_mul_f32 v64, v64, v2
	v_mul_f32 v65, v65, v2
	v_mul_f32 v66, v66, v2
	v_mul_f32 v67, v67, v2
	v_mul_f32 v68, v68, v2
	s_nop 0
	v_exp_f32_e32 v101, v4
	v_sub_f32 v4, v109, v0
	v_mul_f32 v69, v69, v2
	v_mul_f32 v70, v70, v2
	v_mul_f32 v71, v71, v2
	v_mul_f32 v72, v72, v2
	v_mul_f32 v73, v73, v2
	s_nop 0
	v_exp_f32_e32 v102, v4
	v_sub_f32 v4, v110, v0
	v_mul_f32 v74, v74, v2
	v_mul_f32 v75, v75, v2
	v_mul_f32 v76, v76, v2
	v_mul_f32 v77, v77, v2
	v_mul_f32 v78, v78, v2
	s_nop 0
	v_exp_f32_e32 v103, v4
	ds_read2_b64 v[4:7], v104 offset0:128 offset1:130
	v_mul_f32 v79, v79, v2
	v_add_u32_e32 v105, 0x7000, v194
	s_waitcnt lgkmcnt(0)
	v_mfma_f32_32x32x16_bf16 v[64:79], v[4:7], v[8:11], v[64:79]
	ds_read2_b64 v[4:7], v105 offset0:192 offset1:194
	v_mul_f32 v48, v48, v2
	v_mul_f32 v49, v49, v2
	v_mul_f32 v50, v50, v2
	v_mul_f32 v51, v51, v2
	v_mul_f32 v52, v52, v2
	v_mul_f32 v53, v53, v2
	v_mul_f32 v54, v54, v2
	v_mul_f32 v55, v55, v2
	v_mul_f32 v56, v56, v2
	v_mul_f32 v57, v57, v2
	v_mul_f32 v58, v58, v2
	v_mul_f32 v59, v59, v2
	v_mul_f32 v60, v60, v2
	v_mul_f32 v61, v61, v2
	v_mul_f32 v62, v62, v2
	v_mul_f32 v63, v63, v2
	v_add_u32_e32 v106, 0x8000, v194
	v_mfma_f32_32x32x16_bf16 v[48:63], v[12:15], v[8:11], v[48:63]
	ds_read2_b64 v[12:15], v106 offset0:224 offset1:226
	v_mul_f32 v32, v32, v2
	v_mul_f32 v33, v33, v2
	v_mul_f32 v34, v34, v2
	v_mul_f32 v35, v35, v2
	v_mul_f32 v36, v36, v2
	v_mul_f32 v37, v37, v2
	v_mul_f32 v38, v38, v2
	v_mul_f32 v39, v39, v2
	v_mul_f32 v40, v40, v2
	v_mul_f32 v41, v41, v2
	v_mul_f32 v42, v42, v2
	v_mul_f32 v43, v43, v2
	v_mul_f32 v44, v44, v2
	v_mul_f32 v45, v45, v2
	v_mul_f32 v46, v46, v2
	v_mul_f32 v47, v47, v2
	v_mul_f32 v16, v16, v2
	v_mul_f32 v17, v17, v2
	v_mul_f32 v18, v18, v2
	v_mul_f32 v19, v19, v2
	v_mul_f32 v20, v20, v2
	s_waitcnt lgkmcnt(1)
	v_mfma_f32_32x32x16_bf16 v[32:47], v[4:7], v[8:11], v[32:47]
	ds_read2_b64 v[4:7], v104 offset0:132 offset1:134
	v_mul_f32 v21, v21, v2
	v_mul_f32 v22, v22, v2
	v_mul_f32 v23, v23, v2
	v_mul_f32 v24, v24, v2
	v_mul_f32 v25, v25, v2
	v_mul_f32 v26, v26, v2
	v_mul_f32 v27, v27, v2
	v_mul_f32 v28, v28, v2
	v_mul_f32 v29, v29, v2
	v_mul_f32 v30, v30, v2
	v_mul_f32 v31, v31, v2
	v_mov_b32_e32 v195, v0
	s_waitcnt lgkmcnt(1)
	v_mfma_f32_32x32x16_bf16 v[16:31], v[12:15], v[8:11], v[16:31]
	v_sub_f32 v8, v111, v0
	v_cvt_pk_bf16_f32 v9, v99, v100
	v_exp_f32_e32 v107, v8
	v_cvt_pk_bf16_f32 v8, v97, v98
	v_cvt_pk_bf16_f32 v10, v101, v102
	ds_read2_b64 v[12:15], v3 offset0:164 offset1:166
	v_cvt_pk_bf16_f32 v11, v103, v107
	s_waitcnt lgkmcnt(1)
	s_nop 0
	v_mfma_f32_32x32x16_bf16 v[64:79], v[4:7], v[8:11], v[64:79]
	v_add_f32 v4, v96, v97
	s_nop 0
	v_add_f32 v4, v4, v98
	s_nop 0
	v_add_f32 v4, v4, v99
	s_nop 0
	v_add_f32 v96, v4, v100
	v_sub_f32 v4, v80, v0
	s_waitcnt lgkmcnt(0)
	v_mfma_f32_32x32x16_bf16 v[48:63], v[12:15], v[8:11], v[48:63]
	v_exp_f32_e32 v80, v4
	ds_read2_b64 v[4:7], v105 offset0:196 offset1:198
	v_sub_f32 v12, v81, v0
	s_nop 0
	v_exp_f32_e32 v81, v12
	v_sub_f32 v12, v82, v0
	s_nop 0
	v_exp_f32_e32 v82, v12
	v_sub_f32 v12, v83, v0
	s_waitcnt lgkmcnt(0)
	v_mfma_f32_32x32x16_bf16 v[32:47], v[4:7], v[8:11], v[32:47]
	v_exp_f32_e32 v83, v12
	ds_read2_b64 v[12:15], v106 offset0:228 offset1:230
	v_sub_f32 v4, v84, v0
	s_nop 0
	v_exp_f32_e32 v84, v4
	v_sub_f32 v4, v85, v0
	s_nop 0
	v_exp_f32_e32 v85, v4
	v_sub_f32 v4, v86, v0
	s_waitcnt lgkmcnt(0)
	v_mfma_f32_32x32x16_bf16 v[16:31], v[12:15], v[8:11], v[16:31]
	v_exp_f32_e32 v86, v4
	ds_read2_b64 v[4:7], v104 offset0:136 offset1:138
	v_sub_f32 v8, v87, v0
	ds_read2_b64 v[12:15], v3 offset0:168 offset1:170
	v_exp_f32_e32 v87, v8
	v_cvt_pk_bf16_f32 v8, v80, v81
	v_cvt_pk_bf16_f32 v9, v82, v83
	v_cvt_pk_bf16_f32 v10, v84, v85
	v_cvt_pk_bf16_f32 v11, v86, v87
	s_waitcnt lgkmcnt(1)
	s_nop 0
	v_mfma_f32_32x32x16_bf16 v[64:79], v[4:7], v[8:11], v[64:79]
	v_add_f32 v4, v96, v101
	s_nop 0
	v_add_f32 v4, v4, v102
	s_nop 0
	v_add_f32 v4, v4, v103
	s_nop 0
	v_add_f32 v96, v4, v107
	v_sub_f32 v4, v88, v0
	s_waitcnt lgkmcnt(0)
	v_mfma_f32_32x32x16_bf16 v[48:63], v[12:15], v[8:11], v[48:63]
	v_exp_f32_e32 v88, v4
	ds_read2_b64 v[4:7], v105 offset0:200 offset1:202
	v_sub_f32 v12, v89, v0
	s_nop 0
	v_exp_f32_e32 v89, v12
	v_sub_f32 v12, v90, v0
	s_nop 0
	v_exp_f32_e32 v90, v12
	v_sub_f32 v12, v91, v0
	s_waitcnt lgkmcnt(0)
	v_mfma_f32_32x32x16_bf16 v[32:47], v[4:7], v[8:11], v[32:47]
	v_exp_f32_e32 v91, v12
	ds_read2_b64 v[12:15], v106 offset0:232 offset1:234
	v_sub_f32 v4, v92, v0
	s_nop 0
	v_exp_f32_e32 v92, v4
	v_sub_f32 v4, v93, v0
	s_nop 0
	v_exp_f32_e32 v93, v4
	v_sub_f32 v4, v94, v0
	s_waitcnt lgkmcnt(0)
	v_mfma_f32_32x32x16_bf16 v[16:31], v[12:15], v[8:11], v[16:31]
	v_exp_f32_e32 v94, v4
	ds_read2_b64 v[4:7], v104 offset0:140 offset1:142
	ds_read2_b64 v[12:15], v3 offset0:172 offset1:174
	v_sub_f32 v8, v95, v0
	v_cvt_pk_bf16_f32 v9, v90, v91
	v_exp_f32_e32 v95, v8
	v_cvt_pk_bf16_f32 v8, v88, v89
	v_cvt_pk_bf16_f32 v10, v92, v93
	v_add_f32 v3, v96, v80
	v_cvt_pk_bf16_f32 v11, v94, v95
	v_add_f32 v3, v3, v81
	s_nop 0
	v_add_f32 v3, v3, v82
	s_waitcnt lgkmcnt(1)
	v_mfma_f32_32x32x16_bf16 v[64:79], v[4:7], v[8:11], v[64:79]
	ds_read2_b64 v[4:7], v105 offset0:204 offset1:206
	v_add_f32 v3, v3, v83
	s_nop 0
	v_add_f32 v3, v3, v84
	s_nop 0
	v_add_f32 v3, v3, v85
	s_waitcnt lgkmcnt(1)
	v_mfma_f32_32x32x16_bf16 v[48:63], v[12:15], v[8:11], v[48:63]
	ds_read2_b64 v[12:15], v106 offset0:236 offset1:238
	v_add_f32 v3, v3, v86
	s_nop 0
	v_add_f32 v3, v3, v87
	s_nop 0
	v_add_f32 v3, v3, v88
	s_nop 0
	v_add_f32 v3, v3, v89
	s_waitcnt lgkmcnt(1)
	v_mfma_f32_32x32x16_bf16 v[32:47], v[4:7], v[8:11], v[32:47]
	v_add_f32 v3, v3, v90
	s_nop 0
	v_add_f32 v3, v3, v91
	s_nop 0
	v_add_f32 v3, v3, v92
	s_nop 0
	v_add_f32 v3, v3, v93
	s_waitcnt lgkmcnt(0)
	v_mfma_f32_32x32x16_bf16 v[16:31], v[12:15], v[8:11], v[16:31]
	v_add_f32 v3, v3, v94
	s_nop 0
	v_add_f32 v3, v3, v95
	s_nop 0
	v_fmac_f32_e32 v3, v184, v2
	v_mov_b32_e32 v184, v3
	s_branch .LBB0_555

.LBB0_598:
	s_and_saveexec_b64 s[24:25], s[6:7]
	s_cbranch_execz .LBB0_587
	ds_read_b128 v[194:197], v185
	ds_read_b128 v[202:205], v185 offset:32
	ds_read_b128 v[206:209], v185 offset:64
	ds_read_b128 v[210:213], v185 offset:96
	ds_read_b128 v[220:223], v185 offset:128
	ds_read_b128 v[224:227], v185 offset:160
	ds_read_b128 v[2:5], v185 offset:192
	ds_read_b128 v[6:9], v185 offset:224
	s_waitcnt lgkmcnt(7)
	v_mfma_f32_32x32x16_bf16 v[96:111], v[194:197], v[148:151], 0
	ds_read_b128 v[194:197], v185 offset:256
	s_waitcnt lgkmcnt(7)
	v_mfma_f32_32x32x16_bf16 v[96:111], v[202:205], v[144:147], v[96:111]
	ds_read_b128 v[202:205], v185 offset:288
	s_waitcnt lgkmcnt(7)
	v_mfma_f32_32x32x16_bf16 v[96:111], v[206:209], v[140:143], v[96:111]
	ds_read_b128 v[206:209], v185 offset:10752
	s_waitcnt lgkmcnt(7)
	v_mfma_f32_32x32x16_bf16 v[96:111], v[210:213], v[136:139], v[96:111]
	ds_read_b128 v[210:213], v185 offset:10784
	s_waitcnt lgkmcnt(7)
	v_mfma_f32_32x32x16_bf16 v[96:111], v[220:223], v[132:135], v[96:111]
	ds_read_b128 v[220:223], v185 offset:10816
	s_waitcnt lgkmcnt(7)
	v_mfma_f32_32x32x16_bf16 v[96:111], v[224:227], v[128:131], v[96:111]
	ds_read_b128 v[224:227], v185 offset:10848
	s_waitcnt lgkmcnt(7)
	v_mfma_f32_32x32x16_bf16 v[96:111], v[2:5], v[124:127], v[96:111]
	ds_read_b128 v[2:5], v185 offset:10880
	s_waitcnt lgkmcnt(7)
	v_mfma_f32_32x32x16_bf16 v[96:111], v[6:9], v[120:123], v[96:111]
	ds_read_b128 v[6:9], v185 offset:10912
	s_waitcnt lgkmcnt(7)
	v_mfma_f32_32x32x16_bf16 v[96:111], v[194:197], v[116:119], v[96:111]
	ds_read_b128 v[194:197], v185 offset:10944
	s_waitcnt lgkmcnt(7)
	v_mfma_f32_32x32x16_bf16 v[96:111], v[202:205], v[112:115], v[96:111]
	ds_read_b128 v[202:205], v185 offset:10976
	s_waitcnt lgkmcnt(7)
	v_mfma_f32_32x32x16_bf16 v[80:95], v[206:209], v[148:151], 0
	ds_read_b128 v[206:209], v185 offset:11008
	s_waitcnt lgkmcnt(7)
	v_mfma_f32_32x32x16_bf16 v[80:95], v[210:213], v[144:147], v[80:95]
	ds_read_b128 v[210:213], v185 offset:11040
	s_waitcnt lgkmcnt(7)
	v_mfma_f32_32x32x16_bf16 v[80:95], v[220:223], v[140:143], v[80:95]
	s_waitcnt lgkmcnt(6)
	v_mfma_f32_32x32x16_bf16 v[80:95], v[224:227], v[136:139], v[80:95]
	s_waitcnt lgkmcnt(5)
	v_mfma_f32_32x32x16_bf16 v[80:95], v[2:5], v[132:135], v[80:95]
	s_waitcnt lgkmcnt(4)
	v_mfma_f32_32x32x16_bf16 v[80:95], v[6:9], v[128:131], v[80:95]
	s_waitcnt lgkmcnt(3)
	v_mfma_f32_32x32x16_bf16 v[80:95], v[194:197], v[124:127], v[80:95]
	v_max_f32_e32 v0, v97, v97
	v_max_f32_e32 v10, v96, v96
	v_max_f32_e32 v0, v10, v0
	v_max3_f32 v0, v0, v98, v99
	v_max3_f32 v0, v0, v100, v101
	v_max3_f32 v0, v0, v102, v103
	v_max3_f32 v0, v0, v104, v105
	v_max3_f32 v0, v0, v106, v107
	v_max3_f32 v0, v0, v108, v109
	v_max3_f32 v0, v0, v110, v111
	v_and_b32_e32 v3, 64, v218
	v_xor_b32_e32 v2, 32, v218
	v_add_u32_e32 v3, 64, v3
	v_cmp_lt_i32_e32 vcc, v2, v3
	s_nop 1
	v_cndmask_b32_e32 v2, v218, v2, vcc
	s_waitcnt lgkmcnt(2)
	v_mfma_f32_32x32x16_bf16 v[80:95], v[202:205], v[120:123], v[80:95]
	s_waitcnt lgkmcnt(1)
	v_mfma_f32_32x32x16_bf16 v[80:95], v[206:209], v[116:119], v[80:95]
	s_waitcnt lgkmcnt(0)
	v_mfma_f32_32x32x16_bf16 v[80:95], v[210:213], v[112:115], v[80:95]
	v_lshlrev_b32_e32 v2, 2, v2
	s_nop 10
	v_max3_f32 v0, v0, v80, v81
	v_max3_f32 v0, v0, v82, v83
	v_max3_f32 v0, v0, v84, v85
	v_max3_f32 v0, v0, v86, v87
	v_max3_f32 v0, v0, v88, v89
	v_max3_f32 v0, v0, v90, v91
	v_max3_f32 v0, v0, v92, v93
	v_max3_f32 v0, v0, v94, v95
	ds_bpermute_b32 v2, v2, v0
	s_waitcnt lgkmcnt(0)
	v_max3_f32 v0, v192, v0, v2
	v_sub_f32 v4, v97, v0
	v_sub_f32 v3, v96, v0
	v_sub_f32 v5, v100, v0
	v_sub_f32_e32 v2, v192, v0
	v_exp_f32_e32 v8, v4
	v_sub_f32 v4, v98, v0
	v_exp_f32_e32 v3, v3
	v_exp_f32_e32 v9, v4
	v_sub_f32 v4, v99, v0
	v_exp_f32_e32 v11, v5
	v_exp_f32_e32 v10, v4
	v_add_f32 v4, v1, v3
	v_sub_f32 v5, v101, v0
	v_exp_f32_e32 v2, v2
	v_add_f32 v4, v4, v8
	v_exp_f32_e32 v12, v5
	v_add_f32 v4, v4, v9
	v_sub_f32 v5, v102, v0
	v_cvt_pk_bf16_f32 v8, v3, v8
	v_add_f32 v4, v4, v10
	v_exp_f32_e32 v13, v5
	v_add_f32 v4, v4, v11
	v_sub_f32 v5, v103, v0
	v_add_u32_e32 v3, 0x6000, v191
	v_add_f32 v4, v4, v12
	v_exp_f32_e32 v14, v5
	v_add_f32 v4, v4, v13
	v_cvt_pk_bf16_f32 v9, v9, v10
	v_add_f32 v96, v4, v14
	v_sub_f32 v4, v104, v0
	v_add_u32_e32 v104, 0x5000, v191
	v_exp_f32_e32 v97, v4
	v_sub_f32 v4, v105, v0
	v_cvt_pk_bf16_f32 v10, v11, v12
	v_exp_f32_e32 v98, v4
	v_sub_f32 v4, v106, v0
	v_cvt_pk_bf16_f32 v11, v13, v14
	v_exp_f32_e32 v99, v4
	v_sub_f32 v4, v107, v0
	ds_read2_b64 v[12:15], v3 offset0:160 offset1:162
	v_exp_f32_e32 v100, v4
	v_sub_f32 v4, v108, v0
	v_mul_f32 v64, v64, v2
	v_mul_f32 v65, v65, v2
	v_mul_f32 v66, v66, v2
	v_mul_f32 v67, v67, v2
	v_mul_f32 v68, v68, v2
	s_nop 0
	v_exp_f32_e32 v101, v4
	v_sub_f32 v4, v109, v0
	v_mul_f32 v69, v69, v2
	v_mul_f32 v70, v70, v2
	v_mul_f32 v71, v71, v2
	v_mul_f32 v72, v72, v2
	v_mul_f32 v73, v73, v2
	s_nop 0
	v_exp_f32_e32 v102, v4
	v_sub_f32 v4, v110, v0
	v_mul_f32 v74, v74, v2
	v_mul_f32 v75, v75, v2
	v_mul_f32 v76, v76, v2
	v_mul_f32 v77, v77, v2
	v_mul_f32 v78, v78, v2
	s_nop 0
	v_exp_f32_e32 v103, v4
	ds_read2_b64 v[4:7], v104 offset0:128 offset1:130
	v_mul_f32 v79, v79, v2
	v_add_u32_e32 v105, 0x7000, v191
	s_waitcnt lgkmcnt(0)
	v_mfma_f32_32x32x16_bf16 v[64:79], v[4:7], v[8:11], v[64:79]
	ds_read2_b64 v[4:7], v105 offset0:192 offset1:194
	v_mul_f32 v48, v48, v2
	v_mul_f32 v49, v49, v2
	v_mul_f32 v50, v50, v2
	v_mul_f32 v51, v51, v2
	v_mul_f32 v52, v52, v2
	v_mul_f32 v53, v53, v2
	v_mul_f32 v54, v54, v2
	v_mul_f32 v55, v55, v2
	v_mul_f32 v56, v56, v2
	v_mul_f32 v57, v57, v2
	v_mul_f32 v58, v58, v2
	v_mul_f32 v59, v59, v2
	v_mul_f32 v60, v60, v2
	v_mul_f32 v61, v61, v2
	v_mul_f32 v62, v62, v2
	v_mul_f32 v63, v63, v2
	v_add_u32_e32 v106, 0x8000, v191
	v_mfma_f32_32x32x16_bf16 v[48:63], v[12:15], v[8:11], v[48:63]
	ds_read2_b64 v[12:15], v106 offset0:224 offset1:226
	v_mul_f32 v32, v32, v2
	v_mul_f32 v33, v33, v2
	v_mul_f32 v34, v34, v2
	v_mul_f32 v35, v35, v2
	v_mul_f32 v36, v36, v2
	v_mul_f32 v37, v37, v2
	v_mul_f32 v38, v38, v2
	v_mul_f32 v39, v39, v2
	v_mul_f32 v40, v40, v2
	v_mul_f32 v41, v41, v2
	v_mul_f32 v42, v42, v2
	v_mul_f32 v43, v43, v2
	v_mul_f32 v44, v44, v2
	v_mul_f32 v45, v45, v2
	v_mul_f32 v46, v46, v2
	v_mul_f32 v47, v47, v2
	v_mul_f32 v16, v16, v2
	v_mul_f32 v17, v17, v2
	v_mul_f32 v18, v18, v2
	v_mul_f32 v19, v19, v2
	v_mul_f32 v20, v20, v2
	s_waitcnt lgkmcnt(1)
	v_mfma_f32_32x32x16_bf16 v[32:47], v[4:7], v[8:11], v[32:47]
	ds_read2_b64 v[4:7], v104 offset0:132 offset1:134
	v_mul_f32 v21, v21, v2
	v_mul_f32 v22, v22, v2
	v_mul_f32 v23, v23, v2
	v_mul_f32 v24, v24, v2
	v_mul_f32 v25, v25, v2
	v_mul_f32 v26, v26, v2
	v_mul_f32 v27, v27, v2
	v_mul_f32 v28, v28, v2
	v_mul_f32 v29, v29, v2
	v_mul_f32 v30, v30, v2
	v_mul_f32 v31, v31, v2
	v_mov_b32_e32 v192, v0
	s_waitcnt lgkmcnt(1)
	v_mfma_f32_32x32x16_bf16 v[16:31], v[12:15], v[8:11], v[16:31]
	v_sub_f32 v8, v111, v0
	v_cvt_pk_bf16_f32 v9, v99, v100
	v_exp_f32_e32 v107, v8
	v_cvt_pk_bf16_f32 v8, v97, v98
	v_cvt_pk_bf16_f32 v10, v101, v102
	ds_read2_b64 v[12:15], v3 offset0:164 offset1:166
	v_cvt_pk_bf16_f32 v11, v103, v107
	s_waitcnt lgkmcnt(1)
	s_nop 0
	v_mfma_f32_32x32x16_bf16 v[64:79], v[4:7], v[8:11], v[64:79]
	v_add_f32 v4, v96, v97
	s_nop 0
	v_add_f32 v4, v4, v98
	s_nop 0
	v_add_f32 v4, v4, v99
	s_nop 0
	v_add_f32 v96, v4, v100
	v_sub_f32 v4, v80, v0
	s_waitcnt lgkmcnt(0)
	v_mfma_f32_32x32x16_bf16 v[48:63], v[12:15], v[8:11], v[48:63]
	v_exp_f32_e32 v80, v4
	ds_read2_b64 v[4:7], v105 offset0:196 offset1:198
	v_sub_f32 v12, v81, v0
	s_nop 0
	v_exp_f32_e32 v81, v12
	v_sub_f32 v12, v82, v0
	s_nop 0
	v_exp_f32_e32 v82, v12
	v_sub_f32 v12, v83, v0
	s_waitcnt lgkmcnt(0)
	v_mfma_f32_32x32x16_bf16 v[32:47], v[4:7], v[8:11], v[32:47]
	v_exp_f32_e32 v83, v12
	ds_read2_b64 v[12:15], v106 offset0:228 offset1:230
	v_sub_f32 v4, v84, v0
	s_nop 0
	v_exp_f32_e32 v84, v4
	v_sub_f32 v4, v85, v0
	s_nop 0
	v_exp_f32_e32 v85, v4
	v_sub_f32 v4, v86, v0
	s_waitcnt lgkmcnt(0)
	v_mfma_f32_32x32x16_bf16 v[16:31], v[12:15], v[8:11], v[16:31]
	v_exp_f32_e32 v86, v4
	ds_read2_b64 v[4:7], v104 offset0:136 offset1:138
	v_sub_f32 v8, v87, v0
	ds_read2_b64 v[12:15], v3 offset0:168 offset1:170
	v_exp_f32_e32 v87, v8
	v_cvt_pk_bf16_f32 v8, v80, v81
	v_cvt_pk_bf16_f32 v9, v82, v83
	v_cvt_pk_bf16_f32 v10, v84, v85
	v_cvt_pk_bf16_f32 v11, v86, v87
	s_waitcnt lgkmcnt(1)
	s_nop 0
	v_mfma_f32_32x32x16_bf16 v[64:79], v[4:7], v[8:11], v[64:79]
	v_add_f32 v4, v96, v101
	s_nop 0
	v_add_f32 v4, v4, v102
	s_nop 0
	v_add_f32 v4, v4, v103
	s_nop 0
	v_add_f32 v96, v4, v107
	v_sub_f32 v4, v88, v0
	s_waitcnt lgkmcnt(0)
	v_mfma_f32_32x32x16_bf16 v[48:63], v[12:15], v[8:11], v[48:63]
	v_exp_f32_e32 v88, v4
	ds_read2_b64 v[4:7], v105 offset0:200 offset1:202
	v_sub_f32 v12, v89, v0
	s_nop 0
	v_exp_f32_e32 v89, v12
	v_sub_f32 v12, v90, v0
	s_nop 0
	v_exp_f32_e32 v90, v12
	v_sub_f32 v12, v91, v0
	s_waitcnt lgkmcnt(0)
	v_mfma_f32_32x32x16_bf16 v[32:47], v[4:7], v[8:11], v[32:47]
	v_exp_f32_e32 v91, v12
	ds_read2_b64 v[12:15], v106 offset0:232 offset1:234
	v_sub_f32 v4, v92, v0
	s_nop 0
	v_exp_f32_e32 v92, v4
	v_sub_f32 v4, v93, v0
	s_nop 0
	v_exp_f32_e32 v93, v4
	v_sub_f32 v4, v94, v0
	s_waitcnt lgkmcnt(0)
	v_mfma_f32_32x32x16_bf16 v[16:31], v[12:15], v[8:11], v[16:31]
	v_exp_f32_e32 v94, v4
	ds_read2_b64 v[4:7], v104 offset0:140 offset1:142
	ds_read2_b64 v[12:15], v3 offset0:172 offset1:174
	v_sub_f32 v8, v95, v0
	v_cvt_pk_bf16_f32 v9, v90, v91
	v_exp_f32_e32 v95, v8
	v_cvt_pk_bf16_f32 v8, v88, v89
	v_cvt_pk_bf16_f32 v10, v92, v93
	v_add_f32 v3, v96, v80
	v_cvt_pk_bf16_f32 v11, v94, v95
	v_add_f32 v3, v3, v81
	s_nop 0
	v_add_f32 v3, v3, v82
	s_waitcnt lgkmcnt(1)
	v_mfma_f32_32x32x16_bf16 v[64:79], v[4:7], v[8:11], v[64:79]
	ds_read2_b64 v[4:7], v105 offset0:204 offset1:206
	v_add_f32 v3, v3, v83
	s_nop 0
	v_add_f32 v3, v3, v84
	s_nop 0
	v_add_f32 v3, v3, v85
	s_waitcnt lgkmcnt(1)
	v_mfma_f32_32x32x16_bf16 v[48:63], v[12:15], v[8:11], v[48:63]
	ds_read2_b64 v[12:15], v106 offset0:236 offset1:238
	v_add_f32 v3, v3, v86
	s_nop 0
	v_add_f32 v3, v3, v87
	s_nop 0
	v_add_f32 v3, v3, v88
	s_nop 0
	v_add_f32 v3, v3, v89
	s_waitcnt lgkmcnt(1)
	v_mfma_f32_32x32x16_bf16 v[32:47], v[4:7], v[8:11], v[32:47]
	v_add_f32 v3, v3, v90
	s_nop 0
	v_add_f32 v3, v3, v91
	s_nop 0
	v_add_f32 v3, v3, v92
	s_nop 0
	v_add_f32 v3, v3, v93
	s_waitcnt lgkmcnt(0)
	v_mfma_f32_32x32x16_bf16 v[16:31], v[12:15], v[8:11], v[16:31]
	v_add_f32 v3, v3, v94
	s_nop 0
	v_add_f32 v3, v3, v95
	s_nop 0
	v_fmac_f32_e32 v3, v184, v2
	v_mov_b32_e32 v184, v3
	s_branch .LBB0_587

.LBB0_1037:
	s_or_b64 exec, exec, s[10:11]
	s_movk_i32 s11, 0x410
	v_lshrrev_b32_e32 v130, 2, v140
	v_lshlrev_b32_e32 v131, 1, v140
	v_and_b32_e32 v0, 15, v140
	v_and_b32_e32 v130, 0xfffffcc, v130
	v_and_b32_e32 v131, 0x180, v131
	v_add_u32_e32 v131, 0, v131
	v_lshlrev_b32_e32 v0, 2, v0
	v_mul_lo_u32 v130, v130, s11
	v_add3_u32 v130, v131, v0, v130
	s_waitcnt vmcnt(0)
	s_barrier
	ds_write2_b32 v130, v114, v126 offset1:16
	v_add_u32_e32 v114, 0x400, v130
	ds_write2_b32 v114, v115, v127 offset0:4 offset1:20
	v_add_u32_e32 v115, 0x800, v130
	ds_write2_b32 v115, v116, v128 offset0:8 offset1:24
	v_add_u32_e32 v116, 0xc00, v130
	ds_write2_b32 v116, v117, v129 offset0:12 offset1:28
	v_add_u32_e32 v117, 0x4000, v130
	ds_write2_b32 v117, v82, v94 offset0:64 offset1:80
	v_add_u32_e32 v82, 0x4400, v130
	ds_write2_b32 v82, v83, v95 offset0:68 offset1:84
	v_add_u32_e32 v83, 0x4800, v130
	ds_write2_b32 v83, v84, v96 offset0:72 offset1:88
	v_add_u32_e32 v84, 0x4c00, v130
	ds_write2_b32 v84, v85, v97 offset0:76 offset1:92
	v_add_u32_e32 v85, 0x8000, v130
	ds_write2_b32 v85, v74, v78 offset0:128 offset1:144
	v_add_u32_e32 v74, 0x8400, v130
	ds_write2_b32 v74, v75, v79 offset0:132 offset1:148
	v_add_u32_e32 v75, 0x8800, v130
	ds_write2_b32 v75, v76, v80 offset0:136 offset1:152
	v_add_u32_e32 v76, 0x8c00, v130
	v_add_u32_e32 v80, 0xc000, v130
	ds_write2_b32 v76, v77, v81 offset0:140 offset1:156
	ds_write2_b32 v80, v66, v70 offset0:192 offset1:208
	v_add_u32_e32 v77, 0xc400, v130
	v_add_u32_e32 v78, 0xc800, v130
	v_add_u32_e32 v79, 0xcc00, v130
	v_add_u32_e32 v81, 0x9000, v130
	v_lshlrev_b32_e32 v66, 2, v140
	ds_write2_b32 v77, v67, v71 offset0:196 offset1:212
	ds_write2_b32 v78, v68, v72 offset0:200 offset1:216
	ds_write2_b32 v79, v69, v73 offset0:204 offset1:220
	ds_write2_b32 v130, v98, v118 offset0:128 offset1:144
	ds_write2_b32 v114, v99, v119 offset0:132 offset1:148
	ds_write2_b32 v115, v100, v120 offset0:136 offset1:152
	ds_write2_b32 v116, v101, v121 offset0:140 offset1:156
	ds_write2_b32 v117, v102, v122 offset0:192 offset1:208
	ds_write2_b32 v82, v103, v123 offset0:196 offset1:212
	ds_write2_b32 v83, v104, v124 offset0:200 offset1:216
	ds_write2_b32 v84, v105, v125 offset0:204 offset1:220
	ds_write2_b32 v74, v90, v110 offset1:16
	ds_write2_b32 v75, v91, v111 offset0:4 offset1:20
	ds_write2_b32 v76, v92, v112 offset0:8 offset1:24
	ds_write2_b32 v81, v93, v113 offset0:12 offset1:28
	ds_write2_b32 v77, v86, v106 offset0:64 offset1:80
	ds_write2_b32 v78, v87, v107 offset0:68 offset1:84
	ds_write2_b32 v79, v88, v108 offset0:72 offset1:88
	v_lshlrev_b32_e32 v0, 3, v140
	v_and_b32_e32 v66, 12, v66
	s_movk_i32 s10, 0xe0
	v_ashrrev_i32_e32 v87, 5, v140
	v_and_or_b32 v0, v0, s10, v66
	v_add_u32_e32 v68, s17, v87
	v_or_b32_e32 v66, s7, v0
	v_ashrrev_i32_e32 v69, 31, v68
	v_ashrrev_i32_e32 v67, 31, v66
	v_lshlrev_b64 v[70:71], 10, v[68:69]
	v_lshl_add_u64 v[98:99], v[70:71], 0, v[66:67]
	v_add_u32_e32 v86, 0xd000, v130
	v_lshl_add_u64 v[110:111], v[98:99], 2, s[18:19]
	ds_write2_b32 v86, v89, v109 offset0:76 offset1:92
	s_waitcnt lgkmcnt(0)
	s_barrier
	v_lshlrev_b32_e32 v141, 2, v98
	global_load_dwordx4 v[132:135], v141, s[18:19]
	global_load_dwordx4 v[136:139], v141, s[18:19] offset:64
	v_add_u32_e32 v141, 0x10000, v141
	global_load_dwordx4 v[142:145], v141, s[18:19]
	global_load_dwordx4 v[146:149], v141, s[18:19] offset:64
	v_add_u32_e32 v141, 0x10000, v141
	global_load_dwordx4 v[150:153], v141, s[18:19]
	global_load_dwordx4 v[154:157], v141, s[18:19] offset:64
	v_add_u32_e32 v141, 0x10000, v141
	global_load_dwordx4 v[158:161], v141, s[18:19]
	global_load_dwordx4 v[162:165], v141, s[18:19] offset:64
	v_add_u32_e32 v141, 0x10000, v141
	global_load_dwordx4 v[166:169], v141, s[18:19]
	global_load_dwordx4 v[170:173], v141, s[18:19] offset:64
	v_add_u32_e32 v141, 0x10000, v141
	global_load_dwordx4 v[174:177], v141, s[18:19]
	global_load_dwordx4 v[178:181], v141, s[18:19] offset:64
	v_add_u32_e32 v141, 0x10000, v141
	global_load_dwordx4 v[182:185], v141, s[18:19]
	global_load_dwordx4 v[186:189], v141, s[18:19] offset:64
	v_add_u32_e32 v141, 0x10000, v141
	global_load_dwordx4 v[190:193], v141, s[18:19]
	global_load_dwordx4 v[194:197], v141, s[18:19] offset:64
	v_lshl_add_u32 v101, v0, 2, 0
	v_mul_lo_u32 v72, v87, s11
	v_add_u32_e32 v88, v101, v72
	ds_read_b128 v[102:105], v88
	ds_read_b128 v[106:109], v88 offset:64
	v_and_b32_e32 v70, 64, v218
	v_xor_b32_e32 v0, 1, v218
	v_add_u32_e32 v100, 64, v70
	v_cmp_lt_i32_e32 vcc, v0, v100
	v_xor_b32_e32 v70, 2, v218
	v_xor_b32_e32 v71, 4, v218
	v_cndmask_b32_e32 v0, v218, v0, vcc
	v_lshlrev_b32_e32 v0, 2, v0
	v_cmp_lt_i32_e32 vcc, v70, v100
	v_xor_b32_e32 v112, 8, v218
	v_and_b32_e32 v89, 31, v140
	v_cndmask_b32_e32 v70, v218, v70, vcc
	v_lshlrev_b32_e32 v70, 2, v70
	v_cmp_lt_i32_e32 vcc, v71, v100
	s_ashr_i32 s7, s6, 31
	s_lshl_b64 s[10:11], s[6:7], 2
	v_cndmask_b32_e32 v71, v218, v71, vcc
	v_cmp_lt_i32_e32 vcc, v112, v100
	v_lshlrev_b32_e32 v71, 2, v71
	s_add_u32 s10, s40, s10
	s_movk_i32 s20, 0x410
	s_addc_u32 s11, s41, s11
	s_waitcnt lgkmcnt(1)
	s_waitcnt vmcnt(15)
	v_pk_fma_f32 v[90:91], v[102:103], 0.5, v[132:133] op_sel_hi:[1,0,1]
	s_waitcnt vmcnt(15)
	v_pk_fma_f32 v[92:93], v[104:105], 0.5, v[134:135] op_sel_hi:[1,0,1]
	v_pk_mul_f32 v[72:73], v[90:91], v[90:91]
	v_pk_mul_f32 v[102:103], v[92:93], v[92:93]
	v_add_f32_e32 v72, v72, v73
	s_waitcnt lgkmcnt(0)
	s_waitcnt vmcnt(14)
	v_pk_fma_f32 v[94:95], v[106:107], 0.5, v[136:137] op_sel_hi:[1,0,1]
	v_add_f32_e32 v72, v102, v72
	v_pk_mul_f32 v[104:105], v[94:95], v[94:95]
	v_add_f32_e32 v72, v103, v72
	s_waitcnt vmcnt(14)
	v_pk_fma_f32 v[96:97], v[108:109], 0.5, v[138:139] op_sel_hi:[1,0,1]
	v_add_f32_e32 v72, v104, v72
	v_pk_mul_f32 v[106:107], v[96:97], v[96:97]
	v_add_f32_e32 v72, v105, v72
	v_add_f32_e32 v72, v106, v72
	v_add_f32_e32 v72, v107, v72
	ds_bpermute_b32 v102, v0, v72
	v_xor_b32_e32 v103, 16, v218
	v_cndmask_b32_e32 v73, v218, v112, vcc
	v_cmp_lt_i32_e32 vcc, v103, v100
	v_lshlrev_b32_e32 v73, 2, v73
	s_waitcnt lgkmcnt(0)
	v_add_f32_e32 v102, v72, v102
	ds_bpermute_b32 v104, v70, v102
	v_cndmask_b32_e32 v72, v218, v103, vcc
	v_cmp_eq_u32_e32 vcc, 31, v89
	v_lshlrev_b32_e32 v72, 2, v72
	global_store_dwordx4 v[110:111], v[90:93], off
	s_waitcnt lgkmcnt(0)
	v_add_f32_e32 v89, v102, v104
	ds_bpermute_b32 v100, v71, v89
	v_cvt_pk_bf16_f32 v102, v90, v91
	global_store_dwordx4 v[110:111], v[94:97], off offset:64
	v_cvt_pk_bf16_f32 v103, v92, v93
	v_lshl_add_u64 v[92:93], v[98:99], 1, s[38:39]
	s_waitcnt lgkmcnt(0)
	v_add_f32_e32 v89, v89, v100
	ds_bpermute_b32 v100, v73, v89
	v_cvt_pk_bf16_f32 v94, v94, v95
	v_cvt_pk_bf16_f32 v95, v96, v97
	global_store_dwordx2 v[92:93], v[102:103], off
	global_store_dwordx2 v[92:93], v[94:95], off offset:32
	s_waitcnt lgkmcnt(0)
	v_add_f32_e32 v89, v89, v100
	ds_bpermute_b32 v90, v72, v89
	s_and_saveexec_b64 s[12:13], vcc
	s_mov_b32 s75, s46
	s_cbranch_execz .LBB0_1039
	s_waitcnt lgkmcnt(0)
	v_add_f32_e32 v89, v89, v90
	v_lshl_add_u64 v[68:69], v[68:69], 4, s[10:11]
	global_store_dword v[68:69], v89, off
.LBB0_1039:
	s_or_b64 exec, exec, s[12:13]
	v_add_u32_e32 v68, 0x200, v140
	s_waitcnt lgkmcnt(0)
	v_ashrrev_i32_e32 v90, 5, v68
	v_mul_lo_u32 v68, v90, s20
	v_add_u32_e32 v89, v101, v68
	v_add_u32_e32 v68, s17, v90
	v_ashrrev_i32_e32 v69, 31, v68
	v_lshlrev_b64 v[92:93], 10, v[68:69]
	v_lshl_add_u64 v[106:107], v[92:93], 0, v[66:67]
	v_lshl_add_u64 v[108:109], v[106:107], 2, s[18:19]
	ds_read_b128 v[92:95], v89
	s_waitcnt lgkmcnt(0)
	s_waitcnt vmcnt(18)
	v_pk_fma_f32 v[92:93], v[92:93], 0.5, v[142:143] op_sel_hi:[1,0,1]
	s_waitcnt vmcnt(18)
	v_pk_fma_f32 v[94:95], v[94:95], 0.5, v[144:145] op_sel_hi:[1,0,1]
	ds_read_b128 v[96:99], v89 offset:64
	global_store_dwordx4 v[108:109], v[92:95], off
	s_waitcnt lgkmcnt(0)
	s_waitcnt vmcnt(18)
	v_pk_fma_f32 v[96:97], v[96:97], 0.5, v[146:147] op_sel_hi:[1,0,1]
	v_cvt_pk_bf16_f32 v102, v92, v93
	v_pk_mul_f32 v[92:93], v[92:93], v[92:93]
	v_cvt_pk_bf16_f32 v103, v94, v95
	v_pk_mul_f32 v[94:95], v[94:95], v[94:95]
	v_add_f32_e32 v91, v92, v93
	s_waitcnt vmcnt(18)
	v_pk_fma_f32 v[98:99], v[98:99], 0.5, v[148:149] op_sel_hi:[1,0,1]
	v_lshl_add_u64 v[104:105], v[106:107], 1, s[38:39]
	v_add_f32_e32 v91, v94, v91
	global_store_dwordx4 v[108:109], v[96:99], off offset:64
	global_store_dwordx2 v[104:105], v[102:103], off
	v_cvt_pk_bf16_f32 v102, v96, v97
	v_pk_mul_f32 v[96:97], v[96:97], v[96:97]
	v_add_f32_e32 v91, v95, v91
	v_add_f32_e32 v91, v96, v91
	v_cvt_pk_bf16_f32 v103, v98, v99
	v_pk_mul_f32 v[98:99], v[98:99], v[98:99]
	v_add_f32_e32 v91, v97, v91
	v_add_f32_e32 v91, v98, v91
	v_add_f32_e32 v91, v99, v91
	s_nop 1
	v_add_f32_dpp v91, v91, v91 quad_perm:[1,0,3,2] row_mask:0xf bank_mask:0xf
	s_nop 1
	v_add_f32_dpp v91, v91, v91 quad_perm:[2,3,0,1] row_mask:0xf bank_mask:0xf
	s_nop 1
	v_add_f32_dpp v91, v91, v91 row_half_mirror row_mask:0xf bank_mask:0xf
	s_nop 1
	v_add_f32_dpp v91, v91, v91 row_mirror row_mask:0xf bank_mask:0xf
	s_nop 1
	v_add_f32_dpp v91, v91, v91 row_bcast:15 row_mask:0xa bank_mask:0xf
	global_store_dwordx2 v[104:105], v[102:103], off offset:32
	s_and_saveexec_b64 s[12:13], vcc
	s_cbranch_execz .LBB0_1041
	v_lshl_add_u64 v[68:69], v[68:69], 4, s[10:11]
	global_store_dword v[68:69], v91, off
.LBB0_1041:
	s_or_b64 exec, exec, s[12:13]
	v_add_u32_e32 v68, 0x400, v140
	s_waitcnt lgkmcnt(0)
	v_ashrrev_i32_e32 v92, 5, v68
	v_mul_lo_u32 v68, v92, s20
	v_add_u32_e32 v91, v101, v68
	v_add_u32_e32 v68, s17, v92
	v_ashrrev_i32_e32 v69, 31, v68
	v_lshlrev_b64 v[94:95], 10, v[68:69]
	v_lshl_add_u64 v[98:99], v[94:95], 0, v[66:67]
	v_lshl_add_u64 v[110:111], v[98:99], 2, s[18:19]
	ds_read_b128 v[94:97], v91
	v_lshl_add_u64 v[98:99], v[98:99], 1, s[38:39]
	s_waitcnt lgkmcnt(0)
	s_waitcnt vmcnt(21)
	v_pk_fma_f32 v[94:95], v[94:95], 0.5, v[150:151] op_sel_hi:[1,0,1]
	s_waitcnt vmcnt(21)
	v_pk_fma_f32 v[96:97], v[96:97], 0.5, v[152:153] op_sel_hi:[1,0,1]
	ds_read_b128 v[102:105], v91 offset:64
	global_store_dwordx4 v[110:111], v[94:97], off
	s_waitcnt lgkmcnt(0)
	s_waitcnt vmcnt(21)
	v_pk_fma_f32 v[102:103], v[102:103], 0.5, v[154:155] op_sel_hi:[1,0,1]
	v_cvt_pk_bf16_f32 v106, v94, v95
	v_pk_mul_f32 v[94:95], v[94:95], v[94:95]
	s_waitcnt vmcnt(21)
	v_pk_fma_f32 v[104:105], v[104:105], 0.5, v[156:157] op_sel_hi:[1,0,1]
	v_cvt_pk_bf16_f32 v107, v96, v97
	v_pk_mul_f32 v[96:97], v[96:97], v[96:97]
	v_add_f32_e32 v93, v94, v95
	global_store_dwordx4 v[110:111], v[102:105], off offset:64
	global_store_dwordx2 v[98:99], v[106:107], off
	v_cvt_pk_bf16_f32 v106, v102, v103
	v_cvt_pk_bf16_f32 v107, v104, v105
	v_add_f32_e32 v93, v96, v93
	global_store_dwordx2 v[98:99], v[106:107], off offset:32
	v_pk_mul_f32 v[98:99], v[102:103], v[102:103]
	v_add_f32_e32 v93, v97, v93
	v_add_f32_e32 v93, v98, v93
	v_pk_mul_f32 v[102:103], v[104:105], v[104:105]
	v_add_f32_e32 v93, v99, v93
	v_add_f32_e32 v93, v102, v93
	v_add_f32_e32 v93, v103, v93
	s_nop 1
	v_add_f32_dpp v93, v93, v93 quad_perm:[1,0,3,2] row_mask:0xf bank_mask:0xf
	s_nop 1
	v_add_f32_dpp v93, v93, v93 quad_perm:[2,3,0,1] row_mask:0xf bank_mask:0xf
	s_nop 1
	v_add_f32_dpp v93, v93, v93 row_half_mirror row_mask:0xf bank_mask:0xf
	s_nop 1
	v_add_f32_dpp v93, v93, v93 row_mirror row_mask:0xf bank_mask:0xf
	s_nop 1
	v_add_f32_dpp v93, v93, v93 row_bcast:15 row_mask:0xa bank_mask:0xf
	s_and_saveexec_b64 s[12:13], vcc
	s_cbranch_execz .LBB0_1043
	v_lshl_add_u64 v[68:69], v[68:69], 4, s[10:11]
	global_store_dword v[68:69], v93, off
.LBB0_1043:
	s_or_b64 exec, exec, s[12:13]
	v_add_u32_e32 v68, 0x600, v140
	s_waitcnt lgkmcnt(0)
	v_ashrrev_i32_e32 v94, 5, v68
	v_mul_lo_u32 v68, v94, s20
	v_add_u32_e32 v93, v101, v68
	v_add_u32_e32 v68, s17, v94
	v_ashrrev_i32_e32 v69, 31, v68
	v_lshlrev_b64 v[96:97], 10, v[68:69]
	v_lshl_add_u64 v[110:111], v[96:97], 0, v[66:67]
	v_lshl_add_u64 v[112:113], v[110:111], 2, s[18:19]
	ds_read_b128 v[96:99], v93
	s_waitcnt lgkmcnt(0)
	s_waitcnt vmcnt(24)
	v_pk_fma_f32 v[96:97], v[96:97], 0.5, v[158:159] op_sel_hi:[1,0,1]
	s_waitcnt vmcnt(24)
	v_pk_fma_f32 v[98:99], v[98:99], 0.5, v[160:161] op_sel_hi:[1,0,1]
	ds_read_b128 v[102:105], v93 offset:64
	global_store_dwordx4 v[112:113], v[96:99], off
	s_waitcnt lgkmcnt(0)
	s_waitcnt vmcnt(24)
	v_pk_fma_f32 v[102:103], v[102:103], 0.5, v[162:163] op_sel_hi:[1,0,1]
	v_cvt_pk_bf16_f32 v106, v96, v97
	v_pk_mul_f32 v[96:97], v[96:97], v[96:97]
	v_cvt_pk_bf16_f32 v107, v98, v99
	v_pk_mul_f32 v[98:99], v[98:99], v[98:99]
	v_add_f32_e32 v95, v96, v97
	s_waitcnt vmcnt(24)
	v_pk_fma_f32 v[104:105], v[104:105], 0.5, v[164:165] op_sel_hi:[1,0,1]
	v_lshl_add_u64 v[108:109], v[110:111], 1, s[38:39]
	v_add_f32_e32 v95, v98, v95
	global_store_dwordx4 v[112:113], v[102:105], off offset:64
	global_store_dwordx2 v[108:109], v[106:107], off
	v_cvt_pk_bf16_f32 v106, v102, v103
	v_pk_mul_f32 v[102:103], v[102:103], v[102:103]
	v_add_f32_e32 v95, v99, v95
	v_add_f32_e32 v95, v102, v95
	v_cvt_pk_bf16_f32 v107, v104, v105
	v_pk_mul_f32 v[104:105], v[104:105], v[104:105]
	v_add_f32_e32 v95, v103, v95
	v_add_f32_e32 v95, v104, v95
	v_add_f32_e32 v95, v105, v95
	s_nop 1
	v_add_f32_dpp v95, v95, v95 quad_perm:[1,0,3,2] row_mask:0xf bank_mask:0xf
	s_nop 1
	v_add_f32_dpp v95, v95, v95 quad_perm:[2,3,0,1] row_mask:0xf bank_mask:0xf
	s_nop 1
	v_add_f32_dpp v95, v95, v95 row_half_mirror row_mask:0xf bank_mask:0xf
	s_nop 1
	v_add_f32_dpp v95, v95, v95 row_mirror row_mask:0xf bank_mask:0xf
	s_nop 1
	v_add_f32_dpp v95, v95, v95 row_bcast:15 row_mask:0xa bank_mask:0xf
	global_store_dwordx2 v[108:109], v[106:107], off offset:32
	s_and_saveexec_b64 s[12:13], vcc
	s_cbranch_execz .LBB0_1045
	v_lshl_add_u64 v[68:69], v[68:69], 4, s[10:11]
	global_store_dword v[68:69], v95, off
.LBB0_1045:
	s_or_b64 exec, exec, s[12:13]
	v_add_u32_e32 v68, 0x800, v140
	s_waitcnt lgkmcnt(0)
	v_ashrrev_i32_e32 v96, 5, v68
	v_mul_lo_u32 v68, v96, s20
	v_add_u32_e32 v95, v101, v68
	v_add_u32_e32 v68, s17, v96
	v_ashrrev_i32_e32 v69, 31, v68
	v_lshlrev_b64 v[98:99], 10, v[68:69]
	v_lshl_add_u64 v[98:99], v[98:99], 0, v[66:67]
	v_lshl_add_u64 v[118:119], v[98:99], 2, s[18:19]
	ds_read_b128 v[102:105], v95
	v_lshl_add_u64 v[98:99], v[98:99], 1, s[38:39]
	s_waitcnt lgkmcnt(0)
	s_waitcnt vmcnt(27)
	v_pk_fma_f32 v[102:103], v[102:103], 0.5, v[166:167] op_sel_hi:[1,0,1]
	s_waitcnt vmcnt(27)
	v_pk_fma_f32 v[104:105], v[104:105], 0.5, v[168:169] op_sel_hi:[1,0,1]
	ds_read_b128 v[106:109], v95 offset:64
	global_store_dwordx4 v[118:119], v[102:105], off
	s_waitcnt lgkmcnt(0)
	s_waitcnt vmcnt(27)
	v_pk_fma_f32 v[106:107], v[106:107], 0.5, v[170:171] op_sel_hi:[1,0,1]
	s_waitcnt vmcnt(27)
	v_pk_fma_f32 v[108:109], v[108:109], 0.5, v[172:173] op_sel_hi:[1,0,1]
	v_cvt_pk_bf16_f32 v110, v102, v103
	v_cvt_pk_bf16_f32 v111, v104, v105
	global_store_dwordx4 v[118:119], v[106:109], off offset:64
	global_store_dwordx2 v[98:99], v[110:111], off
	v_cvt_pk_bf16_f32 v110, v106, v107
	v_cvt_pk_bf16_f32 v111, v108, v109
	global_store_dwordx2 v[98:99], v[110:111], off offset:32
	v_pk_mul_f32 v[98:99], v[102:103], v[102:103]
	v_pk_mul_f32 v[102:103], v[104:105], v[104:105]
	v_add_f32_e32 v97, v98, v99
	v_add_f32_e32 v97, v102, v97
	v_pk_mul_f32 v[104:105], v[106:107], v[106:107]
	v_add_f32_e32 v97, v103, v97
	v_add_f32_e32 v97, v104, v97
	v_pk_mul_f32 v[106:107], v[108:109], v[108:109]
	v_add_f32_e32 v97, v105, v97
	v_add_f32_e32 v97, v106, v97
	v_add_f32_e32 v97, v107, v97
	s_nop 1
	v_add_f32_dpp v97, v97, v97 quad_perm:[1,0,3,2] row_mask:0xf bank_mask:0xf
	s_nop 1
	v_add_f32_dpp v97, v97, v97 quad_perm:[2,3,0,1] row_mask:0xf bank_mask:0xf
	s_nop 1
	v_add_f32_dpp v97, v97, v97 row_half_mirror row_mask:0xf bank_mask:0xf
	s_nop 1
	v_add_f32_dpp v97, v97, v97 row_mirror row_mask:0xf bank_mask:0xf
	s_nop 1
	v_add_f32_dpp v97, v97, v97 row_bcast:15 row_mask:0xa bank_mask:0xf
	s_and_saveexec_b64 s[12:13], vcc
	s_cbranch_execz .LBB0_1047
	v_lshl_add_u64 v[68:69], v[68:69], 4, s[10:11]
	global_store_dword v[68:69], v97, off
.LBB0_1047:
	s_or_b64 exec, exec, s[12:13]
	v_add_u32_e32 v68, 0xa00, v140
	s_waitcnt lgkmcnt(0)
	v_ashrrev_i32_e32 v98, 5, v68
	v_mul_lo_u32 v68, v98, s20
	v_add_u32_e32 v97, v101, v68
	v_add_u32_e32 v68, s17, v98
	v_ashrrev_i32_e32 v69, 31, v68
	v_lshlrev_b64 v[102:103], 10, v[68:69]
	v_lshl_add_u64 v[118:119], v[102:103], 0, v[66:67]
	v_lshl_add_u64 v[120:121], v[118:119], 2, s[18:19]
	ds_read_b128 v[102:105], v97
	s_waitcnt lgkmcnt(0)
	s_waitcnt vmcnt(30)
	v_pk_fma_f32 v[102:103], v[102:103], 0.5, v[174:175] op_sel_hi:[1,0,1]
	s_waitcnt vmcnt(30)
	v_pk_fma_f32 v[104:105], v[104:105], 0.5, v[176:177] op_sel_hi:[1,0,1]
	ds_read_b128 v[106:109], v97 offset:64
	global_store_dwordx4 v[120:121], v[102:105], off
	s_waitcnt lgkmcnt(0)
	s_waitcnt vmcnt(30)
	v_pk_fma_f32 v[106:107], v[106:107], 0.5, v[178:179] op_sel_hi:[1,0,1]
	v_cvt_pk_bf16_f32 v110, v102, v103
	v_pk_mul_f32 v[102:103], v[102:103], v[102:103]
	v_cvt_pk_bf16_f32 v111, v104, v105
	v_pk_mul_f32 v[104:105], v[104:105], v[104:105]
	v_add_f32_e32 v99, v102, v103
	s_waitcnt vmcnt(30)
	v_pk_fma_f32 v[108:109], v[108:109], 0.5, v[180:181] op_sel_hi:[1,0,1]
	v_lshl_add_u64 v[112:113], v[118:119], 1, s[38:39]
	v_add_f32_e32 v99, v104, v99
	global_store_dwordx4 v[120:121], v[106:109], off offset:64
	global_store_dwordx2 v[112:113], v[110:111], off
	v_cvt_pk_bf16_f32 v110, v106, v107
	v_pk_mul_f32 v[106:107], v[106:107], v[106:107]
	v_add_f32_e32 v99, v105, v99
	v_add_f32_e32 v99, v106, v99
	v_cvt_pk_bf16_f32 v111, v108, v109
	v_pk_mul_f32 v[108:109], v[108:109], v[108:109]
	v_add_f32_e32 v99, v107, v99
	v_add_f32_e32 v99, v108, v99
	v_add_f32_e32 v99, v109, v99
	s_nop 1
	v_add_f32_dpp v99, v99, v99 quad_perm:[1,0,3,2] row_mask:0xf bank_mask:0xf
	s_nop 1
	v_add_f32_dpp v99, v99, v99 quad_perm:[2,3,0,1] row_mask:0xf bank_mask:0xf
	s_nop 1
	v_add_f32_dpp v99, v99, v99 row_half_mirror row_mask:0xf bank_mask:0xf
	s_nop 1
	v_add_f32_dpp v99, v99, v99 row_mirror row_mask:0xf bank_mask:0xf
	s_nop 1
	v_add_f32_dpp v99, v99, v99 row_bcast:15 row_mask:0xa bank_mask:0xf
	global_store_dwordx2 v[112:113], v[110:111], off offset:32
	s_and_saveexec_b64 s[12:13], vcc
	s_cbranch_execz .LBB0_1049
	v_lshl_add_u64 v[68:69], v[68:69], 4, s[10:11]
	global_store_dword v[68:69], v99, off
.LBB0_1049:
	s_or_b64 exec, exec, s[12:13]
	v_add_u32_e32 v68, 0xc00, v140
	s_waitcnt lgkmcnt(0)
	v_ashrrev_i32_e32 v100, 5, v68
	v_mul_lo_u32 v68, v100, s20
	v_add_u32_e32 v99, v101, v68
	v_add_u32_e32 v68, s17, v100
	v_ashrrev_i32_e32 v69, 31, v68
	v_lshlrev_b64 v[102:103], 10, v[68:69]
	v_lshl_add_u64 v[118:119], v[102:103], 0, v[66:67]
	v_lshl_add_u64 v[120:121], v[118:119], 2, s[18:19]
	ds_read_b128 v[102:105], v99
	s_waitcnt lgkmcnt(0)
	s_waitcnt vmcnt(33)
	v_pk_fma_f32 v[102:103], v[102:103], 0.5, v[182:183] op_sel_hi:[1,0,1]
	s_waitcnt vmcnt(33)
	v_pk_fma_f32 v[104:105], v[104:105], 0.5, v[184:185] op_sel_hi:[1,0,1]
	ds_read_b128 v[106:109], v99 offset:64
	global_store_dwordx4 v[120:121], v[102:105], off
	s_waitcnt lgkmcnt(0)
	s_waitcnt vmcnt(33)
	v_pk_fma_f32 v[106:107], v[106:107], 0.5, v[186:187] op_sel_hi:[1,0,1]
	v_cvt_pk_bf16_f32 v110, v102, v103
	v_pk_mul_f32 v[102:103], v[102:103], v[102:103]
	v_cvt_pk_bf16_f32 v111, v104, v105
	v_pk_mul_f32 v[104:105], v[104:105], v[104:105]
	v_add_f32_e32 v102, v102, v103
	s_waitcnt vmcnt(33)
	v_pk_fma_f32 v[108:109], v[108:109], 0.5, v[188:189] op_sel_hi:[1,0,1]
	v_lshl_add_u64 v[112:113], v[118:119], 1, s[38:39]
	v_add_f32_e32 v102, v104, v102
	global_store_dwordx4 v[120:121], v[106:109], off offset:64
	global_store_dwordx2 v[112:113], v[110:111], off
	v_cvt_pk_bf16_f32 v110, v106, v107
	v_pk_mul_f32 v[106:107], v[106:107], v[106:107]
	v_add_f32_e32 v102, v105, v102
	v_add_f32_e32 v102, v106, v102
	v_cvt_pk_bf16_f32 v111, v108, v109
	v_pk_mul_f32 v[108:109], v[108:109], v[108:109]
	v_add_f32_e32 v102, v107, v102
	v_add_f32_e32 v102, v108, v102
	v_add_f32_e32 v102, v109, v102
	s_nop 1
	v_add_f32_dpp v102, v102, v102 quad_perm:[1,0,3,2] row_mask:0xf bank_mask:0xf
	s_nop 1
	v_add_f32_dpp v102, v102, v102 quad_perm:[2,3,0,1] row_mask:0xf bank_mask:0xf
	s_nop 1
	v_add_f32_dpp v102, v102, v102 row_half_mirror row_mask:0xf bank_mask:0xf
	s_nop 1
	v_add_f32_dpp v102, v102, v102 row_mirror row_mask:0xf bank_mask:0xf
	s_nop 1
	v_add_f32_dpp v102, v102, v102 row_bcast:15 row_mask:0xa bank_mask:0xf
	global_store_dwordx2 v[112:113], v[110:111], off offset:32
	s_and_saveexec_b64 s[12:13], vcc
	s_cbranch_execz .LBB0_1051
	v_lshl_add_u64 v[68:69], v[68:69], 4, s[10:11]
	global_store_dword v[68:69], v102, off
.LBB0_1051:
	s_or_b64 exec, exec, s[12:13]
	v_add_u32_e32 v68, 0xe00, v140
	v_ashrrev_i32_e32 v102, 5, v68
	v_mul_lo_u32 v68, v102, s20
	v_add_u32_e32 v101, v101, v68
	v_add_u32_e32 v68, s17, v102
	v_ashrrev_i32_e32 v69, 31, v68
	v_lshlrev_b64 v[104:105], 10, v[68:69]
	v_lshl_add_u64 v[112:113], v[104:105], 0, v[66:67]
	v_lshl_add_u64 v[122:123], v[112:113], 2, s[18:19]
	ds_read_b128 v[104:107], v101
	v_lshl_add_u64 v[112:113], v[112:113], 1, s[38:39]
	s_waitcnt lgkmcnt(0)
	s_waitcnt vmcnt(36)
	v_pk_fma_f32 v[104:105], v[104:105], 0.5, v[190:191] op_sel_hi:[1,0,1]
	s_waitcnt vmcnt(36)
	v_pk_fma_f32 v[106:107], v[106:107], 0.5, v[192:193] op_sel_hi:[1,0,1]
	ds_read_b128 v[108:111], v101 offset:64
	global_store_dwordx4 v[122:123], v[104:107], off
	s_waitcnt lgkmcnt(0)
	s_waitcnt vmcnt(36)
	v_pk_fma_f32 v[108:109], v[108:109], 0.5, v[194:195] op_sel_hi:[1,0,1]
	v_cvt_pk_bf16_f32 v118, v104, v105
	v_pk_mul_f32 v[104:105], v[104:105], v[104:105]
	v_cvt_pk_bf16_f32 v119, v106, v107
	v_pk_mul_f32 v[106:107], v[106:107], v[106:107]
	v_add_f32_e32 v103, v104, v105
	s_waitcnt vmcnt(36)
	v_pk_fma_f32 v[110:111], v[110:111], 0.5, v[196:197] op_sel_hi:[1,0,1]
	v_add_f32_e32 v103, v106, v103
	global_store_dwordx4 v[122:123], v[108:111], off offset:64
	global_store_dwordx2 v[112:113], v[118:119], off
	v_cvt_pk_bf16_f32 v118, v108, v109
	v_pk_mul_f32 v[108:109], v[108:109], v[108:109]
	v_add_f32_e32 v103, v107, v103
	v_add_f32_e32 v103, v108, v103
	v_cvt_pk_bf16_f32 v119, v110, v111
	v_pk_mul_f32 v[110:111], v[110:111], v[110:111]
	v_add_f32_e32 v103, v109, v103
	v_add_f32_e32 v103, v110, v103
	v_add_f32_e32 v103, v111, v103
	s_nop 1
	v_add_f32_dpp v103, v103, v103 quad_perm:[1,0,3,2] row_mask:0xf bank_mask:0xf
	s_nop 1
	v_add_f32_dpp v103, v103, v103 quad_perm:[2,3,0,1] row_mask:0xf bank_mask:0xf
	s_nop 1
	v_add_f32_dpp v103, v103, v103 row_half_mirror row_mask:0xf bank_mask:0xf
	s_nop 1
	v_add_f32_dpp v103, v103, v103 row_mirror row_mask:0xf bank_mask:0xf
	s_nop 1
	v_add_f32_dpp v103, v103, v103 row_bcast:15 row_mask:0xa bank_mask:0xf
	global_store_dwordx2 v[112:113], v[118:119], off offset:32
	s_and_saveexec_b64 s[12:13], vcc
	s_cbranch_execz .LBB0_1053
	v_lshl_add_u64 v[68:69], v[68:69], 4, s[10:11]
	global_store_dword v[68:69], v103, off

.LBB0_1055:
	s_or_b64 exec, exec, s[12:13]
	v_add_u32_e32 v2, s16, v90
	v_ashrrev_i32_e32 v3, 31, v2
	s_waitcnt lgkmcnt(0)
	v_lshlrev_b64 v[4:5], 10, v[2:3]
	v_lshl_add_u64 v[16:17], v[4:5], 0, v[66:67]
	v_lshl_add_u64 v[18:19], v[16:17], 2, s[18:19]
	ds_read_b128 v[4:7], v89
	s_waitcnt lgkmcnt(0)
	s_waitcnt vmcnt(18)
	v_pk_fma_f32 v[4:5], v[4:5], 0.5, v[142:143] op_sel_hi:[1,0,1]
	s_waitcnt vmcnt(18)
	v_pk_fma_f32 v[6:7], v[6:7], 0.5, v[144:145] op_sel_hi:[1,0,1]
	ds_read_b128 v[8:11], v89 offset:64
	global_store_dwordx4 v[18:19], v[4:7], off
	s_waitcnt lgkmcnt(0)
	s_waitcnt vmcnt(18)
	v_pk_fma_f32 v[8:9], v[8:9], 0.5, v[146:147] op_sel_hi:[1,0,1]
	v_cvt_pk_bf16_f32 v12, v4, v5
	v_pk_mul_f32 v[4:5], v[4:5], v[4:5]
	v_cvt_pk_bf16_f32 v13, v6, v7
	v_pk_mul_f32 v[6:7], v[6:7], v[6:7]
	v_add_f32_e32 v4, v4, v5
	s_waitcnt vmcnt(18)
	v_pk_fma_f32 v[10:11], v[10:11], 0.5, v[148:149] op_sel_hi:[1,0,1]
	v_lshl_add_u64 v[14:15], v[16:17], 1, s[38:39]
	v_add_f32_e32 v4, v6, v4
	global_store_dwordx4 v[18:19], v[8:11], off offset:64
	global_store_dwordx2 v[14:15], v[12:13], off
	v_cvt_pk_bf16_f32 v12, v8, v9
	v_pk_mul_f32 v[8:9], v[8:9], v[8:9]
	v_add_f32_e32 v4, v7, v4
	v_add_f32_e32 v4, v8, v4
	v_cvt_pk_bf16_f32 v13, v10, v11
	v_pk_mul_f32 v[10:11], v[10:11], v[10:11]
	v_add_f32_e32 v4, v9, v4
	v_add_f32_e32 v4, v10, v4
	v_add_f32_e32 v4, v11, v4
	s_nop 1
	v_add_f32_dpp v4, v4, v4 quad_perm:[1,0,3,2] row_mask:0xf bank_mask:0xf
	s_nop 1
	v_add_f32_dpp v4, v4, v4 quad_perm:[2,3,0,1] row_mask:0xf bank_mask:0xf
	s_nop 1
	v_add_f32_dpp v4, v4, v4 row_half_mirror row_mask:0xf bank_mask:0xf
	s_nop 1
	v_add_f32_dpp v4, v4, v4 row_mirror row_mask:0xf bank_mask:0xf
	s_nop 1
	v_add_f32_dpp v4, v4, v4 row_bcast:15 row_mask:0xa bank_mask:0xf
	global_store_dwordx2 v[14:15], v[12:13], off offset:32
	s_and_saveexec_b64 s[12:13], vcc
	s_cbranch_execz .LBB0_1057
	v_lshl_add_u64 v[2:3], v[2:3], 4, s[10:11]
	global_store_dword v[2:3], v4, off
.LBB0_1057:
	s_or_b64 exec, exec, s[12:13]
	v_add_u32_e32 v2, s16, v92
	v_ashrrev_i32_e32 v3, 31, v2
	s_waitcnt lgkmcnt(0)
	v_lshlrev_b64 v[4:5], 10, v[2:3]
	v_lshl_add_u64 v[16:17], v[4:5], 0, v[66:67]
	v_lshl_add_u64 v[18:19], v[16:17], 2, s[18:19]
	ds_read_b128 v[4:7], v91
	s_waitcnt lgkmcnt(0)
	s_waitcnt vmcnt(21)
	v_pk_fma_f32 v[4:5], v[4:5], 0.5, v[150:151] op_sel_hi:[1,0,1]
	s_waitcnt vmcnt(21)
	v_pk_fma_f32 v[6:7], v[6:7], 0.5, v[152:153] op_sel_hi:[1,0,1]
	ds_read_b128 v[8:11], v91 offset:64
	global_store_dwordx4 v[18:19], v[4:7], off
	s_waitcnt lgkmcnt(0)
	s_waitcnt vmcnt(21)
	v_pk_fma_f32 v[8:9], v[8:9], 0.5, v[154:155] op_sel_hi:[1,0,1]
	v_cvt_pk_bf16_f32 v12, v4, v5
	v_pk_mul_f32 v[4:5], v[4:5], v[4:5]
	v_cvt_pk_bf16_f32 v13, v6, v7
	v_pk_mul_f32 v[6:7], v[6:7], v[6:7]
	v_add_f32_e32 v4, v4, v5
	s_waitcnt vmcnt(21)
	v_pk_fma_f32 v[10:11], v[10:11], 0.5, v[156:157] op_sel_hi:[1,0,1]
	v_lshl_add_u64 v[14:15], v[16:17], 1, s[38:39]
	v_add_f32_e32 v4, v6, v4
	global_store_dwordx4 v[18:19], v[8:11], off offset:64
	global_store_dwordx2 v[14:15], v[12:13], off
	v_cvt_pk_bf16_f32 v12, v8, v9
	v_pk_mul_f32 v[8:9], v[8:9], v[8:9]
	v_add_f32_e32 v4, v7, v4
	v_add_f32_e32 v4, v8, v4
	v_cvt_pk_bf16_f32 v13, v10, v11
	v_pk_mul_f32 v[10:11], v[10:11], v[10:11]
	v_add_f32_e32 v4, v9, v4
	v_add_f32_e32 v4, v10, v4
	v_add_f32_e32 v4, v11, v4
	s_nop 1
	v_add_f32_dpp v4, v4, v4 quad_perm:[1,0,3,2] row_mask:0xf bank_mask:0xf
	s_nop 1
	v_add_f32_dpp v4, v4, v4 quad_perm:[2,3,0,1] row_mask:0xf bank_mask:0xf
	s_nop 1
	v_add_f32_dpp v4, v4, v4 row_half_mirror row_mask:0xf bank_mask:0xf
	s_nop 1
	v_add_f32_dpp v4, v4, v4 row_mirror row_mask:0xf bank_mask:0xf
	s_nop 1
	v_add_f32_dpp v4, v4, v4 row_bcast:15 row_mask:0xa bank_mask:0xf
	global_store_dwordx2 v[14:15], v[12:13], off offset:32
	s_and_saveexec_b64 s[12:13], vcc
	s_cbranch_execz .LBB0_1059
	v_lshl_add_u64 v[2:3], v[2:3], 4, s[10:11]
	global_store_dword v[2:3], v4, off
.LBB0_1059:
	s_or_b64 exec, exec, s[12:13]
	v_add_u32_e32 v2, s16, v94
	v_ashrrev_i32_e32 v3, 31, v2
	s_waitcnt lgkmcnt(0)
	v_lshlrev_b64 v[4:5], 10, v[2:3]
	v_lshl_add_u64 v[16:17], v[4:5], 0, v[66:67]
	v_lshl_add_u64 v[18:19], v[16:17], 2, s[18:19]
	ds_read_b128 v[4:7], v93
	s_waitcnt lgkmcnt(0)
	s_waitcnt vmcnt(24)
	v_pk_fma_f32 v[4:5], v[4:5], 0.5, v[158:159] op_sel_hi:[1,0,1]
	s_waitcnt vmcnt(24)
	v_pk_fma_f32 v[6:7], v[6:7], 0.5, v[160:161] op_sel_hi:[1,0,1]
	ds_read_b128 v[8:11], v93 offset:64
	global_store_dwordx4 v[18:19], v[4:7], off
	s_waitcnt lgkmcnt(0)
	s_waitcnt vmcnt(24)
	v_pk_fma_f32 v[8:9], v[8:9], 0.5, v[162:163] op_sel_hi:[1,0,1]
	v_cvt_pk_bf16_f32 v12, v4, v5
	v_pk_mul_f32 v[4:5], v[4:5], v[4:5]
	v_cvt_pk_bf16_f32 v13, v6, v7
	v_pk_mul_f32 v[6:7], v[6:7], v[6:7]
	v_add_f32_e32 v4, v4, v5
	s_waitcnt vmcnt(24)
	v_pk_fma_f32 v[10:11], v[10:11], 0.5, v[164:165] op_sel_hi:[1,0,1]
	v_lshl_add_u64 v[14:15], v[16:17], 1, s[38:39]
	v_add_f32_e32 v4, v6, v4
	global_store_dwordx4 v[18:19], v[8:11], off offset:64
	global_store_dwordx2 v[14:15], v[12:13], off
	v_cvt_pk_bf16_f32 v12, v8, v9
	v_pk_mul_f32 v[8:9], v[8:9], v[8:9]
	v_add_f32_e32 v4, v7, v4
	v_add_f32_e32 v4, v8, v4
	v_cvt_pk_bf16_f32 v13, v10, v11
	v_pk_mul_f32 v[10:11], v[10:11], v[10:11]
	v_add_f32_e32 v4, v9, v4
	v_add_f32_e32 v4, v10, v4
	v_add_f32_e32 v4, v11, v4
	s_nop 1
	v_add_f32_dpp v4, v4, v4 quad_perm:[1,0,3,2] row_mask:0xf bank_mask:0xf
	s_nop 1
	v_add_f32_dpp v4, v4, v4 quad_perm:[2,3,0,1] row_mask:0xf bank_mask:0xf
	s_nop 1
	v_add_f32_dpp v4, v4, v4 row_half_mirror row_mask:0xf bank_mask:0xf
	s_nop 1
	v_add_f32_dpp v4, v4, v4 row_mirror row_mask:0xf bank_mask:0xf
	s_nop 1
	v_add_f32_dpp v4, v4, v4 row_bcast:15 row_mask:0xa bank_mask:0xf
	global_store_dwordx2 v[14:15], v[12:13], off offset:32
	s_and_saveexec_b64 s[12:13], vcc
	s_cbranch_execz .LBB0_1061
	v_lshl_add_u64 v[2:3], v[2:3], 4, s[10:11]
	global_store_dword v[2:3], v4, off
.LBB0_1061:
	s_or_b64 exec, exec, s[12:13]
	v_add_u32_e32 v2, s16, v96
	v_ashrrev_i32_e32 v3, 31, v2
	s_waitcnt lgkmcnt(0)
	v_lshlrev_b64 v[4:5], 10, v[2:3]
	v_lshl_add_u64 v[16:17], v[4:5], 0, v[66:67]
	v_lshl_add_u64 v[18:19], v[16:17], 2, s[18:19]
	ds_read_b128 v[4:7], v95
	s_waitcnt lgkmcnt(0)
	s_waitcnt vmcnt(27)
	v_pk_fma_f32 v[4:5], v[4:5], 0.5, v[166:167] op_sel_hi:[1,0,1]
	s_waitcnt vmcnt(27)
	v_pk_fma_f32 v[6:7], v[6:7], 0.5, v[168:169] op_sel_hi:[1,0,1]
	ds_read_b128 v[8:11], v95 offset:64
	global_store_dwordx4 v[18:19], v[4:7], off
	s_waitcnt lgkmcnt(0)
	s_waitcnt vmcnt(27)
	v_pk_fma_f32 v[8:9], v[8:9], 0.5, v[170:171] op_sel_hi:[1,0,1]
	v_cvt_pk_bf16_f32 v12, v4, v5
	v_pk_mul_f32 v[4:5], v[4:5], v[4:5]
	v_cvt_pk_bf16_f32 v13, v6, v7
	v_pk_mul_f32 v[6:7], v[6:7], v[6:7]
	v_add_f32_e32 v4, v4, v5
	s_waitcnt vmcnt(27)
	v_pk_fma_f32 v[10:11], v[10:11], 0.5, v[172:173] op_sel_hi:[1,0,1]
	v_lshl_add_u64 v[14:15], v[16:17], 1, s[38:39]
	v_add_f32_e32 v4, v6, v4
	global_store_dwordx4 v[18:19], v[8:11], off offset:64
	global_store_dwordx2 v[14:15], v[12:13], off
	v_cvt_pk_bf16_f32 v12, v8, v9
	v_pk_mul_f32 v[8:9], v[8:9], v[8:9]
	v_add_f32_e32 v4, v7, v4
	v_add_f32_e32 v4, v8, v4
	v_cvt_pk_bf16_f32 v13, v10, v11
	v_pk_mul_f32 v[10:11], v[10:11], v[10:11]
	v_add_f32_e32 v4, v9, v4
	v_add_f32_e32 v4, v10, v4
	v_add_f32_e32 v4, v11, v4
	s_nop 1
	v_add_f32_dpp v4, v4, v4 quad_perm:[1,0,3,2] row_mask:0xf bank_mask:0xf
	s_nop 1
	v_add_f32_dpp v4, v4, v4 quad_perm:[2,3,0,1] row_mask:0xf bank_mask:0xf
	s_nop 1
	v_add_f32_dpp v4, v4, v4 row_half_mirror row_mask:0xf bank_mask:0xf
	s_nop 1
	v_add_f32_dpp v4, v4, v4 row_mirror row_mask:0xf bank_mask:0xf
	s_nop 1
	v_add_f32_dpp v4, v4, v4 row_bcast:15 row_mask:0xa bank_mask:0xf
	global_store_dwordx2 v[14:15], v[12:13], off offset:32
	s_and_saveexec_b64 s[12:13], vcc
	s_cbranch_execz .LBB0_1063
	v_lshl_add_u64 v[2:3], v[2:3], 4, s[10:11]
	global_store_dword v[2:3], v4, off
.LBB0_1063:
	s_or_b64 exec, exec, s[12:13]
	v_add_u32_e32 v2, s16, v98
	v_ashrrev_i32_e32 v3, 31, v2
	s_waitcnt lgkmcnt(0)
	v_lshlrev_b64 v[4:5], 10, v[2:3]
	v_lshl_add_u64 v[16:17], v[4:5], 0, v[66:67]
	v_lshl_add_u64 v[18:19], v[16:17], 2, s[18:19]
	ds_read_b128 v[4:7], v97
	s_waitcnt lgkmcnt(0)
	s_waitcnt vmcnt(30)
	v_pk_fma_f32 v[4:5], v[4:5], 0.5, v[174:175] op_sel_hi:[1,0,1]
	s_waitcnt vmcnt(30)
	v_pk_fma_f32 v[6:7], v[6:7], 0.5, v[176:177] op_sel_hi:[1,0,1]
	ds_read_b128 v[8:11], v97 offset:64
	global_store_dwordx4 v[18:19], v[4:7], off
	s_waitcnt lgkmcnt(0)
	s_waitcnt vmcnt(30)
	v_pk_fma_f32 v[8:9], v[8:9], 0.5, v[178:179] op_sel_hi:[1,0,1]
	v_cvt_pk_bf16_f32 v12, v4, v5
	v_pk_mul_f32 v[4:5], v[4:5], v[4:5]
	v_cvt_pk_bf16_f32 v13, v6, v7
	v_pk_mul_f32 v[6:7], v[6:7], v[6:7]
	v_add_f32_e32 v4, v4, v5
	s_waitcnt vmcnt(30)
	v_pk_fma_f32 v[10:11], v[10:11], 0.5, v[180:181] op_sel_hi:[1,0,1]
	v_lshl_add_u64 v[14:15], v[16:17], 1, s[38:39]
	v_add_f32_e32 v4, v6, v4
	global_store_dwordx4 v[18:19], v[8:11], off offset:64
	global_store_dwordx2 v[14:15], v[12:13], off
	v_cvt_pk_bf16_f32 v12, v8, v9
	v_pk_mul_f32 v[8:9], v[8:9], v[8:9]
	v_add_f32_e32 v4, v7, v4
	v_add_f32_e32 v4, v8, v4
	v_cvt_pk_bf16_f32 v13, v10, v11
	v_pk_mul_f32 v[10:11], v[10:11], v[10:11]
	v_add_f32_e32 v4, v9, v4
	v_add_f32_e32 v4, v10, v4
	v_add_f32_e32 v4, v11, v4
	s_nop 1
	v_add_f32_dpp v4, v4, v4 quad_perm:[1,0,3,2] row_mask:0xf bank_mask:0xf
	s_nop 1
	v_add_f32_dpp v4, v4, v4 quad_perm:[2,3,0,1] row_mask:0xf bank_mask:0xf
	s_nop 1
	v_add_f32_dpp v4, v4, v4 row_half_mirror row_mask:0xf bank_mask:0xf
	s_nop 1
	v_add_f32_dpp v4, v4, v4 row_mirror row_mask:0xf bank_mask:0xf
	s_nop 1
	v_add_f32_dpp v4, v4, v4 row_bcast:15 row_mask:0xa bank_mask:0xf
	global_store_dwordx2 v[14:15], v[12:13], off offset:32
	s_and_saveexec_b64 s[12:13], vcc
	s_cbranch_execz .LBB0_1065
	v_lshl_add_u64 v[2:3], v[2:3], 4, s[10:11]
	global_store_dword v[2:3], v4, off
.LBB0_1065:
	s_or_b64 exec, exec, s[12:13]
	v_add_u32_e32 v2, s16, v100
	v_ashrrev_i32_e32 v3, 31, v2
	s_waitcnt lgkmcnt(0)
	v_lshlrev_b64 v[4:5], 10, v[2:3]
	v_lshl_add_u64 v[16:17], v[4:5], 0, v[66:67]
	v_lshl_add_u64 v[18:19], v[16:17], 2, s[18:19]
	ds_read_b128 v[4:7], v99
	s_waitcnt lgkmcnt(0)
	s_waitcnt vmcnt(33)
	v_pk_fma_f32 v[4:5], v[4:5], 0.5, v[182:183] op_sel_hi:[1,0,1]
	s_waitcnt vmcnt(33)
	v_pk_fma_f32 v[6:7], v[6:7], 0.5, v[184:185] op_sel_hi:[1,0,1]
	ds_read_b128 v[8:11], v99 offset:64
	global_store_dwordx4 v[18:19], v[4:7], off
	s_waitcnt lgkmcnt(0)
	s_waitcnt vmcnt(33)
	v_pk_fma_f32 v[8:9], v[8:9], 0.5, v[186:187] op_sel_hi:[1,0,1]
	v_cvt_pk_bf16_f32 v12, v4, v5
	v_pk_mul_f32 v[4:5], v[4:5], v[4:5]
	v_cvt_pk_bf16_f32 v13, v6, v7
	v_pk_mul_f32 v[6:7], v[6:7], v[6:7]
	v_add_f32_e32 v4, v4, v5
	s_waitcnt vmcnt(33)
	v_pk_fma_f32 v[10:11], v[10:11], 0.5, v[188:189] op_sel_hi:[1,0,1]
	v_lshl_add_u64 v[14:15], v[16:17], 1, s[38:39]
	v_add_f32_e32 v4, v6, v4
	global_store_dwordx4 v[18:19], v[8:11], off offset:64
	global_store_dwordx2 v[14:15], v[12:13], off
	v_cvt_pk_bf16_f32 v12, v8, v9
	v_pk_mul_f32 v[8:9], v[8:9], v[8:9]
	v_add_f32_e32 v4, v7, v4
	v_add_f32_e32 v4, v8, v4
	v_cvt_pk_bf16_f32 v13, v10, v11
	v_pk_mul_f32 v[10:11], v[10:11], v[10:11]
	v_add_f32_e32 v4, v9, v4
	v_add_f32_e32 v4, v10, v4
	v_add_f32_e32 v4, v11, v4
	s_nop 1
	v_add_f32_dpp v4, v4, v4 quad_perm:[1,0,3,2] row_mask:0xf bank_mask:0xf
	s_nop 1
	v_add_f32_dpp v4, v4, v4 quad_perm:[2,3,0,1] row_mask:0xf bank_mask:0xf
	s_nop 1
	v_add_f32_dpp v4, v4, v4 row_half_mirror row_mask:0xf bank_mask:0xf
	s_nop 1
	v_add_f32_dpp v4, v4, v4 row_mirror row_mask:0xf bank_mask:0xf
	s_nop 1
	v_add_f32_dpp v4, v4, v4 row_bcast:15 row_mask:0xa bank_mask:0xf
	global_store_dwordx2 v[14:15], v[12:13], off offset:32
	s_and_saveexec_b64 s[12:13], vcc
	s_cbranch_execz .LBB0_1067
	v_lshl_add_u64 v[2:3], v[2:3], 4, s[10:11]
	global_store_dword v[2:3], v4, off

.LBB0_1094:
	s_or_b64 exec, exec, s[10:11]
	s_movk_i32 s11, 0x410
	v_lshrrev_b32_e32 v130, 2, v140
	v_lshlrev_b32_e32 v131, 1, v140
	v_and_b32_e32 v0, 15, v140
	v_and_b32_e32 v130, 0xfffffcc, v130
	v_and_b32_e32 v131, 0x180, v131
	v_add_u32_e32 v131, 0, v131
	v_lshlrev_b32_e32 v0, 2, v0
	v_mul_lo_u32 v130, v130, s11
	v_add3_u32 v130, v131, v0, v130
	s_waitcnt vmcnt(0)
	s_barrier
	ds_write2_b32 v130, v114, v126 offset1:16
	v_add_u32_e32 v114, 0x400, v130
	ds_write2_b32 v114, v115, v127 offset0:4 offset1:20
	v_add_u32_e32 v115, 0x800, v130
	ds_write2_b32 v115, v116, v128 offset0:8 offset1:24
	v_add_u32_e32 v116, 0xc00, v130
	ds_write2_b32 v116, v117, v129 offset0:12 offset1:28
	v_add_u32_e32 v117, 0x4000, v130
	ds_write2_b32 v117, v82, v94 offset0:64 offset1:80
	v_add_u32_e32 v82, 0x4400, v130
	ds_write2_b32 v82, v83, v95 offset0:68 offset1:84
	v_add_u32_e32 v83, 0x4800, v130
	ds_write2_b32 v83, v84, v96 offset0:72 offset1:88
	v_add_u32_e32 v84, 0x4c00, v130
	ds_write2_b32 v84, v85, v97 offset0:76 offset1:92
	v_add_u32_e32 v85, 0x8000, v130
	ds_write2_b32 v85, v74, v78 offset0:128 offset1:144
	v_add_u32_e32 v74, 0x8400, v130
	ds_write2_b32 v74, v75, v79 offset0:132 offset1:148
	v_add_u32_e32 v75, 0x8800, v130
	ds_write2_b32 v75, v76, v80 offset0:136 offset1:152
	v_add_u32_e32 v76, 0x8c00, v130
	v_add_u32_e32 v80, 0xc000, v130
	ds_write2_b32 v76, v77, v81 offset0:140 offset1:156
	ds_write2_b32 v80, v66, v70 offset0:192 offset1:208
	v_add_u32_e32 v77, 0xc400, v130
	v_add_u32_e32 v78, 0xc800, v130
	v_add_u32_e32 v79, 0xcc00, v130
	v_add_u32_e32 v81, 0x9000, v130
	v_lshlrev_b32_e32 v66, 2, v140
	ds_write2_b32 v77, v67, v71 offset0:196 offset1:212
	ds_write2_b32 v78, v68, v72 offset0:200 offset1:216
	ds_write2_b32 v79, v69, v73 offset0:204 offset1:220
	ds_write2_b32 v130, v98, v118 offset0:128 offset1:144
	ds_write2_b32 v114, v99, v119 offset0:132 offset1:148
	ds_write2_b32 v115, v100, v120 offset0:136 offset1:152
	ds_write2_b32 v116, v101, v121 offset0:140 offset1:156
	ds_write2_b32 v117, v102, v122 offset0:192 offset1:208
	ds_write2_b32 v82, v103, v123 offset0:196 offset1:212
	ds_write2_b32 v83, v104, v124 offset0:200 offset1:216
	ds_write2_b32 v84, v105, v125 offset0:204 offset1:220
	ds_write2_b32 v74, v90, v110 offset1:16
	ds_write2_b32 v75, v91, v111 offset0:4 offset1:20
	ds_write2_b32 v76, v92, v112 offset0:8 offset1:24
	ds_write2_b32 v81, v93, v113 offset0:12 offset1:28
	ds_write2_b32 v77, v86, v106 offset0:64 offset1:80
	ds_write2_b32 v78, v87, v107 offset0:68 offset1:84
	ds_write2_b32 v79, v88, v108 offset0:72 offset1:88
	v_lshlrev_b32_e32 v0, 3, v140
	v_and_b32_e32 v66, 12, v66
	s_movk_i32 s10, 0xe0
	v_ashrrev_i32_e32 v87, 5, v140
	v_and_or_b32 v0, v0, s10, v66
	v_add_u32_e32 v68, s17, v87
	v_or_b32_e32 v66, s7, v0
	v_ashrrev_i32_e32 v69, 31, v68
	v_ashrrev_i32_e32 v67, 31, v66
	v_lshlrev_b64 v[70:71], 10, v[68:69]
	v_lshl_add_u64 v[98:99], v[70:71], 0, v[66:67]
	v_add_u32_e32 v86, 0xd000, v130
	v_lshl_add_u64 v[110:111], v[98:99], 2, s[18:19]
	ds_write2_b32 v86, v89, v109 offset0:76 offset1:92
	s_waitcnt lgkmcnt(0)
	s_barrier
	v_lshlrev_b32_e32 v141, 2, v98
	global_load_dwordx4 v[132:135], v141, s[18:19]
	global_load_dwordx4 v[136:139], v141, s[18:19] offset:64
	v_add_u32_e32 v141, 0x10000, v141
	global_load_dwordx4 v[142:145], v141, s[18:19]
	global_load_dwordx4 v[146:149], v141, s[18:19] offset:64
	v_add_u32_e32 v141, 0x10000, v141
	global_load_dwordx4 v[150:153], v141, s[18:19]
	global_load_dwordx4 v[154:157], v141, s[18:19] offset:64
	v_add_u32_e32 v141, 0x10000, v141
	global_load_dwordx4 v[158:161], v141, s[18:19]
	global_load_dwordx4 v[162:165], v141, s[18:19] offset:64
	v_add_u32_e32 v141, 0x10000, v141
	global_load_dwordx4 v[166:169], v141, s[18:19]
	global_load_dwordx4 v[170:173], v141, s[18:19] offset:64
	v_add_u32_e32 v141, 0x10000, v141
	global_load_dwordx4 v[174:177], v141, s[18:19]
	global_load_dwordx4 v[178:181], v141, s[18:19] offset:64
	v_add_u32_e32 v141, 0x10000, v141
	global_load_dwordx4 v[182:185], v141, s[18:19]
	global_load_dwordx4 v[186:189], v141, s[18:19] offset:64
	v_add_u32_e32 v141, 0x10000, v141
	global_load_dwordx4 v[190:193], v141, s[18:19]
	global_load_dwordx4 v[194:197], v141, s[18:19] offset:64
	v_lshl_add_u32 v101, v0, 2, 0
	v_mul_lo_u32 v72, v87, s11
	v_add_u32_e32 v88, v101, v72
	ds_read_b128 v[102:105], v88
	ds_read_b128 v[106:109], v88 offset:64
	v_and_b32_e32 v70, 64, v218
	v_xor_b32_e32 v0, 1, v218
	v_add_u32_e32 v100, 64, v70
	v_cmp_lt_i32_e32 vcc, v0, v100
	v_xor_b32_e32 v70, 2, v218
	v_xor_b32_e32 v71, 4, v218
	v_cndmask_b32_e32 v0, v218, v0, vcc
	v_lshlrev_b32_e32 v0, 2, v0
	v_cmp_lt_i32_e32 vcc, v70, v100
	v_xor_b32_e32 v112, 8, v218
	v_and_b32_e32 v89, 31, v140
	v_cndmask_b32_e32 v70, v218, v70, vcc
	v_lshlrev_b32_e32 v70, 2, v70
	v_cmp_lt_i32_e32 vcc, v71, v100
	s_ashr_i32 s7, s6, 31
	s_lshl_b64 s[10:11], s[6:7], 2
	v_cndmask_b32_e32 v71, v218, v71, vcc
	v_cmp_lt_i32_e32 vcc, v112, v100
	v_lshlrev_b32_e32 v71, 2, v71
	s_add_u32 s10, s40, s10
	s_movk_i32 s20, 0x410
	s_addc_u32 s11, s41, s11
	s_waitcnt lgkmcnt(1)
	s_waitcnt vmcnt(15)
	v_pk_fma_f32 v[90:91], v[102:103], 0.5, v[132:133] op_sel_hi:[1,0,1]
	s_waitcnt vmcnt(15)
	v_pk_fma_f32 v[92:93], v[104:105], 0.5, v[134:135] op_sel_hi:[1,0,1]
	v_pk_mul_f32 v[72:73], v[90:91], v[90:91]
	v_pk_mul_f32 v[102:103], v[92:93], v[92:93]
	v_add_f32_e32 v72, v72, v73
	s_waitcnt lgkmcnt(0)
	s_waitcnt vmcnt(14)
	v_pk_fma_f32 v[94:95], v[106:107], 0.5, v[136:137] op_sel_hi:[1,0,1]
	v_add_f32_e32 v72, v102, v72
	v_pk_mul_f32 v[104:105], v[94:95], v[94:95]
	v_add_f32_e32 v72, v103, v72
	s_waitcnt vmcnt(14)
	v_pk_fma_f32 v[96:97], v[108:109], 0.5, v[138:139] op_sel_hi:[1,0,1]
	v_add_f32_e32 v72, v104, v72
	v_pk_mul_f32 v[106:107], v[96:97], v[96:97]
	v_add_f32_e32 v72, v105, v72
	v_add_f32_e32 v72, v106, v72
	v_add_f32_e32 v72, v107, v72
	ds_bpermute_b32 v102, v0, v72
	v_xor_b32_e32 v103, 16, v218
	v_cndmask_b32_e32 v73, v218, v112, vcc
	v_cmp_lt_i32_e32 vcc, v103, v100
	v_lshlrev_b32_e32 v73, 2, v73
	s_waitcnt lgkmcnt(0)
	v_add_f32_e32 v102, v72, v102
	ds_bpermute_b32 v104, v70, v102
	v_cndmask_b32_e32 v72, v218, v103, vcc
	v_cmp_eq_u32_e32 vcc, 31, v89
	v_lshlrev_b32_e32 v72, 2, v72
	global_store_dwordx4 v[110:111], v[90:93], off
	s_waitcnt lgkmcnt(0)
	v_add_f32_e32 v89, v102, v104
	ds_bpermute_b32 v100, v71, v89
	v_cvt_pk_bf16_f32 v102, v90, v91
	global_store_dwordx4 v[110:111], v[94:97], off offset:64
	v_cvt_pk_bf16_f32 v103, v92, v93
	v_lshl_add_u64 v[92:93], v[98:99], 1, s[38:39]
	s_waitcnt lgkmcnt(0)
	v_add_f32_e32 v89, v89, v100
	ds_bpermute_b32 v100, v73, v89
	v_cvt_pk_bf16_f32 v94, v94, v95
	v_cvt_pk_bf16_f32 v95, v96, v97
	global_store_dwordx2 v[92:93], v[102:103], off
	global_store_dwordx2 v[92:93], v[94:95], off offset:32
	s_waitcnt lgkmcnt(0)
	v_add_f32_e32 v89, v89, v100
	ds_bpermute_b32 v90, v72, v89
	s_and_saveexec_b64 s[12:13], vcc
	s_cbranch_execz .LBB0_1096
	s_waitcnt lgkmcnt(0)
	v_add_f32_e32 v89, v89, v90
	v_lshl_add_u64 v[68:69], v[68:69], 4, s[10:11]
	global_store_dword v[68:69], v89, off

.LBB0_1152:
	s_or_b64 exec, exec, s[14:15]
	s_movk_i32 s11, 0x410
	v_lshrrev_b32_e32 v130, 2, v142
	v_lshlrev_b32_e32 v131, 1, v142
	v_and_b32_e32 v0, 15, v142
	v_and_b32_e32 v130, 0xfffffcc, v130
	v_and_b32_e32 v131, 0x180, v131
	v_add_u32_e32 v131, 0, v131
	v_lshlrev_b32_e32 v0, 2, v0
	v_mul_lo_u32 v130, v130, s11
	v_add3_u32 v130, v131, v0, v130
	s_waitcnt vmcnt(0)
	s_barrier
	ds_write2_b32 v130, v114, v126 offset1:16
	v_add_u32_e32 v114, 0x400, v130
	ds_write2_b32 v114, v115, v127 offset0:4 offset1:20
	v_add_u32_e32 v115, 0x800, v130
	ds_write2_b32 v115, v116, v128 offset0:8 offset1:24
	v_add_u32_e32 v116, 0xc00, v130
	ds_write2_b32 v116, v117, v129 offset0:12 offset1:28
	v_add_u32_e32 v117, 0x4000, v130
	ds_write2_b32 v117, v82, v94 offset0:64 offset1:80
	v_add_u32_e32 v82, 0x4400, v130
	ds_write2_b32 v82, v83, v95 offset0:68 offset1:84
	v_add_u32_e32 v83, 0x4800, v130
	ds_write2_b32 v83, v84, v96 offset0:72 offset1:88
	v_add_u32_e32 v84, 0x4c00, v130
	ds_write2_b32 v84, v85, v97 offset0:76 offset1:92
	v_add_u32_e32 v85, 0x8000, v130
	ds_write2_b32 v85, v74, v78 offset0:128 offset1:144
	v_add_u32_e32 v74, 0x8400, v130
	ds_write2_b32 v74, v75, v79 offset0:132 offset1:148
	v_add_u32_e32 v75, 0x8800, v130
	ds_write2_b32 v75, v76, v80 offset0:136 offset1:152
	v_add_u32_e32 v76, 0x8c00, v130
	v_add_u32_e32 v80, 0xc000, v130
	ds_write2_b32 v76, v77, v81 offset0:140 offset1:156
	ds_write2_b32 v80, v66, v70 offset0:192 offset1:208
	v_add_u32_e32 v77, 0xc400, v130
	v_add_u32_e32 v78, 0xc800, v130
	v_add_u32_e32 v79, 0xcc00, v130
	v_add_u32_e32 v81, 0x9000, v130
	v_lshlrev_b32_e32 v66, 2, v142
	ds_write2_b32 v77, v67, v71 offset0:196 offset1:212
	ds_write2_b32 v78, v68, v72 offset0:200 offset1:216
	ds_write2_b32 v79, v69, v73 offset0:204 offset1:220
	ds_write2_b32 v130, v98, v118 offset0:128 offset1:144
	ds_write2_b32 v114, v99, v119 offset0:132 offset1:148
	ds_write2_b32 v115, v100, v120 offset0:136 offset1:152
	ds_write2_b32 v116, v101, v121 offset0:140 offset1:156
	ds_write2_b32 v117, v102, v122 offset0:192 offset1:208
	ds_write2_b32 v82, v103, v123 offset0:196 offset1:212
	ds_write2_b32 v83, v104, v124 offset0:200 offset1:216
	ds_write2_b32 v84, v105, v125 offset0:204 offset1:220
	ds_write2_b32 v74, v90, v110 offset1:16
	ds_write2_b32 v75, v91, v111 offset0:4 offset1:20
	ds_write2_b32 v76, v92, v112 offset0:8 offset1:24
	ds_write2_b32 v81, v93, v113 offset0:12 offset1:28
	ds_write2_b32 v77, v86, v106 offset0:64 offset1:80
	ds_write2_b32 v78, v87, v107 offset0:68 offset1:84
	ds_write2_b32 v79, v88, v108 offset0:72 offset1:88
	v_lshlrev_b32_e32 v0, 3, v142
	v_and_b32_e32 v66, 12, v66
	s_movk_i32 s7, 0xe0
	v_ashrrev_i32_e32 v87, 5, v142
	v_and_or_b32 v0, v0, s7, v66
	v_add_u32_e32 v68, s10, v87
	v_or_b32_e32 v66, s12, v0
	v_ashrrev_i32_e32 v69, 31, v68
	v_ashrrev_i32_e32 v67, 31, v66
	v_lshlrev_b64 v[70:71], 10, v[68:69]
	v_lshl_add_u64 v[98:99], v[70:71], 0, v[66:67]
	v_add_u32_e32 v86, 0xd000, v130
	v_lshl_add_u64 v[110:111], v[98:99], 2, s[18:19]
	ds_write2_b32 v86, v89, v109 offset0:76 offset1:92
	s_waitcnt lgkmcnt(0)
	s_barrier
	v_lshlrev_b32_e32 v140, 2, v98
	global_load_dwordx4 v[132:135], v140, s[18:19]
	global_load_dwordx4 v[136:139], v140, s[18:19] offset:64
	v_add_u32_e32 v140, 0x10000, v140
	global_load_dwordx4 v[144:147], v140, s[18:19]
	global_load_dwordx4 v[148:151], v140, s[18:19] offset:64
	v_add_u32_e32 v140, 0x10000, v140
	global_load_dwordx4 v[152:155], v140, s[18:19]
	global_load_dwordx4 v[156:159], v140, s[18:19] offset:64
	v_add_u32_e32 v140, 0x10000, v140
	global_load_dwordx4 v[160:163], v140, s[18:19]
	global_load_dwordx4 v[164:167], v140, s[18:19] offset:64
	v_add_u32_e32 v140, 0x10000, v140
	global_load_dwordx4 v[168:171], v140, s[18:19]
	global_load_dwordx4 v[172:175], v140, s[18:19] offset:64
	v_add_u32_e32 v140, 0x10000, v140
	global_load_dwordx4 v[176:179], v140, s[18:19]
	global_load_dwordx4 v[180:183], v140, s[18:19] offset:64
	v_add_u32_e32 v140, 0x10000, v140
	global_load_dwordx4 v[184:187], v140, s[18:19]
	global_load_dwordx4 v[188:191], v140, s[18:19] offset:64
	v_add_u32_e32 v140, 0x10000, v140
	global_load_dwordx4 v[192:195], v140, s[18:19]
	global_load_dwordx4 v[196:199], v140, s[18:19] offset:64
	v_lshl_add_u32 v101, v0, 2, 0
	v_mul_lo_u32 v72, v87, s11
	v_add_u32_e32 v88, v101, v72
	ds_read_b128 v[102:105], v88
	ds_read_b128 v[106:109], v88 offset:64
	v_and_b32_e32 v70, 64, v218
	v_xor_b32_e32 v0, 1, v218
	v_add_u32_e32 v100, 64, v70
	v_cmp_lt_i32_e32 vcc, v0, v100
	v_xor_b32_e32 v70, 2, v218
	v_xor_b32_e32 v71, 4, v218
	v_cndmask_b32_e32 v0, v218, v0, vcc
	v_lshlrev_b32_e32 v0, 2, v0
	v_cmp_lt_i32_e32 vcc, v70, v100
	v_xor_b32_e32 v112, 8, v218
	v_and_b32_e32 v89, 31, v142
	v_cndmask_b32_e32 v70, v218, v70, vcc
	v_lshlrev_b32_e32 v70, 2, v70
	v_cmp_lt_i32_e32 vcc, v71, v100
	s_ashr_i32 s7, s6, 31
	s_lshl_b64 s[12:13], s[6:7], 2
	v_cndmask_b32_e32 v71, v218, v71, vcc
	v_cmp_lt_i32_e32 vcc, v112, v100
	v_lshlrev_b32_e32 v71, 2, v71
	s_add_u32 s12, s40, s12
	s_movk_i32 s9, 0x410
	s_addc_u32 s13, s41, s13
	s_waitcnt lgkmcnt(1)
	s_waitcnt vmcnt(15)
	v_pk_add_f32 v[90:91], v[102:103], v[132:133]
	s_waitcnt vmcnt(15)
	v_pk_add_f32 v[92:93], v[104:105], v[134:135]
	v_pk_mul_f32 v[72:73], v[90:91], v[90:91]
	v_pk_mul_f32 v[102:103], v[92:93], v[92:93]
	v_add_f32_e32 v72, v72, v73
	s_waitcnt lgkmcnt(0)
	s_waitcnt vmcnt(14)
	v_pk_add_f32 v[94:95], v[106:107], v[136:137]
	v_add_f32_e32 v72, v102, v72
	v_pk_mul_f32 v[104:105], v[94:95], v[94:95]
	v_add_f32_e32 v72, v103, v72
	s_waitcnt vmcnt(14)
	v_pk_add_f32 v[96:97], v[108:109], v[138:139]
	v_add_f32_e32 v72, v104, v72
	v_pk_mul_f32 v[106:107], v[96:97], v[96:97]
	v_add_f32_e32 v72, v105, v72
	v_add_f32_e32 v72, v106, v72
	v_add_f32_e32 v72, v107, v72
	ds_bpermute_b32 v102, v0, v72
	v_xor_b32_e32 v103, 16, v218
	v_cndmask_b32_e32 v73, v218, v112, vcc
	v_cmp_lt_i32_e32 vcc, v103, v100
	v_lshlrev_b32_e32 v73, 2, v73
	s_waitcnt lgkmcnt(0)
	v_add_f32_e32 v102, v72, v102
	ds_bpermute_b32 v104, v70, v102
	v_cndmask_b32_e32 v72, v218, v103, vcc
	v_cmp_eq_u32_e32 vcc, 31, v89
	v_lshlrev_b32_e32 v72, 2, v72
	global_store_dwordx4 v[110:111], v[90:93], off
	s_waitcnt lgkmcnt(0)
	v_add_f32_e32 v89, v102, v104
	ds_bpermute_b32 v100, v71, v89
	v_cvt_pk_bf16_f32 v102, v90, v91
	global_store_dwordx4 v[110:111], v[94:97], off offset:64
	v_cvt_pk_bf16_f32 v103, v92, v93
	v_lshl_add_u64 v[92:93], v[98:99], 1, s[38:39]
	s_waitcnt lgkmcnt(0)
	v_add_f32_e32 v89, v89, v100
	ds_bpermute_b32 v100, v73, v89
	v_cvt_pk_bf16_f32 v94, v94, v95
	v_cvt_pk_bf16_f32 v95, v96, v97
	global_store_dwordx2 v[92:93], v[102:103], off
	global_store_dwordx2 v[92:93], v[94:95], off offset:32
	s_waitcnt lgkmcnt(0)
	v_add_f32_e32 v89, v89, v100
	ds_bpermute_b32 v90, v72, v89
	s_and_saveexec_b64 s[14:15], vcc
	s_cbranch_execz .LBB0_1154
	s_waitcnt lgkmcnt(0)
	v_add_f32_e32 v89, v89, v90
	v_lshl_add_u64 v[68:69], v[68:69], 4, s[12:13]
	global_store_dword v[68:69], v89, off
.LBB0_1154:
	s_or_b64 exec, exec, s[14:15]
	v_add_u32_e32 v68, 0x200, v142
	s_waitcnt lgkmcnt(0)
	v_ashrrev_i32_e32 v90, 5, v68
	v_mul_lo_u32 v68, v90, s9
	v_add_u32_e32 v89, v101, v68
	v_add_u32_e32 v68, s10, v90
	v_ashrrev_i32_e32 v69, 31, v68
	v_lshlrev_b64 v[92:93], 10, v[68:69]
	v_lshl_add_u64 v[106:107], v[92:93], 0, v[66:67]
	v_lshl_add_u64 v[108:109], v[106:107], 2, s[18:19]
	ds_read_b128 v[92:95], v89
	s_waitcnt lgkmcnt(0)
	s_waitcnt vmcnt(18)
	v_pk_add_f32 v[92:93], v[92:93], v[144:145]
	s_waitcnt vmcnt(18)
	v_pk_add_f32 v[94:95], v[94:95], v[146:147]
	ds_read_b128 v[96:99], v89 offset:64
	global_store_dwordx4 v[108:109], v[92:95], off
	s_waitcnt lgkmcnt(0)
	s_waitcnt vmcnt(18)
	v_pk_add_f32 v[96:97], v[96:97], v[148:149]
	v_cvt_pk_bf16_f32 v102, v92, v93
	v_pk_mul_f32 v[92:93], v[92:93], v[92:93]
	v_cvt_pk_bf16_f32 v103, v94, v95
	v_pk_mul_f32 v[94:95], v[94:95], v[94:95]
	v_add_f32_e32 v91, v92, v93
	s_waitcnt vmcnt(18)
	v_pk_add_f32 v[98:99], v[98:99], v[150:151]
	v_lshl_add_u64 v[104:105], v[106:107], 1, s[38:39]
	v_add_f32_e32 v91, v94, v91
	global_store_dwordx4 v[108:109], v[96:99], off offset:64
	global_store_dwordx2 v[104:105], v[102:103], off
	v_cvt_pk_bf16_f32 v102, v96, v97
	v_pk_mul_f32 v[96:97], v[96:97], v[96:97]
	v_add_f32_e32 v91, v95, v91
	v_add_f32_e32 v91, v96, v91
	v_cvt_pk_bf16_f32 v103, v98, v99
	v_pk_mul_f32 v[98:99], v[98:99], v[98:99]
	v_add_f32_e32 v91, v97, v91
	v_add_f32_e32 v91, v98, v91
	v_add_f32_e32 v91, v99, v91
	s_nop 1
	v_add_f32_dpp v91, v91, v91 quad_perm:[1,0,3,2] row_mask:0xf bank_mask:0xf
	s_nop 1
	v_add_f32_dpp v91, v91, v91 quad_perm:[2,3,0,1] row_mask:0xf bank_mask:0xf
	s_nop 1
	v_add_f32_dpp v91, v91, v91 row_half_mirror row_mask:0xf bank_mask:0xf
	s_nop 1
	v_add_f32_dpp v91, v91, v91 row_mirror row_mask:0xf bank_mask:0xf
	s_nop 1
	v_add_f32_dpp v91, v91, v91 row_bcast:15 row_mask:0xa bank_mask:0xf
	global_store_dwordx2 v[104:105], v[102:103], off offset:32
	s_and_saveexec_b64 s[14:15], vcc
	s_cbranch_execz .LBB0_1156
	v_lshl_add_u64 v[68:69], v[68:69], 4, s[12:13]
	global_store_dword v[68:69], v91, off
.LBB0_1156:
	s_or_b64 exec, exec, s[14:15]
	v_add_u32_e32 v68, 0x400, v142
	s_waitcnt lgkmcnt(0)
	v_ashrrev_i32_e32 v92, 5, v68
	v_mul_lo_u32 v68, v92, s9
	v_add_u32_e32 v91, v101, v68
	v_add_u32_e32 v68, s10, v92
	v_ashrrev_i32_e32 v69, 31, v68
	v_lshlrev_b64 v[94:95], 10, v[68:69]
	v_lshl_add_u64 v[98:99], v[94:95], 0, v[66:67]
	v_lshl_add_u64 v[110:111], v[98:99], 2, s[18:19]
	ds_read_b128 v[94:97], v91
	v_lshl_add_u64 v[98:99], v[98:99], 1, s[38:39]
	s_waitcnt lgkmcnt(0)
	s_waitcnt vmcnt(21)
	v_pk_add_f32 v[94:95], v[94:95], v[152:153]
	s_waitcnt vmcnt(21)
	v_pk_add_f32 v[96:97], v[96:97], v[154:155]
	ds_read_b128 v[102:105], v91 offset:64
	global_store_dwordx4 v[110:111], v[94:97], off
	s_waitcnt lgkmcnt(0)
	s_waitcnt vmcnt(21)
	v_pk_add_f32 v[102:103], v[102:103], v[156:157]
	v_cvt_pk_bf16_f32 v106, v94, v95
	v_pk_mul_f32 v[94:95], v[94:95], v[94:95]
	s_waitcnt vmcnt(21)
	v_pk_add_f32 v[104:105], v[104:105], v[158:159]
	v_cvt_pk_bf16_f32 v107, v96, v97
	v_pk_mul_f32 v[96:97], v[96:97], v[96:97]
	v_add_f32_e32 v93, v94, v95
	global_store_dwordx4 v[110:111], v[102:105], off offset:64
	global_store_dwordx2 v[98:99], v[106:107], off
	v_cvt_pk_bf16_f32 v106, v102, v103
	v_cvt_pk_bf16_f32 v107, v104, v105
	v_add_f32_e32 v93, v96, v93
	global_store_dwordx2 v[98:99], v[106:107], off offset:32
	v_pk_mul_f32 v[98:99], v[102:103], v[102:103]
	v_add_f32_e32 v93, v97, v93
	v_add_f32_e32 v93, v98, v93
	v_pk_mul_f32 v[102:103], v[104:105], v[104:105]
	v_add_f32_e32 v93, v99, v93
	v_add_f32_e32 v93, v102, v93
	v_add_f32_e32 v93, v103, v93
	s_nop 1
	v_add_f32_dpp v93, v93, v93 quad_perm:[1,0,3,2] row_mask:0xf bank_mask:0xf
	s_nop 1
	v_add_f32_dpp v93, v93, v93 quad_perm:[2,3,0,1] row_mask:0xf bank_mask:0xf
	s_nop 1
	v_add_f32_dpp v93, v93, v93 row_half_mirror row_mask:0xf bank_mask:0xf
	s_nop 1
	v_add_f32_dpp v93, v93, v93 row_mirror row_mask:0xf bank_mask:0xf
	s_nop 1
	v_add_f32_dpp v93, v93, v93 row_bcast:15 row_mask:0xa bank_mask:0xf
	s_and_saveexec_b64 s[14:15], vcc
	s_cbranch_execz .LBB0_1158
	v_lshl_add_u64 v[68:69], v[68:69], 4, s[12:13]
	global_store_dword v[68:69], v93, off
.LBB0_1158:
	s_or_b64 exec, exec, s[14:15]
	v_add_u32_e32 v68, 0x600, v142
	s_waitcnt lgkmcnt(0)
	v_ashrrev_i32_e32 v94, 5, v68
	v_mul_lo_u32 v68, v94, s9
	v_add_u32_e32 v93, v101, v68
	v_add_u32_e32 v68, s10, v94
	v_ashrrev_i32_e32 v69, 31, v68
	v_lshlrev_b64 v[96:97], 10, v[68:69]
	v_lshl_add_u64 v[110:111], v[96:97], 0, v[66:67]
	v_lshl_add_u64 v[112:113], v[110:111], 2, s[18:19]
	ds_read_b128 v[96:99], v93
	s_waitcnt lgkmcnt(0)
	s_waitcnt vmcnt(24)
	v_pk_add_f32 v[96:97], v[96:97], v[160:161]
	s_waitcnt vmcnt(24)
	v_pk_add_f32 v[98:99], v[98:99], v[162:163]
	ds_read_b128 v[102:105], v93 offset:64
	global_store_dwordx4 v[112:113], v[96:99], off
	s_waitcnt lgkmcnt(0)
	s_waitcnt vmcnt(24)
	v_pk_add_f32 v[102:103], v[102:103], v[164:165]
	v_cvt_pk_bf16_f32 v106, v96, v97
	v_pk_mul_f32 v[96:97], v[96:97], v[96:97]
	v_cvt_pk_bf16_f32 v107, v98, v99
	v_pk_mul_f32 v[98:99], v[98:99], v[98:99]
	v_add_f32_e32 v95, v96, v97
	s_waitcnt vmcnt(24)
	v_pk_add_f32 v[104:105], v[104:105], v[166:167]
	v_lshl_add_u64 v[108:109], v[110:111], 1, s[38:39]
	v_add_f32_e32 v95, v98, v95
	global_store_dwordx4 v[112:113], v[102:105], off offset:64
	global_store_dwordx2 v[108:109], v[106:107], off
	v_cvt_pk_bf16_f32 v106, v102, v103
	v_pk_mul_f32 v[102:103], v[102:103], v[102:103]
	v_add_f32_e32 v95, v99, v95
	v_add_f32_e32 v95, v102, v95
	v_cvt_pk_bf16_f32 v107, v104, v105
	v_pk_mul_f32 v[104:105], v[104:105], v[104:105]
	v_add_f32_e32 v95, v103, v95
	v_add_f32_e32 v95, v104, v95
	v_add_f32_e32 v95, v105, v95
	s_nop 1
	v_add_f32_dpp v95, v95, v95 quad_perm:[1,0,3,2] row_mask:0xf bank_mask:0xf
	s_nop 1
	v_add_f32_dpp v95, v95, v95 quad_perm:[2,3,0,1] row_mask:0xf bank_mask:0xf
	s_nop 1
	v_add_f32_dpp v95, v95, v95 row_half_mirror row_mask:0xf bank_mask:0xf
	s_nop 1
	v_add_f32_dpp v95, v95, v95 row_mirror row_mask:0xf bank_mask:0xf
	s_nop 1
	v_add_f32_dpp v95, v95, v95 row_bcast:15 row_mask:0xa bank_mask:0xf
	global_store_dwordx2 v[108:109], v[106:107], off offset:32
	s_and_saveexec_b64 s[14:15], vcc
	s_cbranch_execz .LBB0_1160
	v_lshl_add_u64 v[68:69], v[68:69], 4, s[12:13]
	global_store_dword v[68:69], v95, off
.LBB0_1160:
	s_or_b64 exec, exec, s[14:15]
	v_add_u32_e32 v68, 0x800, v142
	s_waitcnt lgkmcnt(0)
	v_ashrrev_i32_e32 v96, 5, v68
	v_mul_lo_u32 v68, v96, s9
	v_add_u32_e32 v95, v101, v68
	v_add_u32_e32 v68, s10, v96
	v_ashrrev_i32_e32 v69, 31, v68
	v_lshlrev_b64 v[98:99], 10, v[68:69]
	v_lshl_add_u64 v[98:99], v[98:99], 0, v[66:67]
	v_lshl_add_u64 v[118:119], v[98:99], 2, s[18:19]
	ds_read_b128 v[102:105], v95
	v_lshl_add_u64 v[98:99], v[98:99], 1, s[38:39]
	s_waitcnt lgkmcnt(0)
	s_waitcnt vmcnt(27)
	v_pk_add_f32 v[102:103], v[102:103], v[168:169]
	s_waitcnt vmcnt(27)
	v_pk_add_f32 v[104:105], v[104:105], v[170:171]
	ds_read_b128 v[106:109], v95 offset:64
	global_store_dwordx4 v[118:119], v[102:105], off
	s_waitcnt lgkmcnt(0)
	s_waitcnt vmcnt(27)
	v_pk_add_f32 v[106:107], v[106:107], v[172:173]
	s_waitcnt vmcnt(27)
	v_pk_add_f32 v[108:109], v[108:109], v[174:175]
	v_cvt_pk_bf16_f32 v110, v102, v103
	v_cvt_pk_bf16_f32 v111, v104, v105
	global_store_dwordx4 v[118:119], v[106:109], off offset:64
	global_store_dwordx2 v[98:99], v[110:111], off
	v_cvt_pk_bf16_f32 v110, v106, v107
	v_cvt_pk_bf16_f32 v111, v108, v109
	global_store_dwordx2 v[98:99], v[110:111], off offset:32
	v_pk_mul_f32 v[98:99], v[102:103], v[102:103]
	v_pk_mul_f32 v[102:103], v[104:105], v[104:105]
	v_add_f32_e32 v97, v98, v99
	v_add_f32_e32 v97, v102, v97
	v_pk_mul_f32 v[104:105], v[106:107], v[106:107]
	v_add_f32_e32 v97, v103, v97
	v_add_f32_e32 v97, v104, v97
	v_pk_mul_f32 v[106:107], v[108:109], v[108:109]
	v_add_f32_e32 v97, v105, v97
	v_add_f32_e32 v97, v106, v97
	v_add_f32_e32 v97, v107, v97
	s_nop 1
	v_add_f32_dpp v97, v97, v97 quad_perm:[1,0,3,2] row_mask:0xf bank_mask:0xf
	s_nop 1
	v_add_f32_dpp v97, v97, v97 quad_perm:[2,3,0,1] row_mask:0xf bank_mask:0xf
	s_nop 1
	v_add_f32_dpp v97, v97, v97 row_half_mirror row_mask:0xf bank_mask:0xf
	s_nop 1
	v_add_f32_dpp v97, v97, v97 row_mirror row_mask:0xf bank_mask:0xf
	s_nop 1
	v_add_f32_dpp v97, v97, v97 row_bcast:15 row_mask:0xa bank_mask:0xf
	s_and_saveexec_b64 s[14:15], vcc
	s_cbranch_execz .LBB0_1162
	v_lshl_add_u64 v[68:69], v[68:69], 4, s[12:13]
	global_store_dword v[68:69], v97, off
.LBB0_1162:
	s_or_b64 exec, exec, s[14:15]
	v_add_u32_e32 v68, 0xa00, v142
	s_waitcnt lgkmcnt(0)
	v_ashrrev_i32_e32 v98, 5, v68
	v_mul_lo_u32 v68, v98, s9
	v_add_u32_e32 v97, v101, v68
	v_add_u32_e32 v68, s10, v98
	v_ashrrev_i32_e32 v69, 31, v68
	v_lshlrev_b64 v[102:103], 10, v[68:69]
	v_lshl_add_u64 v[118:119], v[102:103], 0, v[66:67]
	v_lshl_add_u64 v[120:121], v[118:119], 2, s[18:19]
	ds_read_b128 v[102:105], v97
	s_waitcnt lgkmcnt(0)
	s_waitcnt vmcnt(30)
	v_pk_add_f32 v[102:103], v[102:103], v[176:177]
	s_waitcnt vmcnt(30)
	v_pk_add_f32 v[104:105], v[104:105], v[178:179]
	ds_read_b128 v[106:109], v97 offset:64
	global_store_dwordx4 v[120:121], v[102:105], off
	s_waitcnt lgkmcnt(0)
	s_waitcnt vmcnt(30)
	v_pk_add_f32 v[106:107], v[106:107], v[180:181]
	v_cvt_pk_bf16_f32 v110, v102, v103
	v_pk_mul_f32 v[102:103], v[102:103], v[102:103]
	v_cvt_pk_bf16_f32 v111, v104, v105
	v_pk_mul_f32 v[104:105], v[104:105], v[104:105]
	v_add_f32_e32 v99, v102, v103
	s_waitcnt vmcnt(30)
	v_pk_add_f32 v[108:109], v[108:109], v[182:183]
	v_lshl_add_u64 v[112:113], v[118:119], 1, s[38:39]
	v_add_f32_e32 v99, v104, v99
	global_store_dwordx4 v[120:121], v[106:109], off offset:64
	global_store_dwordx2 v[112:113], v[110:111], off
	v_cvt_pk_bf16_f32 v110, v106, v107
	v_pk_mul_f32 v[106:107], v[106:107], v[106:107]
	v_add_f32_e32 v99, v105, v99
	v_add_f32_e32 v99, v106, v99
	v_cvt_pk_bf16_f32 v111, v108, v109
	v_pk_mul_f32 v[108:109], v[108:109], v[108:109]
	v_add_f32_e32 v99, v107, v99
	v_add_f32_e32 v99, v108, v99
	v_add_f32_e32 v99, v109, v99
	s_nop 1
	v_add_f32_dpp v99, v99, v99 quad_perm:[1,0,3,2] row_mask:0xf bank_mask:0xf
	s_nop 1
	v_add_f32_dpp v99, v99, v99 quad_perm:[2,3,0,1] row_mask:0xf bank_mask:0xf
	s_nop 1
	v_add_f32_dpp v99, v99, v99 row_half_mirror row_mask:0xf bank_mask:0xf
	s_nop 1
	v_add_f32_dpp v99, v99, v99 row_mirror row_mask:0xf bank_mask:0xf
	s_nop 1
	v_add_f32_dpp v99, v99, v99 row_bcast:15 row_mask:0xa bank_mask:0xf
	global_store_dwordx2 v[112:113], v[110:111], off offset:32
	s_and_saveexec_b64 s[14:15], vcc
	s_cbranch_execz .LBB0_1164
	v_lshl_add_u64 v[68:69], v[68:69], 4, s[12:13]
	global_store_dword v[68:69], v99, off
.LBB0_1164:
	s_or_b64 exec, exec, s[14:15]
	v_add_u32_e32 v68, 0xc00, v142
	s_waitcnt lgkmcnt(0)
	v_ashrrev_i32_e32 v100, 5, v68
	v_mul_lo_u32 v68, v100, s9
	v_add_u32_e32 v99, v101, v68
	v_add_u32_e32 v68, s10, v100
	v_ashrrev_i32_e32 v69, 31, v68
	v_lshlrev_b64 v[102:103], 10, v[68:69]
	v_lshl_add_u64 v[118:119], v[102:103], 0, v[66:67]
	v_lshl_add_u64 v[120:121], v[118:119], 2, s[18:19]
	ds_read_b128 v[102:105], v99
	s_waitcnt lgkmcnt(0)
	s_waitcnt vmcnt(33)
	v_pk_add_f32 v[102:103], v[102:103], v[184:185]
	s_waitcnt vmcnt(33)
	v_pk_add_f32 v[104:105], v[104:105], v[186:187]
	ds_read_b128 v[106:109], v99 offset:64
	global_store_dwordx4 v[120:121], v[102:105], off
	s_waitcnt lgkmcnt(0)
	s_waitcnt vmcnt(33)
	v_pk_add_f32 v[106:107], v[106:107], v[188:189]
	v_cvt_pk_bf16_f32 v110, v102, v103
	v_pk_mul_f32 v[102:103], v[102:103], v[102:103]
	v_cvt_pk_bf16_f32 v111, v104, v105
	v_pk_mul_f32 v[104:105], v[104:105], v[104:105]
	v_add_f32_e32 v102, v102, v103
	s_waitcnt vmcnt(33)
	v_pk_add_f32 v[108:109], v[108:109], v[190:191]
	v_lshl_add_u64 v[112:113], v[118:119], 1, s[38:39]
	v_add_f32_e32 v102, v104, v102
	global_store_dwordx4 v[120:121], v[106:109], off offset:64
	global_store_dwordx2 v[112:113], v[110:111], off
	v_cvt_pk_bf16_f32 v110, v106, v107
	v_pk_mul_f32 v[106:107], v[106:107], v[106:107]
	v_add_f32_e32 v102, v105, v102
	v_add_f32_e32 v102, v106, v102
	v_cvt_pk_bf16_f32 v111, v108, v109
	v_pk_mul_f32 v[108:109], v[108:109], v[108:109]
	v_add_f32_e32 v102, v107, v102
	v_add_f32_e32 v102, v108, v102
	v_add_f32_e32 v102, v109, v102
	s_nop 1
	v_add_f32_dpp v102, v102, v102 quad_perm:[1,0,3,2] row_mask:0xf bank_mask:0xf
	s_nop 1
	v_add_f32_dpp v102, v102, v102 quad_perm:[2,3,0,1] row_mask:0xf bank_mask:0xf
	s_nop 1
	v_add_f32_dpp v102, v102, v102 row_half_mirror row_mask:0xf bank_mask:0xf
	s_nop 1
	v_add_f32_dpp v102, v102, v102 row_mirror row_mask:0xf bank_mask:0xf
	s_nop 1
	v_add_f32_dpp v102, v102, v102 row_bcast:15 row_mask:0xa bank_mask:0xf
	global_store_dwordx2 v[112:113], v[110:111], off offset:32
	s_and_saveexec_b64 s[14:15], vcc
	s_cbranch_execz .LBB0_1166
	v_lshl_add_u64 v[68:69], v[68:69], 4, s[12:13]
	global_store_dword v[68:69], v102, off
.LBB0_1166:
	s_or_b64 exec, exec, s[14:15]
	v_add_u32_e32 v68, 0xe00, v142
	v_ashrrev_i32_e32 v102, 5, v68
	v_mul_lo_u32 v68, v102, s9
	v_add_u32_e32 v101, v101, v68
	v_add_u32_e32 v68, s10, v102
	v_ashrrev_i32_e32 v69, 31, v68
	v_lshlrev_b64 v[104:105], 10, v[68:69]
	v_lshl_add_u64 v[112:113], v[104:105], 0, v[66:67]
	v_lshl_add_u64 v[122:123], v[112:113], 2, s[18:19]
	ds_read_b128 v[104:107], v101
	v_lshl_add_u64 v[112:113], v[112:113], 1, s[38:39]
	s_waitcnt lgkmcnt(0)
	s_waitcnt vmcnt(36)
	v_pk_add_f32 v[104:105], v[104:105], v[192:193]
	s_waitcnt vmcnt(36)
	v_pk_add_f32 v[106:107], v[106:107], v[194:195]
	ds_read_b128 v[108:111], v101 offset:64
	global_store_dwordx4 v[122:123], v[104:107], off
	s_waitcnt lgkmcnt(0)
	s_waitcnt vmcnt(36)
	v_pk_add_f32 v[108:109], v[108:109], v[196:197]
	v_cvt_pk_bf16_f32 v118, v104, v105
	v_pk_mul_f32 v[104:105], v[104:105], v[104:105]
	v_cvt_pk_bf16_f32 v119, v106, v107
	v_pk_mul_f32 v[106:107], v[106:107], v[106:107]
	v_add_f32_e32 v103, v104, v105
	s_waitcnt vmcnt(36)
	v_pk_add_f32 v[110:111], v[110:111], v[198:199]
	v_add_f32_e32 v103, v106, v103
	global_store_dwordx4 v[122:123], v[108:111], off offset:64
	global_store_dwordx2 v[112:113], v[118:119], off
	v_cvt_pk_bf16_f32 v118, v108, v109
	v_pk_mul_f32 v[108:109], v[108:109], v[108:109]
	v_add_f32_e32 v103, v107, v103
	v_add_f32_e32 v103, v108, v103
	v_cvt_pk_bf16_f32 v119, v110, v111
	v_pk_mul_f32 v[110:111], v[110:111], v[110:111]
	v_add_f32_e32 v103, v109, v103
	v_add_f32_e32 v103, v110, v103
	v_add_f32_e32 v103, v111, v103
	s_nop 1
	v_add_f32_dpp v103, v103, v103 quad_perm:[1,0,3,2] row_mask:0xf bank_mask:0xf
	s_nop 1
	v_add_f32_dpp v103, v103, v103 quad_perm:[2,3,0,1] row_mask:0xf bank_mask:0xf
	s_nop 1
	v_add_f32_dpp v103, v103, v103 row_half_mirror row_mask:0xf bank_mask:0xf
	s_nop 1
	v_add_f32_dpp v103, v103, v103 row_mirror row_mask:0xf bank_mask:0xf
	s_nop 1
	v_add_f32_dpp v103, v103, v103 row_bcast:15 row_mask:0xa bank_mask:0xf
	global_store_dwordx2 v[112:113], v[118:119], off offset:32
	s_and_saveexec_b64 s[10:11], vcc
	s_cbranch_execz .LBB0_1168
	v_lshl_add_u64 v[68:69], v[68:69], 4, s[12:13]
	global_store_dword v[68:69], v103, off

.LBB0_1170:
	s_or_b64 exec, exec, s[10:11]
	v_add_u32_e32 v2, s8, v90
	v_ashrrev_i32_e32 v3, 31, v2
	s_waitcnt lgkmcnt(0)
	v_lshlrev_b64 v[4:5], 10, v[2:3]
	v_lshl_add_u64 v[16:17], v[4:5], 0, v[66:67]
	v_lshl_add_u64 v[18:19], v[16:17], 2, s[18:19]
	ds_read_b128 v[4:7], v89
	s_waitcnt lgkmcnt(0)
	s_waitcnt vmcnt(18)
	v_pk_add_f32 v[4:5], v[4:5], v[144:145]
	s_waitcnt vmcnt(18)
	v_pk_add_f32 v[6:7], v[6:7], v[146:147]
	ds_read_b128 v[8:11], v89 offset:64
	global_store_dwordx4 v[18:19], v[4:7], off
	s_waitcnt lgkmcnt(0)
	s_waitcnt vmcnt(18)
	v_pk_add_f32 v[8:9], v[8:9], v[148:149]
	v_cvt_pk_bf16_f32 v12, v4, v5
	v_pk_mul_f32 v[4:5], v[4:5], v[4:5]
	v_cvt_pk_bf16_f32 v13, v6, v7
	v_pk_mul_f32 v[6:7], v[6:7], v[6:7]
	v_add_f32_e32 v4, v4, v5
	s_waitcnt vmcnt(18)
	v_pk_add_f32 v[10:11], v[10:11], v[150:151]
	v_lshl_add_u64 v[14:15], v[16:17], 1, s[38:39]
	v_add_f32_e32 v4, v6, v4
	global_store_dwordx4 v[18:19], v[8:11], off offset:64
	global_store_dwordx2 v[14:15], v[12:13], off
	v_cvt_pk_bf16_f32 v12, v8, v9
	v_pk_mul_f32 v[8:9], v[8:9], v[8:9]
	v_add_f32_e32 v4, v7, v4
	v_add_f32_e32 v4, v8, v4
	v_cvt_pk_bf16_f32 v13, v10, v11
	v_pk_mul_f32 v[10:11], v[10:11], v[10:11]
	v_add_f32_e32 v4, v9, v4
	v_add_f32_e32 v4, v10, v4
	v_add_f32_e32 v4, v11, v4
	s_nop 1
	v_add_f32_dpp v4, v4, v4 quad_perm:[1,0,3,2] row_mask:0xf bank_mask:0xf
	s_nop 1
	v_add_f32_dpp v4, v4, v4 quad_perm:[2,3,0,1] row_mask:0xf bank_mask:0xf
	s_nop 1
	v_add_f32_dpp v4, v4, v4 row_half_mirror row_mask:0xf bank_mask:0xf
	s_nop 1
	v_add_f32_dpp v4, v4, v4 row_mirror row_mask:0xf bank_mask:0xf
	s_nop 1
	v_add_f32_dpp v4, v4, v4 row_bcast:15 row_mask:0xa bank_mask:0xf
	global_store_dwordx2 v[14:15], v[12:13], off offset:32
	s_and_saveexec_b64 s[10:11], vcc
	s_cbranch_execz .LBB0_1172
	v_lshl_add_u64 v[2:3], v[2:3], 4, s[12:13]
	global_store_dword v[2:3], v4, off
.LBB0_1172:
	s_or_b64 exec, exec, s[10:11]
	v_add_u32_e32 v2, s8, v92
	v_ashrrev_i32_e32 v3, 31, v2
	s_waitcnt lgkmcnt(0)
	v_lshlrev_b64 v[4:5], 10, v[2:3]
	v_lshl_add_u64 v[16:17], v[4:5], 0, v[66:67]
	v_lshl_add_u64 v[18:19], v[16:17], 2, s[18:19]
	ds_read_b128 v[4:7], v91
	s_waitcnt lgkmcnt(0)
	s_waitcnt vmcnt(21)
	v_pk_add_f32 v[4:5], v[4:5], v[152:153]
	s_waitcnt vmcnt(21)
	v_pk_add_f32 v[6:7], v[6:7], v[154:155]
	ds_read_b128 v[8:11], v91 offset:64
	global_store_dwordx4 v[18:19], v[4:7], off
	s_waitcnt lgkmcnt(0)
	s_waitcnt vmcnt(21)
	v_pk_add_f32 v[8:9], v[8:9], v[156:157]
	v_cvt_pk_bf16_f32 v12, v4, v5
	v_pk_mul_f32 v[4:5], v[4:5], v[4:5]
	v_cvt_pk_bf16_f32 v13, v6, v7
	v_pk_mul_f32 v[6:7], v[6:7], v[6:7]
	v_add_f32_e32 v4, v4, v5
	s_waitcnt vmcnt(21)
	v_pk_add_f32 v[10:11], v[10:11], v[158:159]
	v_lshl_add_u64 v[14:15], v[16:17], 1, s[38:39]
	v_add_f32_e32 v4, v6, v4
	global_store_dwordx4 v[18:19], v[8:11], off offset:64
	global_store_dwordx2 v[14:15], v[12:13], off
	v_cvt_pk_bf16_f32 v12, v8, v9
	v_pk_mul_f32 v[8:9], v[8:9], v[8:9]
	v_add_f32_e32 v4, v7, v4
	v_add_f32_e32 v4, v8, v4
	v_cvt_pk_bf16_f32 v13, v10, v11
	v_pk_mul_f32 v[10:11], v[10:11], v[10:11]
	v_add_f32_e32 v4, v9, v4
	v_add_f32_e32 v4, v10, v4
	v_add_f32_e32 v4, v11, v4
	s_nop 1
	v_add_f32_dpp v4, v4, v4 quad_perm:[1,0,3,2] row_mask:0xf bank_mask:0xf
	s_nop 1
	v_add_f32_dpp v4, v4, v4 quad_perm:[2,3,0,1] row_mask:0xf bank_mask:0xf
	s_nop 1
	v_add_f32_dpp v4, v4, v4 row_half_mirror row_mask:0xf bank_mask:0xf
	s_nop 1
	v_add_f32_dpp v4, v4, v4 row_mirror row_mask:0xf bank_mask:0xf
	s_nop 1
	v_add_f32_dpp v4, v4, v4 row_bcast:15 row_mask:0xa bank_mask:0xf
	global_store_dwordx2 v[14:15], v[12:13], off offset:32
	s_and_saveexec_b64 s[10:11], vcc
	s_cbranch_execz .LBB0_1174
	v_lshl_add_u64 v[2:3], v[2:3], 4, s[12:13]
	global_store_dword v[2:3], v4, off
.LBB0_1174:
	s_or_b64 exec, exec, s[10:11]
	v_add_u32_e32 v2, s8, v94
	v_ashrrev_i32_e32 v3, 31, v2
	s_waitcnt lgkmcnt(0)
	v_lshlrev_b64 v[4:5], 10, v[2:3]
	v_lshl_add_u64 v[16:17], v[4:5], 0, v[66:67]
	v_lshl_add_u64 v[18:19], v[16:17], 2, s[18:19]
	ds_read_b128 v[4:7], v93
	s_waitcnt lgkmcnt(0)
	s_waitcnt vmcnt(24)
	v_pk_add_f32 v[4:5], v[4:5], v[160:161]
	s_waitcnt vmcnt(24)
	v_pk_add_f32 v[6:7], v[6:7], v[162:163]
	ds_read_b128 v[8:11], v93 offset:64
	global_store_dwordx4 v[18:19], v[4:7], off
	s_waitcnt lgkmcnt(0)
	s_waitcnt vmcnt(24)
	v_pk_add_f32 v[8:9], v[8:9], v[164:165]
	v_cvt_pk_bf16_f32 v12, v4, v5
	v_pk_mul_f32 v[4:5], v[4:5], v[4:5]
	v_cvt_pk_bf16_f32 v13, v6, v7
	v_pk_mul_f32 v[6:7], v[6:7], v[6:7]
	v_add_f32_e32 v4, v4, v5
	s_waitcnt vmcnt(24)
	v_pk_add_f32 v[10:11], v[10:11], v[166:167]
	v_lshl_add_u64 v[14:15], v[16:17], 1, s[38:39]
	v_add_f32_e32 v4, v6, v4
	global_store_dwordx4 v[18:19], v[8:11], off offset:64
	global_store_dwordx2 v[14:15], v[12:13], off
	v_cvt_pk_bf16_f32 v12, v8, v9
	v_pk_mul_f32 v[8:9], v[8:9], v[8:9]
	v_add_f32_e32 v4, v7, v4
	v_add_f32_e32 v4, v8, v4
	v_cvt_pk_bf16_f32 v13, v10, v11
	v_pk_mul_f32 v[10:11], v[10:11], v[10:11]
	v_add_f32_e32 v4, v9, v4
	v_add_f32_e32 v4, v10, v4
	v_add_f32_e32 v4, v11, v4
	s_nop 1
	v_add_f32_dpp v4, v4, v4 quad_perm:[1,0,3,2] row_mask:0xf bank_mask:0xf
	s_nop 1
	v_add_f32_dpp v4, v4, v4 quad_perm:[2,3,0,1] row_mask:0xf bank_mask:0xf
	s_nop 1
	v_add_f32_dpp v4, v4, v4 row_half_mirror row_mask:0xf bank_mask:0xf
	s_nop 1
	v_add_f32_dpp v4, v4, v4 row_mirror row_mask:0xf bank_mask:0xf
	s_nop 1
	v_add_f32_dpp v4, v4, v4 row_bcast:15 row_mask:0xa bank_mask:0xf
	global_store_dwordx2 v[14:15], v[12:13], off offset:32
	s_and_saveexec_b64 s[10:11], vcc
	s_cbranch_execz .LBB0_1176
	v_lshl_add_u64 v[2:3], v[2:3], 4, s[12:13]
	global_store_dword v[2:3], v4, off
.LBB0_1176:
	s_or_b64 exec, exec, s[10:11]
	v_add_u32_e32 v2, s8, v96
	v_ashrrev_i32_e32 v3, 31, v2
	s_waitcnt lgkmcnt(0)
	v_lshlrev_b64 v[4:5], 10, v[2:3]
	v_lshl_add_u64 v[16:17], v[4:5], 0, v[66:67]
	v_lshl_add_u64 v[18:19], v[16:17], 2, s[18:19]
	ds_read_b128 v[4:7], v95
	s_waitcnt lgkmcnt(0)
	s_waitcnt vmcnt(27)
	v_pk_add_f32 v[4:5], v[4:5], v[168:169]
	s_waitcnt vmcnt(27)
	v_pk_add_f32 v[6:7], v[6:7], v[170:171]
	ds_read_b128 v[8:11], v95 offset:64
	global_store_dwordx4 v[18:19], v[4:7], off
	s_waitcnt lgkmcnt(0)
	s_waitcnt vmcnt(27)
	v_pk_add_f32 v[8:9], v[8:9], v[172:173]
	v_cvt_pk_bf16_f32 v12, v4, v5
	v_pk_mul_f32 v[4:5], v[4:5], v[4:5]
	v_cvt_pk_bf16_f32 v13, v6, v7
	v_pk_mul_f32 v[6:7], v[6:7], v[6:7]
	v_add_f32_e32 v4, v4, v5
	s_waitcnt vmcnt(27)
	v_pk_add_f32 v[10:11], v[10:11], v[174:175]
	v_lshl_add_u64 v[14:15], v[16:17], 1, s[38:39]
	v_add_f32_e32 v4, v6, v4
	global_store_dwordx4 v[18:19], v[8:11], off offset:64
	global_store_dwordx2 v[14:15], v[12:13], off
	v_cvt_pk_bf16_f32 v12, v8, v9
	v_pk_mul_f32 v[8:9], v[8:9], v[8:9]
	v_add_f32_e32 v4, v7, v4
	v_add_f32_e32 v4, v8, v4
	v_cvt_pk_bf16_f32 v13, v10, v11
	v_pk_mul_f32 v[10:11], v[10:11], v[10:11]
	v_add_f32_e32 v4, v9, v4
	v_add_f32_e32 v4, v10, v4
	v_add_f32_e32 v4, v11, v4
	s_nop 1
	v_add_f32_dpp v4, v4, v4 quad_perm:[1,0,3,2] row_mask:0xf bank_mask:0xf
	s_nop 1
	v_add_f32_dpp v4, v4, v4 quad_perm:[2,3,0,1] row_mask:0xf bank_mask:0xf
	s_nop 1
	v_add_f32_dpp v4, v4, v4 row_half_mirror row_mask:0xf bank_mask:0xf
	s_nop 1
	v_add_f32_dpp v4, v4, v4 row_mirror row_mask:0xf bank_mask:0xf
	s_nop 1
	v_add_f32_dpp v4, v4, v4 row_bcast:15 row_mask:0xa bank_mask:0xf
	global_store_dwordx2 v[14:15], v[12:13], off offset:32
	s_and_saveexec_b64 s[10:11], vcc
	s_cbranch_execz .LBB0_1178
	v_lshl_add_u64 v[2:3], v[2:3], 4, s[12:13]
	global_store_dword v[2:3], v4, off
.LBB0_1178:
	s_or_b64 exec, exec, s[10:11]
	v_add_u32_e32 v2, s8, v98
	v_ashrrev_i32_e32 v3, 31, v2
	s_waitcnt lgkmcnt(0)
	v_lshlrev_b64 v[4:5], 10, v[2:3]
	v_lshl_add_u64 v[16:17], v[4:5], 0, v[66:67]
	v_lshl_add_u64 v[18:19], v[16:17], 2, s[18:19]
	ds_read_b128 v[4:7], v97
	s_waitcnt lgkmcnt(0)
	s_waitcnt vmcnt(30)
	v_pk_add_f32 v[4:5], v[4:5], v[176:177]
	s_waitcnt vmcnt(30)
	v_pk_add_f32 v[6:7], v[6:7], v[178:179]
	ds_read_b128 v[8:11], v97 offset:64
	global_store_dwordx4 v[18:19], v[4:7], off
	s_waitcnt lgkmcnt(0)
	s_waitcnt vmcnt(30)
	v_pk_add_f32 v[8:9], v[8:9], v[180:181]
	v_cvt_pk_bf16_f32 v12, v4, v5
	v_pk_mul_f32 v[4:5], v[4:5], v[4:5]
	v_cvt_pk_bf16_f32 v13, v6, v7
	v_pk_mul_f32 v[6:7], v[6:7], v[6:7]
	v_add_f32_e32 v4, v4, v5
	s_waitcnt vmcnt(30)
	v_pk_add_f32 v[10:11], v[10:11], v[182:183]
	v_lshl_add_u64 v[14:15], v[16:17], 1, s[38:39]
	v_add_f32_e32 v4, v6, v4
	global_store_dwordx4 v[18:19], v[8:11], off offset:64
	global_store_dwordx2 v[14:15], v[12:13], off
	v_cvt_pk_bf16_f32 v12, v8, v9
	v_pk_mul_f32 v[8:9], v[8:9], v[8:9]
	v_add_f32_e32 v4, v7, v4
	v_add_f32_e32 v4, v8, v4
	v_cvt_pk_bf16_f32 v13, v10, v11
	v_pk_mul_f32 v[10:11], v[10:11], v[10:11]
	v_add_f32_e32 v4, v9, v4
	v_add_f32_e32 v4, v10, v4
	v_add_f32_e32 v4, v11, v4
	s_nop 1
	v_add_f32_dpp v4, v4, v4 quad_perm:[1,0,3,2] row_mask:0xf bank_mask:0xf
	s_nop 1
	v_add_f32_dpp v4, v4, v4 quad_perm:[2,3,0,1] row_mask:0xf bank_mask:0xf
	s_nop 1
	v_add_f32_dpp v4, v4, v4 row_half_mirror row_mask:0xf bank_mask:0xf
	s_nop 1
	v_add_f32_dpp v4, v4, v4 row_mirror row_mask:0xf bank_mask:0xf
	s_nop 1
	v_add_f32_dpp v4, v4, v4 row_bcast:15 row_mask:0xa bank_mask:0xf
	global_store_dwordx2 v[14:15], v[12:13], off offset:32
	s_and_saveexec_b64 s[10:11], vcc
	s_cbranch_execz .LBB0_1180
	v_lshl_add_u64 v[2:3], v[2:3], 4, s[12:13]
	global_store_dword v[2:3], v4, off
.LBB0_1180:
	s_or_b64 exec, exec, s[10:11]
	v_add_u32_e32 v2, s8, v100
	v_ashrrev_i32_e32 v3, 31, v2
	s_waitcnt lgkmcnt(0)
	v_lshlrev_b64 v[4:5], 10, v[2:3]
	v_lshl_add_u64 v[16:17], v[4:5], 0, v[66:67]
	v_lshl_add_u64 v[18:19], v[16:17], 2, s[18:19]
	ds_read_b128 v[4:7], v99
	s_waitcnt lgkmcnt(0)
	s_waitcnt vmcnt(33)
	v_pk_add_f32 v[4:5], v[4:5], v[184:185]
	s_waitcnt vmcnt(33)
	v_pk_add_f32 v[6:7], v[6:7], v[186:187]
	ds_read_b128 v[8:11], v99 offset:64
	global_store_dwordx4 v[18:19], v[4:7], off
	s_waitcnt lgkmcnt(0)
	s_waitcnt vmcnt(33)
	v_pk_add_f32 v[8:9], v[8:9], v[188:189]
	v_cvt_pk_bf16_f32 v12, v4, v5
	v_pk_mul_f32 v[4:5], v[4:5], v[4:5]
	v_cvt_pk_bf16_f32 v13, v6, v7
	v_pk_mul_f32 v[6:7], v[6:7], v[6:7]
	v_add_f32_e32 v4, v4, v5
	s_waitcnt vmcnt(33)
	v_pk_add_f32 v[10:11], v[10:11], v[190:191]
	v_lshl_add_u64 v[14:15], v[16:17], 1, s[38:39]
	v_add_f32_e32 v4, v6, v4
	global_store_dwordx4 v[18:19], v[8:11], off offset:64
	global_store_dwordx2 v[14:15], v[12:13], off
	v_cvt_pk_bf16_f32 v12, v8, v9
	v_pk_mul_f32 v[8:9], v[8:9], v[8:9]
	v_add_f32_e32 v4, v7, v4
	v_add_f32_e32 v4, v8, v4
	v_cvt_pk_bf16_f32 v13, v10, v11
	v_pk_mul_f32 v[10:11], v[10:11], v[10:11]
	v_add_f32_e32 v4, v9, v4
	v_add_f32_e32 v4, v10, v4
	v_add_f32_e32 v4, v11, v4
	s_nop 1
	v_add_f32_dpp v4, v4, v4 quad_perm:[1,0,3,2] row_mask:0xf bank_mask:0xf
	s_nop 1
	v_add_f32_dpp v4, v4, v4 quad_perm:[2,3,0,1] row_mask:0xf bank_mask:0xf
	s_nop 1
	v_add_f32_dpp v4, v4, v4 row_half_mirror row_mask:0xf bank_mask:0xf
	s_nop 1
	v_add_f32_dpp v4, v4, v4 row_mirror row_mask:0xf bank_mask:0xf
	s_nop 1
	v_add_f32_dpp v4, v4, v4 row_bcast:15 row_mask:0xa bank_mask:0xf
	global_store_dwordx2 v[14:15], v[12:13], off offset:32
	s_and_saveexec_b64 s[10:11], vcc
	s_cbranch_execz .LBB0_1182
	v_lshl_add_u64 v[2:3], v[2:3], 4, s[12:13]
	global_store_dword v[2:3], v4, off

.LBB0_1215:
	s_and_saveexec_b64 s[70:71], s[8:9]
	s_cbranch_execz .LBB0_1202
	ds_read_b128 v[220:223], v245
	ds_read_b128 v[224:227], v245 offset:32
	ds_read_b128 v[2:5], v245 offset:64
	ds_read_b128 v[6:9], v245 offset:96
	s_waitcnt lgkmcnt(3)
	v_mfma_f32_32x32x16_bf16 v[96:111], v[220:223], v[172:175], 0
	ds_read_b128 v[220:223], v245 offset:128
	s_waitcnt lgkmcnt(3)
	v_mfma_f32_32x32x16_bf16 v[96:111], v[224:227], v[168:171], v[96:111]
	ds_read_b128 v[224:227], v245 offset:160
	s_waitcnt lgkmcnt(3)
	v_mfma_f32_32x32x16_bf16 v[96:111], v[2:5], v[164:167], v[96:111]
	ds_read_b128 v[2:5], v245 offset:192
	s_waitcnt lgkmcnt(3)
	v_mfma_f32_32x32x16_bf16 v[96:111], v[6:9], v[160:163], v[96:111]
	ds_read_b128 v[6:9], v245 offset:224
	s_waitcnt lgkmcnt(3)
	v_mfma_f32_32x32x16_bf16 v[96:111], v[220:223], v[156:159], v[96:111]
	ds_read_b128 v[220:223], v245 offset:256
	s_waitcnt lgkmcnt(3)
	v_mfma_f32_32x32x16_bf16 v[96:111], v[224:227], v[152:155], v[96:111]
	ds_read_b128 v[224:227], v245 offset:288
	s_waitcnt lgkmcnt(3)
	v_mfma_f32_32x32x16_bf16 v[96:111], v[2:5], v[148:151], v[96:111]
	ds_read_b128 v[2:5], v245 offset:320
	s_waitcnt lgkmcnt(3)
	v_mfma_f32_32x32x16_bf16 v[96:111], v[6:9], v[144:147], v[96:111]
	ds_read_b128 v[6:9], v245 offset:352
	s_waitcnt lgkmcnt(3)
	v_mfma_f32_32x32x16_bf16 v[96:111], v[220:223], v[140:143], v[96:111]
	ds_read_b128 v[220:223], v245 offset:384
	s_waitcnt lgkmcnt(3)
	v_mfma_f32_32x32x16_bf16 v[96:111], v[224:227], v[136:139], v[96:111]
	ds_read_b128 v[224:227], v245 offset:416
	s_waitcnt lgkmcnt(3)
	v_mfma_f32_32x32x16_bf16 v[96:111], v[2:5], v[132:135], v[96:111]
	ds_read_b128 v[2:5], v245 offset:448
	s_waitcnt lgkmcnt(3)
	v_mfma_f32_32x32x16_bf16 v[96:111], v[6:9], v[128:131], v[96:111]
	ds_read_b128 v[6:9], v245 offset:480
	s_waitcnt lgkmcnt(3)
	v_mfma_f32_32x32x16_bf16 v[96:111], v[220:223], v[124:127], v[96:111]
	ds_read_b128 v[220:223], v245 offset:16896
	s_waitcnt lgkmcnt(3)
	v_mfma_f32_32x32x16_bf16 v[96:111], v[224:227], v[120:123], v[96:111]
	ds_read_b128 v[224:227], v245 offset:16928
	s_waitcnt lgkmcnt(3)
	v_mfma_f32_32x32x16_bf16 v[96:111], v[2:5], v[116:119], v[96:111]
	ds_read_b128 v[2:5], v245 offset:16960
	s_waitcnt lgkmcnt(3)
	v_mfma_f32_32x32x16_bf16 v[96:111], v[6:9], v[112:115], v[96:111]
	ds_read_b128 v[6:9], v245 offset:16992
	s_waitcnt lgkmcnt(3)
	v_mfma_f32_32x32x16_bf16 v[80:95], v[220:223], v[172:175], 0
	ds_read_b128 v[220:223], v245 offset:17024
	s_waitcnt lgkmcnt(3)
	v_mfma_f32_32x32x16_bf16 v[80:95], v[224:227], v[168:171], v[80:95]
	ds_read_b128 v[224:227], v245 offset:17056
	s_waitcnt lgkmcnt(3)
	v_mfma_f32_32x32x16_bf16 v[80:95], v[2:5], v[164:167], v[80:95]
	ds_read_b128 v[2:5], v245 offset:17088
	s_waitcnt lgkmcnt(3)
	v_mfma_f32_32x32x16_bf16 v[80:95], v[6:9], v[160:163], v[80:95]
	ds_read_b128 v[6:9], v245 offset:17120
	s_waitcnt lgkmcnt(3)
	v_mfma_f32_32x32x16_bf16 v[80:95], v[220:223], v[156:159], v[80:95]
	ds_read_b128 v[220:223], v245 offset:17152
	s_waitcnt lgkmcnt(3)
	v_mfma_f32_32x32x16_bf16 v[80:95], v[224:227], v[152:155], v[80:95]
	ds_read_b128 v[224:227], v245 offset:17184
	s_waitcnt lgkmcnt(3)
	v_mfma_f32_32x32x16_bf16 v[80:95], v[2:5], v[148:151], v[80:95]
	ds_read_b128 v[2:5], v245 offset:17216
	s_waitcnt lgkmcnt(3)
	v_mfma_f32_32x32x16_bf16 v[80:95], v[6:9], v[144:147], v[80:95]
	ds_read_b128 v[6:9], v245 offset:17248
	s_waitcnt lgkmcnt(3)
	v_mfma_f32_32x32x16_bf16 v[80:95], v[220:223], v[140:143], v[80:95]
	ds_read_b128 v[220:223], v245 offset:17280
	s_waitcnt lgkmcnt(3)
	v_mfma_f32_32x32x16_bf16 v[80:95], v[224:227], v[136:139], v[80:95]
	ds_read_b128 v[224:227], v245 offset:17312
	s_waitcnt lgkmcnt(3)
	v_mfma_f32_32x32x16_bf16 v[80:95], v[2:5], v[132:135], v[80:95]
	ds_read_b128 v[2:5], v245 offset:17344
	s_waitcnt lgkmcnt(3)
	v_mfma_f32_32x32x16_bf16 v[80:95], v[6:9], v[128:131], v[80:95]
	ds_read_b128 v[6:9], v245 offset:17376
	s_waitcnt lgkmcnt(3)
	v_mfma_f32_32x32x16_bf16 v[80:95], v[220:223], v[124:127], v[80:95]
	s_waitcnt lgkmcnt(2)
	v_mfma_f32_32x32x16_bf16 v[80:95], v[224:227], v[120:123], v[80:95]
	s_waitcnt lgkmcnt(1)
	v_mfma_f32_32x32x16_bf16 v[80:95], v[2:5], v[116:119], v[80:95]
	s_waitcnt lgkmcnt(0)
	v_mfma_f32_32x32x16_bf16 v[80:95], v[6:9], v[112:115], v[80:95]
	v_max_f32_e32 v0, v97, v97
	v_max_f32_e32 v10, v96, v96
	v_max_f32_e32 v0, v10, v0
	v_max3_f32 v0, v0, v98, v99
	v_max3_f32 v0, v0, v100, v101
	v_max3_f32 v0, v0, v102, v103
	v_max3_f32 v0, v0, v104, v105
	v_max3_f32 v0, v0, v106, v107
	v_max3_f32 v0, v0, v108, v109
	v_max3_f32 v0, v0, v110, v111
	v_and_b32_e32 v3, 64, v218
	v_xor_b32_e32 v2, 32, v218
	v_add_u32_e32 v3, 64, v3
	v_cmp_lt_i32_e32 vcc, v2, v3
	s_nop 1
	v_cndmask_b32_e32 v2, v218, v2, vcc
	v_lshlrev_b32_e32 v2, 2, v2
	s_nop 10
	v_max3_f32 v0, v0, v80, v81
	v_max3_f32 v0, v0, v82, v83
	v_max3_f32 v0, v0, v84, v85
	v_max3_f32 v0, v0, v86, v87
	v_max3_f32 v0, v0, v88, v89
	v_max3_f32 v0, v0, v90, v91
	v_max3_f32 v0, v0, v92, v93
	v_max3_f32 v0, v0, v94, v95
	ds_bpermute_b32 v2, v2, v0
	s_waitcnt lgkmcnt(0)
	v_max3_f32 v0, v236, v0, v2
	v_sub_f32 v4, v97, v0
	v_sub_f32 v3, v96, v0
	v_sub_f32 v5, v100, v0
	v_sub_f32_e32 v2, v236, v0
	v_exp_f32_e32 v8, v4
	v_sub_f32 v4, v98, v0
	v_exp_f32_e32 v3, v3
	v_exp_f32_e32 v9, v4
	v_sub_f32 v4, v99, v0
	v_exp_f32_e32 v11, v5
	v_exp_f32_e32 v10, v4
	v_add_f32 v4, v1, v3
	v_sub_f32 v5, v101, v0
	v_exp_f32_e32 v2, v2
	v_add_f32 v4, v4, v8
	v_exp_f32_e32 v12, v5
	v_add_f32 v4, v4, v9
	v_sub_f32 v5, v102, v0
	v_cvt_pk_bf16_f32 v8, v3, v8
	v_add_f32 v4, v4, v10
	v_exp_f32_e32 v13, v5
	v_add_f32 v4, v4, v11
	v_sub_f32 v5, v103, v0
	v_add_u32_e32 v3, 0x9000, v219
	v_add_f32 v4, v4, v12
	v_exp_f32_e32 v14, v5
	v_add_f32 v4, v4, v13
	v_cvt_pk_bf16_f32 v9, v9, v10
	v_add_f32 v96, v4, v14
	v_sub_f32 v4, v104, v0
	v_add_u32_e32 v104, 0x8000, v219
	v_exp_f32_e32 v97, v4
	v_sub_f32 v4, v105, v0
	v_cvt_pk_bf16_f32 v10, v11, v12
	v_exp_f32_e32 v98, v4
	v_sub_f32 v4, v106, v0
	v_cvt_pk_bf16_f32 v11, v13, v14
	v_exp_f32_e32 v99, v4
	v_sub_f32 v4, v107, v0
	ds_read2_b64 v[12:15], v3 offset0:160 offset1:162
	v_exp_f32_e32 v100, v4
	v_sub_f32 v4, v108, v0
	v_mul_f32 v64, v64, v2
	v_mul_f32 v65, v65, v2
	v_mul_f32 v66, v66, v2
	v_mul_f32 v67, v67, v2
	v_mul_f32 v68, v68, v2
	s_nop 0
	v_exp_f32_e32 v101, v4
	v_sub_f32 v4, v109, v0
	v_mul_f32 v69, v69, v2
	v_mul_f32 v70, v70, v2
	v_mul_f32 v71, v71, v2
	v_mul_f32 v72, v72, v2
	v_mul_f32 v73, v73, v2
	s_nop 0
	v_exp_f32_e32 v102, v4
	v_sub_f32 v4, v110, v0
	v_mul_f32 v74, v74, v2
	v_mul_f32 v75, v75, v2
	v_mul_f32 v76, v76, v2
	v_mul_f32 v77, v77, v2
	v_mul_f32 v78, v78, v2
	s_nop 0
	v_exp_f32_e32 v103, v4
	ds_read2_b64 v[4:7], v104 offset0:128 offset1:130
	v_mul_f32 v79, v79, v2
	v_add_u32_e32 v105, 0xa000, v219
	s_waitcnt lgkmcnt(0)
	v_mfma_f32_32x32x16_bf16 v[64:79], v[4:7], v[8:11], v[64:79]
	ds_read2_b64 v[4:7], v105 offset0:192 offset1:194
	v_mul_f32 v48, v48, v2
	v_mul_f32 v49, v49, v2
	v_mul_f32 v50, v50, v2
	v_mul_f32 v51, v51, v2
	v_mul_f32 v52, v52, v2
	v_mul_f32 v53, v53, v2
	v_mul_f32 v54, v54, v2
	v_mul_f32 v55, v55, v2
	v_mul_f32 v56, v56, v2
	v_mul_f32 v57, v57, v2
	v_mul_f32 v58, v58, v2
	v_mul_f32 v59, v59, v2
	v_mul_f32 v60, v60, v2
	v_mul_f32 v61, v61, v2
	v_mul_f32 v62, v62, v2
	v_mul_f32 v63, v63, v2
	v_add_u32_e32 v106, 0xb000, v219
	v_mfma_f32_32x32x16_bf16 v[48:63], v[12:15], v[8:11], v[48:63]
	ds_read2_b64 v[12:15], v106 offset0:224 offset1:226
	v_mul_f32 v32, v32, v2
	v_mul_f32 v33, v33, v2
	v_mul_f32 v34, v34, v2
	v_mul_f32 v35, v35, v2
	v_mul_f32 v36, v36, v2
	v_mul_f32 v37, v37, v2
	v_mul_f32 v38, v38, v2
	v_mul_f32 v39, v39, v2
	v_mul_f32 v40, v40, v2
	v_mul_f32 v41, v41, v2
	v_mul_f32 v42, v42, v2
	v_mul_f32 v43, v43, v2
	v_mul_f32 v44, v44, v2
	v_mul_f32 v45, v45, v2
	v_mul_f32 v46, v46, v2
	v_mul_f32 v47, v47, v2
	v_mul_f32 v16, v16, v2
	v_mul_f32 v17, v17, v2
	v_mul_f32 v18, v18, v2
	v_mul_f32 v19, v19, v2
	v_mul_f32 v20, v20, v2
	s_waitcnt lgkmcnt(1)
	v_mfma_f32_32x32x16_bf16 v[32:47], v[4:7], v[8:11], v[32:47]
	ds_read2_b64 v[4:7], v104 offset0:132 offset1:134
	v_mul_f32 v21, v21, v2
	v_mul_f32 v22, v22, v2
	v_mul_f32 v23, v23, v2
	v_mul_f32 v24, v24, v2
	v_mul_f32 v25, v25, v2
	v_mul_f32 v26, v26, v2
	v_mul_f32 v27, v27, v2
	v_mul_f32 v28, v28, v2
	v_mul_f32 v29, v29, v2
	v_mul_f32 v30, v30, v2
	v_mul_f32 v31, v31, v2
	v_mov_b32_e32 v236, v0
	s_waitcnt lgkmcnt(1)
	v_mfma_f32_32x32x16_bf16 v[16:31], v[12:15], v[8:11], v[16:31]
	v_sub_f32 v8, v111, v0
	v_cvt_pk_bf16_f32 v9, v99, v100
	v_exp_f32_e32 v107, v8
	v_cvt_pk_bf16_f32 v8, v97, v98
	v_cvt_pk_bf16_f32 v10, v101, v102
	ds_read2_b64 v[12:15], v3 offset0:164 offset1:166
	v_cvt_pk_bf16_f32 v11, v103, v107
	s_waitcnt lgkmcnt(1)
	s_nop 0
	v_mfma_f32_32x32x16_bf16 v[64:79], v[4:7], v[8:11], v[64:79]
	v_add_f32 v4, v96, v97
	s_nop 0
	v_add_f32 v4, v4, v98
	s_nop 0
	v_add_f32 v4, v4, v99
	s_nop 0
	v_add_f32 v96, v4, v100
	v_sub_f32 v4, v80, v0
	s_waitcnt lgkmcnt(0)
	v_mfma_f32_32x32x16_bf16 v[48:63], v[12:15], v[8:11], v[48:63]
	v_exp_f32_e32 v80, v4
	ds_read2_b64 v[4:7], v105 offset0:196 offset1:198
	v_sub_f32 v12, v81, v0
	s_nop 0
	v_exp_f32_e32 v81, v12
	v_sub_f32 v12, v82, v0
	s_nop 0
	v_exp_f32_e32 v82, v12
	v_sub_f32 v12, v83, v0
	s_waitcnt lgkmcnt(0)
	v_mfma_f32_32x32x16_bf16 v[32:47], v[4:7], v[8:11], v[32:47]
	v_exp_f32_e32 v83, v12
	ds_read2_b64 v[12:15], v106 offset0:228 offset1:230
	v_sub_f32 v4, v84, v0
	s_nop 0
	v_exp_f32_e32 v84, v4
	v_sub_f32 v4, v85, v0
	s_nop 0
	v_exp_f32_e32 v85, v4
	v_sub_f32 v4, v86, v0
	s_waitcnt lgkmcnt(0)
	v_mfma_f32_32x32x16_bf16 v[16:31], v[12:15], v[8:11], v[16:31]
	v_exp_f32_e32 v86, v4
	ds_read2_b64 v[4:7], v104 offset0:136 offset1:138
	v_sub_f32 v8, v87, v0
	ds_read2_b64 v[12:15], v3 offset0:168 offset1:170
	v_exp_f32_e32 v87, v8
	v_cvt_pk_bf16_f32 v8, v80, v81
	v_cvt_pk_bf16_f32 v9, v82, v83
	v_cvt_pk_bf16_f32 v10, v84, v85
	v_cvt_pk_bf16_f32 v11, v86, v87
	s_waitcnt lgkmcnt(1)
	s_nop 0
	v_mfma_f32_32x32x16_bf16 v[64:79], v[4:7], v[8:11], v[64:79]
	v_add_f32 v4, v96, v101
	s_nop 0
	v_add_f32 v4, v4, v102
	s_nop 0
	v_add_f32 v4, v4, v103
	s_nop 0
	v_add_f32 v96, v4, v107
	v_sub_f32 v4, v88, v0
	s_waitcnt lgkmcnt(0)
	v_mfma_f32_32x32x16_bf16 v[48:63], v[12:15], v[8:11], v[48:63]
	v_exp_f32_e32 v88, v4
	ds_read2_b64 v[4:7], v105 offset0:200 offset1:202
	v_sub_f32 v12, v89, v0
	s_nop 0
	v_exp_f32_e32 v89, v12
	v_sub_f32 v12, v90, v0
	s_nop 0
	v_exp_f32_e32 v90, v12
	v_sub_f32 v12, v91, v0
	s_waitcnt lgkmcnt(0)
	v_mfma_f32_32x32x16_bf16 v[32:47], v[4:7], v[8:11], v[32:47]
	v_exp_f32_e32 v91, v12
	ds_read2_b64 v[12:15], v106 offset0:232 offset1:234
	v_sub_f32 v4, v92, v0
	s_nop 0
	v_exp_f32_e32 v92, v4
	v_sub_f32 v4, v93, v0
	s_nop 0
	v_exp_f32_e32 v93, v4
	v_sub_f32 v4, v94, v0
	s_waitcnt lgkmcnt(0)
	v_mfma_f32_32x32x16_bf16 v[16:31], v[12:15], v[8:11], v[16:31]
	v_exp_f32_e32 v94, v4
	ds_read2_b64 v[4:7], v104 offset0:140 offset1:142
	ds_read2_b64 v[12:15], v3 offset0:172 offset1:174
	v_sub_f32 v8, v95, v0
	v_cvt_pk_bf16_f32 v9, v90, v91
	v_exp_f32_e32 v95, v8
	v_cvt_pk_bf16_f32 v8, v88, v89
	v_cvt_pk_bf16_f32 v10, v92, v93
	v_add_f32 v3, v96, v80
	v_cvt_pk_bf16_f32 v11, v94, v95
	v_add_f32 v3, v3, v81
	s_nop 0
	v_add_f32 v3, v3, v82
	s_waitcnt lgkmcnt(1)
	v_mfma_f32_32x32x16_bf16 v[64:79], v[4:7], v[8:11], v[64:79]
	ds_read2_b64 v[4:7], v105 offset0:204 offset1:206
	v_add_f32 v3, v3, v83
	s_nop 0
	v_add_f32 v3, v3, v84
	s_nop 0
	v_add_f32 v3, v3, v85
	s_waitcnt lgkmcnt(1)
	v_mfma_f32_32x32x16_bf16 v[48:63], v[12:15], v[8:11], v[48:63]
	ds_read2_b64 v[12:15], v106 offset0:236 offset1:238
	v_add_f32 v3, v3, v86
	s_nop 0
	v_add_f32 v3, v3, v87
	s_nop 0
	v_add_f32 v3, v3, v88
	s_nop 0
	v_add_f32 v3, v3, v89
	s_waitcnt lgkmcnt(1)
	v_mfma_f32_32x32x16_bf16 v[32:47], v[4:7], v[8:11], v[32:47]
	v_add_f32 v3, v3, v90
	s_nop 0
	v_add_f32 v3, v3, v91
	s_nop 0
	v_add_f32 v3, v3, v92
	s_nop 0
	v_add_f32 v3, v3, v93
	s_waitcnt lgkmcnt(0)
	v_mfma_f32_32x32x16_bf16 v[16:31], v[12:15], v[8:11], v[16:31]
	v_add_f32 v3, v3, v94
	s_nop 0
	v_add_f32 v3, v3, v95
	s_nop 0
	v_fmac_f32_e32 v3, v246, v2
	v_mov_b32_e32 v246, v3
	s_branch .LBB0_1202

.LBB0_1309:
	s_or_b64 exec, exec, s[8:9]
	s_movk_i32 s9, 0x410
	v_lshrrev_b32_e32 v130, 2, v142
	v_lshlrev_b32_e32 v131, 1, v142
	v_and_b32_e32 v0, 15, v142
	v_and_b32_e32 v130, 0xfffffcc, v130
	v_and_b32_e32 v131, 0x180, v131
	v_add_u32_e32 v131, 0, v131
	v_lshlrev_b32_e32 v0, 2, v0
	v_mul_lo_u32 v130, v130, s9
	v_add3_u32 v130, v131, v0, v130
	s_waitcnt vmcnt(0)
	s_barrier
	ds_write2_b32 v130, v114, v126 offset1:16
	v_add_u32_e32 v114, 0x400, v130
	ds_write2_b32 v114, v115, v127 offset0:4 offset1:20
	v_add_u32_e32 v115, 0x800, v130
	ds_write2_b32 v115, v116, v128 offset0:8 offset1:24
	v_add_u32_e32 v116, 0xc00, v130
	ds_write2_b32 v116, v117, v129 offset0:12 offset1:28
	v_add_u32_e32 v117, 0x4000, v130
	ds_write2_b32 v117, v82, v94 offset0:64 offset1:80
	v_add_u32_e32 v82, 0x4400, v130
	ds_write2_b32 v82, v83, v95 offset0:68 offset1:84
	v_add_u32_e32 v83, 0x4800, v130
	ds_write2_b32 v83, v84, v96 offset0:72 offset1:88
	v_add_u32_e32 v84, 0x4c00, v130
	ds_write2_b32 v84, v85, v97 offset0:76 offset1:92
	v_add_u32_e32 v85, 0x8000, v130
	ds_write2_b32 v85, v74, v78 offset0:128 offset1:144
	v_add_u32_e32 v74, 0x8400, v130
	ds_write2_b32 v74, v75, v79 offset0:132 offset1:148
	v_add_u32_e32 v75, 0x8800, v130
	ds_write2_b32 v75, v76, v80 offset0:136 offset1:152
	v_add_u32_e32 v76, 0x8c00, v130
	v_add_u32_e32 v80, 0xc000, v130
	ds_write2_b32 v76, v77, v81 offset0:140 offset1:156
	ds_write2_b32 v80, v66, v70 offset0:192 offset1:208
	v_add_u32_e32 v77, 0xc400, v130
	v_add_u32_e32 v78, 0xc800, v130
	v_add_u32_e32 v79, 0xcc00, v130
	v_add_u32_e32 v81, 0x9000, v130
	v_lshlrev_b32_e32 v66, 2, v142
	ds_write2_b32 v77, v67, v71 offset0:196 offset1:212
	ds_write2_b32 v78, v68, v72 offset0:200 offset1:216
	ds_write2_b32 v79, v69, v73 offset0:204 offset1:220
	ds_write2_b32 v130, v98, v118 offset0:128 offset1:144
	ds_write2_b32 v114, v99, v119 offset0:132 offset1:148
	ds_write2_b32 v115, v100, v120 offset0:136 offset1:152
	ds_write2_b32 v116, v101, v121 offset0:140 offset1:156
	ds_write2_b32 v117, v102, v122 offset0:192 offset1:208
	ds_write2_b32 v82, v103, v123 offset0:196 offset1:212
	ds_write2_b32 v83, v104, v124 offset0:200 offset1:216
	ds_write2_b32 v84, v105, v125 offset0:204 offset1:220
	ds_write2_b32 v74, v90, v110 offset1:16
	ds_write2_b32 v75, v91, v111 offset0:4 offset1:20
	ds_write2_b32 v76, v92, v112 offset0:8 offset1:24
	ds_write2_b32 v81, v93, v113 offset0:12 offset1:28
	ds_write2_b32 v77, v86, v106 offset0:64 offset1:80
	ds_write2_b32 v78, v87, v107 offset0:68 offset1:84
	ds_write2_b32 v79, v88, v108 offset0:72 offset1:88
	v_lshlrev_b32_e32 v0, 3, v142
	v_and_b32_e32 v66, 12, v66
	s_movk_i32 s8, 0xe0
	v_ashrrev_i32_e32 v87, 5, v142
	v_and_or_b32 v0, v0, s8, v66
	v_add_u32_e32 v68, s15, v87
	v_or_b32_e32 v66, s7, v0
	v_ashrrev_i32_e32 v69, 31, v68
	v_ashrrev_i32_e32 v67, 31, v66
	v_lshlrev_b64 v[70:71], 10, v[68:69]
	v_lshl_add_u64 v[98:99], v[70:71], 0, v[66:67]
	v_add_u32_e32 v86, 0xd000, v130
	v_lshl_add_u64 v[110:111], v[98:99], 2, s[18:19]
	ds_write2_b32 v86, v89, v109 offset0:76 offset1:92
	s_waitcnt lgkmcnt(0)
	s_barrier
	v_lshlrev_b32_e32 v140, 2, v98
	global_load_dwordx4 v[132:135], v140, s[18:19]
	global_load_dwordx4 v[136:139], v140, s[18:19] offset:64
	v_add_u32_e32 v140, 0x10000, v140
	global_load_dwordx4 v[144:147], v140, s[18:19]
	global_load_dwordx4 v[148:151], v140, s[18:19] offset:64
	v_add_u32_e32 v140, 0x10000, v140
	global_load_dwordx4 v[152:155], v140, s[18:19]
	global_load_dwordx4 v[156:159], v140, s[18:19] offset:64
	v_add_u32_e32 v140, 0x10000, v140
	global_load_dwordx4 v[160:163], v140, s[18:19]
	global_load_dwordx4 v[164:167], v140, s[18:19] offset:64
	v_add_u32_e32 v140, 0x10000, v140
	global_load_dwordx4 v[168:171], v140, s[18:19]
	global_load_dwordx4 v[172:175], v140, s[18:19] offset:64
	v_add_u32_e32 v140, 0x10000, v140
	global_load_dwordx4 v[176:179], v140, s[18:19]
	global_load_dwordx4 v[180:183], v140, s[18:19] offset:64
	v_add_u32_e32 v140, 0x10000, v140
	global_load_dwordx4 v[184:187], v140, s[18:19]
	global_load_dwordx4 v[188:191], v140, s[18:19] offset:64
	v_add_u32_e32 v140, 0x10000, v140
	global_load_dwordx4 v[192:195], v140, s[18:19]
	global_load_dwordx4 v[196:199], v140, s[18:19] offset:64
	v_lshl_add_u32 v101, v0, 2, 0
	v_mul_lo_u32 v72, v87, s9
	v_add_u32_e32 v88, v101, v72
	ds_read_b128 v[102:105], v88
	ds_read_b128 v[106:109], v88 offset:64
	v_and_b32_e32 v70, 64, v218
	v_xor_b32_e32 v0, 1, v218
	v_add_u32_e32 v100, 64, v70
	v_cmp_lt_i32_e32 vcc, v0, v100
	v_xor_b32_e32 v70, 2, v218
	v_xor_b32_e32 v71, 4, v218
	v_cndmask_b32_e32 v0, v218, v0, vcc
	v_lshlrev_b32_e32 v0, 2, v0
	v_cmp_lt_i32_e32 vcc, v70, v100
	v_xor_b32_e32 v112, 8, v218
	v_and_b32_e32 v89, 31, v142
	v_cndmask_b32_e32 v70, v218, v70, vcc
	v_lshlrev_b32_e32 v70, 2, v70
	v_cmp_lt_i32_e32 vcc, v71, v100
	s_ashr_i32 s7, s6, 31
	s_lshl_b64 s[6:7], s[6:7], 2
	v_cndmask_b32_e32 v71, v218, v71, vcc
	v_cmp_lt_i32_e32 vcc, v112, v100
	v_lshlrev_b32_e32 v71, 2, v71
	s_add_u32 s6, s40, s6
	s_movk_i32 s12, 0x410
	s_addc_u32 s7, s41, s7
	s_waitcnt lgkmcnt(1)
	s_waitcnt vmcnt(15)
	v_pk_add_f32 v[90:91], v[102:103], v[132:133]
	s_waitcnt vmcnt(15)
	v_pk_add_f32 v[92:93], v[104:105], v[134:135]
	v_pk_mul_f32 v[72:73], v[90:91], v[90:91]
	v_pk_mul_f32 v[102:103], v[92:93], v[92:93]
	v_add_f32_e32 v72, v72, v73
	s_waitcnt lgkmcnt(0)
	s_waitcnt vmcnt(14)
	v_pk_add_f32 v[94:95], v[106:107], v[136:137]
	v_add_f32_e32 v72, v102, v72
	v_pk_mul_f32 v[104:105], v[94:95], v[94:95]
	v_add_f32_e32 v72, v103, v72
	s_waitcnt vmcnt(14)
	v_pk_add_f32 v[96:97], v[108:109], v[138:139]
	v_add_f32_e32 v72, v104, v72
	v_pk_mul_f32 v[106:107], v[96:97], v[96:97]
	v_add_f32_e32 v72, v105, v72
	v_add_f32_e32 v72, v106, v72
	v_add_f32_e32 v72, v107, v72
	ds_bpermute_b32 v102, v0, v72
	v_xor_b32_e32 v103, 16, v218
	v_cndmask_b32_e32 v73, v218, v112, vcc
	v_cmp_lt_i32_e32 vcc, v103, v100
	v_lshlrev_b32_e32 v73, 2, v73
	s_waitcnt lgkmcnt(0)
	v_add_f32_e32 v102, v72, v102
	ds_bpermute_b32 v104, v70, v102
	v_cndmask_b32_e32 v72, v218, v103, vcc
	v_cmp_eq_u32_e32 vcc, 31, v89
	v_lshlrev_b32_e32 v72, 2, v72
	global_store_dwordx4 v[110:111], v[90:93], off
	s_waitcnt lgkmcnt(0)
	v_add_f32_e32 v89, v102, v104
	ds_bpermute_b32 v100, v71, v89
	v_cvt_pk_bf16_f32 v102, v90, v91
	global_store_dwordx4 v[110:111], v[94:97], off offset:64
	v_cvt_pk_bf16_f32 v103, v92, v93
	v_lshl_add_u64 v[92:93], v[98:99], 1, s[38:39]
	s_waitcnt lgkmcnt(0)
	v_add_f32_e32 v89, v89, v100
	ds_bpermute_b32 v100, v73, v89
	v_cvt_pk_bf16_f32 v94, v94, v95
	v_cvt_pk_bf16_f32 v95, v96, v97
	global_store_dwordx2 v[92:93], v[102:103], off
	global_store_dwordx2 v[92:93], v[94:95], off offset:32
	s_waitcnt lgkmcnt(0)
	v_add_f32_e32 v89, v89, v100
	ds_bpermute_b32 v90, v72, v89
	s_and_saveexec_b64 s[8:9], vcc
	s_cbranch_execz .LBB0_1311
	s_waitcnt lgkmcnt(0)
	v_add_f32_e32 v89, v89, v90
	v_lshl_add_u64 v[68:69], v[68:69], 4, s[6:7]
	global_store_dword v[68:69], v89, off
.LBB0_1311:
	s_or_b64 exec, exec, s[8:9]
	v_add_u32_e32 v68, 0x200, v142
	s_waitcnt lgkmcnt(0)
	v_ashrrev_i32_e32 v90, 5, v68
	v_mul_lo_u32 v68, v90, s12
	v_add_u32_e32 v89, v101, v68
	v_add_u32_e32 v68, s15, v90
	v_ashrrev_i32_e32 v69, 31, v68
	v_lshlrev_b64 v[92:93], 10, v[68:69]
	v_lshl_add_u64 v[106:107], v[92:93], 0, v[66:67]
	v_lshl_add_u64 v[108:109], v[106:107], 2, s[18:19]
	ds_read_b128 v[92:95], v89
	s_waitcnt lgkmcnt(0)
	s_waitcnt vmcnt(18)
	v_pk_add_f32 v[92:93], v[92:93], v[144:145]
	s_waitcnt vmcnt(18)
	v_pk_add_f32 v[94:95], v[94:95], v[146:147]
	ds_read_b128 v[96:99], v89 offset:64
	global_store_dwordx4 v[108:109], v[92:95], off
	s_waitcnt lgkmcnt(0)
	s_waitcnt vmcnt(18)
	v_pk_add_f32 v[96:97], v[96:97], v[148:149]
	v_cvt_pk_bf16_f32 v102, v92, v93
	v_pk_mul_f32 v[92:93], v[92:93], v[92:93]
	v_cvt_pk_bf16_f32 v103, v94, v95
	v_pk_mul_f32 v[94:95], v[94:95], v[94:95]
	v_add_f32_e32 v91, v92, v93
	s_waitcnt vmcnt(18)
	v_pk_add_f32 v[98:99], v[98:99], v[150:151]
	v_lshl_add_u64 v[104:105], v[106:107], 1, s[38:39]
	v_add_f32_e32 v91, v94, v91
	global_store_dwordx4 v[108:109], v[96:99], off offset:64
	global_store_dwordx2 v[104:105], v[102:103], off
	v_cvt_pk_bf16_f32 v102, v96, v97
	v_pk_mul_f32 v[96:97], v[96:97], v[96:97]
	v_add_f32_e32 v91, v95, v91
	v_add_f32_e32 v91, v96, v91
	v_cvt_pk_bf16_f32 v103, v98, v99
	v_pk_mul_f32 v[98:99], v[98:99], v[98:99]
	v_add_f32_e32 v91, v97, v91
	v_add_f32_e32 v91, v98, v91
	v_add_f32_e32 v91, v99, v91
	s_nop 1
	v_add_f32_dpp v91, v91, v91 quad_perm:[1,0,3,2] row_mask:0xf bank_mask:0xf
	s_nop 1
	v_add_f32_dpp v91, v91, v91 quad_perm:[2,3,0,1] row_mask:0xf bank_mask:0xf
	s_nop 1
	v_add_f32_dpp v91, v91, v91 row_half_mirror row_mask:0xf bank_mask:0xf
	s_nop 1
	v_add_f32_dpp v91, v91, v91 row_mirror row_mask:0xf bank_mask:0xf
	s_nop 1
	v_add_f32_dpp v91, v91, v91 row_bcast:15 row_mask:0xa bank_mask:0xf
	global_store_dwordx2 v[104:105], v[102:103], off offset:32
	s_and_saveexec_b64 s[8:9], vcc
	s_cbranch_execz .LBB0_1313
	v_lshl_add_u64 v[68:69], v[68:69], 4, s[6:7]
	global_store_dword v[68:69], v91, off
.LBB0_1313:
	s_or_b64 exec, exec, s[8:9]
	v_add_u32_e32 v68, 0x400, v142
	s_waitcnt lgkmcnt(0)
	v_ashrrev_i32_e32 v92, 5, v68
	v_mul_lo_u32 v68, v92, s12
	v_add_u32_e32 v91, v101, v68
	v_add_u32_e32 v68, s15, v92
	v_ashrrev_i32_e32 v69, 31, v68
	v_lshlrev_b64 v[94:95], 10, v[68:69]
	v_lshl_add_u64 v[98:99], v[94:95], 0, v[66:67]
	v_lshl_add_u64 v[110:111], v[98:99], 2, s[18:19]
	ds_read_b128 v[94:97], v91
	v_lshl_add_u64 v[98:99], v[98:99], 1, s[38:39]
	s_waitcnt lgkmcnt(0)
	s_waitcnt vmcnt(21)
	v_pk_add_f32 v[94:95], v[94:95], v[152:153]
	s_waitcnt vmcnt(21)
	v_pk_add_f32 v[96:97], v[96:97], v[154:155]
	ds_read_b128 v[102:105], v91 offset:64
	global_store_dwordx4 v[110:111], v[94:97], off
	s_waitcnt lgkmcnt(0)
	s_waitcnt vmcnt(21)
	v_pk_add_f32 v[102:103], v[102:103], v[156:157]
	v_cvt_pk_bf16_f32 v106, v94, v95
	v_pk_mul_f32 v[94:95], v[94:95], v[94:95]
	s_waitcnt vmcnt(21)
	v_pk_add_f32 v[104:105], v[104:105], v[158:159]
	v_cvt_pk_bf16_f32 v107, v96, v97
	v_pk_mul_f32 v[96:97], v[96:97], v[96:97]
	v_add_f32_e32 v93, v94, v95
	global_store_dwordx4 v[110:111], v[102:105], off offset:64
	global_store_dwordx2 v[98:99], v[106:107], off
	v_cvt_pk_bf16_f32 v106, v102, v103
	v_cvt_pk_bf16_f32 v107, v104, v105
	v_add_f32_e32 v93, v96, v93
	global_store_dwordx2 v[98:99], v[106:107], off offset:32
	v_pk_mul_f32 v[98:99], v[102:103], v[102:103]
	v_add_f32_e32 v93, v97, v93
	v_add_f32_e32 v93, v98, v93
	v_pk_mul_f32 v[102:103], v[104:105], v[104:105]
	v_add_f32_e32 v93, v99, v93
	v_add_f32_e32 v93, v102, v93
	v_add_f32_e32 v93, v103, v93
	s_nop 1
	v_add_f32_dpp v93, v93, v93 quad_perm:[1,0,3,2] row_mask:0xf bank_mask:0xf
	s_nop 1
	v_add_f32_dpp v93, v93, v93 quad_perm:[2,3,0,1] row_mask:0xf bank_mask:0xf
	s_nop 1
	v_add_f32_dpp v93, v93, v93 row_half_mirror row_mask:0xf bank_mask:0xf
	s_nop 1
	v_add_f32_dpp v93, v93, v93 row_mirror row_mask:0xf bank_mask:0xf
	s_nop 1
	v_add_f32_dpp v93, v93, v93 row_bcast:15 row_mask:0xa bank_mask:0xf
	s_and_saveexec_b64 s[8:9], vcc
	s_cbranch_execz .LBB0_1315
	v_lshl_add_u64 v[68:69], v[68:69], 4, s[6:7]
	global_store_dword v[68:69], v93, off
.LBB0_1315:
	s_or_b64 exec, exec, s[8:9]
	v_add_u32_e32 v68, 0x600, v142
	s_waitcnt lgkmcnt(0)
	v_ashrrev_i32_e32 v94, 5, v68
	v_mul_lo_u32 v68, v94, s12
	v_add_u32_e32 v93, v101, v68
	v_add_u32_e32 v68, s15, v94
	v_ashrrev_i32_e32 v69, 31, v68
	v_lshlrev_b64 v[96:97], 10, v[68:69]
	v_lshl_add_u64 v[110:111], v[96:97], 0, v[66:67]
	v_lshl_add_u64 v[112:113], v[110:111], 2, s[18:19]
	ds_read_b128 v[96:99], v93
	s_waitcnt lgkmcnt(0)
	s_waitcnt vmcnt(24)
	v_pk_add_f32 v[96:97], v[96:97], v[160:161]
	s_waitcnt vmcnt(24)
	v_pk_add_f32 v[98:99], v[98:99], v[162:163]
	ds_read_b128 v[102:105], v93 offset:64
	global_store_dwordx4 v[112:113], v[96:99], off
	s_waitcnt lgkmcnt(0)
	s_waitcnt vmcnt(24)
	v_pk_add_f32 v[102:103], v[102:103], v[164:165]
	v_cvt_pk_bf16_f32 v106, v96, v97
	v_pk_mul_f32 v[96:97], v[96:97], v[96:97]
	v_cvt_pk_bf16_f32 v107, v98, v99
	v_pk_mul_f32 v[98:99], v[98:99], v[98:99]
	v_add_f32_e32 v95, v96, v97
	s_waitcnt vmcnt(24)
	v_pk_add_f32 v[104:105], v[104:105], v[166:167]
	v_lshl_add_u64 v[108:109], v[110:111], 1, s[38:39]
	v_add_f32_e32 v95, v98, v95
	global_store_dwordx4 v[112:113], v[102:105], off offset:64
	global_store_dwordx2 v[108:109], v[106:107], off
	v_cvt_pk_bf16_f32 v106, v102, v103
	v_pk_mul_f32 v[102:103], v[102:103], v[102:103]
	v_add_f32_e32 v95, v99, v95
	v_add_f32_e32 v95, v102, v95
	v_cvt_pk_bf16_f32 v107, v104, v105
	v_pk_mul_f32 v[104:105], v[104:105], v[104:105]
	v_add_f32_e32 v95, v103, v95
	v_add_f32_e32 v95, v104, v95
	v_add_f32_e32 v95, v105, v95
	s_nop 1
	v_add_f32_dpp v95, v95, v95 quad_perm:[1,0,3,2] row_mask:0xf bank_mask:0xf
	s_nop 1
	v_add_f32_dpp v95, v95, v95 quad_perm:[2,3,0,1] row_mask:0xf bank_mask:0xf
	s_nop 1
	v_add_f32_dpp v95, v95, v95 row_half_mirror row_mask:0xf bank_mask:0xf
	s_nop 1
	v_add_f32_dpp v95, v95, v95 row_mirror row_mask:0xf bank_mask:0xf
	s_nop 1
	v_add_f32_dpp v95, v95, v95 row_bcast:15 row_mask:0xa bank_mask:0xf
	global_store_dwordx2 v[108:109], v[106:107], off offset:32
	s_and_saveexec_b64 s[8:9], vcc
	s_cbranch_execz .LBB0_1317
	v_lshl_add_u64 v[68:69], v[68:69], 4, s[6:7]
	global_store_dword v[68:69], v95, off
.LBB0_1317:
	s_or_b64 exec, exec, s[8:9]
	v_add_u32_e32 v68, 0x800, v142
	s_waitcnt lgkmcnt(0)
	v_ashrrev_i32_e32 v96, 5, v68
	v_mul_lo_u32 v68, v96, s12
	v_add_u32_e32 v95, v101, v68
	v_add_u32_e32 v68, s15, v96
	v_ashrrev_i32_e32 v69, 31, v68
	v_lshlrev_b64 v[98:99], 10, v[68:69]
	v_lshl_add_u64 v[98:99], v[98:99], 0, v[66:67]
	v_lshl_add_u64 v[118:119], v[98:99], 2, s[18:19]
	ds_read_b128 v[102:105], v95
	v_lshl_add_u64 v[98:99], v[98:99], 1, s[38:39]
	s_waitcnt lgkmcnt(0)
	s_waitcnt vmcnt(27)
	v_pk_add_f32 v[102:103], v[102:103], v[168:169]
	s_waitcnt vmcnt(27)
	v_pk_add_f32 v[104:105], v[104:105], v[170:171]
	ds_read_b128 v[106:109], v95 offset:64
	global_store_dwordx4 v[118:119], v[102:105], off
	s_waitcnt lgkmcnt(0)
	s_waitcnt vmcnt(27)
	v_pk_add_f32 v[106:107], v[106:107], v[172:173]
	s_waitcnt vmcnt(27)
	v_pk_add_f32 v[108:109], v[108:109], v[174:175]
	v_cvt_pk_bf16_f32 v110, v102, v103
	v_cvt_pk_bf16_f32 v111, v104, v105
	global_store_dwordx4 v[118:119], v[106:109], off offset:64
	global_store_dwordx2 v[98:99], v[110:111], off
	v_cvt_pk_bf16_f32 v110, v106, v107
	v_cvt_pk_bf16_f32 v111, v108, v109
	global_store_dwordx2 v[98:99], v[110:111], off offset:32
	v_pk_mul_f32 v[98:99], v[102:103], v[102:103]
	v_pk_mul_f32 v[102:103], v[104:105], v[104:105]
	v_add_f32_e32 v97, v98, v99
	v_add_f32_e32 v97, v102, v97
	v_pk_mul_f32 v[104:105], v[106:107], v[106:107]
	v_add_f32_e32 v97, v103, v97
	v_add_f32_e32 v97, v104, v97
	v_pk_mul_f32 v[106:107], v[108:109], v[108:109]
	v_add_f32_e32 v97, v105, v97
	v_add_f32_e32 v97, v106, v97
	v_add_f32_e32 v97, v107, v97
	s_nop 1
	v_add_f32_dpp v97, v97, v97 quad_perm:[1,0,3,2] row_mask:0xf bank_mask:0xf
	s_nop 1
	v_add_f32_dpp v97, v97, v97 quad_perm:[2,3,0,1] row_mask:0xf bank_mask:0xf
	s_nop 1
	v_add_f32_dpp v97, v97, v97 row_half_mirror row_mask:0xf bank_mask:0xf
	s_nop 1
	v_add_f32_dpp v97, v97, v97 row_mirror row_mask:0xf bank_mask:0xf
	s_nop 1
	v_add_f32_dpp v97, v97, v97 row_bcast:15 row_mask:0xa bank_mask:0xf
	s_and_saveexec_b64 s[8:9], vcc
	s_cbranch_execz .LBB0_1319
	v_lshl_add_u64 v[68:69], v[68:69], 4, s[6:7]
	global_store_dword v[68:69], v97, off
.LBB0_1319:
	s_or_b64 exec, exec, s[8:9]
	v_add_u32_e32 v68, 0xa00, v142
	s_waitcnt lgkmcnt(0)
	v_ashrrev_i32_e32 v98, 5, v68
	v_mul_lo_u32 v68, v98, s12
	v_add_u32_e32 v97, v101, v68
	v_add_u32_e32 v68, s15, v98
	v_ashrrev_i32_e32 v69, 31, v68
	v_lshlrev_b64 v[102:103], 10, v[68:69]
	v_lshl_add_u64 v[118:119], v[102:103], 0, v[66:67]
	v_lshl_add_u64 v[120:121], v[118:119], 2, s[18:19]
	ds_read_b128 v[102:105], v97
	s_waitcnt lgkmcnt(0)
	s_waitcnt vmcnt(30)
	v_pk_add_f32 v[102:103], v[102:103], v[176:177]
	s_waitcnt vmcnt(30)
	v_pk_add_f32 v[104:105], v[104:105], v[178:179]
	ds_read_b128 v[106:109], v97 offset:64
	global_store_dwordx4 v[120:121], v[102:105], off
	s_waitcnt lgkmcnt(0)
	s_waitcnt vmcnt(30)
	v_pk_add_f32 v[106:107], v[106:107], v[180:181]
	v_cvt_pk_bf16_f32 v110, v102, v103
	v_pk_mul_f32 v[102:103], v[102:103], v[102:103]
	v_cvt_pk_bf16_f32 v111, v104, v105
	v_pk_mul_f32 v[104:105], v[104:105], v[104:105]
	v_add_f32_e32 v99, v102, v103
	s_waitcnt vmcnt(30)
	v_pk_add_f32 v[108:109], v[108:109], v[182:183]
	v_lshl_add_u64 v[112:113], v[118:119], 1, s[38:39]
	v_add_f32_e32 v99, v104, v99
	global_store_dwordx4 v[120:121], v[106:109], off offset:64
	global_store_dwordx2 v[112:113], v[110:111], off
	v_cvt_pk_bf16_f32 v110, v106, v107
	v_pk_mul_f32 v[106:107], v[106:107], v[106:107]
	v_add_f32_e32 v99, v105, v99
	v_add_f32_e32 v99, v106, v99
	v_cvt_pk_bf16_f32 v111, v108, v109
	v_pk_mul_f32 v[108:109], v[108:109], v[108:109]
	v_add_f32_e32 v99, v107, v99
	v_add_f32_e32 v99, v108, v99
	v_add_f32_e32 v99, v109, v99
	s_nop 1
	v_add_f32_dpp v99, v99, v99 quad_perm:[1,0,3,2] row_mask:0xf bank_mask:0xf
	s_nop 1
	v_add_f32_dpp v99, v99, v99 quad_perm:[2,3,0,1] row_mask:0xf bank_mask:0xf
	s_nop 1
	v_add_f32_dpp v99, v99, v99 row_half_mirror row_mask:0xf bank_mask:0xf
	s_nop 1
	v_add_f32_dpp v99, v99, v99 row_mirror row_mask:0xf bank_mask:0xf
	s_nop 1
	v_add_f32_dpp v99, v99, v99 row_bcast:15 row_mask:0xa bank_mask:0xf
	global_store_dwordx2 v[112:113], v[110:111], off offset:32
	s_and_saveexec_b64 s[8:9], vcc
	s_cbranch_execz .LBB0_1321
	v_lshl_add_u64 v[68:69], v[68:69], 4, s[6:7]
	global_store_dword v[68:69], v99, off
.LBB0_1321:
	s_or_b64 exec, exec, s[8:9]
	v_add_u32_e32 v68, 0xc00, v142
	s_waitcnt lgkmcnt(0)
	v_ashrrev_i32_e32 v100, 5, v68
	v_mul_lo_u32 v68, v100, s12
	v_add_u32_e32 v99, v101, v68
	v_add_u32_e32 v68, s15, v100
	v_ashrrev_i32_e32 v69, 31, v68
	v_lshlrev_b64 v[102:103], 10, v[68:69]
	v_lshl_add_u64 v[118:119], v[102:103], 0, v[66:67]
	v_lshl_add_u64 v[120:121], v[118:119], 2, s[18:19]
	ds_read_b128 v[102:105], v99
	s_waitcnt lgkmcnt(0)
	s_waitcnt vmcnt(33)
	v_pk_add_f32 v[102:103], v[102:103], v[184:185]
	s_waitcnt vmcnt(33)
	v_pk_add_f32 v[104:105], v[104:105], v[186:187]
	ds_read_b128 v[106:109], v99 offset:64
	global_store_dwordx4 v[120:121], v[102:105], off
	s_waitcnt lgkmcnt(0)
	s_waitcnt vmcnt(33)
	v_pk_add_f32 v[106:107], v[106:107], v[188:189]
	v_cvt_pk_bf16_f32 v110, v102, v103
	v_pk_mul_f32 v[102:103], v[102:103], v[102:103]
	v_cvt_pk_bf16_f32 v111, v104, v105
	v_pk_mul_f32 v[104:105], v[104:105], v[104:105]
	v_add_f32_e32 v102, v102, v103
	s_waitcnt vmcnt(33)
	v_pk_add_f32 v[108:109], v[108:109], v[190:191]
	v_lshl_add_u64 v[112:113], v[118:119], 1, s[38:39]
	v_add_f32_e32 v102, v104, v102
	global_store_dwordx4 v[120:121], v[106:109], off offset:64
	global_store_dwordx2 v[112:113], v[110:111], off
	v_cvt_pk_bf16_f32 v110, v106, v107
	v_pk_mul_f32 v[106:107], v[106:107], v[106:107]
	v_add_f32_e32 v102, v105, v102
	v_add_f32_e32 v102, v106, v102
	v_cvt_pk_bf16_f32 v111, v108, v109
	v_pk_mul_f32 v[108:109], v[108:109], v[108:109]
	v_add_f32_e32 v102, v107, v102
	v_add_f32_e32 v102, v108, v102
	v_add_f32_e32 v102, v109, v102
	s_nop 1
	v_add_f32_dpp v102, v102, v102 quad_perm:[1,0,3,2] row_mask:0xf bank_mask:0xf
	s_nop 1
	v_add_f32_dpp v102, v102, v102 quad_perm:[2,3,0,1] row_mask:0xf bank_mask:0xf
	s_nop 1
	v_add_f32_dpp v102, v102, v102 row_half_mirror row_mask:0xf bank_mask:0xf
	s_nop 1
	v_add_f32_dpp v102, v102, v102 row_mirror row_mask:0xf bank_mask:0xf
	s_nop 1
	v_add_f32_dpp v102, v102, v102 row_bcast:15 row_mask:0xa bank_mask:0xf
	global_store_dwordx2 v[112:113], v[110:111], off offset:32
	s_and_saveexec_b64 s[8:9], vcc
	s_cbranch_execz .LBB0_1323
	v_lshl_add_u64 v[68:69], v[68:69], 4, s[6:7]
	global_store_dword v[68:69], v102, off
.LBB0_1323:
	s_or_b64 exec, exec, s[8:9]
	v_add_u32_e32 v68, 0xe00, v142
	v_ashrrev_i32_e32 v102, 5, v68
	v_mul_lo_u32 v68, v102, s12
	v_add_u32_e32 v101, v101, v68
	v_add_u32_e32 v68, s15, v102
	v_ashrrev_i32_e32 v69, 31, v68
	v_lshlrev_b64 v[104:105], 10, v[68:69]
	v_lshl_add_u64 v[112:113], v[104:105], 0, v[66:67]
	v_lshl_add_u64 v[122:123], v[112:113], 2, s[18:19]
	ds_read_b128 v[104:107], v101
	v_lshl_add_u64 v[112:113], v[112:113], 1, s[38:39]
	s_waitcnt lgkmcnt(0)
	s_waitcnt vmcnt(36)
	v_pk_add_f32 v[104:105], v[104:105], v[192:193]
	s_waitcnt vmcnt(36)
	v_pk_add_f32 v[106:107], v[106:107], v[194:195]
	ds_read_b128 v[108:111], v101 offset:64
	global_store_dwordx4 v[122:123], v[104:107], off
	s_waitcnt lgkmcnt(0)
	s_waitcnt vmcnt(36)
	v_pk_add_f32 v[108:109], v[108:109], v[196:197]
	v_cvt_pk_bf16_f32 v118, v104, v105
	v_pk_mul_f32 v[104:105], v[104:105], v[104:105]
	v_cvt_pk_bf16_f32 v119, v106, v107
	v_pk_mul_f32 v[106:107], v[106:107], v[106:107]
	v_add_f32_e32 v103, v104, v105
	s_waitcnt vmcnt(36)
	v_pk_add_f32 v[110:111], v[110:111], v[198:199]
	v_add_f32_e32 v103, v106, v103
	global_store_dwordx4 v[122:123], v[108:111], off offset:64
	global_store_dwordx2 v[112:113], v[118:119], off
	v_cvt_pk_bf16_f32 v118, v108, v109
	v_pk_mul_f32 v[108:109], v[108:109], v[108:109]
	v_add_f32_e32 v103, v107, v103
	v_add_f32_e32 v103, v108, v103
	v_cvt_pk_bf16_f32 v119, v110, v111
	v_pk_mul_f32 v[110:111], v[110:111], v[110:111]
	v_add_f32_e32 v103, v109, v103
	v_add_f32_e32 v103, v110, v103
	v_add_f32_e32 v103, v111, v103
	s_nop 1
	v_add_f32_dpp v103, v103, v103 quad_perm:[1,0,3,2] row_mask:0xf bank_mask:0xf
	s_nop 1
	v_add_f32_dpp v103, v103, v103 quad_perm:[2,3,0,1] row_mask:0xf bank_mask:0xf
	s_nop 1
	v_add_f32_dpp v103, v103, v103 row_half_mirror row_mask:0xf bank_mask:0xf
	s_nop 1
	v_add_f32_dpp v103, v103, v103 row_mirror row_mask:0xf bank_mask:0xf
	s_nop 1
	v_add_f32_dpp v103, v103, v103 row_bcast:15 row_mask:0xa bank_mask:0xf
	global_store_dwordx2 v[112:113], v[118:119], off offset:32
	s_and_saveexec_b64 s[8:9], vcc
	s_cbranch_execz .LBB0_1325
	v_lshl_add_u64 v[68:69], v[68:69], 4, s[6:7]
	global_store_dword v[68:69], v103, off

.LBB0_1327:
	s_or_b64 exec, exec, s[8:9]
	v_add_u32_e32 v2, s14, v90
	v_ashrrev_i32_e32 v3, 31, v2
	s_waitcnt lgkmcnt(0)
	v_lshlrev_b64 v[4:5], 10, v[2:3]
	v_lshl_add_u64 v[16:17], v[4:5], 0, v[66:67]
	v_lshl_add_u64 v[18:19], v[16:17], 2, s[18:19]
	ds_read_b128 v[4:7], v89
	s_waitcnt lgkmcnt(0)
	s_waitcnt vmcnt(18)
	v_pk_add_f32 v[4:5], v[4:5], v[144:145]
	s_waitcnt vmcnt(18)
	v_pk_add_f32 v[6:7], v[6:7], v[146:147]
	ds_read_b128 v[8:11], v89 offset:64
	global_store_dwordx4 v[18:19], v[4:7], off
	s_waitcnt lgkmcnt(0)
	s_waitcnt vmcnt(18)
	v_pk_add_f32 v[8:9], v[8:9], v[148:149]
	v_cvt_pk_bf16_f32 v12, v4, v5
	v_pk_mul_f32 v[4:5], v[4:5], v[4:5]
	v_cvt_pk_bf16_f32 v13, v6, v7
	v_pk_mul_f32 v[6:7], v[6:7], v[6:7]
	v_add_f32_e32 v4, v4, v5
	s_waitcnt vmcnt(18)
	v_pk_add_f32 v[10:11], v[10:11], v[150:151]
	v_lshl_add_u64 v[14:15], v[16:17], 1, s[38:39]
	v_add_f32_e32 v4, v6, v4
	global_store_dwordx4 v[18:19], v[8:11], off offset:64
	global_store_dwordx2 v[14:15], v[12:13], off
	v_cvt_pk_bf16_f32 v12, v8, v9
	v_pk_mul_f32 v[8:9], v[8:9], v[8:9]
	v_add_f32_e32 v4, v7, v4
	v_add_f32_e32 v4, v8, v4
	v_cvt_pk_bf16_f32 v13, v10, v11
	v_pk_mul_f32 v[10:11], v[10:11], v[10:11]
	v_add_f32_e32 v4, v9, v4
	v_add_f32_e32 v4, v10, v4
	v_add_f32_e32 v4, v11, v4
	s_nop 1
	v_add_f32_dpp v4, v4, v4 quad_perm:[1,0,3,2] row_mask:0xf bank_mask:0xf
	s_nop 1
	v_add_f32_dpp v4, v4, v4 quad_perm:[2,3,0,1] row_mask:0xf bank_mask:0xf
	s_nop 1
	v_add_f32_dpp v4, v4, v4 row_half_mirror row_mask:0xf bank_mask:0xf
	s_nop 1
	v_add_f32_dpp v4, v4, v4 row_mirror row_mask:0xf bank_mask:0xf
	s_nop 1
	v_add_f32_dpp v4, v4, v4 row_bcast:15 row_mask:0xa bank_mask:0xf
	global_store_dwordx2 v[14:15], v[12:13], off offset:32
	s_and_saveexec_b64 s[8:9], vcc
	s_cbranch_execz .LBB0_1329
	v_lshl_add_u64 v[2:3], v[2:3], 4, s[6:7]
	global_store_dword v[2:3], v4, off
.LBB0_1329:
	s_or_b64 exec, exec, s[8:9]
	v_add_u32_e32 v2, s14, v92
	v_ashrrev_i32_e32 v3, 31, v2
	s_waitcnt lgkmcnt(0)
	v_lshlrev_b64 v[4:5], 10, v[2:3]
	v_lshl_add_u64 v[16:17], v[4:5], 0, v[66:67]
	v_lshl_add_u64 v[18:19], v[16:17], 2, s[18:19]
	ds_read_b128 v[4:7], v91
	s_waitcnt lgkmcnt(0)
	s_waitcnt vmcnt(21)
	v_pk_add_f32 v[4:5], v[4:5], v[152:153]
	s_waitcnt vmcnt(21)
	v_pk_add_f32 v[6:7], v[6:7], v[154:155]
	ds_read_b128 v[8:11], v91 offset:64
	global_store_dwordx4 v[18:19], v[4:7], off
	s_waitcnt lgkmcnt(0)
	s_waitcnt vmcnt(21)
	v_pk_add_f32 v[8:9], v[8:9], v[156:157]
	v_cvt_pk_bf16_f32 v12, v4, v5
	v_pk_mul_f32 v[4:5], v[4:5], v[4:5]
	v_cvt_pk_bf16_f32 v13, v6, v7
	v_pk_mul_f32 v[6:7], v[6:7], v[6:7]
	v_add_f32_e32 v4, v4, v5
	s_waitcnt vmcnt(21)
	v_pk_add_f32 v[10:11], v[10:11], v[158:159]
	v_lshl_add_u64 v[14:15], v[16:17], 1, s[38:39]
	v_add_f32_e32 v4, v6, v4
	global_store_dwordx4 v[18:19], v[8:11], off offset:64
	global_store_dwordx2 v[14:15], v[12:13], off
	v_cvt_pk_bf16_f32 v12, v8, v9
	v_pk_mul_f32 v[8:9], v[8:9], v[8:9]
	v_add_f32_e32 v4, v7, v4
	v_add_f32_e32 v4, v8, v4
	v_cvt_pk_bf16_f32 v13, v10, v11
	v_pk_mul_f32 v[10:11], v[10:11], v[10:11]
	v_add_f32_e32 v4, v9, v4
	v_add_f32_e32 v4, v10, v4
	v_add_f32_e32 v4, v11, v4
	s_nop 1
	v_add_f32_dpp v4, v4, v4 quad_perm:[1,0,3,2] row_mask:0xf bank_mask:0xf
	s_nop 1
	v_add_f32_dpp v4, v4, v4 quad_perm:[2,3,0,1] row_mask:0xf bank_mask:0xf
	s_nop 1
	v_add_f32_dpp v4, v4, v4 row_half_mirror row_mask:0xf bank_mask:0xf
	s_nop 1
	v_add_f32_dpp v4, v4, v4 row_mirror row_mask:0xf bank_mask:0xf
	s_nop 1
	v_add_f32_dpp v4, v4, v4 row_bcast:15 row_mask:0xa bank_mask:0xf
	global_store_dwordx2 v[14:15], v[12:13], off offset:32
	s_and_saveexec_b64 s[8:9], vcc
	s_cbranch_execz .LBB0_1331
	v_lshl_add_u64 v[2:3], v[2:3], 4, s[6:7]
	global_store_dword v[2:3], v4, off
.LBB0_1331:
	s_or_b64 exec, exec, s[8:9]
	v_add_u32_e32 v2, s14, v94
	v_ashrrev_i32_e32 v3, 31, v2
	s_waitcnt lgkmcnt(0)
	v_lshlrev_b64 v[4:5], 10, v[2:3]
	v_lshl_add_u64 v[16:17], v[4:5], 0, v[66:67]
	v_lshl_add_u64 v[18:19], v[16:17], 2, s[18:19]
	ds_read_b128 v[4:7], v93
	s_waitcnt lgkmcnt(0)
	s_waitcnt vmcnt(24)
	v_pk_add_f32 v[4:5], v[4:5], v[160:161]
	s_waitcnt vmcnt(24)
	v_pk_add_f32 v[6:7], v[6:7], v[162:163]
	ds_read_b128 v[8:11], v93 offset:64
	global_store_dwordx4 v[18:19], v[4:7], off
	s_waitcnt lgkmcnt(0)
	s_waitcnt vmcnt(24)
	v_pk_add_f32 v[8:9], v[8:9], v[164:165]
	v_cvt_pk_bf16_f32 v12, v4, v5
	v_pk_mul_f32 v[4:5], v[4:5], v[4:5]
	v_cvt_pk_bf16_f32 v13, v6, v7
	v_pk_mul_f32 v[6:7], v[6:7], v[6:7]
	v_add_f32_e32 v4, v4, v5
	s_waitcnt vmcnt(24)
	v_pk_add_f32 v[10:11], v[10:11], v[166:167]
	v_lshl_add_u64 v[14:15], v[16:17], 1, s[38:39]
	v_add_f32_e32 v4, v6, v4
	global_store_dwordx4 v[18:19], v[8:11], off offset:64
	global_store_dwordx2 v[14:15], v[12:13], off
	v_cvt_pk_bf16_f32 v12, v8, v9
	v_pk_mul_f32 v[8:9], v[8:9], v[8:9]
	v_add_f32_e32 v4, v7, v4
	v_add_f32_e32 v4, v8, v4
	v_cvt_pk_bf16_f32 v13, v10, v11
	v_pk_mul_f32 v[10:11], v[10:11], v[10:11]
	v_add_f32_e32 v4, v9, v4
	v_add_f32_e32 v4, v10, v4
	v_add_f32_e32 v4, v11, v4
	s_nop 1
	v_add_f32_dpp v4, v4, v4 quad_perm:[1,0,3,2] row_mask:0xf bank_mask:0xf
	s_nop 1
	v_add_f32_dpp v4, v4, v4 quad_perm:[2,3,0,1] row_mask:0xf bank_mask:0xf
	s_nop 1
	v_add_f32_dpp v4, v4, v4 row_half_mirror row_mask:0xf bank_mask:0xf
	s_nop 1
	v_add_f32_dpp v4, v4, v4 row_mirror row_mask:0xf bank_mask:0xf
	s_nop 1
	v_add_f32_dpp v4, v4, v4 row_bcast:15 row_mask:0xa bank_mask:0xf
	global_store_dwordx2 v[14:15], v[12:13], off offset:32
	s_and_saveexec_b64 s[8:9], vcc
	s_cbranch_execz .LBB0_1333
	v_lshl_add_u64 v[2:3], v[2:3], 4, s[6:7]
	global_store_dword v[2:3], v4, off
.LBB0_1333:
	s_or_b64 exec, exec, s[8:9]
	v_add_u32_e32 v2, s14, v96
	v_ashrrev_i32_e32 v3, 31, v2
	s_waitcnt lgkmcnt(0)
	v_lshlrev_b64 v[4:5], 10, v[2:3]
	v_lshl_add_u64 v[16:17], v[4:5], 0, v[66:67]
	v_lshl_add_u64 v[18:19], v[16:17], 2, s[18:19]
	ds_read_b128 v[4:7], v95
	s_waitcnt lgkmcnt(0)
	s_waitcnt vmcnt(27)
	v_pk_add_f32 v[4:5], v[4:5], v[168:169]
	s_waitcnt vmcnt(27)
	v_pk_add_f32 v[6:7], v[6:7], v[170:171]
	ds_read_b128 v[8:11], v95 offset:64
	global_store_dwordx4 v[18:19], v[4:7], off
	s_waitcnt lgkmcnt(0)
	s_waitcnt vmcnt(27)
	v_pk_add_f32 v[8:9], v[8:9], v[172:173]
	v_cvt_pk_bf16_f32 v12, v4, v5
	v_pk_mul_f32 v[4:5], v[4:5], v[4:5]
	v_cvt_pk_bf16_f32 v13, v6, v7
	v_pk_mul_f32 v[6:7], v[6:7], v[6:7]
	v_add_f32_e32 v4, v4, v5
	s_waitcnt vmcnt(27)
	v_pk_add_f32 v[10:11], v[10:11], v[174:175]
	v_lshl_add_u64 v[14:15], v[16:17], 1, s[38:39]
	v_add_f32_e32 v4, v6, v4
	global_store_dwordx4 v[18:19], v[8:11], off offset:64
	global_store_dwordx2 v[14:15], v[12:13], off
	v_cvt_pk_bf16_f32 v12, v8, v9
	v_pk_mul_f32 v[8:9], v[8:9], v[8:9]
	v_add_f32_e32 v4, v7, v4
	v_add_f32_e32 v4, v8, v4
	v_cvt_pk_bf16_f32 v13, v10, v11
	v_pk_mul_f32 v[10:11], v[10:11], v[10:11]
	v_add_f32_e32 v4, v9, v4
	v_add_f32_e32 v4, v10, v4
	v_add_f32_e32 v4, v11, v4
	s_nop 1
	v_add_f32_dpp v4, v4, v4 quad_perm:[1,0,3,2] row_mask:0xf bank_mask:0xf
	s_nop 1
	v_add_f32_dpp v4, v4, v4 quad_perm:[2,3,0,1] row_mask:0xf bank_mask:0xf
	s_nop 1
	v_add_f32_dpp v4, v4, v4 row_half_mirror row_mask:0xf bank_mask:0xf
	s_nop 1
	v_add_f32_dpp v4, v4, v4 row_mirror row_mask:0xf bank_mask:0xf
	s_nop 1
	v_add_f32_dpp v4, v4, v4 row_bcast:15 row_mask:0xa bank_mask:0xf
	global_store_dwordx2 v[14:15], v[12:13], off offset:32
	s_and_saveexec_b64 s[8:9], vcc
	s_cbranch_execz .LBB0_1335
	v_lshl_add_u64 v[2:3], v[2:3], 4, s[6:7]
	global_store_dword v[2:3], v4, off
.LBB0_1335:
	s_or_b64 exec, exec, s[8:9]
	v_add_u32_e32 v2, s14, v98
	v_ashrrev_i32_e32 v3, 31, v2
	s_waitcnt lgkmcnt(0)
	v_lshlrev_b64 v[4:5], 10, v[2:3]
	v_lshl_add_u64 v[16:17], v[4:5], 0, v[66:67]
	v_lshl_add_u64 v[18:19], v[16:17], 2, s[18:19]
	ds_read_b128 v[4:7], v97
	s_waitcnt lgkmcnt(0)
	s_waitcnt vmcnt(30)
	v_pk_add_f32 v[4:5], v[4:5], v[176:177]
	s_waitcnt vmcnt(30)
	v_pk_add_f32 v[6:7], v[6:7], v[178:179]
	ds_read_b128 v[8:11], v97 offset:64
	global_store_dwordx4 v[18:19], v[4:7], off
	s_waitcnt lgkmcnt(0)
	s_waitcnt vmcnt(30)
	v_pk_add_f32 v[8:9], v[8:9], v[180:181]
	v_cvt_pk_bf16_f32 v12, v4, v5
	v_pk_mul_f32 v[4:5], v[4:5], v[4:5]
	v_cvt_pk_bf16_f32 v13, v6, v7
	v_pk_mul_f32 v[6:7], v[6:7], v[6:7]
	v_add_f32_e32 v4, v4, v5
	s_waitcnt vmcnt(30)
	v_pk_add_f32 v[10:11], v[10:11], v[182:183]
	v_lshl_add_u64 v[14:15], v[16:17], 1, s[38:39]
	v_add_f32_e32 v4, v6, v4
	global_store_dwordx4 v[18:19], v[8:11], off offset:64
	global_store_dwordx2 v[14:15], v[12:13], off
	v_cvt_pk_bf16_f32 v12, v8, v9
	v_pk_mul_f32 v[8:9], v[8:9], v[8:9]
	v_add_f32_e32 v4, v7, v4
	v_add_f32_e32 v4, v8, v4
	v_cvt_pk_bf16_f32 v13, v10, v11
	v_pk_mul_f32 v[10:11], v[10:11], v[10:11]
	v_add_f32_e32 v4, v9, v4
	v_add_f32_e32 v4, v10, v4
	v_add_f32_e32 v4, v11, v4
	s_nop 1
	v_add_f32_dpp v4, v4, v4 quad_perm:[1,0,3,2] row_mask:0xf bank_mask:0xf
	s_nop 1
	v_add_f32_dpp v4, v4, v4 quad_perm:[2,3,0,1] row_mask:0xf bank_mask:0xf
	s_nop 1
	v_add_f32_dpp v4, v4, v4 row_half_mirror row_mask:0xf bank_mask:0xf
	s_nop 1
	v_add_f32_dpp v4, v4, v4 row_mirror row_mask:0xf bank_mask:0xf
	s_nop 1
	v_add_f32_dpp v4, v4, v4 row_bcast:15 row_mask:0xa bank_mask:0xf
	global_store_dwordx2 v[14:15], v[12:13], off offset:32
	s_and_saveexec_b64 s[8:9], vcc
	s_cbranch_execz .LBB0_1337
	v_lshl_add_u64 v[2:3], v[2:3], 4, s[6:7]
	global_store_dword v[2:3], v4, off
.LBB0_1337:
	s_or_b64 exec, exec, s[8:9]
	v_add_u32_e32 v2, s14, v100
	v_ashrrev_i32_e32 v3, 31, v2
	s_waitcnt lgkmcnt(0)
	v_lshlrev_b64 v[4:5], 10, v[2:3]
	v_lshl_add_u64 v[16:17], v[4:5], 0, v[66:67]
	v_lshl_add_u64 v[18:19], v[16:17], 2, s[18:19]
	ds_read_b128 v[4:7], v99
	s_waitcnt lgkmcnt(0)
	s_waitcnt vmcnt(33)
	v_pk_add_f32 v[4:5], v[4:5], v[184:185]
	s_waitcnt vmcnt(33)
	v_pk_add_f32 v[6:7], v[6:7], v[186:187]
	ds_read_b128 v[8:11], v99 offset:64
	global_store_dwordx4 v[18:19], v[4:7], off
	s_waitcnt lgkmcnt(0)
	s_waitcnt vmcnt(33)
	v_pk_add_f32 v[8:9], v[8:9], v[188:189]
	v_cvt_pk_bf16_f32 v12, v4, v5
	v_pk_mul_f32 v[4:5], v[4:5], v[4:5]
	v_cvt_pk_bf16_f32 v13, v6, v7
	v_pk_mul_f32 v[6:7], v[6:7], v[6:7]
	v_add_f32_e32 v4, v4, v5
	s_waitcnt vmcnt(33)
	v_pk_add_f32 v[10:11], v[10:11], v[190:191]
	v_lshl_add_u64 v[14:15], v[16:17], 1, s[38:39]
	v_add_f32_e32 v4, v6, v4
	global_store_dwordx4 v[18:19], v[8:11], off offset:64
	global_store_dwordx2 v[14:15], v[12:13], off
	v_cvt_pk_bf16_f32 v12, v8, v9
	v_pk_mul_f32 v[8:9], v[8:9], v[8:9]
	v_add_f32_e32 v4, v7, v4
	v_add_f32_e32 v4, v8, v4
	v_cvt_pk_bf16_f32 v13, v10, v11
	v_pk_mul_f32 v[10:11], v[10:11], v[10:11]
	v_add_f32_e32 v4, v9, v4
	v_add_f32_e32 v4, v10, v4
	v_add_f32_e32 v4, v11, v4
	s_nop 1
	v_add_f32_dpp v4, v4, v4 quad_perm:[1,0,3,2] row_mask:0xf bank_mask:0xf
	s_nop 1
	v_add_f32_dpp v4, v4, v4 quad_perm:[2,3,0,1] row_mask:0xf bank_mask:0xf
	s_nop 1
	v_add_f32_dpp v4, v4, v4 row_half_mirror row_mask:0xf bank_mask:0xf
	s_nop 1
	v_add_f32_dpp v4, v4, v4 row_mirror row_mask:0xf bank_mask:0xf
	s_nop 1
	v_add_f32_dpp v4, v4, v4 row_bcast:15 row_mask:0xa bank_mask:0xf
	global_store_dwordx2 v[14:15], v[12:13], off offset:32
	s_and_saveexec_b64 s[8:9], vcc
	s_cbranch_execz .LBB0_1339
	v_lshl_add_u64 v[2:3], v[2:3], 4, s[6:7]
	global_store_dword v[2:3], v4, off
